# baseline (speedup 1.0000x reference)
.LBB0_109:
	s_lshl_b32 s62, s86, 3
	v_cvt_f32_u32_e32 v2, s62
	s_sub_i32 s65, 0, s62
	s_abs_i32 s63, s85
	s_ashr_i32 s64, s85, 31
	v_rcp_iflag_f32_e32 v2, v2
	v_bfe_i32 v5, v171, 27, 1
	v_lshlrev_b32_e32 v169, 4, v171
	v_lshrrev_b32_e32 v5, 22, v5
	v_mul_f32_e32 v2, 0x4f7ffffe, v2
	v_cvt_u32_f32_e32 v2, v2
	v_add_u32_e32 v5, v169, v5
	v_and_b32_e32 v5, 0xfffffc00, v5
	v_sub_u32_e32 v5, v169, v5
	v_readfirstlane_b32 s68, v2
	s_mul_i32 s65, s65, s68
	s_mul_hi_u32 s65, s68, s65
	s_add_i32 s68, s68, s65
	s_mul_hi_u32 s65, s63, s68
	s_mul_i32 s68, s65, s62
	s_sub_i32 s63, s63, s68
	s_add_i32 s69, s65, 1
	s_sub_i32 s68, s63, s62
	s_cmp_ge_u32 s63, s62
	s_cselect_b32 s65, s69, s65
	s_cselect_b32 s63, s68, s63
	s_add_i32 s68, s65, 1
	s_cmp_ge_u32 s63, s62
	s_cselect_b32 s63, s68, s65
	s_xor_b32 s65, s63, s64
	s_sub_i32 s70, s65, s64
	v_lshrrev_b32_e32 v6, 4, v5
	s_mul_i32 s62, s70, s62
	v_bitop3_b32 v5, v6, v5, 32 bitop3:0x6c
	s_sub_i32 s62, s85, s62
	v_ashrrev_i32_e32 v6, 31, v5
	s_ashr_i32 s89, s62, 3
	s_lshl_b32 s62, s62, 8
	v_lshrrev_b32_e32 v6, 26, v6
	s_and_b32 s71, s62, 0x700
	s_lshl_b32 s62, s89, 8
	v_ashrrev_i32_e32 v2, 31, v171
	v_add_u32_e32 v6, v5, v6
	v_lshrrev_b32_e32 v2, 26, v2
	v_ashrrev_i32_e32 v133, 6, v6
	v_and_b32_e32 v6, 0xc0, v6
	s_ashr_i32 s63, s62, 31
	v_and_b32_e32 v3, 15, v0
	v_and_b32_e32 v4, 48, v0
	v_add_u32_e32 v2, v171, v2
	v_sub_u32_e32 v5, v5, v6
	v_and_b32_e32 v6, 32, v0
	v_lshlrev_b32_e32 v10, 2, v0
	s_lshl_b64 s[72:73], s[62:63], 6
	v_lshlrev_b32_e32 v0, 6, v0
	s_lshl_b32 s63, s65, 11
	v_ashrrev_i32_e32 v131, 6, v2
	v_lshlrev_b32_e32 v3, 6, v3
	v_and_b32_e32 v10, 32, v10
	v_and_b32_e32 v0, 0x3c0, v0
	s_or_b32 s63, s63, s71
	s_lshl_b32 s64, s64, 11
	v_or_b32_e32 v9, v3, v4
	v_bitop3_b32 v3, v3, v10, v4 bitop3:0x36
	v_bitop3_b32 v4, v0, v10, v4 bitop3:0x36
	s_sub_i32 s64, s63, s64
	v_lshlrev_b32_e32 v0, 15, v131
	s_ashr_i32 s65, s64, 31
	v_and_b32_e32 v0, 0xffff0000, v0
	v_ashrrev_i16_sdwa v5, v167, sext(v5) dst_sel:DWORD dst_unused:UNUSED_PAD src0_sel:DWORD src1_sel:BYTE_0
	s_lshl_b64 s[64:65], s[64:65], 12
	v_lshl_add_u32 v0, v133, 12, v0
	v_bfe_i32 v134, v5, 0, 16
	v_and_or_b32 v0, v2, 64, v0
	s_add_u32 s64, s54, s64
	s_waitcnt vmcnt(0)
	v_lshl_add_u32 v164, v134, 1, v0
	s_addc_u32 s65, s55, s65
	v_lshlrev_b32_e32 v14, 13, v1
	v_lshl_add_u64 v[0:1], s[64:65], 0, v[164:165]
	s_mul_i32 s64, s4, 0x1800
	s_mul_hi_u32 s63, s4, 0x1800
	s_add_u32 s64, s64, s72
	s_addc_u32 s63, s63, s73
	s_add_u32 s64, s66, s64
	v_bfe_i32 v7, v171, 6, 1
	s_addc_u32 s65, s67, s63
	s_lshl_b64 s[68:69], s[4:5], 12
	v_and_b32_e32 v7, s4, v7
	v_lshrrev_b32_e32 v8, 7, v171
	s_add_u32 s4, s68, s72
	v_add_lshl_u32 v7, v7, v8, 10
	v_lshlrev_b32_e32 v8, 6, v171
	s_addc_u32 s63, s69, s73
	v_and_b32_e32 v5, 0x3f0, v169
	v_and_b32_e32 v8, 0x3000, v8
	v_bitop3_b32 v11, v9, s77, v10 bitop3:0xde
	v_bitop3_b32 v12, v9, s78, v10 bitop3:0xde
	v_bitop3_b32 v13, v9, s79, v10 bitop3:0xde
	v_bitop3_b32 v9, v9, s80, v10 bitop3:0xde
	v_or_b32_e32 v10, 0x800, v14
	v_or_b32_e32 v15, 0x1000, v14
	s_waitcnt vmcnt(0)
	v_or_b32_e32 v16, 0x1800, v14
	v_lshl_add_u64 v[128:129], v[0:1], 0, s[20:21]
	s_add_u32 s66, s66, s4
	v_mov_b32_e32 v0, 0
	v_bitop3_b32 v164, v5, v7, v6 bitop3:0xde
	s_addc_u32 s67, s67, s63
	s_mov_b32 s4, -2
	v_add_u32_e32 v138, v11, v8
	v_add_u32_e32 v192, v3, v14
	v_add_u32_e32 v191, v4, v10
	v_add_u32_e32 v190, v4, v15
	v_add_u32_e32 v189, v4, v16
	v_add_u32_e32 v137, 0xc000, v169
	v_add_u32_e32 v136, 0xe000, v169
	v_add_u32_e32 v135, v12, v8
	v_add_u32_e32 v188, 0x10000, v169
	v_add_u32_e32 v187, 0x12000, v169
	v_add_u32_e32 v186, 0x2000, v169
	v_add_u32_e32 v185, 0x14000, v169
	v_add_u32_e32 v184, 0x16000, v169
	v_add_u32_e32 v130, v13, v8
	v_add_u32_e32 v183, 0x4000, v169
	v_add_u32_e32 v182, 0x6000, v169
	v_add_u32_e32 v132, v9, v8
	v_add_u32_e32 v181, 0x18000, v169
	v_add_u32_e32 v180, 0x1a000, v169
	v_add_u32_e32 v179, 0x8000, v169
	v_add_u32_e32 v177, 0xa000, v169
	v_add_u32_e32 v175, 0x1c000, v169
	v_add_u32_e32 v173, 0x1e000, v169
	v_mov_b32_e32 v1, v0
	v_mov_b32_e32 v2, v0
	v_mov_b32_e32 v3, v0
	v_mov_b32_e32 v4, v0
	v_mov_b32_e32 v5, v0
	v_mov_b32_e32 v6, v0
	v_mov_b32_e32 v7, v0
	v_mov_b32_e32 v8, v0
	v_mov_b32_e32 v9, v0
	v_mov_b32_e32 v10, v0
	v_mov_b32_e32 v11, v0
	v_mov_b32_e32 v12, v0
	v_mov_b32_e32 v13, v0
	v_mov_b32_e32 v14, v0
	v_mov_b32_e32 v15, v0
	v_mov_b32_e32 v16, v0
	v_mov_b32_e32 v17, v0
	v_mov_b32_e32 v18, v0
	v_mov_b32_e32 v19, v0
	v_mov_b32_e32 v20, v0
	v_mov_b32_e32 v21, v0
	v_mov_b32_e32 v22, v0
	v_mov_b32_e32 v23, v0
	v_mov_b32_e32 v24, v0
	v_mov_b32_e32 v25, v0
	v_mov_b32_e32 v26, v0
	v_mov_b32_e32 v27, v0
	v_mov_b32_e32 v28, v0
	v_mov_b32_e32 v29, v0
	v_mov_b32_e32 v30, v0
	v_mov_b32_e32 v31, v0
	v_mov_b32_e32 v32, v0
	v_mov_b32_e32 v33, v0
	v_mov_b32_e32 v34, v0
	v_mov_b32_e32 v35, v0
	v_mov_b32_e32 v36, v0
	v_mov_b32_e32 v37, v0
	v_mov_b32_e32 v38, v0
	v_mov_b32_e32 v39, v0
	v_mov_b32_e32 v40, v0
	v_mov_b32_e32 v41, v0
	v_mov_b32_e32 v42, v0
	v_mov_b32_e32 v43, v0
	v_mov_b32_e32 v44, v0
	v_mov_b32_e32 v45, v0
	v_mov_b32_e32 v46, v0
	v_mov_b32_e32 v47, v0
	v_mov_b32_e32 v48, v0
	v_mov_b32_e32 v49, v0
	v_mov_b32_e32 v50, v0
	v_mov_b32_e32 v51, v0
	v_mov_b32_e32 v52, v0
	v_mov_b32_e32 v53, v0
	v_mov_b32_e32 v54, v0
	v_mov_b32_e32 v55, v0
	v_mov_b32_e32 v56, v0
	v_mov_b32_e32 v57, v0
	v_mov_b32_e32 v58, v0
	v_mov_b32_e32 v59, v0
	v_mov_b32_e32 v60, v0
	v_mov_b32_e32 v61, v0
	v_mov_b32_e32 v62, v0
	v_mov_b32_e32 v63, v0
	v_mov_b32_e32 v64, v0
	v_mov_b32_e32 v65, v0
	v_mov_b32_e32 v66, v0
	v_mov_b32_e32 v67, v0
	v_mov_b32_e32 v68, v0
	v_mov_b32_e32 v69, v0
	v_mov_b32_e32 v70, v0
	v_mov_b32_e32 v71, v0
	v_mov_b32_e32 v72, v0
	v_mov_b32_e32 v73, v0
	v_mov_b32_e32 v74, v0
	v_mov_b32_e32 v75, v0
	v_mov_b32_e32 v76, v0
	v_mov_b32_e32 v77, v0
	v_mov_b32_e32 v78, v0
	v_mov_b32_e32 v79, v0
	v_mov_b32_e32 v80, v0
	v_mov_b32_e32 v81, v0
	v_mov_b32_e32 v82, v0
	v_mov_b32_e32 v83, v0
	v_mov_b32_e32 v84, v0
	v_mov_b32_e32 v85, v0
	v_mov_b32_e32 v86, v0
	v_mov_b32_e32 v87, v0
	v_mov_b32_e32 v88, v0
	v_mov_b32_e32 v89, v0
	v_mov_b32_e32 v90, v0
	v_mov_b32_e32 v91, v0
	v_mov_b32_e32 v92, v0
	v_mov_b32_e32 v93, v0
	v_mov_b32_e32 v94, v0
	v_mov_b32_e32 v95, v0
	v_mov_b32_e32 v96, v0
	v_mov_b32_e32 v97, v0
	v_mov_b32_e32 v98, v0
	v_mov_b32_e32 v99, v0
	v_mov_b32_e32 v100, v0
	v_mov_b32_e32 v101, v0
	v_mov_b32_e32 v102, v0
	v_mov_b32_e32 v103, v0
	v_mov_b32_e32 v104, v0
	v_mov_b32_e32 v105, v0
	v_mov_b32_e32 v106, v0
	v_mov_b32_e32 v107, v0
	v_mov_b32_e32 v108, v0
	v_mov_b32_e32 v109, v0
	v_mov_b32_e32 v110, v0
	v_mov_b32_e32 v111, v0
	v_mov_b32_e32 v112, v0
	v_mov_b32_e32 v113, v0
	v_mov_b32_e32 v114, v0
	v_mov_b32_e32 v115, v0
	v_mov_b32_e32 v116, v0
	v_mov_b32_e32 v117, v0
	v_mov_b32_e32 v118, v0
	v_mov_b32_e32 v119, v0
	v_mov_b32_e32 v120, v0
	v_mov_b32_e32 v121, v0
	v_mov_b32_e32 v122, v0
	v_mov_b32_e32 v123, v0
	v_mov_b32_e32 v124, v0
	v_mov_b32_e32 v125, v0
	v_mov_b32_e32 v126, v0
	v_mov_b32_e32 v127, v0
	s_barrier
	v_readfirstlane_b32 s63, v137
	v_lshl_add_u64 v[142:143], v[128:129], 0, s[22:23]
	s_mov_b32 m0, s63
	v_readfirstlane_b32 s63, v136
	global_load_lds_dwordx4 v[142:143], off
	v_lshl_add_u64 v[142:143], v[128:129], 0, s[24:25]
	s_mov_b32 m0, s63
	s_nop 0
	global_load_lds_dwordx4 v[142:143], off
	ds_read_b128 v[140:143], v138
	ds_read_b128 v[144:147], v138 offset:1024
	ds_read_b128 v[148:151], v138 offset:2048
	ds_read_b128 v[152:155], v138 offset:3072
	ds_read_b128 v[156:159], v192
	ds_read_b128 v[160:163], v192 offset:1024
	ds_read_b128 v[194:197], v191
	ds_read_b128 v[198:201], v191 offset:1024
	ds_read_b128 v[202:205], v190
	ds_read_b128 v[206:209], v190 offset:1024
	ds_read_b128 v[210:213], v189
	ds_read_b128 v[214:217], v189 offset:1024
	s_waitcnt lgkmcnt(8)
	s_barrier
	s_branch .Lkent_110

.Lkent_110:
	s_waitcnt lgkmcnt(0)
	s_setprio 1
	s_waitcnt lgkmcnt(0)
	v_mfma_f32_16x16x32_bf16 v[124:127], v[140:143], v[156:159], v[124:127]
	v_mfma_f32_16x16x32_bf16 v[120:123], v[148:151], v[156:159], v[120:123]
	v_mfma_f32_16x16x32_bf16 v[116:119], v[140:143], v[194:197], v[116:119]
	v_mfma_f32_16x16x32_bf16 v[112:115], v[148:151], v[194:197], v[112:115]
	v_mfma_f32_16x16x32_bf16 v[108:111], v[140:143], v[202:205], v[108:111]
	v_mfma_f32_16x16x32_bf16 v[104:107], v[148:151], v[202:205], v[104:107]
	v_mfma_f32_16x16x32_bf16 v[100:103], v[140:143], v[210:213], v[100:103]
	v_mfma_f32_16x16x32_bf16 v[96:99], v[148:151], v[210:213], v[96:99]
	v_mfma_f32_16x16x32_bf16 v[124:127], v[144:147], v[160:163], v[124:127]
	v_mfma_f32_16x16x32_bf16 v[120:123], v[152:155], v[160:163], v[120:123]
	v_mfma_f32_16x16x32_bf16 v[116:119], v[144:147], v[198:201], v[116:119]
	v_mfma_f32_16x16x32_bf16 v[112:115], v[152:155], v[198:201], v[112:115]
	v_mfma_f32_16x16x32_bf16 v[108:111], v[144:147], v[206:209], v[108:111]
	v_mfma_f32_16x16x32_bf16 v[104:107], v[152:155], v[206:209], v[104:107]
	v_mfma_f32_16x16x32_bf16 v[100:103], v[144:147], v[214:217], v[100:103]
	v_mfma_f32_16x16x32_bf16 v[96:99], v[152:155], v[214:217], v[96:99]
	s_setprio 0
	s_barrier
	v_readfirstlane_b32 s63, v188
	v_lshl_add_u64 v[234:235], s[66:67], 0, v[164:165]
	s_mov_b32 m0, s63
	v_readfirstlane_b32 s63, v187
	ds_read_b128 v[218:221], v135
	ds_read_b128 v[222:225], v135 offset:1024
	ds_read_b128 v[226:229], v135 offset:2048
	ds_read_b128 v[230:233], v135 offset:3072
	global_load_lds_dwordx4 v[234:235], off
	v_lshl_add_u64 v[236:237], v[234:235], 0, s[10:11]
	s_mov_b32 m0, s63
	s_nop 0
	global_load_lds_dwordx4 v[236:237], off
	v_readfirstlane_b32 s63, v169
	v_lshl_add_u64 v[236:237], v[128:129], 0, s[26:27]
	s_mov_b32 m0, s63
	v_readfirstlane_b32 s63, v186
	global_load_lds_dwordx4 v[236:237], off
	v_lshl_add_u64 v[236:237], v[128:129], 0, s[28:29]
	s_mov_b32 m0, s63
	s_nop 0
	global_load_lds_dwordx4 v[236:237], off
	s_waitcnt vmcnt(12)
	s_barrier
	s_waitcnt lgkmcnt(0)
	s_setprio 1
	s_waitcnt lgkmcnt(0)
	v_mfma_f32_16x16x32_bf16 v[92:95], v[218:221], v[156:159], v[92:95]
	v_mfma_f32_16x16x32_bf16 v[88:91], v[226:229], v[156:159], v[88:91]
	v_mfma_f32_16x16x32_bf16 v[84:87], v[218:221], v[194:197], v[84:87]
	v_mfma_f32_16x16x32_bf16 v[80:83], v[226:229], v[194:197], v[80:83]
	v_mfma_f32_16x16x32_bf16 v[76:79], v[218:221], v[202:205], v[76:79]
	v_mfma_f32_16x16x32_bf16 v[72:75], v[226:229], v[202:205], v[72:75]
	v_mfma_f32_16x16x32_bf16 v[68:71], v[218:221], v[210:213], v[68:71]
	v_mfma_f32_16x16x32_bf16 v[64:67], v[226:229], v[210:213], v[64:67]
	v_mfma_f32_16x16x32_bf16 v[92:95], v[222:225], v[160:163], v[92:95]
	v_mfma_f32_16x16x32_bf16 v[88:91], v[230:233], v[160:163], v[88:91]
	v_mfma_f32_16x16x32_bf16 v[84:87], v[222:225], v[198:201], v[84:87]
	v_mfma_f32_16x16x32_bf16 v[80:83], v[230:233], v[198:201], v[80:83]
	v_mfma_f32_16x16x32_bf16 v[76:79], v[222:225], v[206:209], v[76:79]
	v_mfma_f32_16x16x32_bf16 v[72:75], v[230:233], v[206:209], v[72:75]
	v_mfma_f32_16x16x32_bf16 v[68:71], v[222:225], v[214:217], v[68:71]
	v_mfma_f32_16x16x32_bf16 v[64:67], v[230:233], v[214:217], v[64:67]
	s_setprio 0
	s_barrier
	ds_read_b128 v[156:159], v192 offset:16384
	ds_read_b128 v[160:163], v192 offset:17408
	ds_read_b128 v[194:197], v191 offset:16384
	ds_read_b128 v[198:201], v191 offset:17408
	ds_read_b128 v[202:205], v190 offset:16384
	ds_read_b128 v[206:209], v190 offset:17408
	ds_read_b128 v[210:213], v189 offset:16384
	ds_read_b128 v[214:217], v189 offset:17408
	v_readfirstlane_b32 s63, v185
	v_lshl_add_u64 v[236:237], v[234:235], 0, s[30:31]
	s_mov_b32 m0, s63
	v_readfirstlane_b32 s63, v184
	global_load_lds_dwordx4 v[236:237], off
	v_lshl_add_u64 v[236:237], v[234:235], 0, s[34:35]
	s_mov_b32 m0, s63
	s_nop 0
	global_load_lds_dwordx4 v[236:237], off
	s_barrier
	s_waitcnt lgkmcnt(0)
	s_setprio 1
	s_waitcnt lgkmcnt(0)
	v_mfma_f32_16x16x32_bf16 v[60:63], v[140:143], v[156:159], v[60:63]
	v_mfma_f32_16x16x32_bf16 v[56:59], v[148:151], v[156:159], v[56:59]
	v_mfma_f32_16x16x32_bf16 v[52:55], v[140:143], v[194:197], v[52:55]
	v_mfma_f32_16x16x32_bf16 v[48:51], v[148:151], v[194:197], v[48:51]
	v_mfma_f32_16x16x32_bf16 v[44:47], v[140:143], v[202:205], v[44:47]
	v_mfma_f32_16x16x32_bf16 v[40:43], v[148:151], v[202:205], v[40:43]
	v_mfma_f32_16x16x32_bf16 v[36:39], v[140:143], v[210:213], v[36:39]
	v_mfma_f32_16x16x32_bf16 v[32:35], v[148:151], v[210:213], v[32:35]
	v_mfma_f32_16x16x32_bf16 v[60:63], v[144:147], v[160:163], v[60:63]
	v_mfma_f32_16x16x32_bf16 v[56:59], v[152:155], v[160:163], v[56:59]
	v_mfma_f32_16x16x32_bf16 v[52:55], v[144:147], v[198:201], v[52:55]
	v_mfma_f32_16x16x32_bf16 v[48:51], v[152:155], v[198:201], v[48:51]
	v_mfma_f32_16x16x32_bf16 v[44:47], v[144:147], v[206:209], v[44:47]
	v_mfma_f32_16x16x32_bf16 v[40:43], v[152:155], v[206:209], v[40:43]
	v_mfma_f32_16x16x32_bf16 v[36:39], v[144:147], v[214:217], v[36:39]
	v_mfma_f32_16x16x32_bf16 v[32:35], v[152:155], v[214:217], v[32:35]
	s_setprio 0
	s_barrier
	v_readfirstlane_b32 s63, v183
	v_lshl_add_u64 v[142:143], v[128:129], 0, s[40:41]
	s_mov_b32 m0, s63
	v_readfirstlane_b32 s63, v182
	global_load_lds_dwordx4 v[142:143], off
	s_mov_b32 m0, s63
	s_nop 0
	global_load_lds_dwordx4 v[128:129], off
	s_waitcnt vmcnt(12)
	s_barrier
	s_setprio 1
	v_mfma_f32_16x16x32_bf16 v[28:31], v[218:221], v[156:159], v[28:31]
	v_mfma_f32_16x16x32_bf16 v[24:27], v[226:229], v[156:159], v[24:27]
	v_mfma_f32_16x16x32_bf16 v[20:23], v[218:221], v[194:197], v[20:23]
	v_mfma_f32_16x16x32_bf16 v[16:19], v[226:229], v[194:197], v[16:19]
	v_mfma_f32_16x16x32_bf16 v[12:15], v[218:221], v[202:205], v[12:15]
	v_mfma_f32_16x16x32_bf16 v[8:11], v[226:229], v[202:205], v[8:11]
	v_mfma_f32_16x16x32_bf16 v[4:7], v[218:221], v[210:213], v[4:7]
	v_mfma_f32_16x16x32_bf16 v[0:3], v[226:229], v[210:213], v[0:3]
	v_mfma_f32_16x16x32_bf16 v[28:31], v[222:225], v[160:163], v[28:31]
	v_mfma_f32_16x16x32_bf16 v[24:27], v[230:233], v[160:163], v[24:27]
	v_mfma_f32_16x16x32_bf16 v[20:23], v[222:225], v[198:201], v[20:23]
	v_mfma_f32_16x16x32_bf16 v[16:19], v[230:233], v[198:201], v[16:19]
	v_mfma_f32_16x16x32_bf16 v[12:15], v[222:225], v[206:209], v[12:15]
	v_mfma_f32_16x16x32_bf16 v[8:11], v[230:233], v[206:209], v[8:11]
	v_mfma_f32_16x16x32_bf16 v[4:7], v[222:225], v[214:217], v[4:7]
	v_mfma_f32_16x16x32_bf16 v[0:3], v[230:233], v[214:217], v[0:3]
	s_setprio 0
	s_barrier
	ds_read_b128 v[140:143], v130
	ds_read_b128 v[144:147], v130 offset:1024
	ds_read_b128 v[148:151], v130 offset:2048
	ds_read_b128 v[152:155], v130 offset:3072
	ds_read_b128 v[156:159], v192 offset:32768
	ds_read_b128 v[160:163], v192 offset:33792
	ds_read_b128 v[194:197], v191 offset:32768
	ds_read_b128 v[198:201], v191 offset:33792
	ds_read_b128 v[202:205], v190 offset:32768
	ds_read_b128 v[206:209], v190 offset:33792
	ds_read_b128 v[210:213], v189 offset:32768
	ds_read_b128 v[214:217], v189 offset:33792
	s_waitcnt lgkmcnt(8)
	s_waitcnt vmcnt(10)
	s_barrier
	s_waitcnt lgkmcnt(0)
	s_setprio 1
	s_waitcnt lgkmcnt(0)
	v_mfma_f32_16x16x32_bf16 v[124:127], v[140:143], v[156:159], v[124:127]
	v_mfma_f32_16x16x32_bf16 v[120:123], v[148:151], v[156:159], v[120:123]
	v_mfma_f32_16x16x32_bf16 v[116:119], v[140:143], v[194:197], v[116:119]
	v_mfma_f32_16x16x32_bf16 v[112:115], v[148:151], v[194:197], v[112:115]
	v_mfma_f32_16x16x32_bf16 v[108:111], v[140:143], v[202:205], v[108:111]
	v_mfma_f32_16x16x32_bf16 v[104:107], v[148:151], v[202:205], v[104:107]
	v_mfma_f32_16x16x32_bf16 v[100:103], v[140:143], v[210:213], v[100:103]
	v_mfma_f32_16x16x32_bf16 v[96:99], v[148:151], v[210:213], v[96:99]
	v_mfma_f32_16x16x32_bf16 v[124:127], v[144:147], v[160:163], v[124:127]
	v_mfma_f32_16x16x32_bf16 v[120:123], v[152:155], v[160:163], v[120:123]
	v_mfma_f32_16x16x32_bf16 v[116:119], v[144:147], v[198:201], v[116:119]
	v_mfma_f32_16x16x32_bf16 v[112:115], v[152:155], v[198:201], v[112:115]
	v_mfma_f32_16x16x32_bf16 v[108:111], v[144:147], v[206:209], v[108:111]
	v_mfma_f32_16x16x32_bf16 v[104:107], v[152:155], v[206:209], v[104:107]
	v_mfma_f32_16x16x32_bf16 v[100:103], v[144:147], v[214:217], v[100:103]
	v_mfma_f32_16x16x32_bf16 v[96:99], v[152:155], v[214:217], v[96:99]
	s_setprio 0
	s_barrier
	v_readfirstlane_b32 s63, v181
	v_lshl_add_u64 v[234:235], s[64:65], 0, v[164:165]
	s_mov_b32 m0, s63
	v_readfirstlane_b32 s63, v180
	ds_read_b128 v[218:221], v132
	ds_read_b128 v[222:225], v132 offset:1024
	ds_read_b128 v[226:229], v132 offset:2048
	ds_read_b128 v[230:233], v132 offset:3072
	global_load_lds_dwordx4 v[234:235], off
	v_lshl_add_u64 v[236:237], v[234:235], 0, s[10:11]
	s_mov_b32 m0, s63
	s_nop 0
	global_load_lds_dwordx4 v[236:237], off
	v_readfirstlane_b32 s63, v179
	v_lshl_add_u64 v[236:237], v[128:129], 0, s[44:45]
	s_mov_b32 m0, s63
	v_readfirstlane_b32 s63, v177
	global_load_lds_dwordx4 v[236:237], off
	v_lshl_add_u64 v[236:237], v[128:129], 0, s[46:47]
	s_mov_b32 m0, s63
	s_nop 0
	global_load_lds_dwordx4 v[236:237], off
	s_waitcnt vmcnt(12)
	s_barrier
	s_waitcnt lgkmcnt(0)
	s_setprio 1
	s_waitcnt lgkmcnt(0)
	v_mfma_f32_16x16x32_bf16 v[92:95], v[218:221], v[156:159], v[92:95]
	v_mfma_f32_16x16x32_bf16 v[88:91], v[226:229], v[156:159], v[88:91]
	v_mfma_f32_16x16x32_bf16 v[84:87], v[218:221], v[194:197], v[84:87]
	v_mfma_f32_16x16x32_bf16 v[80:83], v[226:229], v[194:197], v[80:83]
	v_mfma_f32_16x16x32_bf16 v[76:79], v[218:221], v[202:205], v[76:79]
	v_mfma_f32_16x16x32_bf16 v[72:75], v[226:229], v[202:205], v[72:75]
	v_mfma_f32_16x16x32_bf16 v[68:71], v[218:221], v[210:213], v[68:71]
	v_mfma_f32_16x16x32_bf16 v[64:67], v[226:229], v[210:213], v[64:67]
	v_mfma_f32_16x16x32_bf16 v[92:95], v[222:225], v[160:163], v[92:95]
	v_mfma_f32_16x16x32_bf16 v[88:91], v[230:233], v[160:163], v[88:91]
	v_mfma_f32_16x16x32_bf16 v[84:87], v[222:225], v[198:201], v[84:87]
	v_mfma_f32_16x16x32_bf16 v[80:83], v[230:233], v[198:201], v[80:83]
	v_mfma_f32_16x16x32_bf16 v[76:79], v[222:225], v[206:209], v[76:79]
	v_mfma_f32_16x16x32_bf16 v[72:75], v[230:233], v[206:209], v[72:75]
	v_mfma_f32_16x16x32_bf16 v[68:71], v[222:225], v[214:217], v[68:71]
	v_mfma_f32_16x16x32_bf16 v[64:67], v[230:233], v[214:217], v[64:67]
	s_setprio 0
	s_barrier
	ds_read_b128 v[156:159], v192 offset:49152
	ds_read_b128 v[160:163], v192 offset:50176
	ds_read_b128 v[194:197], v191 offset:49152
	ds_read_b128 v[198:201], v191 offset:50176
	ds_read_b128 v[202:205], v190 offset:49152
	ds_read_b128 v[206:209], v190 offset:50176
	ds_read_b128 v[210:213], v189 offset:49152
	ds_read_b128 v[214:217], v189 offset:50176
	v_readfirstlane_b32 s63, v175
	v_lshl_add_u64 v[236:237], v[234:235], 0, s[30:31]
	s_mov_b32 m0, s63
	v_readfirstlane_b32 s63, v173
	global_load_lds_dwordx4 v[236:237], off
	v_lshl_add_u64 v[236:237], v[234:235], 0, s[34:35]
	s_mov_b32 m0, s63
	s_nop 0
	global_load_lds_dwordx4 v[236:237], off
	s_barrier
	s_waitcnt lgkmcnt(0)
	s_setprio 1
	s_waitcnt lgkmcnt(0)
	v_mfma_f32_16x16x32_bf16 v[60:63], v[140:143], v[156:159], v[60:63]
	v_mfma_f32_16x16x32_bf16 v[56:59], v[148:151], v[156:159], v[56:59]
	v_mfma_f32_16x16x32_bf16 v[52:55], v[140:143], v[194:197], v[52:55]
	v_mfma_f32_16x16x32_bf16 v[48:51], v[148:151], v[194:197], v[48:51]
	v_mfma_f32_16x16x32_bf16 v[44:47], v[140:143], v[202:205], v[44:47]
	v_mfma_f32_16x16x32_bf16 v[40:43], v[148:151], v[202:205], v[40:43]
	v_mfma_f32_16x16x32_bf16 v[36:39], v[140:143], v[210:213], v[36:39]
	v_mfma_f32_16x16x32_bf16 v[32:35], v[148:151], v[210:213], v[32:35]
	v_mfma_f32_16x16x32_bf16 v[60:63], v[144:147], v[160:163], v[60:63]
	v_mfma_f32_16x16x32_bf16 v[56:59], v[152:155], v[160:163], v[56:59]
	v_mfma_f32_16x16x32_bf16 v[52:55], v[144:147], v[198:201], v[52:55]
	v_mfma_f32_16x16x32_bf16 v[48:51], v[152:155], v[198:201], v[48:51]
	v_mfma_f32_16x16x32_bf16 v[44:47], v[144:147], v[206:209], v[44:47]
	v_mfma_f32_16x16x32_bf16 v[40:43], v[152:155], v[206:209], v[40:43]
	v_mfma_f32_16x16x32_bf16 v[36:39], v[144:147], v[214:217], v[36:39]
	v_mfma_f32_16x16x32_bf16 v[32:35], v[152:155], v[214:217], v[32:35]
	s_setprio 0
	s_barrier
	v_lshl_add_u64 v[128:129], v[128:129], 0, s[56:57]
	v_readfirstlane_b32 s63, v137
	v_lshl_add_u64 v[142:143], v[128:129], 0, s[22:23]
	s_mov_b32 m0, s63
	v_readfirstlane_b32 s63, v136
	global_load_lds_dwordx4 v[142:143], off
	v_lshl_add_u64 v[142:143], v[128:129], 0, s[24:25]
	s_mov_b32 m0, s63
	s_nop 0
	global_load_lds_dwordx4 v[142:143], off
	s_waitcnt vmcnt(12)
	s_barrier
	s_setprio 1
	v_mfma_f32_16x16x32_bf16 v[28:31], v[218:221], v[156:159], v[28:31]
	v_mfma_f32_16x16x32_bf16 v[24:27], v[226:229], v[156:159], v[24:27]
	v_mfma_f32_16x16x32_bf16 v[20:23], v[218:221], v[194:197], v[20:23]
	v_mfma_f32_16x16x32_bf16 v[16:19], v[226:229], v[194:197], v[16:19]
	v_mfma_f32_16x16x32_bf16 v[12:15], v[218:221], v[202:205], v[12:15]
	v_mfma_f32_16x16x32_bf16 v[8:11], v[226:229], v[202:205], v[8:11]
	v_mfma_f32_16x16x32_bf16 v[4:7], v[218:221], v[210:213], v[4:7]
	v_mfma_f32_16x16x32_bf16 v[0:3], v[226:229], v[210:213], v[0:3]
	v_mfma_f32_16x16x32_bf16 v[28:31], v[222:225], v[160:163], v[28:31]
	v_mfma_f32_16x16x32_bf16 v[24:27], v[230:233], v[160:163], v[24:27]
	v_mfma_f32_16x16x32_bf16 v[20:23], v[222:225], v[198:201], v[20:23]
	v_mfma_f32_16x16x32_bf16 v[16:19], v[230:233], v[198:201], v[16:19]
	v_mfma_f32_16x16x32_bf16 v[12:15], v[222:225], v[206:209], v[12:15]
	v_mfma_f32_16x16x32_bf16 v[8:11], v[230:233], v[206:209], v[8:11]
	v_mfma_f32_16x16x32_bf16 v[4:7], v[222:225], v[214:217], v[4:7]
	v_mfma_f32_16x16x32_bf16 v[0:3], v[230:233], v[214:217], v[0:3]
	s_setprio 0
	s_add_i32 s4, s4, 2
	s_add_u32 s64, s64, s68
	s_addc_u32 s65, s65, s69
	s_add_u32 s66, s66, s68
	s_addc_u32 s67, s67, s69
	s_cmp_lt_u32 s4, 28
	s_barrier
	s_cbranch_scc1 .LBB0_110
	s_lshl_b32 s4, s70, 11
	s_or_b32 s64, s71, s4
	s_or_b32 s66, s64, 0x80
	v_lshlrev_b32_e32 v128, 3, v131
	v_lshlrev_b32_e32 v129, 5, v131
	s_ashr_i32 s67, s66, 31
	v_and_b32_e32 v128, 0xffff0, v128
	v_and_b32_e32 v129, 32, v129
	s_lshl_b64 s[66:67], s[66:67], 12
	v_add_u32_e32 v129, v129, v134
	v_add_lshl_u32 v128, v133, v128, 12
	s_add_u32 s66, s54, s66
	v_lshl_add_u32 v164, v129, 1, v128
	s_addc_u32 s67, s55, s67
	v_lshl_add_u64 v[128:129], s[66:67], 0, v[164:165]
	v_readfirstlane_b32 s4, v137
	ds_read_b128 v[140:143], v138
	ds_read_b128 v[144:147], v138 offset:1024
	ds_read_b128 v[148:151], v138 offset:2048
	ds_read_b128 v[152:155], v138 offset:3072
	ds_read_b128 v[156:159], v192
	ds_read_b128 v[160:163], v192 offset:1024
	ds_read_b128 v[194:197], v191
	ds_read_b128 v[198:201], v191 offset:1024
	ds_read_b128 v[202:205], v190
	ds_read_b128 v[206:209], v190 offset:1024
	ds_read_b128 v[210:213], v189
	ds_read_b128 v[214:217], v189 offset:1024
	v_lshl_add_u64 v[138:139], v[128:129], 0, s[58:59]
	s_mov_b32 m0, s4
	v_readfirstlane_b32 s4, v136
	global_load_lds_dwordx4 v[138:139], off
	v_lshl_add_u64 v[128:129], v[128:129], 0, s[60:61]
	s_mov_b32 m0, s4
	s_ashr_i32 s65, s64, 31
	global_load_lds_dwordx4 v[128:129], off
	s_waitcnt vmcnt(10)
	s_barrier
	s_waitcnt lgkmcnt(0)
	s_setprio 1
	s_waitcnt lgkmcnt(0)
	v_mfma_f32_16x16x32_bf16 v[124:127], v[140:143], v[156:159], v[124:127]
	v_mfma_f32_16x16x32_bf16 v[120:123], v[148:151], v[156:159], v[120:123]
	v_mfma_f32_16x16x32_bf16 v[116:119], v[140:143], v[194:197], v[116:119]
	v_mfma_f32_16x16x32_bf16 v[112:115], v[148:151], v[194:197], v[112:115]
	v_mfma_f32_16x16x32_bf16 v[108:111], v[140:143], v[202:205], v[108:111]
	v_mfma_f32_16x16x32_bf16 v[104:107], v[148:151], v[202:205], v[104:107]
	v_mfma_f32_16x16x32_bf16 v[100:103], v[140:143], v[210:213], v[100:103]
	v_mfma_f32_16x16x32_bf16 v[96:99], v[148:151], v[210:213], v[96:99]
	v_mfma_f32_16x16x32_bf16 v[124:127], v[144:147], v[160:163], v[124:127]
	v_mfma_f32_16x16x32_bf16 v[120:123], v[152:155], v[160:163], v[120:123]
	v_mfma_f32_16x16x32_bf16 v[116:119], v[144:147], v[198:201], v[116:119]
	v_mfma_f32_16x16x32_bf16 v[112:115], v[152:155], v[198:201], v[112:115]
	v_mfma_f32_16x16x32_bf16 v[108:111], v[144:147], v[206:209], v[108:111]
	v_mfma_f32_16x16x32_bf16 v[104:107], v[152:155], v[206:209], v[104:107]
	v_mfma_f32_16x16x32_bf16 v[100:103], v[144:147], v[214:217], v[100:103]
	v_mfma_f32_16x16x32_bf16 v[96:99], v[152:155], v[214:217], v[96:99]
	s_setprio 0
	s_barrier
	ds_read_b128 v[136:139], v135
	ds_read_b128 v[218:221], v135 offset:1024
	ds_read_b128 v[222:225], v135 offset:2048
	ds_read_b128 v[226:229], v135 offset:3072
	s_barrier
	s_waitcnt lgkmcnt(0)
	s_setprio 1
	s_waitcnt lgkmcnt(0)
	v_mfma_f32_16x16x32_bf16 v[92:95], v[136:139], v[156:159], v[92:95]
	v_mfma_f32_16x16x32_bf16 v[88:91], v[222:225], v[156:159], v[88:91]
	v_mfma_f32_16x16x32_bf16 v[84:87], v[136:139], v[194:197], v[84:87]
	v_mfma_f32_16x16x32_bf16 v[80:83], v[222:225], v[194:197], v[80:83]
	v_mfma_f32_16x16x32_bf16 v[76:79], v[136:139], v[202:205], v[76:79]
	v_mfma_f32_16x16x32_bf16 v[72:75], v[222:225], v[202:205], v[72:75]
	v_mfma_f32_16x16x32_bf16 v[68:71], v[136:139], v[210:213], v[68:71]
	v_mfma_f32_16x16x32_bf16 v[64:67], v[222:225], v[210:213], v[64:67]
	v_mfma_f32_16x16x32_bf16 v[156:159], v[218:221], v[160:163], v[92:95]
	v_mfma_f32_16x16x32_bf16 v[160:163], v[226:229], v[160:163], v[88:91]
	v_mfma_f32_16x16x32_bf16 v[194:197], v[218:221], v[198:201], v[84:87]
	v_mfma_f32_16x16x32_bf16 v[198:201], v[226:229], v[198:201], v[80:83]
	v_mfma_f32_16x16x32_bf16 v[202:205], v[218:221], v[206:209], v[76:79]
	v_mfma_f32_16x16x32_bf16 v[206:209], v[226:229], v[206:209], v[72:75]
	v_mfma_f32_16x16x32_bf16 v[210:213], v[218:221], v[214:217], v[68:71]
	v_mfma_f32_16x16x32_bf16 v[214:217], v[226:229], v[214:217], v[64:67]
	s_setprio 0
	s_barrier
	s_nop 0
	ds_read_b128 v[64:67], v192 offset:16384
	ds_read_b128 v[68:71], v192 offset:17408
	ds_read_b128 v[72:75], v191 offset:16384
	ds_read_b128 v[76:79], v191 offset:17408
	ds_read_b128 v[80:83], v190 offset:16384
	ds_read_b128 v[84:87], v190 offset:17408
	ds_read_b128 v[88:91], v189 offset:16384
	ds_read_b128 v[92:95], v189 offset:17408
	s_waitcnt vmcnt(4)
	s_barrier
	s_waitcnt lgkmcnt(0)
	s_setprio 1
	s_waitcnt lgkmcnt(0)
	v_mfma_f32_16x16x32_bf16 v[60:63], v[140:143], v[64:67], v[60:63]
	v_mfma_f32_16x16x32_bf16 v[56:59], v[148:151], v[64:67], v[56:59]
	v_mfma_f32_16x16x32_bf16 v[52:55], v[140:143], v[72:75], v[52:55]
	v_mfma_f32_16x16x32_bf16 v[48:51], v[148:151], v[72:75], v[48:51]
	v_mfma_f32_16x16x32_bf16 v[230:233], v[140:143], v[80:83], v[44:47]
	v_mfma_f32_16x16x32_bf16 v[234:237], v[148:151], v[80:83], v[40:43]
	v_mfma_f32_16x16x32_bf16 v[140:143], v[140:143], v[88:91], v[36:39]
	v_mfma_f32_16x16x32_bf16 v[148:151], v[148:151], v[88:91], v[32:35]
	v_mfma_f32_16x16x32_bf16 v[32:35], v[144:147], v[68:71], v[60:63]
	v_mfma_f32_16x16x32_bf16 v[36:39], v[152:155], v[68:71], v[56:59]
	v_mfma_f32_16x16x32_bf16 v[40:43], v[144:147], v[76:79], v[52:55]
	v_mfma_f32_16x16x32_bf16 v[44:47], v[152:155], v[76:79], v[48:51]
	v_mfma_f32_16x16x32_bf16 v[48:51], v[144:147], v[84:87], v[230:233]
	v_mfma_f32_16x16x32_bf16 v[52:55], v[152:155], v[84:87], v[234:237]
	v_mfma_f32_16x16x32_bf16 v[56:59], v[144:147], v[92:95], v[140:143]
	v_mfma_f32_16x16x32_bf16 v[60:63], v[152:155], v[92:95], v[148:151]
	s_setprio 0
	s_setprio 1
	v_mfma_f32_16x16x32_bf16 v[28:31], v[136:139], v[64:67], v[28:31]
	v_mfma_f32_16x16x32_bf16 v[24:27], v[222:225], v[64:67], v[24:27]
	v_mfma_f32_16x16x32_bf16 v[20:23], v[136:139], v[72:75], v[20:23]
	v_mfma_f32_16x16x32_bf16 v[64:67], v[222:225], v[72:75], v[16:19]
	v_mfma_f32_16x16x32_bf16 v[12:15], v[136:139], v[80:83], v[12:15]
	v_mfma_f32_16x16x32_bf16 v[8:11], v[222:225], v[80:83], v[8:11]
	v_mfma_f32_16x16x32_bf16 v[72:75], v[136:139], v[88:91], v[4:7]
	v_mfma_f32_16x16x32_bf16 v[80:83], v[222:225], v[88:91], v[0:3]
	v_mfma_f32_16x16x32_bf16 v[0:3], v[218:221], v[68:71], v[28:31]
	v_mfma_f32_16x16x32_bf16 v[4:7], v[226:229], v[68:71], v[24:27]
	v_mfma_f32_16x16x32_bf16 v[16:19], v[218:221], v[76:79], v[20:23]
	v_mfma_f32_16x16x32_bf16 v[20:23], v[226:229], v[76:79], v[64:67]
	v_mfma_f32_16x16x32_bf16 v[64:67], v[218:221], v[84:87], v[12:15]
	v_mfma_f32_16x16x32_bf16 v[68:71], v[226:229], v[84:87], v[8:11]
	v_mfma_f32_16x16x32_bf16 v[72:75], v[218:221], v[92:95], v[72:75]
	v_mfma_f32_16x16x32_bf16 v[76:79], v[226:229], v[92:95], v[80:83]
	s_setprio 0
	s_barrier
	ds_read_b128 v[12:15], v130
	ds_read_b128 v[8:11], v130 offset:1024
	ds_read_b128 v[24:27], v130 offset:2048
	ds_read_b128 v[80:83], v130 offset:3072
	ds_read_b128 v[140:143], v192 offset:32768
	ds_read_b128 v[148:151], v192 offset:33792
	ds_read_b128 v[218:221], v191 offset:32768
	ds_read_b128 v[222:225], v191 offset:33792
	ds_read_b128 v[226:229], v190 offset:32768
	ds_read_b128 v[230:233], v190 offset:33792
	ds_read_b128 v[234:237], v189 offset:32768
	ds_read_b128 v[238:241], v189 offset:33792
	s_waitcnt vmcnt(2)
	s_barrier
	s_waitcnt lgkmcnt(0)
	s_setprio 1
	s_waitcnt lgkmcnt(0)
	v_mfma_f32_16x16x32_bf16 v[28:31], v[12:15], v[140:143], v[124:127]
	v_mfma_f32_16x16x32_bf16 v[84:87], v[24:27], v[140:143], v[120:123]
	v_mfma_f32_16x16x32_bf16 v[88:91], v[12:15], v[218:221], v[116:119]
	v_mfma_f32_16x16x32_bf16 v[92:95], v[24:27], v[218:221], v[112:115]
	v_mfma_f32_16x16x32_bf16 v[108:111], v[12:15], v[226:229], v[108:111]
	v_mfma_f32_16x16x32_bf16 v[104:107], v[24:27], v[226:229], v[104:107]
	v_mfma_f32_16x16x32_bf16 v[100:103], v[12:15], v[234:237], v[100:103]
	v_mfma_f32_16x16x32_bf16 v[96:99], v[24:27], v[234:237], v[96:99]
	v_mfma_f32_16x16x32_bf16 v[152:155], v[8:11], v[148:151], v[28:31]
	v_mfma_f32_16x16x32_bf16 v[144:147], v[80:83], v[148:151], v[84:87]
	v_mfma_f32_16x16x32_bf16 v[136:139], v[8:11], v[222:225], v[88:91]
	v_mfma_f32_16x16x32_bf16 v[128:131], v[80:83], v[222:225], v[92:95]
	v_mfma_f32_16x16x32_bf16 v[120:123], v[8:11], v[230:233], v[108:111]
	v_mfma_f32_16x16x32_bf16 v[112:115], v[80:83], v[230:233], v[104:107]
	v_mfma_f32_16x16x32_bf16 v[104:107], v[8:11], v[238:241], v[100:103]
	v_mfma_f32_16x16x32_bf16 v[28:31], v[80:83], v[238:241], v[96:99]
	s_setprio 0
	s_barrier
	ds_read_b128 v[92:95], v132
	ds_read_b128 v[84:87], v132 offset:1024
	ds_read_b128 v[96:99], v132 offset:2048
	ds_read_b128 v[88:91], v132 offset:3072
	s_waitcnt vmcnt(0)
	s_barrier
	s_waitcnt lgkmcnt(0)
	s_setprio 1
	s_waitcnt lgkmcnt(0)
	v_mfma_f32_16x16x32_bf16 v[100:103], v[92:95], v[140:143], v[156:159]
	v_mfma_f32_16x16x32_bf16 v[108:111], v[96:99], v[140:143], v[160:163]
	v_mfma_f32_16x16x32_bf16 v[116:119], v[92:95], v[218:221], v[194:197]
	v_mfma_f32_16x16x32_bf16 v[124:127], v[96:99], v[218:221], v[198:201]
	v_mfma_f32_16x16x32_bf16 v[160:163], v[92:95], v[226:229], v[202:205]
	v_mfma_f32_16x16x32_bf16 v[194:197], v[96:99], v[226:229], v[206:209]
	v_mfma_f32_16x16x32_bf16 v[198:201], v[92:95], v[234:237], v[210:213]
	v_mfma_f32_16x16x32_bf16 v[202:205], v[96:99], v[234:237], v[214:217]
	v_mfma_f32_16x16x32_bf16 v[156:159], v[84:87], v[148:151], v[100:103]
	v_mfma_f32_16x16x32_bf16 v[148:151], v[88:91], v[148:151], v[108:111]
	v_mfma_f32_16x16x32_bf16 v[140:143], v[84:87], v[222:225], v[116:119]
	v_mfma_f32_16x16x32_bf16 v[132:135], v[88:91], v[222:225], v[124:127]
	v_mfma_f32_16x16x32_bf16 v[124:127], v[84:87], v[230:233], v[160:163]
	v_mfma_f32_16x16x32_bf16 v[116:119], v[88:91], v[230:233], v[194:197]
	v_mfma_f32_16x16x32_bf16 v[108:111], v[84:87], v[238:241], v[198:201]
	v_mfma_f32_16x16x32_bf16 v[100:103], v[88:91], v[238:241], v[202:205]
	s_setprio 0
	s_lshl_b64 s[66:67], s[64:65], 2
	s_barrier
	v_mbcnt_lo_u32_b32 v162, -1, 0
	v_mbcnt_hi_u32_b32 v162, -1, v162
	s_add_u32 s66, s87, s66
	v_add_u32_e32 v160, s76, v162
	s_addc_u32 s67, s88, s67
	v_and_b32_e32 v164, 0x100, v160
	v_and_b32_e32 v162, 15, v162
	v_lshl_add_u64 v[160:161], s[66:67], 0, v[164:165]
	v_lshlrev_b32_e32 v164, 2, v162
	v_lshl_add_u64 v[160:161], v[160:161], 0, v[164:165]
	global_load_dword v178, v[160:161], off
	global_load_dword v176, v[160:161], off offset:64
	global_load_dword v174, v[160:161], off offset:128
	global_load_dword v164, v[160:161], off offset:192
	global_load_dword v172, v[160:161], off offset:512
	global_load_dword v170, v[160:161], off offset:576
	global_load_dword v168, v[160:161], off offset:640
	global_load_dword v166, v[160:161], off offset:704
	v_mbcnt_lo_u32_b32 v194, -1, 0
	v_mbcnt_hi_u32_b32 v194, -1, v194
	s_mov_b64 s[66:67], -1
	v_add_u32_e32 v160, s76, v194
	v_bfe_u32 v161, v160, 8, 1
	v_ashrrev_i32_e32 v196, 6, v160
	v_bfe_u32 v160, v194, 4, 2
	v_and_b32_e32 v198, 3, v196
	v_and_b32_e32 v195, 15, v194
	s_cmp_gt_i32 s74, 1
	v_lshlrev_b32_e32 v193, 6, v161
	v_lshlrev_b32_e32 v197, 4, v160
	s_cbranch_scc0 .LBB0_113
	v_lshlrev_b32_e32 v161, 6, v198
	v_or3_b32 v160, v193, v195, s64
	v_or3_b32 v161, v161, v197, s62
	v_lshl_add_u32 v199, v160, 12, v161
	s_waitcnt vmcnt(0)
	v_mul_f32_e32 v160, v178, v178
	v_pk_mul_f32 v[200:201], v[152:153], v[160:161] op_sel_hi:[1,0]
	v_pk_mul_f32 v[162:163], v[154:155], v[160:161] op_sel_hi:[1,0]
	v_pk_mul_f32 v[202:203], v[158:159], v[160:161] op_sel_hi:[1,0]
	v_pk_mul_f32 v[204:205], v[156:157], v[160:161] op_sel_hi:[1,0]
	v_mul_f32_e32 v160, v144, v200
	v_mul_f32_e32 v161, v145, v201
	v_cvt_pk_bf16_f32 v160, v160, v161
	v_mul_f32_e32 v161, v146, v162
	v_mul_f32_e32 v162, v147, v163
	v_cvt_pk_bf16_f32 v161, v161, v162
	v_mul_f32_e32 v162, v148, v204
	v_mul_f32_e32 v163, v149, v205
	v_cvt_pk_bf16_f32 v162, v162, v163
	v_mul_f32_e32 v163, v150, v202
	v_mul_f32_e32 v200, v151, v203
	v_cvt_pk_bf16_f32 v163, v163, v200
	global_store_dwordx4 v199, v[160:163], s[6:7]
	v_add_u32_e32 v206, 0x10000, v199
	s_mov_b64 s[66:67], 0
	v_mul_f32_e32 v160, v176, v176
	v_pk_mul_f32 v[200:201], v[136:137], v[160:161] op_sel_hi:[1,0]
	v_pk_mul_f32 v[162:163], v[138:139], v[160:161] op_sel_hi:[1,0]
	v_pk_mul_f32 v[202:203], v[142:143], v[160:161] op_sel_hi:[1,0]
	v_pk_mul_f32 v[204:205], v[140:141], v[160:161] op_sel_hi:[1,0]
	v_mul_f32_e32 v160, v128, v200
	v_mul_f32_e32 v161, v129, v201
	v_cvt_pk_bf16_f32 v160, v160, v161
	v_mul_f32_e32 v161, v130, v162
	v_mul_f32_e32 v162, v131, v163
	v_cvt_pk_bf16_f32 v161, v161, v162
	v_mul_f32_e32 v162, v132, v204
	v_mul_f32_e32 v163, v133, v205
	v_cvt_pk_bf16_f32 v162, v162, v163
	v_mul_f32_e32 v163, v134, v202
	v_mul_f32_e32 v200, v135, v203
	v_cvt_pk_bf16_f32 v163, v163, v200
	global_store_dwordx4 v206, v[160:163], s[6:7]
	v_add_u32_e32 v206, 0x20000, v199
	v_add_u32_e32 v199, 0x30000, v199
	v_mul_f32_e32 v160, v174, v174
	v_pk_mul_f32 v[200:201], v[120:121], v[160:161] op_sel_hi:[1,0]
	v_pk_mul_f32 v[162:163], v[122:123], v[160:161] op_sel_hi:[1,0]
	v_pk_mul_f32 v[202:203], v[126:127], v[160:161] op_sel_hi:[1,0]
	v_pk_mul_f32 v[204:205], v[124:125], v[160:161] op_sel_hi:[1,0]
	v_mul_f32_e32 v160, v112, v200
	v_mul_f32_e32 v161, v113, v201
	v_cvt_pk_bf16_f32 v160, v160, v161
	v_mul_f32_e32 v161, v114, v162
	v_mul_f32_e32 v162, v115, v163
	v_cvt_pk_bf16_f32 v161, v161, v162
	v_mul_f32_e32 v162, v116, v204
	v_mul_f32_e32 v163, v117, v205
	v_cvt_pk_bf16_f32 v162, v162, v163
	v_mul_f32_e32 v163, v118, v202
	v_mul_f32_e32 v200, v119, v203
	v_cvt_pk_bf16_f32 v163, v163, v200
	global_store_dwordx4 v206, v[160:163], s[6:7]
	s_nop 1
	v_mul_f32_e32 v160, v164, v164
	v_pk_mul_f32 v[200:201], v[104:105], v[160:161] op_sel_hi:[1,0]
	v_pk_mul_f32 v[162:163], v[106:107], v[160:161] op_sel_hi:[1,0]
	v_pk_mul_f32 v[202:203], v[110:111], v[160:161] op_sel_hi:[1,0]
	v_pk_mul_f32 v[204:205], v[108:109], v[160:161] op_sel_hi:[1,0]
	v_mul_f32_e32 v160, v28, v200
	v_mul_f32_e32 v161, v29, v201
	v_cvt_pk_bf16_f32 v160, v160, v161
	v_mul_f32_e32 v161, v30, v162
	v_mul_f32_e32 v162, v31, v163
	v_cvt_pk_bf16_f32 v161, v161, v162
	v_mul_f32_e32 v162, v100, v204
	v_mul_f32_e32 v163, v101, v205
	v_cvt_pk_bf16_f32 v162, v162, v163
	v_mul_f32_e32 v163, v102, v202
	v_mul_f32_e32 v200, v103, v203
	v_cvt_pk_bf16_f32 v163, v163, v200

.LBB0_177:
	v_bfe_i32 v5, v136, 27, 1
	v_lshlrev_b32_e32 v135, 4, v136
	v_lshrrev_b32_e32 v5, 22, v5
	v_add_u32_e32 v5, v135, v5
	v_and_b32_e32 v5, 0xfffffc00, v5
	v_sub_u32_e32 v5, v135, v5
	v_lshrrev_b32_e32 v6, 4, v5
	v_bitop3_b32 v5, v6, v5, 32 bitop3:0x6c
	v_ashrrev_i32_e32 v6, 31, v5
	v_lshrrev_b32_e32 v6, 26, v6
	v_add_u32_e32 v6, v5, v6
	v_ashrrev_i32_e32 v157, 6, v6
	v_and_b32_e32 v6, 0xc0, v6
	v_sub_u32_e32 v5, v5, v6
	v_ashrrev_i16_sdwa v5, v134, sext(v5) dst_sel:DWORD dst_unused:UNUSED_PAD src0_sel:DWORD src1_sel:BYTE_0
	v_and_b32_e32 v2, 15, v0
	v_and_b32_e32 v3, 48, v0
	v_bfe_i32 v158, v5, 0, 16
	v_and_b32_e32 v5, 32, v0
	v_lshlrev_b32_e32 v8, 2, v0
	v_lshlrev_b32_e32 v0, 6, v0
	s_movk_i32 s65, 0x3f0
	v_lshlrev_b32_e32 v2, 6, v2
	v_and_b32_e32 v8, 32, v8
	v_and_b32_e32 v0, 0x3c0, v0
	v_ashrrev_i32_e32 v4, 31, v136
	v_bitop3_b32 v5, v135, v5, s65 bitop3:0x6c
	v_or_b32_e32 v7, v2, v3
	v_bitop3_b32 v2, v2, v8, v3 bitop3:0x36
	v_bitop3_b32 v3, v0, v8, v3 bitop3:0x36
	v_lshlrev_b32_e32 v0, 11, v136
	v_lshrrev_b32_e32 v4, 26, v4
	v_and_or_b32 v0, v0, s76, v5
	v_lshlrev_b32_e32 v5, 3, v136
	s_bfe_u32 s64, s85, 0x30003
	v_add_u32_e32 v4, v136, v4
	s_mov_b32 s65, 0x14000
	v_and_b32_e32 v5, 0xfffffc00, v5
	s_lshl_b32 s24, s64, 14
	v_ashrrev_i32_e32 v156, 6, v4
	v_bitop3_b32 v10, v7, s65, v8 bitop3:0xde
	s_mov_b32 s65, 0x1c000
	v_add_u32_e32 v128, v0, v5
	v_bitop3_b32 v9, v7, s74, v8 bitop3:0xde
	v_bitop3_b32 v11, v7, s75, v8 bitop3:0xde
	v_bitop3_b32 v7, v7, s65, v8 bitop3:0xde
	v_lshl_add_u64 v[130:131], s[24:25], 0, v[128:129]
	v_lshlrev_b32_e32 v0, 15, v156
	s_lshl_b32 s24, s85, 17
	s_and_b32 s65, s85, 7
	v_and_b32_e32 v0, 0xffff0000, v0
	s_and_b32 s24, s24, 0x1800000
	s_lshl_b32 s65, s65, 20
	v_lshl_add_u32 v0, v157, 12, v0
	s_or_b32 s24, s24, s65
	v_lshlrev_b32_e32 v6, 6, v136
	v_lshlrev_b32_e32 v1, 13, v1
	v_and_or_b32 v0, v4, 64, v0
	s_add_u32 s66, s24, s90
	v_and_b32_e32 v6, 0x3000, v6
	v_or_b32_e32 v8, 0x800, v1
	v_or_b32_e32 v12, 0x1000, v1
	v_or_b32_e32 v13, 0x1800, v1
	v_lshl_add_u32 v128, v158, 1, v0
	s_addc_u32 s67, 0, 0
	v_mov_b32_e32 v0, 0
	v_lshl_add_u64 v[132:133], s[66:67], 0, v[128:129]
	s_mov_b32 s24, -2
	v_add_u32_e32 v162, v9, v6
	v_add_u32_e32 v153, v2, v1
	v_add_u32_e32 v152, v3, v8
	v_add_u32_e32 v151, v3, v12
	v_add_u32_e32 v150, v3, v13
	v_add_u32_e32 v161, 0xc000, v135
	v_add_u32_e32 v160, 0xe000, v135
	v_add_u32_e32 v159, v10, v6
	v_add_u32_e32 v149, 0x10000, v135
	v_add_u32_e32 v148, 0x12000, v135
	v_add_u32_e32 v147, 0x2000, v135
	v_add_u32_e32 v146, 0x14000, v135
	v_add_u32_e32 v145, 0x16000, v135
	v_add_u32_e32 v155, v11, v6
	v_add_u32_e32 v144, 0x4000, v135
	v_add_u32_e32 v143, 0x6000, v135
	v_add_u32_e32 v154, v7, v6
	v_add_u32_e32 v142, 0x18000, v135
	v_add_u32_e32 v141, 0x1a000, v135
	v_add_u32_e32 v140, 0x8000, v135
	v_add_u32_e32 v139, 0xa000, v135
	v_add_u32_e32 v138, 0x1c000, v135
	v_add_u32_e32 v137, 0x1e000, v135
	v_mov_b32_e32 v1, v0
	v_mov_b32_e32 v2, v0
	v_mov_b32_e32 v3, v0
	v_mov_b32_e32 v4, v0
	v_mov_b32_e32 v5, v0
	v_mov_b32_e32 v6, v0
	v_mov_b32_e32 v7, v0
	v_mov_b32_e32 v8, v0
	v_mov_b32_e32 v9, v0
	v_mov_b32_e32 v10, v0
	v_mov_b32_e32 v11, v0
	v_mov_b32_e32 v12, v0
	v_mov_b32_e32 v13, v0
	v_mov_b32_e32 v14, v0
	v_mov_b32_e32 v15, v0
	v_mov_b32_e32 v16, v0
	v_mov_b32_e32 v17, v0
	v_mov_b32_e32 v18, v0
	v_mov_b32_e32 v19, v0
	v_mov_b32_e32 v20, v0
	v_mov_b32_e32 v21, v0
	v_mov_b32_e32 v22, v0
	v_mov_b32_e32 v23, v0
	v_mov_b32_e32 v24, v0
	v_mov_b32_e32 v25, v0
	v_mov_b32_e32 v26, v0
	v_mov_b32_e32 v27, v0
	v_mov_b32_e32 v28, v0
	v_mov_b32_e32 v29, v0
	v_mov_b32_e32 v30, v0
	v_mov_b32_e32 v31, v0
	v_mov_b32_e32 v32, v0
	v_mov_b32_e32 v33, v0
	v_mov_b32_e32 v34, v0
	v_mov_b32_e32 v35, v0
	v_mov_b32_e32 v36, v0
	v_mov_b32_e32 v37, v0
	v_mov_b32_e32 v38, v0
	v_mov_b32_e32 v39, v0
	v_mov_b32_e32 v40, v0
	v_mov_b32_e32 v41, v0
	v_mov_b32_e32 v42, v0
	v_mov_b32_e32 v43, v0
	v_mov_b32_e32 v44, v0
	v_mov_b32_e32 v45, v0
	v_mov_b32_e32 v46, v0
	v_mov_b32_e32 v47, v0
	v_mov_b32_e32 v48, v0
	v_mov_b32_e32 v49, v0
	v_mov_b32_e32 v50, v0
	v_mov_b32_e32 v51, v0
	v_mov_b32_e32 v52, v0
	v_mov_b32_e32 v53, v0
	v_mov_b32_e32 v54, v0
	v_mov_b32_e32 v55, v0
	v_mov_b32_e32 v56, v0
	v_mov_b32_e32 v57, v0
	v_mov_b32_e32 v58, v0
	v_mov_b32_e32 v59, v0
	v_mov_b32_e32 v60, v0
	v_mov_b32_e32 v61, v0
	v_mov_b32_e32 v62, v0
	v_mov_b32_e32 v63, v0
	v_mov_b32_e32 v64, v0
	v_mov_b32_e32 v65, v0
	v_mov_b32_e32 v66, v0
	v_mov_b32_e32 v67, v0
	v_mov_b32_e32 v68, v0
	v_mov_b32_e32 v69, v0
	v_mov_b32_e32 v70, v0
	v_mov_b32_e32 v71, v0
	v_mov_b32_e32 v72, v0
	v_mov_b32_e32 v73, v0
	v_mov_b32_e32 v74, v0
	v_mov_b32_e32 v75, v0
	v_mov_b32_e32 v76, v0
	v_mov_b32_e32 v77, v0
	v_mov_b32_e32 v78, v0
	v_mov_b32_e32 v79, v0
	v_mov_b32_e32 v80, v0
	v_mov_b32_e32 v81, v0
	v_mov_b32_e32 v82, v0
	v_mov_b32_e32 v83, v0
	v_mov_b32_e32 v84, v0
	v_mov_b32_e32 v85, v0
	v_mov_b32_e32 v86, v0
	v_mov_b32_e32 v87, v0
	v_mov_b32_e32 v88, v0
	v_mov_b32_e32 v89, v0
	v_mov_b32_e32 v90, v0
	v_mov_b32_e32 v91, v0
	v_mov_b32_e32 v92, v0
	v_mov_b32_e32 v93, v0
	v_mov_b32_e32 v94, v0
	v_mov_b32_e32 v95, v0
	v_mov_b32_e32 v96, v0
	v_mov_b32_e32 v97, v0
	v_mov_b32_e32 v98, v0
	v_mov_b32_e32 v99, v0
	v_mov_b32_e32 v100, v0
	v_mov_b32_e32 v101, v0
	v_mov_b32_e32 v102, v0
	v_mov_b32_e32 v103, v0
	v_mov_b32_e32 v104, v0
	v_mov_b32_e32 v105, v0
	v_mov_b32_e32 v106, v0
	v_mov_b32_e32 v107, v0
	v_mov_b32_e32 v108, v0
	v_mov_b32_e32 v109, v0
	v_mov_b32_e32 v110, v0
	v_mov_b32_e32 v111, v0
	v_mov_b32_e32 v112, v0
	v_mov_b32_e32 v113, v0
	v_mov_b32_e32 v114, v0
	v_mov_b32_e32 v115, v0
	v_mov_b32_e32 v116, v0
	v_mov_b32_e32 v117, v0
	v_mov_b32_e32 v118, v0
	v_mov_b32_e32 v119, v0
	v_mov_b32_e32 v120, v0
	v_mov_b32_e32 v121, v0
	v_mov_b32_e32 v122, v0
	v_mov_b32_e32 v123, v0
	v_mov_b32_e32 v124, v0
	v_mov_b32_e32 v125, v0
	v_mov_b32_e32 v126, v0
	v_mov_b32_e32 v127, v0
	s_barrier
	v_lshl_add_u64 v[228:229], s[50:51], 0, v[132:133]
	s_mov_b64 s[66:67], 0xe080080
	v_readfirstlane_b32 s65, v161
	v_lshl_add_u64 v[166:167], v[228:229], 0, s[66:67]
	s_mov_b32 m0, s65
	s_mov_b64 s[66:67], 0xe0c0080
	v_readfirstlane_b32 s65, v160
	global_load_lds_dwordx4 v[166:167], off
	v_lshl_add_u64 v[166:167], v[228:229], 0, s[66:67]
	s_mov_b32 m0, s65
	s_nop 0
	global_load_lds_dwordx4 v[166:167], off
	ds_read_b128 v[164:167], v162
	ds_read_b128 v[168:171], v162 offset:1024
	ds_read_b128 v[172:175], v162 offset:2048
	ds_read_b128 v[176:179], v162 offset:3072
	ds_read_b128 v[180:183], v153
	ds_read_b128 v[184:187], v153 offset:1024
	ds_read_b128 v[188:191], v152
	ds_read_b128 v[192:195], v152 offset:1024
	ds_read_b128 v[196:199], v151
	ds_read_b128 v[200:203], v151 offset:1024
	ds_read_b128 v[204:207], v150
	ds_read_b128 v[208:211], v150 offset:1024
	s_waitcnt lgkmcnt(8)
	s_barrier
	s_branch .Lkent_178

.Lkent_178:
	s_waitcnt lgkmcnt(0)
	s_setprio 1
	s_waitcnt lgkmcnt(0)
	v_mfma_f32_16x16x32_bf16 v[124:127], v[164:167], v[180:183], v[124:127]
	v_mfma_f32_16x16x32_bf16 v[120:123], v[172:175], v[180:183], v[120:123]
	v_mfma_f32_16x16x32_bf16 v[116:119], v[164:167], v[188:191], v[116:119]
	v_mfma_f32_16x16x32_bf16 v[112:115], v[172:175], v[188:191], v[112:115]
	v_mfma_f32_16x16x32_bf16 v[108:111], v[164:167], v[196:199], v[108:111]
	v_mfma_f32_16x16x32_bf16 v[104:107], v[172:175], v[196:199], v[104:107]
	v_mfma_f32_16x16x32_bf16 v[100:103], v[164:167], v[204:207], v[100:103]
	v_mfma_f32_16x16x32_bf16 v[96:99], v[172:175], v[204:207], v[96:99]
	v_mfma_f32_16x16x32_bf16 v[124:127], v[168:171], v[184:187], v[124:127]
	v_mfma_f32_16x16x32_bf16 v[120:123], v[176:179], v[184:187], v[120:123]
	v_mfma_f32_16x16x32_bf16 v[116:119], v[168:171], v[192:195], v[116:119]
	v_mfma_f32_16x16x32_bf16 v[112:115], v[176:179], v[192:195], v[112:115]
	v_mfma_f32_16x16x32_bf16 v[108:111], v[168:171], v[200:203], v[108:111]
	v_mfma_f32_16x16x32_bf16 v[104:107], v[176:179], v[200:203], v[104:107]
	v_mfma_f32_16x16x32_bf16 v[100:103], v[168:171], v[208:211], v[100:103]
	v_mfma_f32_16x16x32_bf16 v[96:99], v[176:179], v[208:211], v[96:99]
	s_setprio 0
	s_barrier
	v_lshl_add_u64 v[230:231], s[50:51], 0, v[130:131]
	s_mov_b64 s[66:67], 0x1880000
	v_readfirstlane_b32 s65, v149
	v_lshl_add_u64 v[232:233], v[230:231], 0, s[66:67]
	s_mov_b32 m0, s65
	s_mov_b64 s[66:67], 0x1881000
	v_readfirstlane_b32 s65, v148
	ds_read_b128 v[212:215], v159
	ds_read_b128 v[216:219], v159 offset:1024
	ds_read_b128 v[220:223], v159 offset:2048
	ds_read_b128 v[224:227], v159 offset:3072
	global_load_lds_dwordx4 v[232:233], off
	v_lshl_add_u64 v[232:233], v[230:231], 0, s[66:67]
	s_mov_b32 m0, s65
	s_nop 0
	global_load_lds_dwordx4 v[232:233], off
	s_mov_b64 s[66:67], 0xe000100
	v_readfirstlane_b32 s65, v135
	v_lshl_add_u64 v[232:233], v[228:229], 0, s[66:67]
	s_mov_b32 m0, s65
	s_mov_b64 s[66:67], 0xe040100
	v_readfirstlane_b32 s65, v147
	global_load_lds_dwordx4 v[232:233], off
	v_lshl_add_u64 v[232:233], v[228:229], 0, s[66:67]
	s_mov_b32 m0, s65
	s_nop 0
	global_load_lds_dwordx4 v[232:233], off
	s_waitcnt vmcnt(12)
	s_barrier
	s_waitcnt lgkmcnt(0)
	s_setprio 1
	s_waitcnt lgkmcnt(0)
	v_mfma_f32_16x16x32_bf16 v[92:95], v[212:215], v[180:183], v[92:95]
	v_mfma_f32_16x16x32_bf16 v[88:91], v[220:223], v[180:183], v[88:91]
	v_mfma_f32_16x16x32_bf16 v[84:87], v[212:215], v[188:191], v[84:87]
	v_mfma_f32_16x16x32_bf16 v[80:83], v[220:223], v[188:191], v[80:83]
	v_mfma_f32_16x16x32_bf16 v[76:79], v[212:215], v[196:199], v[76:79]
	v_mfma_f32_16x16x32_bf16 v[72:75], v[220:223], v[196:199], v[72:75]
	v_mfma_f32_16x16x32_bf16 v[68:71], v[212:215], v[204:207], v[68:71]
	v_mfma_f32_16x16x32_bf16 v[64:67], v[220:223], v[204:207], v[64:67]
	v_mfma_f32_16x16x32_bf16 v[92:95], v[216:219], v[184:187], v[92:95]
	v_mfma_f32_16x16x32_bf16 v[88:91], v[224:227], v[184:187], v[88:91]
	v_mfma_f32_16x16x32_bf16 v[84:87], v[216:219], v[192:195], v[84:87]
	v_mfma_f32_16x16x32_bf16 v[80:83], v[224:227], v[192:195], v[80:83]
	v_mfma_f32_16x16x32_bf16 v[76:79], v[216:219], v[200:203], v[76:79]
	v_mfma_f32_16x16x32_bf16 v[72:75], v[224:227], v[200:203], v[72:75]
	v_mfma_f32_16x16x32_bf16 v[68:71], v[216:219], v[208:211], v[68:71]
	v_mfma_f32_16x16x32_bf16 v[64:67], v[224:227], v[208:211], v[64:67]
	s_setprio 0
	s_barrier
	ds_read_b128 v[180:183], v153 offset:16384
	ds_read_b128 v[184:187], v153 offset:17408
	ds_read_b128 v[188:191], v152 offset:16384
	ds_read_b128 v[192:195], v152 offset:17408
	ds_read_b128 v[196:199], v151 offset:16384
	ds_read_b128 v[200:203], v151 offset:17408
	ds_read_b128 v[204:207], v150 offset:16384
	ds_read_b128 v[208:211], v150 offset:17408
	s_mov_b64 s[66:67], 0x1882000
	v_readfirstlane_b32 s65, v146
	v_lshl_add_u64 v[232:233], v[230:231], 0, s[66:67]
	s_mov_b32 m0, s65
	s_mov_b64 s[66:67], 0x1883000
	v_readfirstlane_b32 s65, v145
	global_load_lds_dwordx4 v[232:233], off
	v_lshl_add_u64 v[232:233], v[230:231], 0, s[66:67]
	s_mov_b32 m0, s65
	s_nop 0
	global_load_lds_dwordx4 v[232:233], off
	s_barrier
	s_waitcnt lgkmcnt(0)
	s_setprio 1
	s_waitcnt lgkmcnt(0)
	v_mfma_f32_16x16x32_bf16 v[60:63], v[164:167], v[180:183], v[60:63]
	v_mfma_f32_16x16x32_bf16 v[56:59], v[172:175], v[180:183], v[56:59]
	v_mfma_f32_16x16x32_bf16 v[52:55], v[164:167], v[188:191], v[52:55]
	v_mfma_f32_16x16x32_bf16 v[48:51], v[172:175], v[188:191], v[48:51]
	v_mfma_f32_16x16x32_bf16 v[44:47], v[164:167], v[196:199], v[44:47]
	v_mfma_f32_16x16x32_bf16 v[40:43], v[172:175], v[196:199], v[40:43]
	v_mfma_f32_16x16x32_bf16 v[36:39], v[164:167], v[204:207], v[36:39]
	v_mfma_f32_16x16x32_bf16 v[32:35], v[172:175], v[204:207], v[32:35]
	v_mfma_f32_16x16x32_bf16 v[60:63], v[168:171], v[184:187], v[60:63]
	v_mfma_f32_16x16x32_bf16 v[56:59], v[176:179], v[184:187], v[56:59]
	v_mfma_f32_16x16x32_bf16 v[52:55], v[168:171], v[192:195], v[52:55]
	v_mfma_f32_16x16x32_bf16 v[48:51], v[176:179], v[192:195], v[48:51]
	v_mfma_f32_16x16x32_bf16 v[44:47], v[168:171], v[200:203], v[44:47]
	v_mfma_f32_16x16x32_bf16 v[40:43], v[176:179], v[200:203], v[40:43]
	v_mfma_f32_16x16x32_bf16 v[36:39], v[168:171], v[208:211], v[36:39]
	v_mfma_f32_16x16x32_bf16 v[32:35], v[176:179], v[208:211], v[32:35]
	s_setprio 0
	s_barrier
	v_readfirstlane_b32 s65, v144
	v_lshl_add_u64 v[166:167], v[228:229], 0, s[26:27]
	s_mov_b32 m0, s65
	v_readfirstlane_b32 s65, v143
	global_load_lds_dwordx4 v[166:167], off
	v_lshl_add_u64 v[166:167], v[228:229], 0, s[28:29]
	s_mov_b32 m0, s65
	s_nop 0
	global_load_lds_dwordx4 v[166:167], off
	s_waitcnt vmcnt(12)
	s_barrier
	s_setprio 1
	v_mfma_f32_16x16x32_bf16 v[28:31], v[212:215], v[180:183], v[28:31]
	v_mfma_f32_16x16x32_bf16 v[24:27], v[220:223], v[180:183], v[24:27]
	v_mfma_f32_16x16x32_bf16 v[20:23], v[212:215], v[188:191], v[20:23]
	v_mfma_f32_16x16x32_bf16 v[16:19], v[220:223], v[188:191], v[16:19]
	v_mfma_f32_16x16x32_bf16 v[12:15], v[212:215], v[196:199], v[12:15]
	v_mfma_f32_16x16x32_bf16 v[8:11], v[220:223], v[196:199], v[8:11]
	v_mfma_f32_16x16x32_bf16 v[4:7], v[212:215], v[204:207], v[4:7]
	v_mfma_f32_16x16x32_bf16 v[0:3], v[220:223], v[204:207], v[0:3]
	v_mfma_f32_16x16x32_bf16 v[28:31], v[216:219], v[184:187], v[28:31]
	v_mfma_f32_16x16x32_bf16 v[24:27], v[224:227], v[184:187], v[24:27]
	v_mfma_f32_16x16x32_bf16 v[20:23], v[216:219], v[192:195], v[20:23]
	v_mfma_f32_16x16x32_bf16 v[16:19], v[224:227], v[192:195], v[16:19]
	v_mfma_f32_16x16x32_bf16 v[12:15], v[216:219], v[200:203], v[12:15]
	v_mfma_f32_16x16x32_bf16 v[8:11], v[224:227], v[200:203], v[8:11]
	v_mfma_f32_16x16x32_bf16 v[4:7], v[216:219], v[208:211], v[4:7]
	v_mfma_f32_16x16x32_bf16 v[0:3], v[224:227], v[208:211], v[0:3]
	s_setprio 0
	s_barrier
	ds_read_b128 v[164:167], v155
	ds_read_b128 v[168:171], v155 offset:1024
	ds_read_b128 v[172:175], v155 offset:2048
	ds_read_b128 v[176:179], v155 offset:3072
	ds_read_b128 v[180:183], v153 offset:32768
	ds_read_b128 v[184:187], v153 offset:33792
	ds_read_b128 v[188:191], v152 offset:32768
	ds_read_b128 v[192:195], v152 offset:33792
	ds_read_b128 v[196:199], v151 offset:32768
	ds_read_b128 v[200:203], v151 offset:33792
	ds_read_b128 v[204:207], v150 offset:32768
	ds_read_b128 v[208:211], v150 offset:33792
	s_waitcnt lgkmcnt(8)
	s_waitcnt vmcnt(10)
	s_barrier
	s_waitcnt lgkmcnt(0)
	s_setprio 1
	s_waitcnt lgkmcnt(0)
	v_mfma_f32_16x16x32_bf16 v[124:127], v[164:167], v[180:183], v[124:127]
	v_mfma_f32_16x16x32_bf16 v[120:123], v[172:175], v[180:183], v[120:123]
	v_mfma_f32_16x16x32_bf16 v[116:119], v[164:167], v[188:191], v[116:119]
	v_mfma_f32_16x16x32_bf16 v[112:115], v[172:175], v[188:191], v[112:115]
	v_mfma_f32_16x16x32_bf16 v[108:111], v[164:167], v[196:199], v[108:111]
	v_mfma_f32_16x16x32_bf16 v[104:107], v[172:175], v[196:199], v[104:107]
	v_mfma_f32_16x16x32_bf16 v[100:103], v[164:167], v[204:207], v[100:103]
	v_mfma_f32_16x16x32_bf16 v[96:99], v[172:175], v[204:207], v[96:99]
	v_mfma_f32_16x16x32_bf16 v[124:127], v[168:171], v[184:187], v[124:127]
	v_mfma_f32_16x16x32_bf16 v[120:123], v[176:179], v[184:187], v[120:123]
	v_mfma_f32_16x16x32_bf16 v[116:119], v[168:171], v[192:195], v[116:119]
	v_mfma_f32_16x16x32_bf16 v[112:115], v[176:179], v[192:195], v[112:115]
	v_mfma_f32_16x16x32_bf16 v[108:111], v[168:171], v[200:203], v[108:111]
	v_mfma_f32_16x16x32_bf16 v[104:107], v[176:179], v[200:203], v[104:107]
	v_mfma_f32_16x16x32_bf16 v[100:103], v[168:171], v[208:211], v[100:103]
	v_mfma_f32_16x16x32_bf16 v[96:99], v[176:179], v[208:211], v[96:99]
	s_setprio 0
	s_barrier
	v_readfirstlane_b32 s65, v142
	v_lshl_add_u64 v[232:233], v[230:231], 0, s[30:31]
	s_mov_b32 m0, s65
	v_readfirstlane_b32 s65, v141
	ds_read_b128 v[212:215], v154
	ds_read_b128 v[216:219], v154 offset:1024
	ds_read_b128 v[220:223], v154 offset:2048
	ds_read_b128 v[224:227], v154 offset:3072
	global_load_lds_dwordx4 v[232:233], off
	v_lshl_add_u64 v[232:233], v[230:231], 0, s[34:35]
	s_mov_b32 m0, s65
	s_nop 0
	global_load_lds_dwordx4 v[232:233], off
	v_readfirstlane_b32 s65, v140
	v_lshl_add_u64 v[232:233], v[228:229], 0, s[40:41]
	s_mov_b32 m0, s65
	v_readfirstlane_b32 s65, v139
	global_load_lds_dwordx4 v[232:233], off
	v_lshl_add_u64 v[228:229], v[228:229], 0, s[44:45]
	s_mov_b32 m0, s65
	s_nop 0
	global_load_lds_dwordx4 v[228:229], off
	s_waitcnt vmcnt(12)
	s_barrier
	s_waitcnt lgkmcnt(0)
	s_setprio 1
	s_waitcnt lgkmcnt(0)
	v_mfma_f32_16x16x32_bf16 v[92:95], v[212:215], v[180:183], v[92:95]
	v_mfma_f32_16x16x32_bf16 v[88:91], v[220:223], v[180:183], v[88:91]
	v_mfma_f32_16x16x32_bf16 v[84:87], v[212:215], v[188:191], v[84:87]
	v_mfma_f32_16x16x32_bf16 v[80:83], v[220:223], v[188:191], v[80:83]
	v_mfma_f32_16x16x32_bf16 v[76:79], v[212:215], v[196:199], v[76:79]
	v_mfma_f32_16x16x32_bf16 v[72:75], v[220:223], v[196:199], v[72:75]
	v_mfma_f32_16x16x32_bf16 v[68:71], v[212:215], v[204:207], v[68:71]
	v_mfma_f32_16x16x32_bf16 v[64:67], v[220:223], v[204:207], v[64:67]
	v_mfma_f32_16x16x32_bf16 v[92:95], v[216:219], v[184:187], v[92:95]
	v_mfma_f32_16x16x32_bf16 v[88:91], v[224:227], v[184:187], v[88:91]
	v_mfma_f32_16x16x32_bf16 v[84:87], v[216:219], v[192:195], v[84:87]
	v_mfma_f32_16x16x32_bf16 v[80:83], v[224:227], v[192:195], v[80:83]
	v_mfma_f32_16x16x32_bf16 v[76:79], v[216:219], v[200:203], v[76:79]
	v_mfma_f32_16x16x32_bf16 v[72:75], v[224:227], v[200:203], v[72:75]
	v_mfma_f32_16x16x32_bf16 v[68:71], v[216:219], v[208:211], v[68:71]
	v_mfma_f32_16x16x32_bf16 v[64:67], v[224:227], v[208:211], v[64:67]
	s_setprio 0
	s_barrier
	ds_read_b128 v[180:183], v153 offset:49152
	ds_read_b128 v[184:187], v153 offset:50176
	ds_read_b128 v[188:191], v152 offset:49152
	ds_read_b128 v[192:195], v152 offset:50176
	ds_read_b128 v[196:199], v151 offset:49152
	ds_read_b128 v[200:203], v151 offset:50176
	ds_read_b128 v[204:207], v150 offset:49152
	ds_read_b128 v[208:211], v150 offset:50176
	v_readfirstlane_b32 s65, v138
	v_lshl_add_u64 v[232:233], v[230:231], 0, s[46:47]
	s_mov_b32 m0, s65
	v_readfirstlane_b32 s65, v137
	global_load_lds_dwordx4 v[232:233], off
	v_lshl_add_u64 v[232:233], v[230:231], 0, s[56:57]
	s_mov_b32 m0, s65
	s_nop 0
	global_load_lds_dwordx4 v[232:233], off
	s_barrier
	s_waitcnt lgkmcnt(0)
	s_setprio 1
	s_waitcnt lgkmcnt(0)
	v_mfma_f32_16x16x32_bf16 v[60:63], v[164:167], v[180:183], v[60:63]
	v_mfma_f32_16x16x32_bf16 v[56:59], v[172:175], v[180:183], v[56:59]
	v_mfma_f32_16x16x32_bf16 v[52:55], v[164:167], v[188:191], v[52:55]
	v_mfma_f32_16x16x32_bf16 v[48:51], v[172:175], v[188:191], v[48:51]
	v_mfma_f32_16x16x32_bf16 v[44:47], v[164:167], v[196:199], v[44:47]
	v_mfma_f32_16x16x32_bf16 v[40:43], v[172:175], v[196:199], v[40:43]
	v_mfma_f32_16x16x32_bf16 v[36:39], v[164:167], v[204:207], v[36:39]
	v_mfma_f32_16x16x32_bf16 v[32:35], v[172:175], v[204:207], v[32:35]
	v_mfma_f32_16x16x32_bf16 v[60:63], v[168:171], v[184:187], v[60:63]
	v_mfma_f32_16x16x32_bf16 v[56:59], v[176:179], v[184:187], v[56:59]
	v_mfma_f32_16x16x32_bf16 v[52:55], v[168:171], v[192:195], v[52:55]
	v_mfma_f32_16x16x32_bf16 v[48:51], v[176:179], v[192:195], v[48:51]
	v_mfma_f32_16x16x32_bf16 v[44:47], v[168:171], v[200:203], v[44:47]
	v_mfma_f32_16x16x32_bf16 v[40:43], v[176:179], v[200:203], v[40:43]
	v_mfma_f32_16x16x32_bf16 v[36:39], v[168:171], v[208:211], v[36:39]
	v_mfma_f32_16x16x32_bf16 v[32:35], v[176:179], v[208:211], v[32:35]
	s_setprio 0
	s_barrier
	v_lshl_add_u64 v[132:133], v[132:133], 0, s[58:59]
	v_lshl_add_u64 v[228:229], s[50:51], 0, v[132:133]
	s_mov_b64 s[66:67], 0xe080080
	v_readfirstlane_b32 s65, v161
	v_lshl_add_u64 v[166:167], v[228:229], 0, s[66:67]
	s_mov_b32 m0, s65
	s_mov_b64 s[66:67], 0xe0c0080
	v_readfirstlane_b32 s65, v160
	global_load_lds_dwordx4 v[166:167], off
	v_lshl_add_u64 v[166:167], v[228:229], 0, s[66:67]
	s_mov_b32 m0, s65
	s_nop 0
	global_load_lds_dwordx4 v[166:167], off
	s_waitcnt vmcnt(12)
	s_barrier
	s_setprio 1
	v_mfma_f32_16x16x32_bf16 v[28:31], v[212:215], v[180:183], v[28:31]
	v_mfma_f32_16x16x32_bf16 v[24:27], v[220:223], v[180:183], v[24:27]
	v_mfma_f32_16x16x32_bf16 v[20:23], v[212:215], v[188:191], v[20:23]
	v_mfma_f32_16x16x32_bf16 v[16:19], v[220:223], v[188:191], v[16:19]
	v_mfma_f32_16x16x32_bf16 v[12:15], v[212:215], v[196:199], v[12:15]
	v_mfma_f32_16x16x32_bf16 v[8:11], v[220:223], v[196:199], v[8:11]
	v_mfma_f32_16x16x32_bf16 v[4:7], v[212:215], v[204:207], v[4:7]
	v_mfma_f32_16x16x32_bf16 v[0:3], v[220:223], v[204:207], v[0:3]
	v_mfma_f32_16x16x32_bf16 v[28:31], v[216:219], v[184:187], v[28:31]
	v_mfma_f32_16x16x32_bf16 v[24:27], v[224:227], v[184:187], v[24:27]
	v_mfma_f32_16x16x32_bf16 v[20:23], v[216:219], v[192:195], v[20:23]
	v_mfma_f32_16x16x32_bf16 v[16:19], v[224:227], v[192:195], v[16:19]
	v_mfma_f32_16x16x32_bf16 v[12:15], v[216:219], v[200:203], v[12:15]
	v_mfma_f32_16x16x32_bf16 v[8:11], v[224:227], v[200:203], v[8:11]
	v_mfma_f32_16x16x32_bf16 v[4:7], v[216:219], v[208:211], v[4:7]
	v_mfma_f32_16x16x32_bf16 v[0:3], v[224:227], v[208:211], v[0:3]
	s_setprio 0
	s_add_i32 s24, s24, 2
	v_lshl_add_u64 v[130:131], v[130:131], 0, s[10:11]
	s_cmp_lt_u32 s24, 28
	s_barrier
	s_cbranch_scc1 .LBB0_178
	s_lshl_b32 s24, s85, 5
	s_lshl_b32 s65, s85, 8
	s_and_b32 s24, s24, 0x1800
	s_and_b32 s65, s65, 0x700
	s_or_b32 s24, s65, s24
	v_lshlrev_b32_e32 v128, 3, v156
	v_lshlrev_b32_e32 v130, 5, v156
	v_and_b32_e32 v128, 0xffff0, v128
	v_and_b32_e32 v130, 32, v130
	s_lshl_b32 s65, s24, 12
	v_add_u32_e32 v130, v130, v158
	v_add_lshl_u32 v128, v157, v128, 12
	s_add_u32 s66, s68, s65
	v_lshl_add_u32 v128, v130, 1, v128
	s_addc_u32 s67, s69, 0
	v_lshl_add_u64 v[156:157], s[66:67], 0, v[128:129]
	v_readfirstlane_b32 s65, v161
	ds_read_b128 v[130:133], v162
	ds_read_b128 v[164:167], v162 offset:1024
	ds_read_b128 v[168:171], v162 offset:2048
	ds_read_b128 v[172:175], v162 offset:3072
	ds_read_b128 v[176:179], v153
	ds_read_b128 v[180:183], v153 offset:1024
	ds_read_b128 v[184:187], v152
	ds_read_b128 v[188:191], v152 offset:1024
	ds_read_b128 v[192:195], v151
	ds_read_b128 v[196:199], v151 offset:1024
	ds_read_b128 v[200:203], v150
	ds_read_b128 v[204:207], v150 offset:1024
	v_lshl_add_u64 v[162:163], v[156:157], 0, s[60:61]
	s_mov_b32 m0, s65
	v_readfirstlane_b32 s65, v160
	global_load_lds_dwordx4 v[162:163], off
	v_lshl_add_u64 v[156:157], v[156:157], 0, s[62:63]
	s_mov_b32 m0, s65
	s_nop 0
	global_load_lds_dwordx4 v[156:157], off
	s_waitcnt vmcnt(10)
	s_barrier
	s_waitcnt lgkmcnt(0)
	s_setprio 1
	s_waitcnt lgkmcnt(0)
	v_mfma_f32_16x16x32_bf16 v[124:127], v[130:133], v[176:179], v[124:127]
	v_mfma_f32_16x16x32_bf16 v[120:123], v[168:171], v[176:179], v[120:123]
	v_mfma_f32_16x16x32_bf16 v[116:119], v[130:133], v[184:187], v[116:119]
	v_mfma_f32_16x16x32_bf16 v[112:115], v[168:171], v[184:187], v[112:115]
	v_mfma_f32_16x16x32_bf16 v[108:111], v[130:133], v[192:195], v[108:111]
	v_mfma_f32_16x16x32_bf16 v[104:107], v[168:171], v[192:195], v[104:107]
	v_mfma_f32_16x16x32_bf16 v[100:103], v[130:133], v[200:203], v[100:103]
	v_mfma_f32_16x16x32_bf16 v[96:99], v[168:171], v[200:203], v[96:99]
	v_mfma_f32_16x16x32_bf16 v[124:127], v[164:167], v[180:183], v[124:127]
	v_mfma_f32_16x16x32_bf16 v[120:123], v[172:175], v[180:183], v[120:123]
	v_mfma_f32_16x16x32_bf16 v[116:119], v[164:167], v[188:191], v[116:119]
	v_mfma_f32_16x16x32_bf16 v[112:115], v[172:175], v[188:191], v[112:115]
	v_mfma_f32_16x16x32_bf16 v[108:111], v[164:167], v[196:199], v[108:111]
	v_mfma_f32_16x16x32_bf16 v[104:107], v[172:175], v[196:199], v[104:107]
	v_mfma_f32_16x16x32_bf16 v[100:103], v[164:167], v[204:207], v[100:103]
	v_mfma_f32_16x16x32_bf16 v[96:99], v[172:175], v[204:207], v[96:99]
	s_setprio 0
	s_barrier
	ds_read_b128 v[160:163], v159
	ds_read_b128 v[208:211], v159 offset:1024
	ds_read_b128 v[212:215], v159 offset:2048
	ds_read_b128 v[156:159], v159 offset:3072
	s_barrier
	s_waitcnt lgkmcnt(0)
	s_setprio 1
	s_waitcnt lgkmcnt(0)
	v_mfma_f32_16x16x32_bf16 v[92:95], v[160:163], v[176:179], v[92:95]
	v_mfma_f32_16x16x32_bf16 v[88:91], v[212:215], v[176:179], v[88:91]
	v_mfma_f32_16x16x32_bf16 v[84:87], v[160:163], v[184:187], v[84:87]
	v_mfma_f32_16x16x32_bf16 v[80:83], v[212:215], v[184:187], v[80:83]
	v_mfma_f32_16x16x32_bf16 v[76:79], v[160:163], v[192:195], v[76:79]
	v_mfma_f32_16x16x32_bf16 v[72:75], v[212:215], v[192:195], v[72:75]
	v_mfma_f32_16x16x32_bf16 v[68:71], v[160:163], v[200:203], v[68:71]
	v_mfma_f32_16x16x32_bf16 v[64:67], v[212:215], v[200:203], v[64:67]
	v_mfma_f32_16x16x32_bf16 v[176:179], v[208:211], v[180:183], v[92:95]
	v_mfma_f32_16x16x32_bf16 v[180:183], v[156:159], v[180:183], v[88:91]
	v_mfma_f32_16x16x32_bf16 v[184:187], v[208:211], v[188:191], v[84:87]
	v_mfma_f32_16x16x32_bf16 v[188:191], v[156:159], v[188:191], v[80:83]
	v_mfma_f32_16x16x32_bf16 v[192:195], v[208:211], v[196:199], v[76:79]
	v_mfma_f32_16x16x32_bf16 v[196:199], v[156:159], v[196:199], v[72:75]
	v_mfma_f32_16x16x32_bf16 v[200:203], v[208:211], v[204:207], v[68:71]
	v_mfma_f32_16x16x32_bf16 v[204:207], v[156:159], v[204:207], v[64:67]
	s_setprio 0
	s_barrier
	s_nop 0
	ds_read_b128 v[64:67], v153 offset:16384
	ds_read_b128 v[68:71], v153 offset:17408
	ds_read_b128 v[72:75], v152 offset:16384
	ds_read_b128 v[76:79], v152 offset:17408
	ds_read_b128 v[80:83], v151 offset:16384
	ds_read_b128 v[84:87], v151 offset:17408
	ds_read_b128 v[88:91], v150 offset:16384
	ds_read_b128 v[92:95], v150 offset:17408
	s_waitcnt vmcnt(4)
	s_barrier
	s_waitcnt lgkmcnt(0)
	s_setprio 1
	s_waitcnt lgkmcnt(0)
	v_mfma_f32_16x16x32_bf16 v[60:63], v[130:133], v[64:67], v[60:63]
	v_mfma_f32_16x16x32_bf16 v[56:59], v[168:171], v[64:67], v[56:59]
	v_mfma_f32_16x16x32_bf16 v[52:55], v[130:133], v[72:75], v[52:55]
	v_mfma_f32_16x16x32_bf16 v[48:51], v[168:171], v[72:75], v[48:51]
	v_mfma_f32_16x16x32_bf16 v[216:219], v[130:133], v[80:83], v[44:47]
	v_mfma_f32_16x16x32_bf16 v[220:223], v[168:171], v[80:83], v[40:43]
	v_mfma_f32_16x16x32_bf16 v[130:133], v[130:133], v[88:91], v[36:39]
	v_mfma_f32_16x16x32_bf16 v[168:171], v[168:171], v[88:91], v[32:35]
	v_mfma_f32_16x16x32_bf16 v[32:35], v[164:167], v[68:71], v[60:63]
	v_mfma_f32_16x16x32_bf16 v[36:39], v[172:175], v[68:71], v[56:59]
	v_mfma_f32_16x16x32_bf16 v[40:43], v[164:167], v[76:79], v[52:55]
	v_mfma_f32_16x16x32_bf16 v[44:47], v[172:175], v[76:79], v[48:51]
	v_mfma_f32_16x16x32_bf16 v[48:51], v[164:167], v[84:87], v[216:219]
	v_mfma_f32_16x16x32_bf16 v[52:55], v[172:175], v[84:87], v[220:223]
	v_mfma_f32_16x16x32_bf16 v[56:59], v[164:167], v[92:95], v[130:133]
	v_mfma_f32_16x16x32_bf16 v[60:63], v[172:175], v[92:95], v[168:171]
	s_setprio 0
	s_setprio 1
	v_mfma_f32_16x16x32_bf16 v[28:31], v[160:163], v[64:67], v[28:31]
	v_mfma_f32_16x16x32_bf16 v[24:27], v[212:215], v[64:67], v[24:27]
	v_mfma_f32_16x16x32_bf16 v[20:23], v[160:163], v[72:75], v[20:23]
	v_mfma_f32_16x16x32_bf16 v[64:67], v[212:215], v[72:75], v[16:19]
	v_mfma_f32_16x16x32_bf16 v[72:75], v[160:163], v[80:83], v[12:15]
	v_mfma_f32_16x16x32_bf16 v[8:11], v[212:215], v[80:83], v[8:11]
	v_mfma_f32_16x16x32_bf16 v[80:83], v[160:163], v[88:91], v[4:7]
	v_mfma_f32_16x16x32_bf16 v[0:3], v[212:215], v[88:91], v[0:3]
	v_mfma_f32_16x16x32_bf16 v[4:7], v[208:211], v[68:71], v[28:31]
	v_mfma_f32_16x16x32_bf16 v[12:15], v[156:159], v[68:71], v[24:27]
	v_mfma_f32_16x16x32_bf16 v[16:19], v[208:211], v[76:79], v[20:23]
	v_mfma_f32_16x16x32_bf16 v[20:23], v[156:159], v[76:79], v[64:67]
	v_mfma_f32_16x16x32_bf16 v[24:27], v[208:211], v[84:87], v[72:75]
	v_mfma_f32_16x16x32_bf16 v[28:31], v[156:159], v[84:87], v[8:11]
	v_mfma_f32_16x16x32_bf16 v[64:67], v[208:211], v[92:95], v[80:83]
	v_mfma_f32_16x16x32_bf16 v[68:71], v[156:159], v[92:95], v[0:3]
	s_setprio 0
	s_barrier
	ds_read_b128 v[8:11], v155
	ds_read_b128 v[0:3], v155 offset:1024
	ds_read_b128 v[76:79], v155 offset:2048
	ds_read_b128 v[72:75], v155 offset:3072
	ds_read_b128 v[130:133], v153 offset:32768
	ds_read_b128 v[156:159], v153 offset:33792
	ds_read_b128 v[160:163], v152 offset:32768
	ds_read_b128 v[164:167], v152 offset:33792
	ds_read_b128 v[168:171], v151 offset:32768
	ds_read_b128 v[172:175], v151 offset:33792
	ds_read_b128 v[208:211], v150 offset:32768
	ds_read_b128 v[212:215], v150 offset:33792
	s_waitcnt vmcnt(2)
	s_barrier
	s_waitcnt lgkmcnt(0)
	s_setprio 1
	s_waitcnt lgkmcnt(0)
	v_mfma_f32_16x16x32_bf16 v[80:83], v[8:11], v[130:133], v[124:127]
	v_mfma_f32_16x16x32_bf16 v[84:87], v[76:79], v[130:133], v[120:123]
	v_mfma_f32_16x16x32_bf16 v[88:91], v[8:11], v[160:163], v[116:119]
	v_mfma_f32_16x16x32_bf16 v[92:95], v[76:79], v[160:163], v[112:115]
	v_mfma_f32_16x16x32_bf16 v[108:111], v[8:11], v[168:171], v[108:111]
	v_mfma_f32_16x16x32_bf16 v[104:107], v[76:79], v[168:171], v[104:107]
	v_mfma_f32_16x16x32_bf16 v[100:103], v[8:11], v[208:211], v[100:103]
	v_mfma_f32_16x16x32_bf16 v[96:99], v[76:79], v[208:211], v[96:99]
	v_mfma_f32_16x16x32_bf16 v[112:115], v[0:3], v[156:159], v[80:83]
	v_mfma_f32_16x16x32_bf16 v[116:119], v[72:75], v[156:159], v[84:87]
	v_mfma_f32_16x16x32_bf16 v[120:123], v[0:3], v[164:167], v[88:91]
	v_mfma_f32_16x16x32_bf16 v[124:127], v[72:75], v[164:167], v[92:95]
	v_mfma_f32_16x16x32_bf16 v[108:111], v[0:3], v[172:175], v[108:111]
	v_mfma_f32_16x16x32_bf16 v[104:107], v[72:75], v[172:175], v[104:107]
	v_mfma_f32_16x16x32_bf16 v[100:103], v[0:3], v[212:215], v[100:103]
	v_mfma_f32_16x16x32_bf16 v[96:99], v[72:75], v[212:215], v[96:99]
	s_setprio 0
	s_barrier
	ds_read_b128 v[88:91], v154
	ds_read_b128 v[80:83], v154 offset:1024
	ds_read_b128 v[92:95], v154 offset:2048
	ds_read_b128 v[84:87], v154 offset:3072
	s_waitcnt vmcnt(0)
	s_barrier
	s_waitcnt lgkmcnt(0)
	s_setprio 1
	s_waitcnt lgkmcnt(0)
	v_mfma_f32_16x16x32_bf16 v[176:179], v[88:91], v[130:133], v[176:179]
	v_mfma_f32_16x16x32_bf16 v[130:133], v[92:95], v[130:133], v[180:183]
	v_mfma_f32_16x16x32_bf16 v[180:183], v[88:91], v[160:163], v[184:187]
	v_mfma_f32_16x16x32_bf16 v[160:163], v[92:95], v[160:163], v[188:191]
	v_mfma_f32_16x16x32_bf16 v[184:187], v[88:91], v[168:171], v[192:195]
	v_mfma_f32_16x16x32_bf16 v[168:171], v[92:95], v[168:171], v[196:199]
	v_mfma_f32_16x16x32_bf16 v[188:191], v[88:91], v[208:211], v[200:203]
	v_mfma_f32_16x16x32_bf16 v[192:195], v[92:95], v[208:211], v[204:207]
	v_mfma_f32_16x16x32_bf16 v[176:179], v[80:83], v[156:159], v[176:179]
	v_mfma_f32_16x16x32_bf16 v[130:133], v[84:87], v[156:159], v[130:133]
	v_mfma_f32_16x16x32_bf16 v[154:157], v[80:83], v[164:167], v[180:183]
	v_mfma_f32_16x16x32_bf16 v[158:161], v[84:87], v[164:167], v[160:163]
	v_mfma_f32_16x16x32_bf16 v[162:165], v[80:83], v[172:175], v[184:187]
	v_mfma_f32_16x16x32_bf16 v[166:169], v[84:87], v[172:175], v[168:171]
	v_mfma_f32_16x16x32_bf16 v[170:173], v[80:83], v[212:215], v[188:191]
	v_mfma_f32_16x16x32_bf16 v[180:183], v[84:87], v[212:215], v[192:195]
	s_setprio 0
	s_barrier
	v_mbcnt_lo_u32_b32 v128, -1, 0
	v_mbcnt_hi_u32_b32 v128, -1, v128
	v_cvt_pk_bf16_f32 v112, v112, v113
	v_cvt_pk_bf16_f32 v113, v114, v115
	v_cvt_pk_bf16_f32 v114, v116, v117
	v_cvt_pk_bf16_f32 v115, v118, v119
	s_lshl_b32 s66, s64, 9
	v_add_u32_e32 v174, s72, v128
	v_ashrrev_i32_e32 v175, 6, v174
	v_and_b32_e32 v184, 15, v128
	v_and_b32_e32 v185, 48, v128
	v_mul_lo_u32 v186, v175, s77
	v_bfe_u32 v187, v128, 3, 3
	v_lshlrev_b32_e32 v128, 4, v128
	v_add_u32_e32 v186, 0x20000, v186
	v_lshrrev_b32_e32 v174, 2, v174
	v_and_b32_e32 v128, 0x70, v128
	v_mul_u32_u24_e32 v184, 0x90, v184
	v_and_b32_e32 v174, 64, v174
	v_add3_u32 v184, v186, v184, v185
	v_or_b32_e32 v185, v186, v128
	v_or3_b32 v174, s24, v174, v187
	v_mad_u32_u24 v185, v187, s78, v185
	ds_write_b128 v184, v[112:115]
	v_cvt_pk_bf16_f32 v112, v176, v177
	v_cvt_pk_bf16_f32 v113, v178, v179
	v_cvt_pk_bf16_f32 v114, v130, v131
	v_cvt_pk_bf16_f32 v115, v132, v133
	ds_write_b128 v184, v[112:115] offset:64
	v_lshlrev_b32_e32 v175, 7, v175
	ds_read_b128 v[112:115], v185
	v_lshlrev_b32_e32 v116, 12, v174
	v_and_or_b32 v116, v175, s79, v116
	v_or3_b32 v128, v116, s66, v128
	ds_read_b128 v[116:119], v185 offset:1152
	v_lshl_add_u64 v[130:131], s[0:1], 0, v[128:129]
	s_mov_b32 s64, 0x8000
	s_waitcnt lgkmcnt(0)
	global_store_dwordx4 v128, v[112:115], s[0:1]
	v_cvt_pk_bf16_f32 v108, v108, v109
	v_cvt_pk_bf16_f32 v109, v110, v111
	v_cvt_pk_bf16_f32 v110, v104, v105
	v_cvt_pk_bf16_f32 v111, v106, v107
	v_cvt_pk_bf16_f32 v104, v162, v163
	s_nop 1
	v_add_co_u32_e32 v112, vcc, s64, v130
	v_cvt_pk_bf16_f32 v114, v124, v125
	v_cvt_pk_bf16_f32 v115, v126, v127
	v_cvt_pk_bf16_f32 v105, v164, v165
	v_cvt_pk_bf16_f32 v106, v166, v167
	s_nop 1
	v_addc_co_u32_e32 v113, vcc, 0, v131, vcc
	global_store_dwordx4 v[112:113], v[116:119], off
	v_cvt_pk_bf16_f32 v112, v120, v121
	v_cvt_pk_bf16_f32 v113, v122, v123
	ds_write_b128 v184, v[112:115]
	v_cvt_pk_bf16_f32 v112, v154, v155
	v_cvt_pk_bf16_f32 v113, v156, v157
	v_cvt_pk_bf16_f32 v114, v158, v159
	v_cvt_pk_bf16_f32 v115, v160, v161
	ds_write_b128 v184, v[112:115] offset:64
	ds_read_b128 v[112:115], v185
	ds_read_b128 v[116:119], v185 offset:1152
	v_add_co_u32_e32 v120, vcc, s74, v130
	ds_write_b128 v184, v[108:111]
	v_cvt_pk_bf16_f32 v107, v168, v169
	ds_write_b128 v184, v[104:107] offset:64
	v_addc_co_u32_e32 v121, vcc, 0, v131, vcc
	ds_read_b128 v[104:107], v185
	ds_read_b128 v[108:111], v185 offset:1152
	s_waitcnt lgkmcnt(0)
	global_store_dwordx4 v[120:121], v[112:115], off
	v_cvt_pk_bf16_f32 v100, v100, v101
	v_cvt_pk_bf16_f32 v101, v102, v103
	v_cvt_pk_bf16_f32 v102, v96, v97
	v_cvt_pk_bf16_f32 v103, v98, v99
	ds_write_b128 v184, v[100:103]
	s_nop 0
	v_add_co_u32_e32 v112, vcc, s75, v130
	v_cvt_pk_bf16_f32 v96, v170, v171
	v_cvt_pk_bf16_f32 v97, v172, v173
	v_cvt_pk_bf16_f32 v98, v180, v181
	v_cvt_pk_bf16_f32 v99, v182, v183
	s_nop 1
	v_addc_co_u32_e32 v113, vcc, 0, v131, vcc
	global_store_dwordx4 v[112:113], v[116:119], off
	v_add_co_u32_e32 v112, vcc, s76, v130
	ds_write_b128 v184, v[96:99] offset:64
	s_nop 0
	v_addc_co_u32_e32 v113, vcc, 0, v131, vcc
	ds_read_b128 v[96:99], v185
	ds_read_b128 v[100:103], v185 offset:1152
	global_store_dwordx4 v[112:113], v[104:107], off
	s_nop 1
	v_add_co_u32_e32 v104, vcc, s80, v130
	s_nop 1
	v_addc_co_u32_e32 v105, vcc, 0, v131, vcc
	global_store_dwordx4 v[104:105], v[108:111], off
	v_add_co_u32_e32 v104, vcc, s81, v130
	s_nop 1
	v_addc_co_u32_e32 v105, vcc, 0, v131, vcc
	s_waitcnt lgkmcnt(0)
	global_store_dwordx4 v[104:105], v[96:99], off
	s_nop 1
	v_add_co_u32_e32 v96, vcc, s82, v130
	s_nop 1
	v_addc_co_u32_e32 v97, vcc, 0, v131, vcc
	global_store_dwordx4 v[96:97], v[100:103], off
	ds_read_b128 v[96:99], v153 offset:49152
	ds_read_b128 v[100:103], v153 offset:50176
	ds_read_b128 v[104:107], v152 offset:49152
	ds_read_b128 v[108:111], v152 offset:50176
	ds_read_b128 v[112:115], v151 offset:49152
	ds_read_b128 v[116:119], v151 offset:50176
	ds_read_b128 v[120:123], v150 offset:49152
	ds_read_b128 v[124:127], v150 offset:50176
	s_barrier
	s_waitcnt lgkmcnt(0)
	s_setprio 1
	s_waitcnt lgkmcnt(0)
	v_mfma_f32_16x16x32_bf16 v[32:35], v[8:11], v[96:99], v[32:35]
	v_mfma_f32_16x16x32_bf16 v[36:39], v[76:79], v[96:99], v[36:39]
	v_mfma_f32_16x16x32_bf16 v[40:43], v[8:11], v[104:107], v[40:43]
	v_mfma_f32_16x16x32_bf16 v[130:133], v[76:79], v[104:107], v[44:47]
	v_mfma_f32_16x16x32_bf16 v[150:153], v[8:11], v[112:115], v[48:51]
	v_mfma_f32_16x16x32_bf16 v[52:55], v[76:79], v[112:115], v[52:55]
	v_mfma_f32_16x16x32_bf16 v[8:11], v[8:11], v[120:123], v[56:59]
	v_mfma_f32_16x16x32_bf16 v[60:63], v[76:79], v[120:123], v[60:63]
	v_mfma_f32_16x16x32_bf16 v[56:59], v[0:3], v[100:103], v[32:35]
	v_mfma_f32_16x16x32_bf16 v[48:51], v[72:75], v[100:103], v[36:39]
	v_mfma_f32_16x16x32_bf16 v[44:47], v[0:3], v[108:111], v[40:43]
	v_mfma_f32_16x16x32_bf16 v[40:43], v[72:75], v[108:111], v[130:133]
	v_mfma_f32_16x16x32_bf16 v[36:39], v[0:3], v[116:119], v[150:153]
	v_mfma_f32_16x16x32_bf16 v[32:35], v[72:75], v[116:119], v[52:55]
	v_mfma_f32_16x16x32_bf16 v[8:11], v[0:3], v[124:127], v[8:11]
	v_mfma_f32_16x16x32_bf16 v[0:3], v[72:75], v[124:127], v[60:63]
	s_setprio 0
	s_setprio 1
	v_mfma_f32_16x16x32_bf16 v[4:7], v[88:91], v[96:99], v[4:7]
	v_mfma_f32_16x16x32_bf16 v[12:15], v[92:95], v[96:99], v[12:15]
	v_mfma_f32_16x16x32_bf16 v[16:19], v[88:91], v[104:107], v[16:19]
	v_mfma_f32_16x16x32_bf16 v[20:23], v[92:95], v[104:107], v[20:23]
	v_mfma_f32_16x16x32_bf16 v[72:75], v[88:91], v[112:115], v[24:27]
	v_mfma_f32_16x16x32_bf16 v[76:79], v[92:95], v[112:115], v[28:31]
	v_mfma_f32_16x16x32_bf16 v[64:67], v[88:91], v[120:123], v[64:67]
	v_mfma_f32_16x16x32_bf16 v[68:71], v[92:95], v[120:123], v[68:71]
	v_mfma_f32_16x16x32_bf16 v[60:63], v[80:83], v[100:103], v[4:7]
	v_mfma_f32_16x16x32_bf16 v[52:55], v[84:87], v[100:103], v[12:15]
	v_mfma_f32_16x16x32_bf16 v[28:31], v[80:83], v[108:111], v[16:19]
	v_mfma_f32_16x16x32_bf16 v[24:27], v[84:87], v[108:111], v[20:23]
	v_mfma_f32_16x16x32_bf16 v[20:23], v[80:83], v[116:119], v[72:75]
	v_mfma_f32_16x16x32_bf16 v[16:19], v[84:87], v[116:119], v[76:79]
	v_mfma_f32_16x16x32_bf16 v[12:15], v[80:83], v[124:127], v[64:67]
	v_mfma_f32_16x16x32_bf16 v[4:7], v[84:87], v[124:127], v[68:71]
	s_setprio 0
	v_cmp_gt_u32_e32 vcc, s83, v136
	s_barrier
	s_and_saveexec_b64 s[64:65], vcc
	s_cbranch_execz .LBB0_181
	s_barrier

.LBB0_233:
	v_bfe_i32 v5, v179, 27, 1
	v_lshlrev_b32_e32 v169, 4, v179
	v_lshrrev_b32_e32 v5, 22, v5
	v_add_u32_e32 v5, v169, v5
	v_and_b32_e32 v5, 0xfffffc00, v5
	v_sub_u32_e32 v5, v169, v5
	v_lshrrev_b32_e32 v6, 4, v5
	v_bitop3_b32 v5, v6, v5, 32 bitop3:0x6c
	v_ashrrev_i32_e32 v6, 31, v5
	v_lshrrev_b32_e32 v6, 26, v6
	v_ashrrev_i32_e32 v4, 31, v179
	v_add_u32_e32 v6, v5, v6
	s_lshl_b32 s56, s83, 3
	v_lshrrev_b32_e32 v4, 26, v4
	v_ashrrev_i32_e32 v133, 6, v6
	v_and_b32_e32 v6, 0xc0, v6
	s_ff1_i32_b32 s57, s56
	s_add_i32 s56, s56, -1
	v_and_b32_e32 v2, 15, v0
	v_and_b32_e32 v3, 48, v0
	v_add_u32_e32 v4, v179, v4
	v_sub_u32_e32 v5, v5, v6
	v_and_b32_e32 v6, 32, v0
	v_lshlrev_b32_e32 v10, 2, v0
	v_lshlrev_b32_e32 v0, 6, v0
	s_lshr_b32 s62, s85, s57
	s_and_b32 s56, s85, s56
	s_and_b32 s63, s85, 7
	v_ashrrev_i32_e32 v131, 6, v4
	v_lshlrev_b32_e32 v2, 6, v2
	v_and_b32_e32 v10, 32, v10
	v_and_b32_e32 v0, 0x3c0, v0
	s_lshr_b32 s80, s56, 3
	v_or_b32_e32 v9, v2, v3
	v_bitop3_b32 v2, v2, v10, v3 bitop3:0x36
	v_bitop3_b32 v3, v0, v10, v3 bitop3:0x36
	s_lshl_b32 s56, s62, 11
	s_lshl_b32 s57, s63, 8
	v_lshlrev_b32_e32 v0, 16, v131
	s_or_b32 s56, s56, s57
	s_mov_b32 s57, s15
	v_and_b32_e32 v0, 0xfffe0000, v0
	s_lshl_b32 s60, s80, 14
	v_ashrrev_i16_sdwa v5, v167, sext(v5) dst_sel:DWORD dst_unused:UNUSED_PAD src0_sel:DWORD src1_sel:BYTE_0
	s_lshl_b64 s[56:57], s[56:57], 13
	v_lshl_add_u32 v0, v133, 13, v0
	v_bfe_i32 v134, v5, 0, 16
	v_and_or_b32 v0, v4, 64, v0
	s_add_u32 s56, s40, s56
	v_lshl_add_u32 v164, v134, 1, v0
	s_addc_u32 s57, s41, s57
	v_lshlrev_b32_e32 v14, 13, v1
	v_lshl_add_u64 v[0:1], s[56:57], 0, v[164:165]
	s_mul_i32 s57, s14, 0x1800
	s_mul_hi_u32 s56, s14, 0x1800
	s_add_u32 s57, s57, s60
	s_addc_u32 s58, s56, 0
	s_add_u32 s56, s65, s57
	v_bfe_i32 v7, v179, 6, 1
	s_addc_u32 s57, s66, s58
	s_lshl_b64 s[58:59], s[14:15], 12
	v_and_b32_e32 v7, s14, v7
	v_lshrrev_b32_e32 v8, 7, v179
	s_add_u32 s14, s58, s60
	v_add_lshl_u32 v7, v7, v8, 10
	v_lshlrev_b32_e32 v8, 6, v179
	s_addc_u32 s61, s59, 0
	v_and_b32_e32 v5, 0x3f0, v169
	v_and_b32_e32 v8, 0x3000, v8
	v_bitop3_b32 v11, v9, s67, v10 bitop3:0xde
	v_bitop3_b32 v12, v9, s69, v10 bitop3:0xde
	v_bitop3_b32 v13, v9, s70, v10 bitop3:0xde
	v_bitop3_b32 v9, v9, s71, v10 bitop3:0xde
	v_or_b32_e32 v10, 0x800, v14
	v_or_b32_e32 v15, 0x1000, v14
	v_or_b32_e32 v16, 0x1800, v14
	v_lshl_add_u64 v[128:129], v[0:1], 0, s[16:17]
	s_add_u32 s60, s65, s14
	v_mov_b32_e32 v0, 0
	v_bitop3_b32 v164, v5, v7, v6 bitop3:0xde
	s_addc_u32 s61, s66, s61
	s_mov_b32 s14, -2
	v_add_u32_e32 v138, v11, v8
	v_add_u32_e32 v193, v2, v14
	v_add_u32_e32 v192, v3, v10
	v_add_u32_e32 v191, v3, v15
	v_add_u32_e32 v190, v3, v16
	v_add_u32_e32 v137, 0xc000, v169
	v_add_u32_e32 v136, 0xe000, v169
	v_add_u32_e32 v135, v12, v8
	v_add_u32_e32 v189, 0x10000, v169
	v_add_u32_e32 v188, 0x12000, v169
	v_add_u32_e32 v187, 0x2000, v169
	v_add_u32_e32 v186, 0x14000, v169
	v_add_u32_e32 v185, 0x16000, v169
	v_add_u32_e32 v130, v13, v8
	v_add_u32_e32 v184, 0x4000, v169
	v_add_u32_e32 v183, 0x6000, v169
	v_add_u32_e32 v132, v9, v8
	v_add_u32_e32 v182, 0x18000, v169
	v_add_u32_e32 v181, 0x1a000, v169
	v_add_u32_e32 v177, 0x8000, v169
	v_add_u32_e32 v175, 0xa000, v169
	v_add_u32_e32 v173, 0x1c000, v169
	v_add_u32_e32 v171, 0x1e000, v169
	v_mov_b32_e32 v1, v0
	v_mov_b32_e32 v2, v0
	v_mov_b32_e32 v3, v0
	v_mov_b32_e32 v4, v0
	v_mov_b32_e32 v5, v0
	v_mov_b32_e32 v6, v0
	v_mov_b32_e32 v7, v0
	v_mov_b32_e32 v8, v0
	v_mov_b32_e32 v9, v0
	v_mov_b32_e32 v10, v0
	v_mov_b32_e32 v11, v0
	v_mov_b32_e32 v12, v0
	v_mov_b32_e32 v13, v0
	v_mov_b32_e32 v14, v0
	v_mov_b32_e32 v15, v0
	v_mov_b32_e32 v16, v0
	v_mov_b32_e32 v17, v0
	v_mov_b32_e32 v18, v0
	v_mov_b32_e32 v19, v0
	v_mov_b32_e32 v20, v0
	v_mov_b32_e32 v21, v0
	v_mov_b32_e32 v22, v0
	v_mov_b32_e32 v23, v0
	v_mov_b32_e32 v24, v0
	v_mov_b32_e32 v25, v0
	v_mov_b32_e32 v26, v0
	v_mov_b32_e32 v27, v0
	v_mov_b32_e32 v28, v0
	v_mov_b32_e32 v29, v0
	v_mov_b32_e32 v30, v0
	v_mov_b32_e32 v31, v0
	v_mov_b32_e32 v32, v0
	v_mov_b32_e32 v33, v0
	v_mov_b32_e32 v34, v0
	v_mov_b32_e32 v35, v0
	v_mov_b32_e32 v36, v0
	v_mov_b32_e32 v37, v0
	v_mov_b32_e32 v38, v0
	v_mov_b32_e32 v39, v0
	v_mov_b32_e32 v40, v0
	v_mov_b32_e32 v41, v0
	v_mov_b32_e32 v42, v0
	v_mov_b32_e32 v43, v0
	v_mov_b32_e32 v44, v0
	v_mov_b32_e32 v45, v0
	v_mov_b32_e32 v46, v0
	v_mov_b32_e32 v47, v0
	v_mov_b32_e32 v48, v0
	v_mov_b32_e32 v49, v0
	v_mov_b32_e32 v50, v0
	v_mov_b32_e32 v51, v0
	v_mov_b32_e32 v52, v0
	v_mov_b32_e32 v53, v0
	v_mov_b32_e32 v54, v0
	v_mov_b32_e32 v55, v0
	v_mov_b32_e32 v56, v0
	v_mov_b32_e32 v57, v0
	v_mov_b32_e32 v58, v0
	v_mov_b32_e32 v59, v0
	v_mov_b32_e32 v60, v0
	v_mov_b32_e32 v61, v0
	v_mov_b32_e32 v62, v0
	v_mov_b32_e32 v63, v0
	v_mov_b32_e32 v64, v0
	v_mov_b32_e32 v65, v0
	v_mov_b32_e32 v66, v0
	v_mov_b32_e32 v67, v0
	v_mov_b32_e32 v68, v0
	v_mov_b32_e32 v69, v0
	v_mov_b32_e32 v70, v0
	v_mov_b32_e32 v71, v0
	v_mov_b32_e32 v72, v0
	v_mov_b32_e32 v73, v0
	v_mov_b32_e32 v74, v0
	v_mov_b32_e32 v75, v0
	v_mov_b32_e32 v76, v0
	v_mov_b32_e32 v77, v0
	v_mov_b32_e32 v78, v0
	v_mov_b32_e32 v79, v0
	v_mov_b32_e32 v80, v0
	v_mov_b32_e32 v81, v0
	v_mov_b32_e32 v82, v0
	v_mov_b32_e32 v83, v0
	v_mov_b32_e32 v84, v0
	v_mov_b32_e32 v85, v0
	v_mov_b32_e32 v86, v0
	v_mov_b32_e32 v87, v0
	v_mov_b32_e32 v88, v0
	v_mov_b32_e32 v89, v0
	v_mov_b32_e32 v90, v0
	v_mov_b32_e32 v91, v0
	v_mov_b32_e32 v92, v0
	v_mov_b32_e32 v93, v0
	v_mov_b32_e32 v94, v0
	v_mov_b32_e32 v95, v0
	v_mov_b32_e32 v96, v0
	v_mov_b32_e32 v97, v0
	v_mov_b32_e32 v98, v0
	v_mov_b32_e32 v99, v0
	v_mov_b32_e32 v100, v0
	v_mov_b32_e32 v101, v0
	v_mov_b32_e32 v102, v0
	v_mov_b32_e32 v103, v0
	v_mov_b32_e32 v104, v0
	v_mov_b32_e32 v105, v0
	v_mov_b32_e32 v106, v0
	v_mov_b32_e32 v107, v0
	v_mov_b32_e32 v108, v0
	v_mov_b32_e32 v109, v0
	v_mov_b32_e32 v110, v0
	v_mov_b32_e32 v111, v0
	v_mov_b32_e32 v112, v0
	v_mov_b32_e32 v113, v0
	v_mov_b32_e32 v114, v0
	v_mov_b32_e32 v115, v0
	v_mov_b32_e32 v116, v0
	v_mov_b32_e32 v117, v0
	v_mov_b32_e32 v118, v0
	v_mov_b32_e32 v119, v0
	v_mov_b32_e32 v120, v0
	v_mov_b32_e32 v121, v0
	v_mov_b32_e32 v122, v0
	v_mov_b32_e32 v123, v0
	v_mov_b32_e32 v124, v0
	v_mov_b32_e32 v125, v0
	v_mov_b32_e32 v126, v0
	v_mov_b32_e32 v127, v0
	s_barrier
	v_readfirstlane_b32 s82, v137
	v_lshl_add_u64 v[142:143], v[128:129], 0, s[18:19]
	s_mov_b32 m0, s82
	v_readfirstlane_b32 s82, v136
	global_load_lds_dwordx4 v[142:143], off
	v_lshl_add_u64 v[142:143], v[128:129], 0, s[20:21]
	s_mov_b32 m0, s82
	s_nop 0
	global_load_lds_dwordx4 v[142:143], off
	ds_read_b128 v[140:143], v138
	ds_read_b128 v[144:147], v138 offset:1024
	ds_read_b128 v[148:151], v138 offset:2048
	ds_read_b128 v[152:155], v138 offset:3072
	ds_read_b128 v[156:159], v193
	ds_read_b128 v[160:163], v193 offset:1024
	ds_read_b128 v[194:197], v192
	ds_read_b128 v[198:201], v192 offset:1024
	ds_read_b128 v[202:205], v191
	ds_read_b128 v[206:209], v191 offset:1024
	ds_read_b128 v[210:213], v190
	ds_read_b128 v[214:217], v190 offset:1024
	s_waitcnt lgkmcnt(8)
	s_barrier
	s_branch .Lkent_234

.Lkent_234:
	s_waitcnt lgkmcnt(0)
	s_setprio 1
	s_waitcnt lgkmcnt(0)
	v_mfma_f32_16x16x32_bf16 v[124:127], v[140:143], v[156:159], v[124:127]
	v_mfma_f32_16x16x32_bf16 v[120:123], v[148:151], v[156:159], v[120:123]
	v_mfma_f32_16x16x32_bf16 v[116:119], v[140:143], v[194:197], v[116:119]
	v_mfma_f32_16x16x32_bf16 v[112:115], v[148:151], v[194:197], v[112:115]
	v_mfma_f32_16x16x32_bf16 v[108:111], v[140:143], v[202:205], v[108:111]
	v_mfma_f32_16x16x32_bf16 v[104:107], v[148:151], v[202:205], v[104:107]
	v_mfma_f32_16x16x32_bf16 v[100:103], v[140:143], v[210:213], v[100:103]
	v_mfma_f32_16x16x32_bf16 v[96:99], v[148:151], v[210:213], v[96:99]
	v_mfma_f32_16x16x32_bf16 v[124:127], v[144:147], v[160:163], v[124:127]
	v_mfma_f32_16x16x32_bf16 v[120:123], v[152:155], v[160:163], v[120:123]
	v_mfma_f32_16x16x32_bf16 v[116:119], v[144:147], v[198:201], v[116:119]
	v_mfma_f32_16x16x32_bf16 v[112:115], v[152:155], v[198:201], v[112:115]
	v_mfma_f32_16x16x32_bf16 v[108:111], v[144:147], v[206:209], v[108:111]
	v_mfma_f32_16x16x32_bf16 v[104:107], v[152:155], v[206:209], v[104:107]
	v_mfma_f32_16x16x32_bf16 v[100:103], v[144:147], v[214:217], v[100:103]
	v_mfma_f32_16x16x32_bf16 v[96:99], v[152:155], v[214:217], v[96:99]
	s_setprio 0
	s_barrier
	v_readfirstlane_b32 s82, v189
	v_lshl_add_u64 v[234:235], s[60:61], 0, v[164:165]
	s_mov_b32 m0, s82
	v_readfirstlane_b32 s82, v188
	ds_read_b128 v[218:221], v135
	ds_read_b128 v[222:225], v135 offset:1024
	ds_read_b128 v[226:229], v135 offset:2048
	ds_read_b128 v[230:233], v135 offset:3072
	global_load_lds_dwordx4 v[234:235], off
	v_lshl_add_u64 v[236:237], v[234:235], 0, s[2:3]
	s_mov_b32 m0, s82
	s_nop 0
	global_load_lds_dwordx4 v[236:237], off
	v_readfirstlane_b32 s82, v169
	v_lshl_add_u64 v[236:237], v[128:129], 0, s[22:23]
	s_mov_b32 m0, s82
	v_readfirstlane_b32 s82, v187
	global_load_lds_dwordx4 v[236:237], off
	v_lshl_add_u64 v[236:237], v[128:129], 0, s[24:25]
	s_mov_b32 m0, s82
	s_nop 0
	global_load_lds_dwordx4 v[236:237], off
	s_waitcnt vmcnt(12)
	s_barrier
	s_waitcnt lgkmcnt(0)
	s_setprio 1
	s_waitcnt lgkmcnt(0)
	v_mfma_f32_16x16x32_bf16 v[92:95], v[218:221], v[156:159], v[92:95]
	v_mfma_f32_16x16x32_bf16 v[88:91], v[226:229], v[156:159], v[88:91]
	v_mfma_f32_16x16x32_bf16 v[84:87], v[218:221], v[194:197], v[84:87]
	v_mfma_f32_16x16x32_bf16 v[80:83], v[226:229], v[194:197], v[80:83]
	v_mfma_f32_16x16x32_bf16 v[76:79], v[218:221], v[202:205], v[76:79]
	v_mfma_f32_16x16x32_bf16 v[72:75], v[226:229], v[202:205], v[72:75]
	v_mfma_f32_16x16x32_bf16 v[68:71], v[218:221], v[210:213], v[68:71]
	v_mfma_f32_16x16x32_bf16 v[64:67], v[226:229], v[210:213], v[64:67]
	v_mfma_f32_16x16x32_bf16 v[92:95], v[222:225], v[160:163], v[92:95]
	v_mfma_f32_16x16x32_bf16 v[88:91], v[230:233], v[160:163], v[88:91]
	v_mfma_f32_16x16x32_bf16 v[84:87], v[222:225], v[198:201], v[84:87]
	v_mfma_f32_16x16x32_bf16 v[80:83], v[230:233], v[198:201], v[80:83]
	v_mfma_f32_16x16x32_bf16 v[76:79], v[222:225], v[206:209], v[76:79]
	v_mfma_f32_16x16x32_bf16 v[72:75], v[230:233], v[206:209], v[72:75]
	v_mfma_f32_16x16x32_bf16 v[68:71], v[222:225], v[214:217], v[68:71]
	v_mfma_f32_16x16x32_bf16 v[64:67], v[230:233], v[214:217], v[64:67]
	s_setprio 0
	s_barrier
	ds_read_b128 v[156:159], v193 offset:16384
	ds_read_b128 v[160:163], v193 offset:17408
	ds_read_b128 v[194:197], v192 offset:16384
	ds_read_b128 v[198:201], v192 offset:17408
	ds_read_b128 v[202:205], v191 offset:16384
	ds_read_b128 v[206:209], v191 offset:17408
	ds_read_b128 v[210:213], v190 offset:16384
	ds_read_b128 v[214:217], v190 offset:17408
	v_readfirstlane_b32 s82, v186
	v_lshl_add_u64 v[236:237], v[234:235], 0, s[6:7]
	s_mov_b32 m0, s82
	v_readfirstlane_b32 s82, v185
	global_load_lds_dwordx4 v[236:237], off
	v_lshl_add_u64 v[236:237], v[234:235], 0, s[8:9]
	s_mov_b32 m0, s82
	s_nop 0
	global_load_lds_dwordx4 v[236:237], off
	s_barrier
	s_waitcnt lgkmcnt(0)
	s_setprio 1
	s_waitcnt lgkmcnt(0)
	v_mfma_f32_16x16x32_bf16 v[60:63], v[140:143], v[156:159], v[60:63]
	v_mfma_f32_16x16x32_bf16 v[56:59], v[148:151], v[156:159], v[56:59]
	v_mfma_f32_16x16x32_bf16 v[52:55], v[140:143], v[194:197], v[52:55]
	v_mfma_f32_16x16x32_bf16 v[48:51], v[148:151], v[194:197], v[48:51]
	v_mfma_f32_16x16x32_bf16 v[44:47], v[140:143], v[202:205], v[44:47]
	v_mfma_f32_16x16x32_bf16 v[40:43], v[148:151], v[202:205], v[40:43]
	v_mfma_f32_16x16x32_bf16 v[36:39], v[140:143], v[210:213], v[36:39]
	v_mfma_f32_16x16x32_bf16 v[32:35], v[148:151], v[210:213], v[32:35]
	v_mfma_f32_16x16x32_bf16 v[60:63], v[144:147], v[160:163], v[60:63]
	v_mfma_f32_16x16x32_bf16 v[56:59], v[152:155], v[160:163], v[56:59]
	v_mfma_f32_16x16x32_bf16 v[52:55], v[144:147], v[198:201], v[52:55]
	v_mfma_f32_16x16x32_bf16 v[48:51], v[152:155], v[198:201], v[48:51]
	v_mfma_f32_16x16x32_bf16 v[44:47], v[144:147], v[206:209], v[44:47]
	v_mfma_f32_16x16x32_bf16 v[40:43], v[152:155], v[206:209], v[40:43]
	v_mfma_f32_16x16x32_bf16 v[36:39], v[144:147], v[214:217], v[36:39]
	v_mfma_f32_16x16x32_bf16 v[32:35], v[152:155], v[214:217], v[32:35]
	s_setprio 0
	s_barrier
	v_readfirstlane_b32 s82, v184
	v_lshl_add_u64 v[142:143], v[128:129], 0, s[26:27]
	s_mov_b32 m0, s82
	v_readfirstlane_b32 s82, v183
	global_load_lds_dwordx4 v[142:143], off
	s_mov_b32 m0, s82
	s_nop 0
	global_load_lds_dwordx4 v[128:129], off
	s_waitcnt vmcnt(12)
	s_barrier
	s_setprio 1
	v_mfma_f32_16x16x32_bf16 v[28:31], v[218:221], v[156:159], v[28:31]
	v_mfma_f32_16x16x32_bf16 v[24:27], v[226:229], v[156:159], v[24:27]
	v_mfma_f32_16x16x32_bf16 v[20:23], v[218:221], v[194:197], v[20:23]
	v_mfma_f32_16x16x32_bf16 v[16:19], v[226:229], v[194:197], v[16:19]
	v_mfma_f32_16x16x32_bf16 v[12:15], v[218:221], v[202:205], v[12:15]
	v_mfma_f32_16x16x32_bf16 v[8:11], v[226:229], v[202:205], v[8:11]
	v_mfma_f32_16x16x32_bf16 v[4:7], v[218:221], v[210:213], v[4:7]
	v_mfma_f32_16x16x32_bf16 v[0:3], v[226:229], v[210:213], v[0:3]
	v_mfma_f32_16x16x32_bf16 v[28:31], v[222:225], v[160:163], v[28:31]
	v_mfma_f32_16x16x32_bf16 v[24:27], v[230:233], v[160:163], v[24:27]
	v_mfma_f32_16x16x32_bf16 v[20:23], v[222:225], v[198:201], v[20:23]
	v_mfma_f32_16x16x32_bf16 v[16:19], v[230:233], v[198:201], v[16:19]
	v_mfma_f32_16x16x32_bf16 v[12:15], v[222:225], v[206:209], v[12:15]
	v_mfma_f32_16x16x32_bf16 v[8:11], v[230:233], v[206:209], v[8:11]
	v_mfma_f32_16x16x32_bf16 v[4:7], v[222:225], v[214:217], v[4:7]
	v_mfma_f32_16x16x32_bf16 v[0:3], v[230:233], v[214:217], v[0:3]
	s_setprio 0
	s_barrier
	ds_read_b128 v[140:143], v130
	ds_read_b128 v[144:147], v130 offset:1024
	ds_read_b128 v[148:151], v130 offset:2048
	ds_read_b128 v[152:155], v130 offset:3072
	ds_read_b128 v[156:159], v193 offset:32768
	ds_read_b128 v[160:163], v193 offset:33792
	ds_read_b128 v[194:197], v192 offset:32768
	ds_read_b128 v[198:201], v192 offset:33792
	ds_read_b128 v[202:205], v191 offset:32768
	ds_read_b128 v[206:209], v191 offset:33792
	ds_read_b128 v[210:213], v190 offset:32768
	ds_read_b128 v[214:217], v190 offset:33792
	s_waitcnt lgkmcnt(8)
	s_waitcnt vmcnt(10)
	s_barrier
	s_waitcnt lgkmcnt(0)
	s_setprio 1
	s_waitcnt lgkmcnt(0)
	v_mfma_f32_16x16x32_bf16 v[124:127], v[140:143], v[156:159], v[124:127]
	v_mfma_f32_16x16x32_bf16 v[120:123], v[148:151], v[156:159], v[120:123]
	v_mfma_f32_16x16x32_bf16 v[116:119], v[140:143], v[194:197], v[116:119]
	v_mfma_f32_16x16x32_bf16 v[112:115], v[148:151], v[194:197], v[112:115]
	v_mfma_f32_16x16x32_bf16 v[108:111], v[140:143], v[202:205], v[108:111]
	v_mfma_f32_16x16x32_bf16 v[104:107], v[148:151], v[202:205], v[104:107]
	v_mfma_f32_16x16x32_bf16 v[100:103], v[140:143], v[210:213], v[100:103]
	v_mfma_f32_16x16x32_bf16 v[96:99], v[148:151], v[210:213], v[96:99]
	v_mfma_f32_16x16x32_bf16 v[124:127], v[144:147], v[160:163], v[124:127]
	v_mfma_f32_16x16x32_bf16 v[120:123], v[152:155], v[160:163], v[120:123]
	v_mfma_f32_16x16x32_bf16 v[116:119], v[144:147], v[198:201], v[116:119]
	v_mfma_f32_16x16x32_bf16 v[112:115], v[152:155], v[198:201], v[112:115]
	v_mfma_f32_16x16x32_bf16 v[108:111], v[144:147], v[206:209], v[108:111]
	v_mfma_f32_16x16x32_bf16 v[104:107], v[152:155], v[206:209], v[104:107]
	v_mfma_f32_16x16x32_bf16 v[100:103], v[144:147], v[214:217], v[100:103]
	v_mfma_f32_16x16x32_bf16 v[96:99], v[152:155], v[214:217], v[96:99]
	s_setprio 0
	s_barrier
	v_readfirstlane_b32 s82, v182
	v_lshl_add_u64 v[234:235], s[56:57], 0, v[164:165]
	s_mov_b32 m0, s82
	v_readfirstlane_b32 s82, v181
	ds_read_b128 v[218:221], v132
	ds_read_b128 v[222:225], v132 offset:1024
	ds_read_b128 v[226:229], v132 offset:2048
	ds_read_b128 v[230:233], v132 offset:3072
	global_load_lds_dwordx4 v[234:235], off
	v_lshl_add_u64 v[236:237], v[234:235], 0, s[2:3]
	s_mov_b32 m0, s82
	s_nop 0
	global_load_lds_dwordx4 v[236:237], off
	v_readfirstlane_b32 s82, v177
	v_lshl_add_u64 v[236:237], v[128:129], 0, s[28:29]
	s_mov_b32 m0, s82
	v_readfirstlane_b32 s82, v175
	global_load_lds_dwordx4 v[236:237], off
	v_lshl_add_u64 v[236:237], v[128:129], 0, s[30:31]
	s_mov_b32 m0, s82
	s_nop 0
	global_load_lds_dwordx4 v[236:237], off
	s_waitcnt vmcnt(12)
	s_barrier
	s_waitcnt lgkmcnt(0)
	s_setprio 1
	s_waitcnt lgkmcnt(0)
	v_mfma_f32_16x16x32_bf16 v[92:95], v[218:221], v[156:159], v[92:95]
	v_mfma_f32_16x16x32_bf16 v[88:91], v[226:229], v[156:159], v[88:91]
	v_mfma_f32_16x16x32_bf16 v[84:87], v[218:221], v[194:197], v[84:87]
	v_mfma_f32_16x16x32_bf16 v[80:83], v[226:229], v[194:197], v[80:83]
	v_mfma_f32_16x16x32_bf16 v[76:79], v[218:221], v[202:205], v[76:79]
	v_mfma_f32_16x16x32_bf16 v[72:75], v[226:229], v[202:205], v[72:75]
	v_mfma_f32_16x16x32_bf16 v[68:71], v[218:221], v[210:213], v[68:71]
	v_mfma_f32_16x16x32_bf16 v[64:67], v[226:229], v[210:213], v[64:67]
	v_mfma_f32_16x16x32_bf16 v[92:95], v[222:225], v[160:163], v[92:95]
	v_mfma_f32_16x16x32_bf16 v[88:91], v[230:233], v[160:163], v[88:91]
	v_mfma_f32_16x16x32_bf16 v[84:87], v[222:225], v[198:201], v[84:87]
	v_mfma_f32_16x16x32_bf16 v[80:83], v[230:233], v[198:201], v[80:83]
	v_mfma_f32_16x16x32_bf16 v[76:79], v[222:225], v[206:209], v[76:79]
	v_mfma_f32_16x16x32_bf16 v[72:75], v[230:233], v[206:209], v[72:75]
	v_mfma_f32_16x16x32_bf16 v[68:71], v[222:225], v[214:217], v[68:71]
	v_mfma_f32_16x16x32_bf16 v[64:67], v[230:233], v[214:217], v[64:67]
	s_setprio 0
	s_barrier
	ds_read_b128 v[156:159], v193 offset:49152
	ds_read_b128 v[160:163], v193 offset:50176
	ds_read_b128 v[194:197], v192 offset:49152
	ds_read_b128 v[198:201], v192 offset:50176
	ds_read_b128 v[202:205], v191 offset:49152
	ds_read_b128 v[206:209], v191 offset:50176
	ds_read_b128 v[210:213], v190 offset:49152
	ds_read_b128 v[214:217], v190 offset:50176
	v_readfirstlane_b32 s82, v173
	v_lshl_add_u64 v[236:237], v[234:235], 0, s[6:7]
	s_mov_b32 m0, s82
	v_readfirstlane_b32 s82, v171
	global_load_lds_dwordx4 v[236:237], off
	v_lshl_add_u64 v[236:237], v[234:235], 0, s[8:9]
	s_mov_b32 m0, s82
	s_nop 0
	global_load_lds_dwordx4 v[236:237], off
	s_barrier
	s_waitcnt lgkmcnt(0)
	s_setprio 1
	s_waitcnt lgkmcnt(0)
	v_mfma_f32_16x16x32_bf16 v[60:63], v[140:143], v[156:159], v[60:63]
	v_mfma_f32_16x16x32_bf16 v[56:59], v[148:151], v[156:159], v[56:59]
	v_mfma_f32_16x16x32_bf16 v[52:55], v[140:143], v[194:197], v[52:55]
	v_mfma_f32_16x16x32_bf16 v[48:51], v[148:151], v[194:197], v[48:51]
	v_mfma_f32_16x16x32_bf16 v[44:47], v[140:143], v[202:205], v[44:47]
	v_mfma_f32_16x16x32_bf16 v[40:43], v[148:151], v[202:205], v[40:43]
	v_mfma_f32_16x16x32_bf16 v[36:39], v[140:143], v[210:213], v[36:39]
	v_mfma_f32_16x16x32_bf16 v[32:35], v[148:151], v[210:213], v[32:35]
	v_mfma_f32_16x16x32_bf16 v[60:63], v[144:147], v[160:163], v[60:63]
	v_mfma_f32_16x16x32_bf16 v[56:59], v[152:155], v[160:163], v[56:59]
	v_mfma_f32_16x16x32_bf16 v[52:55], v[144:147], v[198:201], v[52:55]
	v_mfma_f32_16x16x32_bf16 v[48:51], v[152:155], v[198:201], v[48:51]
	v_mfma_f32_16x16x32_bf16 v[44:47], v[144:147], v[206:209], v[44:47]
	v_mfma_f32_16x16x32_bf16 v[40:43], v[152:155], v[206:209], v[40:43]
	v_mfma_f32_16x16x32_bf16 v[36:39], v[144:147], v[214:217], v[36:39]
	v_mfma_f32_16x16x32_bf16 v[32:35], v[152:155], v[214:217], v[32:35]
	s_setprio 0
	s_barrier
	v_lshl_add_u64 v[128:129], v[128:129], 0, s[34:35]
	v_readfirstlane_b32 s82, v137
	v_lshl_add_u64 v[142:143], v[128:129], 0, s[18:19]
	s_mov_b32 m0, s82
	v_readfirstlane_b32 s82, v136
	global_load_lds_dwordx4 v[142:143], off
	v_lshl_add_u64 v[142:143], v[128:129], 0, s[20:21]
	s_mov_b32 m0, s82
	s_nop 0
	global_load_lds_dwordx4 v[142:143], off
	s_waitcnt vmcnt(12)
	s_barrier
	s_setprio 1
	v_mfma_f32_16x16x32_bf16 v[28:31], v[218:221], v[156:159], v[28:31]
	v_mfma_f32_16x16x32_bf16 v[24:27], v[226:229], v[156:159], v[24:27]
	v_mfma_f32_16x16x32_bf16 v[20:23], v[218:221], v[194:197], v[20:23]
	v_mfma_f32_16x16x32_bf16 v[16:19], v[226:229], v[194:197], v[16:19]
	v_mfma_f32_16x16x32_bf16 v[12:15], v[218:221], v[202:205], v[12:15]
	v_mfma_f32_16x16x32_bf16 v[8:11], v[226:229], v[202:205], v[8:11]
	v_mfma_f32_16x16x32_bf16 v[4:7], v[218:221], v[210:213], v[4:7]
	v_mfma_f32_16x16x32_bf16 v[0:3], v[226:229], v[210:213], v[0:3]
	v_mfma_f32_16x16x32_bf16 v[28:31], v[222:225], v[160:163], v[28:31]
	v_mfma_f32_16x16x32_bf16 v[24:27], v[230:233], v[160:163], v[24:27]
	v_mfma_f32_16x16x32_bf16 v[20:23], v[222:225], v[198:201], v[20:23]
	v_mfma_f32_16x16x32_bf16 v[16:19], v[230:233], v[198:201], v[16:19]
	v_mfma_f32_16x16x32_bf16 v[12:15], v[222:225], v[206:209], v[12:15]
	v_mfma_f32_16x16x32_bf16 v[8:11], v[230:233], v[206:209], v[8:11]
	v_mfma_f32_16x16x32_bf16 v[4:7], v[222:225], v[214:217], v[4:7]
	v_mfma_f32_16x16x32_bf16 v[0:3], v[230:233], v[214:217], v[0:3]
	s_setprio 0
	s_add_i32 s14, s14, 2
	s_add_u32 s56, s56, s58
	s_addc_u32 s57, s57, s59
	s_add_u32 s60, s60, s58
	s_addc_u32 s61, s61, s59
	s_cmp_lt_u32 s14, 28
	s_barrier
	s_cbranch_scc1 .LBB0_234
	s_lshl_b32 s14, s62, 3
	s_or_b32 s82, s63, s14
	s_lshl_b32 s56, s82, 8
	v_lshlrev_b32_e32 v128, 3, v131
	v_lshlrev_b32_e32 v129, 5, v131
	s_or_b32 s14, s56, 0x80
	v_and_b32_e32 v128, 0x7fff0, v128
	v_and_b32_e32 v129, 32, v129
	s_lshl_b64 s[58:59], s[14:15], 13
	v_add_u32_e32 v129, v129, v134
	v_add_lshl_u32 v128, v133, v128, 13
	s_add_u32 s58, s40, s58
	v_lshl_add_u32 v164, v129, 1, v128
	s_addc_u32 s59, s41, s59
	v_lshl_add_u64 v[128:129], s[58:59], 0, v[164:165]
	v_readfirstlane_b32 s14, v137
	ds_read_b128 v[140:143], v138
	ds_read_b128 v[144:147], v138 offset:1024
	ds_read_b128 v[148:151], v138 offset:2048
	ds_read_b128 v[152:155], v138 offset:3072
	ds_read_b128 v[156:159], v193
	ds_read_b128 v[160:163], v193 offset:1024
	ds_read_b128 v[194:197], v192
	ds_read_b128 v[198:201], v192 offset:1024
	ds_read_b128 v[202:205], v191
	ds_read_b128 v[206:209], v191 offset:1024
	ds_read_b128 v[210:213], v190
	ds_read_b128 v[214:217], v190 offset:1024
	v_lshl_add_u64 v[138:139], v[128:129], 0, s[44:45]
	s_mov_b32 m0, s14
	v_readfirstlane_b32 s14, v136
	global_load_lds_dwordx4 v[138:139], off
	v_lshl_add_u64 v[128:129], v[128:129], 0, s[46:47]
	s_mov_b32 m0, s14
	s_mov_b32 s57, s15
	global_load_lds_dwordx4 v[128:129], off
	s_waitcnt vmcnt(10)
	s_barrier
	s_waitcnt lgkmcnt(0)
	s_setprio 1
	s_waitcnt lgkmcnt(0)
	v_mfma_f32_16x16x32_bf16 v[124:127], v[140:143], v[156:159], v[124:127]
	v_mfma_f32_16x16x32_bf16 v[120:123], v[148:151], v[156:159], v[120:123]
	v_mfma_f32_16x16x32_bf16 v[116:119], v[140:143], v[194:197], v[116:119]
	v_mfma_f32_16x16x32_bf16 v[112:115], v[148:151], v[194:197], v[112:115]
	v_mfma_f32_16x16x32_bf16 v[108:111], v[140:143], v[202:205], v[108:111]
	v_mfma_f32_16x16x32_bf16 v[104:107], v[148:151], v[202:205], v[104:107]
	v_mfma_f32_16x16x32_bf16 v[100:103], v[140:143], v[210:213], v[100:103]
	v_mfma_f32_16x16x32_bf16 v[96:99], v[148:151], v[210:213], v[96:99]
	v_mfma_f32_16x16x32_bf16 v[124:127], v[144:147], v[160:163], v[124:127]
	v_mfma_f32_16x16x32_bf16 v[120:123], v[152:155], v[160:163], v[120:123]
	v_mfma_f32_16x16x32_bf16 v[116:119], v[144:147], v[198:201], v[116:119]
	v_mfma_f32_16x16x32_bf16 v[112:115], v[152:155], v[198:201], v[112:115]
	v_mfma_f32_16x16x32_bf16 v[108:111], v[144:147], v[206:209], v[108:111]
	v_mfma_f32_16x16x32_bf16 v[104:107], v[152:155], v[206:209], v[104:107]
	v_mfma_f32_16x16x32_bf16 v[100:103], v[144:147], v[214:217], v[100:103]
	v_mfma_f32_16x16x32_bf16 v[96:99], v[152:155], v[214:217], v[96:99]
	s_setprio 0
	s_barrier
	ds_read_b128 v[136:139], v135
	ds_read_b128 v[218:221], v135 offset:1024
	ds_read_b128 v[222:225], v135 offset:2048
	ds_read_b128 v[226:229], v135 offset:3072
	s_barrier
	s_waitcnt lgkmcnt(0)
	s_setprio 1
	s_waitcnt lgkmcnt(0)
	v_mfma_f32_16x16x32_bf16 v[92:95], v[136:139], v[156:159], v[92:95]
	v_mfma_f32_16x16x32_bf16 v[84:87], v[136:139], v[194:197], v[84:87]
	v_mfma_f32_16x16x32_bf16 v[80:83], v[222:225], v[194:197], v[80:83]
	v_mfma_f32_16x16x32_bf16 v[88:91], v[222:225], v[156:159], v[88:91]
	v_mfma_f32_16x16x32_bf16 v[76:79], v[136:139], v[202:205], v[76:79]
	v_mfma_f32_16x16x32_bf16 v[72:75], v[222:225], v[202:205], v[72:75]
	v_mfma_f32_16x16x32_bf16 v[68:71], v[136:139], v[210:213], v[68:71]
	v_mfma_f32_16x16x32_bf16 v[64:67], v[222:225], v[210:213], v[64:67]
	v_mfma_f32_16x16x32_bf16 v[156:159], v[218:221], v[160:163], v[92:95]
	v_mfma_f32_16x16x32_bf16 v[194:197], v[218:221], v[198:201], v[84:87]
	v_mfma_f32_16x16x32_bf16 v[198:201], v[226:229], v[198:201], v[80:83]
	v_mfma_f32_16x16x32_bf16 v[160:163], v[226:229], v[160:163], v[88:91]
	v_mfma_f32_16x16x32_bf16 v[202:205], v[218:221], v[206:209], v[76:79]
	v_mfma_f32_16x16x32_bf16 v[206:209], v[226:229], v[206:209], v[72:75]
	v_mfma_f32_16x16x32_bf16 v[210:213], v[218:221], v[214:217], v[68:71]
	v_mfma_f32_16x16x32_bf16 v[214:217], v[226:229], v[214:217], v[64:67]
	s_setprio 0
	s_barrier
	s_nop 0
	ds_read_b128 v[64:67], v193 offset:16384
	ds_read_b128 v[68:71], v193 offset:17408
	ds_read_b128 v[72:75], v192 offset:16384
	ds_read_b128 v[76:79], v192 offset:17408
	ds_read_b128 v[80:83], v191 offset:16384
	ds_read_b128 v[84:87], v191 offset:17408
	ds_read_b128 v[88:91], v190 offset:16384
	ds_read_b128 v[92:95], v190 offset:17408
	s_waitcnt vmcnt(4)
	s_barrier
	s_waitcnt lgkmcnt(0)
	s_setprio 1
	s_waitcnt lgkmcnt(0)
	v_mfma_f32_16x16x32_bf16 v[60:63], v[140:143], v[64:67], v[60:63]
	v_mfma_f32_16x16x32_bf16 v[56:59], v[148:151], v[64:67], v[56:59]
	v_mfma_f32_16x16x32_bf16 v[52:55], v[140:143], v[72:75], v[52:55]
	v_mfma_f32_16x16x32_bf16 v[48:51], v[148:151], v[72:75], v[48:51]
	v_mfma_f32_16x16x32_bf16 v[230:233], v[140:143], v[80:83], v[44:47]
	v_mfma_f32_16x16x32_bf16 v[234:237], v[148:151], v[80:83], v[40:43]
	v_mfma_f32_16x16x32_bf16 v[140:143], v[140:143], v[88:91], v[36:39]
	v_mfma_f32_16x16x32_bf16 v[148:151], v[148:151], v[88:91], v[32:35]
	v_mfma_f32_16x16x32_bf16 v[32:35], v[144:147], v[68:71], v[60:63]
	v_mfma_f32_16x16x32_bf16 v[36:39], v[152:155], v[68:71], v[56:59]
	v_mfma_f32_16x16x32_bf16 v[40:43], v[144:147], v[76:79], v[52:55]
	v_mfma_f32_16x16x32_bf16 v[44:47], v[152:155], v[76:79], v[48:51]
	v_mfma_f32_16x16x32_bf16 v[48:51], v[144:147], v[84:87], v[230:233]
	v_mfma_f32_16x16x32_bf16 v[52:55], v[152:155], v[84:87], v[234:237]
	v_mfma_f32_16x16x32_bf16 v[56:59], v[144:147], v[92:95], v[140:143]
	v_mfma_f32_16x16x32_bf16 v[60:63], v[152:155], v[92:95], v[148:151]
	s_setprio 0
	s_setprio 1
	v_mfma_f32_16x16x32_bf16 v[28:31], v[136:139], v[64:67], v[28:31]
	v_mfma_f32_16x16x32_bf16 v[24:27], v[222:225], v[64:67], v[24:27]
	v_mfma_f32_16x16x32_bf16 v[20:23], v[136:139], v[72:75], v[20:23]
	v_mfma_f32_16x16x32_bf16 v[64:67], v[222:225], v[72:75], v[16:19]
	v_mfma_f32_16x16x32_bf16 v[12:15], v[136:139], v[80:83], v[12:15]
	v_mfma_f32_16x16x32_bf16 v[8:11], v[222:225], v[80:83], v[8:11]
	v_mfma_f32_16x16x32_bf16 v[72:75], v[136:139], v[88:91], v[4:7]
	v_mfma_f32_16x16x32_bf16 v[80:83], v[222:225], v[88:91], v[0:3]
	v_mfma_f32_16x16x32_bf16 v[0:3], v[218:221], v[68:71], v[28:31]
	v_mfma_f32_16x16x32_bf16 v[4:7], v[226:229], v[68:71], v[24:27]
	v_mfma_f32_16x16x32_bf16 v[16:19], v[218:221], v[76:79], v[20:23]
	v_mfma_f32_16x16x32_bf16 v[20:23], v[226:229], v[76:79], v[64:67]
	v_mfma_f32_16x16x32_bf16 v[24:27], v[218:221], v[84:87], v[12:15]
	v_mfma_f32_16x16x32_bf16 v[28:31], v[226:229], v[84:87], v[8:11]
	v_mfma_f32_16x16x32_bf16 v[64:67], v[218:221], v[92:95], v[72:75]
	v_mfma_f32_16x16x32_bf16 v[68:71], v[226:229], v[92:95], v[80:83]
	s_setprio 0
	s_barrier
	ds_read_b128 v[12:15], v130
	ds_read_b128 v[8:11], v130 offset:1024
	ds_read_b128 v[76:79], v130 offset:2048
	ds_read_b128 v[72:75], v130 offset:3072
	ds_read_b128 v[140:143], v193 offset:32768
	ds_read_b128 v[148:151], v193 offset:33792
	ds_read_b128 v[218:221], v192 offset:32768
	ds_read_b128 v[222:225], v192 offset:33792
	ds_read_b128 v[226:229], v191 offset:32768
	ds_read_b128 v[230:233], v191 offset:33792
	ds_read_b128 v[234:237], v190 offset:32768
	ds_read_b128 v[238:241], v190 offset:33792
	s_waitcnt vmcnt(2)
	s_barrier
	s_waitcnt lgkmcnt(0)
	s_setprio 1
	s_waitcnt lgkmcnt(0)
	v_mfma_f32_16x16x32_bf16 v[80:83], v[12:15], v[140:143], v[124:127]
	v_mfma_f32_16x16x32_bf16 v[84:87], v[76:79], v[140:143], v[120:123]
	v_mfma_f32_16x16x32_bf16 v[88:91], v[12:15], v[218:221], v[116:119]
	v_mfma_f32_16x16x32_bf16 v[92:95], v[76:79], v[218:221], v[112:115]
	v_mfma_f32_16x16x32_bf16 v[108:111], v[12:15], v[226:229], v[108:111]
	v_mfma_f32_16x16x32_bf16 v[104:107], v[76:79], v[226:229], v[104:107]
	v_mfma_f32_16x16x32_bf16 v[100:103], v[12:15], v[234:237], v[100:103]
	v_mfma_f32_16x16x32_bf16 v[96:99], v[76:79], v[234:237], v[96:99]
	v_mfma_f32_16x16x32_bf16 v[152:155], v[8:11], v[148:151], v[80:83]
	v_mfma_f32_16x16x32_bf16 v[144:147], v[72:75], v[148:151], v[84:87]
	v_mfma_f32_16x16x32_bf16 v[136:139], v[8:11], v[222:225], v[88:91]
	v_mfma_f32_16x16x32_bf16 v[128:131], v[72:75], v[222:225], v[92:95]
	v_mfma_f32_16x16x32_bf16 v[120:123], v[8:11], v[230:233], v[108:111]
	v_mfma_f32_16x16x32_bf16 v[112:115], v[72:75], v[230:233], v[104:107]
	v_mfma_f32_16x16x32_bf16 v[104:107], v[8:11], v[238:241], v[100:103]
	v_mfma_f32_16x16x32_bf16 v[96:99], v[72:75], v[238:241], v[96:99]
	s_setprio 0
	s_barrier
	ds_read_b128 v[88:91], v132
	ds_read_b128 v[80:83], v132 offset:1024
	ds_read_b128 v[92:95], v132 offset:2048
	ds_read_b128 v[84:87], v132 offset:3072
	s_waitcnt vmcnt(0)
	s_barrier
	s_waitcnt lgkmcnt(0)
	s_setprio 1
	s_waitcnt lgkmcnt(0)
	v_mfma_f32_16x16x32_bf16 v[100:103], v[88:91], v[140:143], v[156:159]
	v_mfma_f32_16x16x32_bf16 v[108:111], v[92:95], v[140:143], v[160:163]
	v_mfma_f32_16x16x32_bf16 v[116:119], v[88:91], v[218:221], v[194:197]
	v_mfma_f32_16x16x32_bf16 v[124:127], v[92:95], v[218:221], v[198:201]
	v_mfma_f32_16x16x32_bf16 v[160:163], v[88:91], v[226:229], v[202:205]
	v_mfma_f32_16x16x32_bf16 v[194:197], v[92:95], v[226:229], v[206:209]
	v_mfma_f32_16x16x32_bf16 v[198:201], v[88:91], v[234:237], v[210:213]
	v_mfma_f32_16x16x32_bf16 v[202:205], v[92:95], v[234:237], v[214:217]
	v_mfma_f32_16x16x32_bf16 v[156:159], v[80:83], v[148:151], v[100:103]
	v_mfma_f32_16x16x32_bf16 v[148:151], v[84:87], v[148:151], v[108:111]
	v_mfma_f32_16x16x32_bf16 v[140:143], v[80:83], v[222:225], v[116:119]
	v_mfma_f32_16x16x32_bf16 v[132:135], v[84:87], v[222:225], v[124:127]
	v_mfma_f32_16x16x32_bf16 v[124:127], v[80:83], v[230:233], v[160:163]
	v_mfma_f32_16x16x32_bf16 v[116:119], v[84:87], v[230:233], v[194:197]
	v_mfma_f32_16x16x32_bf16 v[108:111], v[80:83], v[238:241], v[198:201]
	v_mfma_f32_16x16x32_bf16 v[100:103], v[84:87], v[238:241], v[202:205]
	s_setprio 0
	s_lshl_b64 s[58:59], s[56:57], 2
	s_barrier
	v_mbcnt_lo_u32_b32 v162, -1, 0
	v_mbcnt_hi_u32_b32 v162, -1, v162
	s_add_u32 s58, s87, s58
	v_add_u32_e32 v160, s64, v162
	s_addc_u32 s59, s88, s59
	v_and_b32_e32 v164, 0x100, v160
	v_and_b32_e32 v162, 15, v162
	v_lshl_add_u64 v[160:161], s[58:59], 0, v[164:165]
	v_lshlrev_b32_e32 v164, 2, v162
	v_lshl_add_u64 v[160:161], v[160:161], 0, v[164:165]
	global_load_dword v180, v[160:161], off
	global_load_dword v178, v[160:161], off offset:64
	global_load_dword v176, v[160:161], off offset:128
	global_load_dword v174, v[160:161], off offset:192
	global_load_dword v172, v[160:161], off offset:512
	global_load_dword v170, v[160:161], off offset:576
	global_load_dword v168, v[160:161], off offset:640
	global_load_dword v166, v[160:161], off offset:704
	v_mbcnt_lo_u32_b32 v194, -1, 0
	v_mbcnt_hi_u32_b32 v194, -1, v194
	s_cmp_lg_u32 s81, 0
	v_add_u32_e32 v160, s64, v194
	v_bfe_u32 v196, v160, 8, 1
	v_ashrrev_i32_e32 v199, 6, v160
	v_bfe_u32 v160, v194, 4, 2
	s_cselect_b64 s[58:59], -1, 0
	v_and_b32_e32 v197, 3, v199
	v_and_b32_e32 v195, 15, v194
	s_and_b64 vcc, exec, s[58:59]
	v_lshlrev_b32_e32 v198, 4, v160
	s_cbranch_vccz .LBB0_246
	s_lshl_b32 s14, s80, 22
	s_lshl_b32 s57, s82, 14
	s_add_i32 s57, s57, s14
	v_lshlrev_b32_e32 v160, 6, v195
	v_or3_b32 v160, s57, v160, v198
	v_lshl_add_u32 v160, v197, 20, v160
	v_lshl_or_b32 v164, v196, 12, v160
	s_waitcnt vmcnt(0)
	v_pk_mul_f32 v[160:161], v[154:155], v[180:181] op_sel_hi:[1,0]
	v_pk_mul_f32 v[200:201], v[146:147], v[180:181] op_sel_hi:[1,0]
	v_max_f32_e32 v160, 0, v160
	v_mul_f32_e32 v204, v160, v160
	v_max_f32_e32 v160, 0, v200
	v_pk_mul_f32 v[162:163], v[152:153], v[180:181] op_sel_hi:[1,0]
	v_mul_f32_e32 v200, v160, v160
	v_max_f32_e32 v160, 0, v161
	v_pk_mul_f32 v[202:203], v[144:145], v[180:181] op_sel_hi:[1,0]
	v_max_f32_e32 v162, 0, v162
	v_max_f32_e32 v163, 0, v163
	v_mul_f32_e32 v161, v160, v160
	v_max_f32_e32 v160, 0, v201
	v_mul_f32_e32 v162, v162, v162
	v_max_f32_e32 v202, 0, v202
	v_mul_f32_e32 v163, v163, v163
	v_max_f32_e32 v203, 0, v203
	v_mul_f32_e32 v201, v160, v160
	v_cvt_pk_bf16_f32 v160, v162, v163
	v_cvt_pk_bf16_f32 v161, v204, v161
	v_mul_f32_e32 v202, v202, v202
	v_mul_f32_e32 v203, v203, v203
	v_cvt_pk_bf16_f32 v162, v202, v203
	v_cvt_pk_bf16_f32 v163, v200, v201
	global_store_dwordx4 v164, v[160:163], s[0:1]
	v_pk_mul_f32 v[202:203], v[150:151], v[180:181] op_sel_hi:[1,0]
	v_lshl_add_u64 v[200:201], s[0:1], 0, v[164:165]
	v_pk_mul_f32 v[160:161], v[158:159], v[180:181] op_sel_hi:[1,0]
	v_pk_mul_f32 v[162:163], v[156:157], v[180:181] op_sel_hi:[1,0]
	v_max_f32_e32 v160, 0, v160
	v_mul_f32_e32 v206, v160, v160
	v_max_f32_e32 v160, 0, v202
	v_mul_f32_e32 v202, v160, v160
	v_max_f32_e32 v160, 0, v161
	v_pk_mul_f32 v[204:205], v[148:149], v[180:181] op_sel_hi:[1,0]
	v_max_f32_e32 v162, 0, v162
	v_max_f32_e32 v163, 0, v163
	v_mul_f32_e32 v161, v160, v160
	v_max_f32_e32 v160, 0, v203
	v_add_co_u32_e32 v200, vcc, s74, v200
	v_mul_f32_e32 v162, v162, v162
	v_max_f32_e32 v204, 0, v204
	v_mul_f32_e32 v163, v163, v163
	v_max_f32_e32 v205, 0, v205
	v_mul_f32_e32 v203, v160, v160
	v_cvt_pk_bf16_f32 v160, v162, v163
	v_cvt_pk_bf16_f32 v161, v206, v161
	v_addc_co_u32_e32 v201, vcc, 0, v201, vcc
	v_mul_f32_e32 v204, v204, v204
	v_mul_f32_e32 v205, v205, v205
	v_cvt_pk_bf16_f32 v162, v204, v205
	v_cvt_pk_bf16_f32 v163, v202, v203
	global_store_dwordx4 v[200:201], v[160:163], off
	v_pk_mul_f32 v[202:203], v[130:131], v[178:179] op_sel_hi:[1,0]
	v_pk_mul_f32 v[204:205], v[128:129], v[178:179] op_sel_hi:[1,0]
	v_pk_mul_f32 v[160:161], v[138:139], v[178:179] op_sel_hi:[1,0]
	v_pk_mul_f32 v[162:163], v[136:137], v[178:179] op_sel_hi:[1,0]
	v_max_f32_e32 v160, 0, v160
	v_mul_f32_e32 v206, v160, v160
	v_max_f32_e32 v160, 0, v202
	v_mul_f32_e32 v202, v160, v160
	v_max_f32_e32 v160, 0, v161
	v_max_f32_e32 v162, 0, v162
	v_max_f32_e32 v163, 0, v163
	v_mul_f32_e32 v161, v160, v160
	v_max_f32_e32 v160, 0, v203
	v_mul_f32_e32 v162, v162, v162
	v_max_f32_e32 v204, 0, v204
	v_mul_f32_e32 v163, v163, v163
	v_max_f32_e32 v205, 0, v205
	v_mul_f32_e32 v203, v160, v160
	v_cvt_pk_bf16_f32 v160, v162, v163
	v_cvt_pk_bf16_f32 v161, v206, v161
	v_mul_f32_e32 v204, v204, v204
	v_mul_f32_e32 v205, v205, v205
	v_cvt_pk_bf16_f32 v162, v204, v205
	v_cvt_pk_bf16_f32 v163, v202, v203
	global_store_dwordx4 v164, v[160:163], s[0:1] offset:1024
	v_pk_mul_f32 v[202:203], v[134:135], v[178:179] op_sel_hi:[1,0]
	v_pk_mul_f32 v[204:205], v[132:133], v[178:179] op_sel_hi:[1,0]
	v_pk_mul_f32 v[160:161], v[142:143], v[178:179] op_sel_hi:[1,0]
	v_pk_mul_f32 v[162:163], v[140:141], v[178:179] op_sel_hi:[1,0]
	v_max_f32_e32 v160, 0, v160
	v_mul_f32_e32 v206, v160, v160
	v_max_f32_e32 v160, 0, v202
	v_mul_f32_e32 v202, v160, v160
	v_max_f32_e32 v160, 0, v161
	v_max_f32_e32 v162, 0, v162
	v_max_f32_e32 v163, 0, v163
	v_mul_f32_e32 v161, v160, v160
	v_max_f32_e32 v160, 0, v203
	v_mul_f32_e32 v162, v162, v162
	v_max_f32_e32 v204, 0, v204
	v_mul_f32_e32 v163, v163, v163
	v_max_f32_e32 v205, 0, v205
	v_mul_f32_e32 v203, v160, v160
	v_cvt_pk_bf16_f32 v160, v162, v163
	v_cvt_pk_bf16_f32 v161, v206, v161
	v_mul_f32_e32 v204, v204, v204
	v_mul_f32_e32 v205, v205, v205
	v_cvt_pk_bf16_f32 v162, v204, v205
	v_cvt_pk_bf16_f32 v163, v202, v203
	global_store_dwordx4 v[200:201], v[160:163], off offset:1024
	v_pk_mul_f32 v[202:203], v[114:115], v[176:177] op_sel_hi:[1,0]
	v_pk_mul_f32 v[204:205], v[112:113], v[176:177] op_sel_hi:[1,0]
	v_pk_mul_f32 v[160:161], v[122:123], v[176:177] op_sel_hi:[1,0]
	v_pk_mul_f32 v[162:163], v[120:121], v[176:177] op_sel_hi:[1,0]
	v_max_f32_e32 v160, 0, v160
	v_mul_f32_e32 v206, v160, v160
	v_max_f32_e32 v160, 0, v202
	v_mul_f32_e32 v202, v160, v160
	v_max_f32_e32 v160, 0, v161
	v_max_f32_e32 v162, 0, v162
	v_max_f32_e32 v163, 0, v163
	v_mul_f32_e32 v161, v160, v160
	v_max_f32_e32 v160, 0, v203
	v_mul_f32_e32 v162, v162, v162
	v_max_f32_e32 v204, 0, v204
	v_mul_f32_e32 v163, v163, v163
	v_max_f32_e32 v205, 0, v205
	v_mul_f32_e32 v203, v160, v160
	v_cvt_pk_bf16_f32 v160, v162, v163
	v_cvt_pk_bf16_f32 v161, v206, v161
	v_mul_f32_e32 v204, v204, v204
	v_mul_f32_e32 v205, v205, v205
	v_cvt_pk_bf16_f32 v162, v204, v205
	v_cvt_pk_bf16_f32 v163, v202, v203
	global_store_dwordx4 v164, v[160:163], s[0:1] offset:2048
	v_pk_mul_f32 v[202:203], v[118:119], v[176:177] op_sel_hi:[1,0]
	v_pk_mul_f32 v[204:205], v[116:117], v[176:177] op_sel_hi:[1,0]
	v_pk_mul_f32 v[160:161], v[126:127], v[176:177] op_sel_hi:[1,0]
	v_pk_mul_f32 v[162:163], v[124:125], v[176:177] op_sel_hi:[1,0]
	v_max_f32_e32 v160, 0, v160
	v_mul_f32_e32 v206, v160, v160
	v_max_f32_e32 v160, 0, v202
	v_mul_f32_e32 v202, v160, v160
	v_max_f32_e32 v160, 0, v161
	v_max_f32_e32 v162, 0, v162
	v_max_f32_e32 v163, 0, v163
	v_mul_f32_e32 v161, v160, v160
	v_max_f32_e32 v160, 0, v203
	v_mul_f32_e32 v162, v162, v162
	v_max_f32_e32 v204, 0, v204
	v_mul_f32_e32 v163, v163, v163
	v_max_f32_e32 v205, 0, v205
	v_mul_f32_e32 v203, v160, v160
	v_cvt_pk_bf16_f32 v160, v162, v163
	v_cvt_pk_bf16_f32 v161, v206, v161
	v_mul_f32_e32 v204, v204, v204
	v_mul_f32_e32 v205, v205, v205
	v_cvt_pk_bf16_f32 v162, v204, v205
	v_cvt_pk_bf16_f32 v163, v202, v203
	global_store_dwordx4 v[200:201], v[160:163], off offset:2048
	v_pk_mul_f32 v[200:201], v[98:99], v[174:175] op_sel_hi:[1,0]
	v_pk_mul_f32 v[202:203], v[96:97], v[174:175] op_sel_hi:[1,0]
	v_pk_mul_f32 v[160:161], v[106:107], v[174:175] op_sel_hi:[1,0]
	v_pk_mul_f32 v[162:163], v[104:105], v[174:175] op_sel_hi:[1,0]
	v_max_f32_e32 v160, 0, v160
	v_mul_f32_e32 v204, v160, v160
	v_max_f32_e32 v160, 0, v200
	v_mul_f32_e32 v200, v160, v160
	v_max_f32_e32 v160, 0, v161
	v_max_f32_e32 v162, 0, v162
	v_max_f32_e32 v163, 0, v163
	v_mul_f32_e32 v161, v160, v160
	v_max_f32_e32 v160, 0, v201
	v_mul_f32_e32 v162, v162, v162
	v_max_f32_e32 v202, 0, v202
	v_mul_f32_e32 v163, v163, v163
	v_max_f32_e32 v203, 0, v203
	v_mul_f32_e32 v201, v160, v160
	v_cvt_pk_bf16_f32 v160, v162, v163
	v_cvt_pk_bf16_f32 v161, v204, v161
	v_mul_f32_e32 v202, v202, v202
	v_mul_f32_e32 v203, v203, v203
	v_cvt_pk_bf16_f32 v162, v202, v203
	v_cvt_pk_bf16_f32 v163, v200, v201
	global_store_dwordx4 v164, v[160:163], s[0:1] offset:3072
	v_pk_mul_f32 v[200:201], v[102:103], v[174:175] op_sel_hi:[1,0]
	v_pk_mul_f32 v[202:203], v[100:101], v[174:175] op_sel_hi:[1,0]
	v_pk_mul_f32 v[160:161], v[110:111], v[174:175] op_sel_hi:[1,0]
	v_pk_mul_f32 v[162:163], v[108:109], v[174:175] op_sel_hi:[1,0]
	v_max_f32_e32 v160, 0, v160
	v_mul_f32_e32 v204, v160, v160
	v_max_f32_e32 v160, 0, v200
	v_max_f32_e32 v162, 0, v162
	v_max_f32_e32 v163, 0, v163
	v_mul_f32_e32 v200, v160, v160
	v_max_f32_e32 v160, 0, v161
	v_mul_f32_e32 v162, v162, v162
	v_max_f32_e32 v202, 0, v202
	v_mul_f32_e32 v163, v163, v163
	v_max_f32_e32 v203, 0, v203
	v_mul_f32_e32 v161, v160, v160
	v_max_f32_e32 v160, 0, v201
	v_mul_f32_e32 v202, v202, v202
	v_mul_f32_e32 v203, v203, v203
	v_mul_f32_e32 v201, v160, v160
	v_cvt_pk_bf16_f32 v160, v162, v163
	v_cvt_pk_bf16_f32 v161, v204, v161
	v_cvt_pk_bf16_f32 v162, v202, v203
	v_cvt_pk_bf16_f32 v163, v200, v201
	v_add_u32_e32 v164, 0x80c00, v164
	s_cbranch_execnz .LBB0_238

.LBB0_273:
	v_and_b32_e32 v2, 15, v0
	s_bfe_u32 s64, s86, 0x30003
	v_and_b32_e32 v3, 48, v0
	v_lshlrev_b32_e32 v134, 4, v135
	v_and_b32_e32 v5, 32, v0
	s_movk_i32 s65, 0x3f0
	v_and_b32_e32 v6, 64, v135
	v_lshlrev_b32_e32 v2, 6, v2
	v_lshlrev_b32_e32 v9, 2, v0
	v_lshlrev_b32_e32 v0, 6, v0
	s_lshl_b32 s66, s64, 14
	v_and_b32_e32 v4, 0x3f0, v134
	v_bitop3_b32 v155, v134, v5, s65 bitop3:0x6c
	v_lshlrev_b32_e32 v156, 13, v6
	v_lshlrev_b32_e32 v7, 3, v135
	v_mul_i32_i24_e32 v6, 0xffffe800, v6
	s_add_i32 s65, s20, -2
	v_or_b32_e32 v8, v2, v3
	v_and_b32_e32 v9, 32, v9
	s_mov_b32 s67, 0x14000
	v_and_b32_e32 v0, 0x3c0, v0
	v_and_b32_e32 v157, 0xfffffc00, v7
	v_bitop3_b32 v2, v2, v9, v3 bitop3:0x36
	v_bitop3_b32 v11, v8, s67, v9 bitop3:0xde
	s_mov_b32 s67, 0x1c000
	v_bitop3_b32 v3, v0, v9, v3 bitop3:0x36
	v_bitop3_b32 v0, v6, v4, v5 bitop3:0xf6
	s_add_u32 s66, s70, s66
	v_bitop3_b32 v10, v8, s74, v9 bitop3:0xde
	v_bitop3_b32 v12, v8, s75, v9 bitop3:0xde
	v_bitop3_b32 v8, v8, s67, v9 bitop3:0xde
	v_add3_u32 v128, v0, v156, v157
	s_addc_u32 s67, s71, 0
	v_lshlrev_b32_e32 v13, 13, v1
	v_lshl_add_u64 v[0:1], s[66:67], 0, v[128:129]
	s_mov_b64 s[66:67], 0xc3000
	v_lshl_add_u64 v[130:131], v[0:1], 0, s[66:67]
	s_lshl_b32 s66, s86, 11
	s_and_b32 s67, s86, 7
	s_and_b32 s66, s66, 0x60000
	s_lshl_b32 s67, s67, 14
	s_or_b32 s66, s66, s67
	v_bitop3_b32 v0, v4, v156, v5 bitop3:0xde
	s_add_u32 s66, s68, s66
	v_add_u32_e32 v128, v0, v157
	s_addc_u32 s67, s69, 0
	v_lshlrev_b32_e32 v7, 6, v135
	v_lshl_add_u64 v[0:1], s[66:67], 0, v[128:129]
	s_mov_b64 s[66:67], 0x301000
	v_and_b32_e32 v7, 0x3000, v7
	v_or_b32_e32 v9, 0x800, v13
	v_or_b32_e32 v14, 0x1000, v13
	v_or_b32_e32 v15, 0x1800, v13
	v_lshl_add_u64 v[132:133], v[0:1], 0, s[66:67]
	v_mov_b32_e32 v0, 0
	s_mov_b32 s66, 0
	v_add_u32_e32 v161, v10, v7
	v_add_u32_e32 v152, v2, v13
	v_add_u32_e32 v151, v3, v9
	v_add_u32_e32 v150, v3, v14
	v_add_u32_e32 v149, v3, v15
	v_add_u32_e32 v160, 0xc000, v134
	v_add_u32_e32 v159, 0xe000, v134
	v_add_u32_e32 v158, v11, v7
	v_add_u32_e32 v148, 0x10000, v134
	v_add_u32_e32 v147, 0x12000, v134
	v_add_u32_e32 v146, 0x2000, v134
	v_add_u32_e32 v145, 0x14000, v134
	v_add_u32_e32 v144, 0x16000, v134
	v_add_u32_e32 v154, v12, v7
	v_add_u32_e32 v143, 0x4000, v134
	v_add_u32_e32 v142, 0x6000, v134
	v_add_u32_e32 v153, v8, v7
	v_add_u32_e32 v141, 0x18000, v134
	v_add_u32_e32 v140, 0x1a000, v134
	v_add_u32_e32 v139, 0x8000, v134
	v_add_u32_e32 v138, 0xa000, v134
	v_add_u32_e32 v137, 0x1c000, v134
	v_add_u32_e32 v136, 0x1e000, v134
	v_mov_b32_e32 v1, v0
	v_mov_b32_e32 v2, v0
	v_mov_b32_e32 v3, v0
	v_mov_b32_e32 v4, v0
	v_mov_b32_e32 v5, v0
	v_mov_b32_e32 v6, v0
	v_mov_b32_e32 v7, v0
	v_mov_b32_e32 v8, v0
	v_mov_b32_e32 v9, v0
	v_mov_b32_e32 v10, v0
	v_mov_b32_e32 v11, v0
	v_mov_b32_e32 v12, v0
	v_mov_b32_e32 v13, v0
	v_mov_b32_e32 v14, v0
	v_mov_b32_e32 v15, v0
	v_mov_b32_e32 v16, v0
	v_mov_b32_e32 v17, v0
	v_mov_b32_e32 v18, v0
	v_mov_b32_e32 v19, v0
	v_mov_b32_e32 v20, v0
	v_mov_b32_e32 v21, v0
	v_mov_b32_e32 v22, v0
	v_mov_b32_e32 v23, v0
	v_mov_b32_e32 v24, v0
	v_mov_b32_e32 v25, v0
	v_mov_b32_e32 v26, v0
	v_mov_b32_e32 v27, v0
	v_mov_b32_e32 v28, v0
	v_mov_b32_e32 v29, v0
	v_mov_b32_e32 v30, v0
	v_mov_b32_e32 v31, v0
	v_mov_b32_e32 v32, v0
	v_mov_b32_e32 v33, v0
	v_mov_b32_e32 v34, v0
	v_mov_b32_e32 v35, v0
	v_mov_b32_e32 v36, v0
	v_mov_b32_e32 v37, v0
	v_mov_b32_e32 v38, v0
	v_mov_b32_e32 v39, v0
	v_mov_b32_e32 v40, v0
	v_mov_b32_e32 v41, v0
	v_mov_b32_e32 v42, v0
	v_mov_b32_e32 v43, v0
	v_mov_b32_e32 v44, v0
	v_mov_b32_e32 v45, v0
	v_mov_b32_e32 v46, v0
	v_mov_b32_e32 v47, v0
	v_mov_b32_e32 v48, v0
	v_mov_b32_e32 v49, v0
	v_mov_b32_e32 v50, v0
	v_mov_b32_e32 v51, v0
	v_mov_b32_e32 v52, v0
	v_mov_b32_e32 v53, v0
	v_mov_b32_e32 v54, v0
	v_mov_b32_e32 v55, v0
	v_mov_b32_e32 v56, v0
	v_mov_b32_e32 v57, v0
	v_mov_b32_e32 v58, v0
	v_mov_b32_e32 v59, v0
	v_mov_b32_e32 v60, v0
	v_mov_b32_e32 v61, v0
	v_mov_b32_e32 v62, v0
	v_mov_b32_e32 v63, v0
	v_mov_b32_e32 v64, v0
	v_mov_b32_e32 v65, v0
	v_mov_b32_e32 v66, v0
	v_mov_b32_e32 v67, v0
	v_mov_b32_e32 v68, v0
	v_mov_b32_e32 v69, v0
	v_mov_b32_e32 v70, v0
	v_mov_b32_e32 v71, v0
	v_mov_b32_e32 v72, v0
	v_mov_b32_e32 v73, v0
	v_mov_b32_e32 v74, v0
	v_mov_b32_e32 v75, v0
	v_mov_b32_e32 v76, v0
	v_mov_b32_e32 v77, v0
	v_mov_b32_e32 v78, v0
	v_mov_b32_e32 v79, v0
	v_mov_b32_e32 v80, v0
	v_mov_b32_e32 v81, v0
	v_mov_b32_e32 v82, v0
	v_mov_b32_e32 v83, v0
	v_mov_b32_e32 v84, v0
	v_mov_b32_e32 v85, v0
	v_mov_b32_e32 v86, v0
	v_mov_b32_e32 v87, v0
	v_mov_b32_e32 v88, v0
	v_mov_b32_e32 v89, v0
	v_mov_b32_e32 v90, v0
	v_mov_b32_e32 v91, v0
	v_mov_b32_e32 v92, v0
	v_mov_b32_e32 v93, v0
	v_mov_b32_e32 v94, v0
	v_mov_b32_e32 v95, v0
	v_mov_b32_e32 v96, v0
	v_mov_b32_e32 v97, v0
	v_mov_b32_e32 v98, v0
	v_mov_b32_e32 v99, v0
	v_mov_b32_e32 v100, v0
	v_mov_b32_e32 v101, v0
	v_mov_b32_e32 v102, v0
	v_mov_b32_e32 v103, v0
	v_mov_b32_e32 v104, v0
	v_mov_b32_e32 v105, v0
	v_mov_b32_e32 v106, v0
	v_mov_b32_e32 v107, v0
	v_mov_b32_e32 v108, v0
	v_mov_b32_e32 v109, v0
	v_mov_b32_e32 v110, v0
	v_mov_b32_e32 v111, v0
	v_mov_b32_e32 v112, v0
	v_mov_b32_e32 v113, v0
	v_mov_b32_e32 v114, v0
	v_mov_b32_e32 v115, v0
	v_mov_b32_e32 v116, v0
	v_mov_b32_e32 v117, v0
	v_mov_b32_e32 v118, v0
	v_mov_b32_e32 v119, v0
	v_mov_b32_e32 v120, v0
	v_mov_b32_e32 v121, v0
	v_mov_b32_e32 v122, v0
	v_mov_b32_e32 v123, v0
	v_mov_b32_e32 v124, v0
	v_mov_b32_e32 v125, v0
	v_mov_b32_e32 v126, v0
	v_mov_b32_e32 v127, v0
	s_barrier
	s_mov_b32 vcc_lo, 0xffe01000
	s_mov_b32 vcc_hi, -1
	v_lshl_add_u64 v[164:165], v[132:133], 0, vcc
	v_readfirstlane_b32 s67, v160
	s_mov_b32 vcc_lo, 0xffe02000
	s_mov_b32 m0, s67
	s_mov_b32 vcc_hi, -1
	v_readfirstlane_b32 s67, v159
	global_load_lds_dwordx4 v[164:165], off
	v_lshl_add_u64 v[164:165], v[132:133], 0, vcc
	s_mov_b32 m0, s67
	s_nop 0
	global_load_lds_dwordx4 v[164:165], off
	ds_read_b128 v[162:165], v161
	ds_read_b128 v[166:169], v161 offset:1024
	ds_read_b128 v[170:173], v161 offset:2048
	ds_read_b128 v[174:177], v161 offset:3072
	ds_read_b128 v[178:181], v152
	ds_read_b128 v[182:185], v152 offset:1024
	ds_read_b128 v[186:189], v151
	ds_read_b128 v[190:193], v151 offset:1024
	ds_read_b128 v[194:197], v150
	ds_read_b128 v[198:201], v150 offset:1024
	ds_read_b128 v[202:205], v149
	ds_read_b128 v[206:209], v149 offset:1024
	s_waitcnt lgkmcnt(8)
	s_barrier
	s_branch .Lkent_274

.Lkent_274:
	s_waitcnt lgkmcnt(0)
	s_setprio 1
	s_waitcnt lgkmcnt(0)
	v_mfma_f32_16x16x32_bf16 v[124:127], v[162:165], v[178:181], v[124:127]
	v_mfma_f32_16x16x32_bf16 v[120:123], v[170:173], v[178:181], v[120:123]
	v_mfma_f32_16x16x32_bf16 v[116:119], v[162:165], v[186:189], v[116:119]
	v_mfma_f32_16x16x32_bf16 v[112:115], v[170:173], v[186:189], v[112:115]
	v_mfma_f32_16x16x32_bf16 v[108:111], v[162:165], v[194:197], v[108:111]
	v_mfma_f32_16x16x32_bf16 v[104:107], v[170:173], v[194:197], v[104:107]
	v_mfma_f32_16x16x32_bf16 v[100:103], v[162:165], v[202:205], v[100:103]
	v_mfma_f32_16x16x32_bf16 v[96:99], v[170:173], v[202:205], v[96:99]
	v_mfma_f32_16x16x32_bf16 v[124:127], v[166:169], v[182:185], v[124:127]
	v_mfma_f32_16x16x32_bf16 v[120:123], v[174:177], v[182:185], v[120:123]
	v_mfma_f32_16x16x32_bf16 v[116:119], v[166:169], v[190:193], v[116:119]
	v_mfma_f32_16x16x32_bf16 v[112:115], v[174:177], v[190:193], v[112:115]
	v_mfma_f32_16x16x32_bf16 v[108:111], v[166:169], v[198:201], v[108:111]
	v_mfma_f32_16x16x32_bf16 v[104:107], v[174:177], v[198:201], v[104:107]
	v_mfma_f32_16x16x32_bf16 v[100:103], v[166:169], v[206:209], v[100:103]
	v_mfma_f32_16x16x32_bf16 v[96:99], v[174:177], v[206:209], v[96:99]
	s_setprio 0
	s_barrier
	s_mov_b32 vcc_lo, 0xfffbd000
	s_mov_b32 vcc_hi, -1
	v_readfirstlane_b32 s67, v148
	v_lshl_add_u64 v[226:227], v[130:131], 0, vcc
	s_mov_b32 m0, s67
	v_readfirstlane_b32 s67, v147
	ds_read_b128 v[210:213], v158
	ds_read_b128 v[214:217], v158 offset:1024
	ds_read_b128 v[218:221], v158 offset:2048
	ds_read_b128 v[222:225], v158 offset:3072
	global_load_lds_dwordx4 v[226:227], off
	v_lshl_add_u64 v[226:227], v[130:131], 0, s[22:23]
	s_mov_b32 m0, s67
	s_add_i32 s66, s66, 2
	global_load_lds_dwordx4 v[226:227], off
	v_readfirstlane_b32 s67, v134
	v_lshl_add_u64 v[226:227], v[132:133], 0, s[24:25]
	s_mov_b32 m0, s67
	v_readfirstlane_b32 s67, v146
	global_load_lds_dwordx4 v[226:227], off
	v_lshl_add_u64 v[226:227], v[132:133], 0, s[26:27]
	s_mov_b32 m0, s67
	s_nop 0
	global_load_lds_dwordx4 v[226:227], off
	s_waitcnt vmcnt(12)
	s_barrier
	s_waitcnt lgkmcnt(0)
	s_setprio 1
	s_waitcnt lgkmcnt(0)
	v_mfma_f32_16x16x32_bf16 v[92:95], v[210:213], v[178:181], v[92:95]
	v_mfma_f32_16x16x32_bf16 v[88:91], v[218:221], v[178:181], v[88:91]
	v_mfma_f32_16x16x32_bf16 v[84:87], v[210:213], v[186:189], v[84:87]
	v_mfma_f32_16x16x32_bf16 v[80:83], v[218:221], v[186:189], v[80:83]
	v_mfma_f32_16x16x32_bf16 v[76:79], v[210:213], v[194:197], v[76:79]
	v_mfma_f32_16x16x32_bf16 v[72:75], v[218:221], v[194:197], v[72:75]
	v_mfma_f32_16x16x32_bf16 v[68:71], v[210:213], v[202:205], v[68:71]
	v_mfma_f32_16x16x32_bf16 v[64:67], v[218:221], v[202:205], v[64:67]
	v_mfma_f32_16x16x32_bf16 v[92:95], v[214:217], v[182:185], v[92:95]
	v_mfma_f32_16x16x32_bf16 v[88:91], v[222:225], v[182:185], v[88:91]
	v_mfma_f32_16x16x32_bf16 v[84:87], v[214:217], v[190:193], v[84:87]
	v_mfma_f32_16x16x32_bf16 v[80:83], v[222:225], v[190:193], v[80:83]
	v_mfma_f32_16x16x32_bf16 v[76:79], v[214:217], v[198:201], v[76:79]
	v_mfma_f32_16x16x32_bf16 v[72:75], v[222:225], v[198:201], v[72:75]
	v_mfma_f32_16x16x32_bf16 v[68:71], v[214:217], v[206:209], v[68:71]
	v_mfma_f32_16x16x32_bf16 v[64:67], v[222:225], v[206:209], v[64:67]
	s_setprio 0
	s_barrier
	ds_read_b128 v[178:181], v152 offset:16384
	ds_read_b128 v[182:185], v152 offset:17408
	ds_read_b128 v[186:189], v151 offset:16384
	ds_read_b128 v[190:193], v151 offset:17408
	ds_read_b128 v[194:197], v150 offset:16384
	ds_read_b128 v[198:201], v150 offset:17408
	ds_read_b128 v[202:205], v149 offset:16384
	ds_read_b128 v[206:209], v149 offset:17408
	v_readfirstlane_b32 s67, v145
	v_lshl_add_u64 v[226:227], v[130:131], 0, s[28:29]
	s_mov_b32 m0, s67
	v_readfirstlane_b32 s67, v144
	global_load_lds_dwordx4 v[226:227], off
	v_lshl_add_u64 v[226:227], v[130:131], 0, s[30:31]
	s_mov_b32 m0, s67
	s_nop 0
	global_load_lds_dwordx4 v[226:227], off
	s_barrier
	s_waitcnt lgkmcnt(0)
	s_setprio 1
	s_waitcnt lgkmcnt(0)
	v_mfma_f32_16x16x32_bf16 v[60:63], v[162:165], v[178:181], v[60:63]
	v_mfma_f32_16x16x32_bf16 v[56:59], v[170:173], v[178:181], v[56:59]
	v_mfma_f32_16x16x32_bf16 v[52:55], v[162:165], v[186:189], v[52:55]
	v_mfma_f32_16x16x32_bf16 v[48:51], v[170:173], v[186:189], v[48:51]
	v_mfma_f32_16x16x32_bf16 v[44:47], v[162:165], v[194:197], v[44:47]
	v_mfma_f32_16x16x32_bf16 v[40:43], v[170:173], v[194:197], v[40:43]
	v_mfma_f32_16x16x32_bf16 v[36:39], v[162:165], v[202:205], v[36:39]
	v_mfma_f32_16x16x32_bf16 v[32:35], v[170:173], v[202:205], v[32:35]
	v_mfma_f32_16x16x32_bf16 v[60:63], v[166:169], v[182:185], v[60:63]
	v_mfma_f32_16x16x32_bf16 v[56:59], v[174:177], v[182:185], v[56:59]
	v_mfma_f32_16x16x32_bf16 v[52:55], v[166:169], v[190:193], v[52:55]
	v_mfma_f32_16x16x32_bf16 v[48:51], v[174:177], v[190:193], v[48:51]
	v_mfma_f32_16x16x32_bf16 v[44:47], v[166:169], v[198:201], v[44:47]
	v_mfma_f32_16x16x32_bf16 v[40:43], v[174:177], v[198:201], v[40:43]
	v_mfma_f32_16x16x32_bf16 v[36:39], v[166:169], v[206:209], v[36:39]
	v_mfma_f32_16x16x32_bf16 v[32:35], v[174:177], v[206:209], v[32:35]
	s_setprio 0
	s_barrier
	v_readfirstlane_b32 s67, v143
	v_lshl_add_u64 v[164:165], v[132:133], 0, s[34:35]
	s_mov_b32 m0, s67
	v_readfirstlane_b32 s67, v142
	global_load_lds_dwordx4 v[164:165], off
	v_lshl_add_u64 v[164:165], v[132:133], 0, s[44:45]
	s_mov_b32 m0, s67
	s_nop 0
	global_load_lds_dwordx4 v[164:165], off
	s_waitcnt vmcnt(12)
	s_barrier
	s_setprio 1
	v_mfma_f32_16x16x32_bf16 v[28:31], v[210:213], v[178:181], v[28:31]
	v_mfma_f32_16x16x32_bf16 v[24:27], v[218:221], v[178:181], v[24:27]
	v_mfma_f32_16x16x32_bf16 v[20:23], v[210:213], v[186:189], v[20:23]
	v_mfma_f32_16x16x32_bf16 v[16:19], v[218:221], v[186:189], v[16:19]
	v_mfma_f32_16x16x32_bf16 v[12:15], v[210:213], v[194:197], v[12:15]
	v_mfma_f32_16x16x32_bf16 v[8:11], v[218:221], v[194:197], v[8:11]
	v_mfma_f32_16x16x32_bf16 v[4:7], v[210:213], v[202:205], v[4:7]
	v_mfma_f32_16x16x32_bf16 v[0:3], v[218:221], v[202:205], v[0:3]
	v_mfma_f32_16x16x32_bf16 v[28:31], v[214:217], v[182:185], v[28:31]
	v_mfma_f32_16x16x32_bf16 v[24:27], v[222:225], v[182:185], v[24:27]
	v_mfma_f32_16x16x32_bf16 v[20:23], v[214:217], v[190:193], v[20:23]
	v_mfma_f32_16x16x32_bf16 v[16:19], v[222:225], v[190:193], v[16:19]
	v_mfma_f32_16x16x32_bf16 v[12:15], v[214:217], v[198:201], v[12:15]
	v_mfma_f32_16x16x32_bf16 v[8:11], v[222:225], v[198:201], v[8:11]
	v_mfma_f32_16x16x32_bf16 v[4:7], v[214:217], v[206:209], v[4:7]
	v_mfma_f32_16x16x32_bf16 v[0:3], v[222:225], v[206:209], v[0:3]
	s_setprio 0
	s_barrier
	ds_read_b128 v[162:165], v154
	ds_read_b128 v[166:169], v154 offset:1024
	ds_read_b128 v[170:173], v154 offset:2048
	ds_read_b128 v[174:177], v154 offset:3072
	ds_read_b128 v[178:181], v152 offset:32768
	ds_read_b128 v[182:185], v152 offset:33792
	ds_read_b128 v[186:189], v151 offset:32768
	ds_read_b128 v[190:193], v151 offset:33792
	ds_read_b128 v[194:197], v150 offset:32768
	ds_read_b128 v[198:201], v150 offset:33792
	ds_read_b128 v[202:205], v149 offset:32768
	ds_read_b128 v[206:209], v149 offset:33792
	s_waitcnt lgkmcnt(8)
	s_waitcnt vmcnt(10)
	s_barrier
	s_waitcnt lgkmcnt(0)
	s_setprio 1
	s_waitcnt lgkmcnt(0)
	v_mfma_f32_16x16x32_bf16 v[124:127], v[162:165], v[178:181], v[124:127]
	v_mfma_f32_16x16x32_bf16 v[120:123], v[170:173], v[178:181], v[120:123]
	v_mfma_f32_16x16x32_bf16 v[116:119], v[162:165], v[186:189], v[116:119]
	v_mfma_f32_16x16x32_bf16 v[112:115], v[170:173], v[186:189], v[112:115]
	v_mfma_f32_16x16x32_bf16 v[108:111], v[162:165], v[194:197], v[108:111]
	v_mfma_f32_16x16x32_bf16 v[104:107], v[170:173], v[194:197], v[104:107]
	v_mfma_f32_16x16x32_bf16 v[100:103], v[162:165], v[202:205], v[100:103]
	v_mfma_f32_16x16x32_bf16 v[96:99], v[170:173], v[202:205], v[96:99]
	v_mfma_f32_16x16x32_bf16 v[124:127], v[166:169], v[182:185], v[124:127]
	v_mfma_f32_16x16x32_bf16 v[120:123], v[174:177], v[182:185], v[120:123]
	v_mfma_f32_16x16x32_bf16 v[116:119], v[166:169], v[190:193], v[116:119]
	v_mfma_f32_16x16x32_bf16 v[112:115], v[174:177], v[190:193], v[112:115]
	v_mfma_f32_16x16x32_bf16 v[108:111], v[166:169], v[198:201], v[108:111]
	v_mfma_f32_16x16x32_bf16 v[104:107], v[174:177], v[198:201], v[104:107]
	v_mfma_f32_16x16x32_bf16 v[100:103], v[166:169], v[206:209], v[100:103]
	v_mfma_f32_16x16x32_bf16 v[96:99], v[174:177], v[206:209], v[96:99]
	s_setprio 0
	s_barrier
	v_readfirstlane_b32 s67, v141
	v_lshl_add_u64 v[226:227], v[130:131], 0, s[46:47]
	s_mov_b32 m0, s67
	v_readfirstlane_b32 s67, v140
	ds_read_b128 v[210:213], v153
	ds_read_b128 v[214:217], v153 offset:1024
	ds_read_b128 v[218:221], v153 offset:2048
	ds_read_b128 v[222:225], v153 offset:3072
	global_load_lds_dwordx4 v[226:227], off
	v_lshl_add_u64 v[226:227], v[130:131], 0, s[56:57]
	s_mov_b32 m0, s67
	s_nop 0
	global_load_lds_dwordx4 v[226:227], off
	v_readfirstlane_b32 s67, v139
	v_lshl_add_u64 v[226:227], v[132:133], 0, s[58:59]
	s_mov_b32 m0, s67
	v_readfirstlane_b32 s67, v138
	global_load_lds_dwordx4 v[226:227], off
	s_mov_b32 m0, s67
	s_nop 0
	global_load_lds_dwordx4 v[132:133], off
	s_waitcnt vmcnt(12)
	s_barrier
	s_waitcnt lgkmcnt(0)
	s_setprio 1
	s_waitcnt lgkmcnt(0)
	v_mfma_f32_16x16x32_bf16 v[92:95], v[210:213], v[178:181], v[92:95]
	v_mfma_f32_16x16x32_bf16 v[88:91], v[218:221], v[178:181], v[88:91]
	v_mfma_f32_16x16x32_bf16 v[84:87], v[210:213], v[186:189], v[84:87]
	v_mfma_f32_16x16x32_bf16 v[80:83], v[218:221], v[186:189], v[80:83]
	v_mfma_f32_16x16x32_bf16 v[76:79], v[210:213], v[194:197], v[76:79]
	v_mfma_f32_16x16x32_bf16 v[72:75], v[218:221], v[194:197], v[72:75]
	v_mfma_f32_16x16x32_bf16 v[68:71], v[210:213], v[202:205], v[68:71]
	v_mfma_f32_16x16x32_bf16 v[64:67], v[218:221], v[202:205], v[64:67]
	v_mfma_f32_16x16x32_bf16 v[92:95], v[214:217], v[182:185], v[92:95]
	v_mfma_f32_16x16x32_bf16 v[88:91], v[222:225], v[182:185], v[88:91]
	v_mfma_f32_16x16x32_bf16 v[84:87], v[214:217], v[190:193], v[84:87]
	v_mfma_f32_16x16x32_bf16 v[80:83], v[222:225], v[190:193], v[80:83]
	v_mfma_f32_16x16x32_bf16 v[76:79], v[214:217], v[198:201], v[76:79]
	v_mfma_f32_16x16x32_bf16 v[72:75], v[222:225], v[198:201], v[72:75]
	v_mfma_f32_16x16x32_bf16 v[68:71], v[214:217], v[206:209], v[68:71]
	v_mfma_f32_16x16x32_bf16 v[64:67], v[222:225], v[206:209], v[64:67]
	s_setprio 0
	s_barrier
	ds_read_b128 v[178:181], v152 offset:49152
	ds_read_b128 v[182:185], v152 offset:50176
	ds_read_b128 v[186:189], v151 offset:49152
	ds_read_b128 v[190:193], v151 offset:50176
	ds_read_b128 v[194:197], v150 offset:49152
	ds_read_b128 v[198:201], v150 offset:50176
	ds_read_b128 v[202:205], v149 offset:49152
	ds_read_b128 v[206:209], v149 offset:50176
	v_readfirstlane_b32 s67, v137
	v_lshl_add_u64 v[226:227], v[130:131], 0, s[58:59]
	s_mov_b32 m0, s67
	v_readfirstlane_b32 s67, v136
	global_load_lds_dwordx4 v[226:227], off
	s_mov_b32 m0, s67
	s_nop 0
	global_load_lds_dwordx4 v[130:131], off
	s_barrier
	s_waitcnt lgkmcnt(0)
	s_setprio 1
	s_waitcnt lgkmcnt(0)
	v_mfma_f32_16x16x32_bf16 v[60:63], v[162:165], v[178:181], v[60:63]
	v_mfma_f32_16x16x32_bf16 v[56:59], v[170:173], v[178:181], v[56:59]
	v_mfma_f32_16x16x32_bf16 v[52:55], v[162:165], v[186:189], v[52:55]
	v_mfma_f32_16x16x32_bf16 v[48:51], v[170:173], v[186:189], v[48:51]
	v_mfma_f32_16x16x32_bf16 v[44:47], v[162:165], v[194:197], v[44:47]
	v_mfma_f32_16x16x32_bf16 v[40:43], v[170:173], v[194:197], v[40:43]
	v_mfma_f32_16x16x32_bf16 v[36:39], v[162:165], v[202:205], v[36:39]
	v_mfma_f32_16x16x32_bf16 v[32:35], v[170:173], v[202:205], v[32:35]
	v_mfma_f32_16x16x32_bf16 v[60:63], v[166:169], v[182:185], v[60:63]
	v_mfma_f32_16x16x32_bf16 v[56:59], v[174:177], v[182:185], v[56:59]
	v_mfma_f32_16x16x32_bf16 v[52:55], v[166:169], v[190:193], v[52:55]
	v_mfma_f32_16x16x32_bf16 v[48:51], v[174:177], v[190:193], v[48:51]
	v_mfma_f32_16x16x32_bf16 v[44:47], v[166:169], v[198:201], v[44:47]
	v_mfma_f32_16x16x32_bf16 v[40:43], v[174:177], v[198:201], v[40:43]
	v_mfma_f32_16x16x32_bf16 v[36:39], v[166:169], v[206:209], v[36:39]
	v_mfma_f32_16x16x32_bf16 v[32:35], v[174:177], v[206:209], v[32:35]
	s_setprio 0
	s_barrier
	v_lshl_add_u64 v[132:133], v[132:133], 0, s[62:63]
	s_mov_b32 vcc_lo, 0xffe01000
	s_mov_b32 vcc_hi, -1
	v_lshl_add_u64 v[164:165], v[132:133], 0, vcc
	v_readfirstlane_b32 s67, v160
	s_mov_b32 vcc_lo, 0xffe02000
	s_mov_b32 m0, s67
	s_mov_b32 vcc_hi, -1
	v_readfirstlane_b32 s67, v159
	global_load_lds_dwordx4 v[164:165], off
	v_lshl_add_u64 v[164:165], v[132:133], 0, vcc
	s_mov_b32 m0, s67
	s_nop 0
	global_load_lds_dwordx4 v[164:165], off
	s_waitcnt vmcnt(12)
	s_barrier
	s_setprio 1
	v_mfma_f32_16x16x32_bf16 v[28:31], v[210:213], v[178:181], v[28:31]
	v_mfma_f32_16x16x32_bf16 v[24:27], v[218:221], v[178:181], v[24:27]
	v_mfma_f32_16x16x32_bf16 v[20:23], v[210:213], v[186:189], v[20:23]
	v_mfma_f32_16x16x32_bf16 v[16:19], v[218:221], v[186:189], v[16:19]
	v_mfma_f32_16x16x32_bf16 v[12:15], v[210:213], v[194:197], v[12:15]
	v_mfma_f32_16x16x32_bf16 v[8:11], v[218:221], v[194:197], v[8:11]
	v_mfma_f32_16x16x32_bf16 v[4:7], v[210:213], v[202:205], v[4:7]
	v_mfma_f32_16x16x32_bf16 v[0:3], v[218:221], v[202:205], v[0:3]
	v_mfma_f32_16x16x32_bf16 v[28:31], v[214:217], v[182:185], v[28:31]
	v_mfma_f32_16x16x32_bf16 v[24:27], v[222:225], v[182:185], v[24:27]
	v_mfma_f32_16x16x32_bf16 v[20:23], v[214:217], v[190:193], v[20:23]
	v_mfma_f32_16x16x32_bf16 v[16:19], v[222:225], v[190:193], v[16:19]
	v_mfma_f32_16x16x32_bf16 v[12:15], v[214:217], v[198:201], v[12:15]
	v_mfma_f32_16x16x32_bf16 v[8:11], v[222:225], v[198:201], v[8:11]
	v_mfma_f32_16x16x32_bf16 v[4:7], v[214:217], v[206:209], v[4:7]
	v_mfma_f32_16x16x32_bf16 v[0:3], v[222:225], v[206:209], v[0:3]
	s_setprio 0
	v_lshl_add_u64 v[130:131], v[130:131], 0, s[60:61]
	s_cmp_lt_u32 s66, s65
	s_barrier
	s_cbranch_scc1 .LBB0_274
	s_lshl_b32 s65, s86, 5
	s_lshl_b32 s66, s86, 8
	s_and_b32 s65, s65, 0x1800
	s_and_b32 s66, s66, 0x700
	s_or_b32 s97, s66, s65
	s_lshl_b32 s65, s97, 6
	s_add_u32 s65, s68, s65
	s_addc_u32 s86, s69, 0
	s_add_i32 s20, s20, -1
	s_lshl_b64 s[66:67], s[20:21], 20
	v_add_u32_e32 v128, v156, v157
	s_add_u32 s66, s65, s66
	v_or_b32_e32 v128, v128, v155
	s_addc_u32 s67, s86, s67
	v_lshl_add_u64 v[156:157], s[66:67], 0, v[128:129]
	v_readfirstlane_b32 s20, v160
	v_lshl_add_u64 v[206:207], v[156:157], 0, s[4:5]
	s_mov_b32 m0, s20
	v_readfirstlane_b32 s20, v159
	ds_read_b128 v[130:133], v161
	ds_read_b128 v[162:165], v161 offset:1024
	ds_read_b128 v[166:169], v161 offset:2048
	ds_read_b128 v[170:173], v161 offset:3072
	ds_read_b128 v[174:177], v152
	ds_read_b128 v[178:181], v152 offset:1024
	ds_read_b128 v[182:185], v151
	ds_read_b128 v[186:189], v151 offset:1024
	ds_read_b128 v[190:193], v150
	ds_read_b128 v[194:197], v150 offset:1024
	ds_read_b128 v[198:201], v149
	ds_read_b128 v[202:205], v149 offset:1024
	global_load_lds_dwordx4 v[206:207], off
	v_lshl_add_u64 v[156:157], v[156:157], 0, s[6:7]
	s_mov_b32 m0, s20
	s_nop 0
	global_load_lds_dwordx4 v[156:157], off
	s_waitcnt vmcnt(10)
	s_barrier
	s_waitcnt lgkmcnt(0)
	s_setprio 1
	s_waitcnt lgkmcnt(0)
	v_mfma_f32_16x16x32_bf16 v[124:127], v[130:133], v[174:177], v[124:127]
	v_mfma_f32_16x16x32_bf16 v[120:123], v[166:169], v[174:177], v[120:123]
	v_mfma_f32_16x16x32_bf16 v[116:119], v[130:133], v[182:185], v[116:119]
	v_mfma_f32_16x16x32_bf16 v[112:115], v[166:169], v[182:185], v[112:115]
	v_mfma_f32_16x16x32_bf16 v[108:111], v[130:133], v[190:193], v[108:111]
	v_mfma_f32_16x16x32_bf16 v[104:107], v[166:169], v[190:193], v[104:107]
	v_mfma_f32_16x16x32_bf16 v[100:103], v[130:133], v[198:201], v[100:103]
	v_mfma_f32_16x16x32_bf16 v[96:99], v[166:169], v[198:201], v[96:99]
	v_mfma_f32_16x16x32_bf16 v[124:127], v[162:165], v[178:181], v[124:127]
	v_mfma_f32_16x16x32_bf16 v[120:123], v[170:173], v[178:181], v[120:123]
	v_mfma_f32_16x16x32_bf16 v[116:119], v[162:165], v[186:189], v[116:119]
	v_mfma_f32_16x16x32_bf16 v[112:115], v[170:173], v[186:189], v[112:115]
	v_mfma_f32_16x16x32_bf16 v[108:111], v[162:165], v[194:197], v[108:111]
	v_mfma_f32_16x16x32_bf16 v[104:107], v[170:173], v[194:197], v[104:107]
	v_mfma_f32_16x16x32_bf16 v[100:103], v[162:165], v[202:205], v[100:103]
	v_mfma_f32_16x16x32_bf16 v[96:99], v[170:173], v[202:205], v[96:99]
	s_setprio 0
	s_barrier
	ds_read_b128 v[206:209], v158
	ds_read_b128 v[210:213], v158 offset:1024
	ds_read_b128 v[214:217], v158 offset:2048
	ds_read_b128 v[156:159], v158 offset:3072
	s_barrier
	s_waitcnt lgkmcnt(0)
	s_setprio 1
	s_waitcnt lgkmcnt(0)
	v_mfma_f32_16x16x32_bf16 v[92:95], v[206:209], v[174:177], v[92:95]
	v_mfma_f32_16x16x32_bf16 v[88:91], v[214:217], v[174:177], v[88:91]
	v_mfma_f32_16x16x32_bf16 v[84:87], v[206:209], v[182:185], v[84:87]
	v_mfma_f32_16x16x32_bf16 v[80:83], v[214:217], v[182:185], v[80:83]
	v_mfma_f32_16x16x32_bf16 v[76:79], v[206:209], v[190:193], v[76:79]
	v_mfma_f32_16x16x32_bf16 v[72:75], v[214:217], v[190:193], v[72:75]
	v_mfma_f32_16x16x32_bf16 v[68:71], v[206:209], v[198:201], v[68:71]
	v_mfma_f32_16x16x32_bf16 v[64:67], v[214:217], v[198:201], v[64:67]
	v_mfma_f32_16x16x32_bf16 v[174:177], v[210:213], v[178:181], v[92:95]
	v_mfma_f32_16x16x32_bf16 v[178:181], v[156:159], v[178:181], v[88:91]
	v_mfma_f32_16x16x32_bf16 v[182:185], v[210:213], v[186:189], v[84:87]
	v_mfma_f32_16x16x32_bf16 v[186:189], v[156:159], v[186:189], v[80:83]
	v_mfma_f32_16x16x32_bf16 v[190:193], v[210:213], v[194:197], v[76:79]
	v_mfma_f32_16x16x32_bf16 v[194:197], v[156:159], v[194:197], v[72:75]
	v_mfma_f32_16x16x32_bf16 v[198:201], v[210:213], v[202:205], v[68:71]
	v_mfma_f32_16x16x32_bf16 v[202:205], v[156:159], v[202:205], v[64:67]
	s_setprio 0
	s_barrier
	s_nop 0
	ds_read_b128 v[64:67], v152 offset:16384
	ds_read_b128 v[68:71], v152 offset:17408
	ds_read_b128 v[72:75], v151 offset:16384
	ds_read_b128 v[76:79], v151 offset:17408
	ds_read_b128 v[80:83], v150 offset:16384
	ds_read_b128 v[84:87], v150 offset:17408
	ds_read_b128 v[88:91], v149 offset:16384
	ds_read_b128 v[92:95], v149 offset:17408
	s_waitcnt vmcnt(4)
	s_barrier
	s_waitcnt lgkmcnt(0)
	s_setprio 1
	s_waitcnt lgkmcnt(0)
	v_mfma_f32_16x16x32_bf16 v[60:63], v[130:133], v[64:67], v[60:63]
	v_mfma_f32_16x16x32_bf16 v[56:59], v[166:169], v[64:67], v[56:59]
	v_mfma_f32_16x16x32_bf16 v[52:55], v[130:133], v[72:75], v[52:55]
	v_mfma_f32_16x16x32_bf16 v[48:51], v[166:169], v[72:75], v[48:51]
	v_mfma_f32_16x16x32_bf16 v[218:221], v[130:133], v[80:83], v[44:47]
	v_mfma_f32_16x16x32_bf16 v[222:225], v[166:169], v[80:83], v[40:43]
	v_mfma_f32_16x16x32_bf16 v[130:133], v[130:133], v[88:91], v[36:39]
	v_mfma_f32_16x16x32_bf16 v[166:169], v[166:169], v[88:91], v[32:35]
	v_mfma_f32_16x16x32_bf16 v[32:35], v[162:165], v[68:71], v[60:63]
	v_mfma_f32_16x16x32_bf16 v[36:39], v[170:173], v[68:71], v[56:59]
	v_mfma_f32_16x16x32_bf16 v[40:43], v[162:165], v[76:79], v[52:55]
	v_mfma_f32_16x16x32_bf16 v[44:47], v[170:173], v[76:79], v[48:51]
	v_mfma_f32_16x16x32_bf16 v[48:51], v[162:165], v[84:87], v[218:221]
	v_mfma_f32_16x16x32_bf16 v[52:55], v[170:173], v[84:87], v[222:225]
	v_mfma_f32_16x16x32_bf16 v[56:59], v[162:165], v[92:95], v[130:133]
	v_mfma_f32_16x16x32_bf16 v[60:63], v[170:173], v[92:95], v[166:169]
	s_setprio 0
	s_setprio 1
	v_mfma_f32_16x16x32_bf16 v[28:31], v[206:209], v[64:67], v[28:31]
	v_mfma_f32_16x16x32_bf16 v[24:27], v[214:217], v[64:67], v[24:27]
	v_mfma_f32_16x16x32_bf16 v[20:23], v[206:209], v[72:75], v[20:23]
	v_mfma_f32_16x16x32_bf16 v[64:67], v[214:217], v[72:75], v[16:19]
	v_mfma_f32_16x16x32_bf16 v[72:75], v[206:209], v[80:83], v[12:15]
	v_mfma_f32_16x16x32_bf16 v[8:11], v[214:217], v[80:83], v[8:11]
	v_mfma_f32_16x16x32_bf16 v[80:83], v[206:209], v[88:91], v[4:7]
	v_mfma_f32_16x16x32_bf16 v[0:3], v[214:217], v[88:91], v[0:3]
	v_mfma_f32_16x16x32_bf16 v[4:7], v[210:213], v[68:71], v[28:31]
	v_mfma_f32_16x16x32_bf16 v[12:15], v[156:159], v[68:71], v[24:27]
	v_mfma_f32_16x16x32_bf16 v[16:19], v[210:213], v[76:79], v[20:23]
	v_mfma_f32_16x16x32_bf16 v[20:23], v[156:159], v[76:79], v[64:67]
	v_mfma_f32_16x16x32_bf16 v[24:27], v[210:213], v[84:87], v[72:75]
	v_mfma_f32_16x16x32_bf16 v[28:31], v[156:159], v[84:87], v[8:11]
	v_mfma_f32_16x16x32_bf16 v[64:67], v[210:213], v[92:95], v[80:83]
	v_mfma_f32_16x16x32_bf16 v[68:71], v[156:159], v[92:95], v[0:3]
	s_setprio 0
	s_barrier
	ds_read_b128 v[8:11], v154
	ds_read_b128 v[0:3], v154 offset:1024
	ds_read_b128 v[76:79], v154 offset:2048
	ds_read_b128 v[72:75], v154 offset:3072
	ds_read_b128 v[130:133], v152 offset:32768
	ds_read_b128 v[154:157], v152 offset:33792
	ds_read_b128 v[158:161], v151 offset:32768
	ds_read_b128 v[162:165], v151 offset:33792
	ds_read_b128 v[166:169], v150 offset:32768
	ds_read_b128 v[170:173], v150 offset:33792
	ds_read_b128 v[206:209], v149 offset:32768
	ds_read_b128 v[210:213], v149 offset:33792
	s_waitcnt vmcnt(2)
	s_barrier
	s_waitcnt lgkmcnt(0)
	s_setprio 1
	s_waitcnt lgkmcnt(0)
	v_mfma_f32_16x16x32_bf16 v[80:83], v[8:11], v[130:133], v[124:127]
	v_mfma_f32_16x16x32_bf16 v[84:87], v[76:79], v[130:133], v[120:123]
	v_mfma_f32_16x16x32_bf16 v[88:91], v[8:11], v[158:161], v[116:119]
	v_mfma_f32_16x16x32_bf16 v[92:95], v[76:79], v[158:161], v[112:115]
	v_mfma_f32_16x16x32_bf16 v[108:111], v[8:11], v[166:169], v[108:111]
	v_mfma_f32_16x16x32_bf16 v[104:107], v[76:79], v[166:169], v[104:107]
	v_mfma_f32_16x16x32_bf16 v[100:103], v[8:11], v[206:209], v[100:103]
	v_mfma_f32_16x16x32_bf16 v[96:99], v[76:79], v[206:209], v[96:99]
	v_mfma_f32_16x16x32_bf16 v[112:115], v[0:3], v[154:157], v[80:83]
	v_mfma_f32_16x16x32_bf16 v[116:119], v[72:75], v[154:157], v[84:87]
	v_mfma_f32_16x16x32_bf16 v[120:123], v[0:3], v[162:165], v[88:91]
	v_mfma_f32_16x16x32_bf16 v[124:127], v[72:75], v[162:165], v[92:95]
	v_mfma_f32_16x16x32_bf16 v[108:111], v[0:3], v[170:173], v[108:111]
	v_mfma_f32_16x16x32_bf16 v[104:107], v[72:75], v[170:173], v[104:107]
	v_mfma_f32_16x16x32_bf16 v[100:103], v[0:3], v[210:213], v[100:103]
	v_mfma_f32_16x16x32_bf16 v[96:99], v[72:75], v[210:213], v[96:99]
	s_setprio 0
	s_barrier
	ds_read_b128 v[88:91], v153
	ds_read_b128 v[80:83], v153 offset:1024
	ds_read_b128 v[92:95], v153 offset:2048
	ds_read_b128 v[84:87], v153 offset:3072
	s_waitcnt vmcnt(0)
	s_barrier
	s_waitcnt lgkmcnt(0)
	s_setprio 1
	s_waitcnt lgkmcnt(0)
	v_mfma_f32_16x16x32_bf16 v[174:177], v[88:91], v[130:133], v[174:177]
	v_mfma_f32_16x16x32_bf16 v[130:133], v[92:95], v[130:133], v[178:181]
	v_mfma_f32_16x16x32_bf16 v[178:181], v[88:91], v[158:161], v[182:185]
	v_mfma_f32_16x16x32_bf16 v[158:161], v[92:95], v[158:161], v[186:189]
	v_mfma_f32_16x16x32_bf16 v[182:185], v[88:91], v[166:169], v[190:193]
	v_mfma_f32_16x16x32_bf16 v[166:169], v[92:95], v[166:169], v[194:197]
	v_mfma_f32_16x16x32_bf16 v[186:189], v[88:91], v[206:209], v[198:201]
	v_mfma_f32_16x16x32_bf16 v[190:193], v[92:95], v[206:209], v[202:205]
	v_mfma_f32_16x16x32_bf16 v[174:177], v[80:83], v[154:157], v[174:177]
	v_mfma_f32_16x16x32_bf16 v[130:133], v[84:87], v[154:157], v[130:133]
	v_mfma_f32_16x16x32_bf16 v[154:157], v[80:83], v[162:165], v[178:181]
	v_mfma_f32_16x16x32_bf16 v[158:161], v[84:87], v[162:165], v[158:161]
	v_mfma_f32_16x16x32_bf16 v[162:165], v[80:83], v[170:173], v[182:185]
	v_mfma_f32_16x16x32_bf16 v[166:169], v[84:87], v[170:173], v[166:169]
	v_mfma_f32_16x16x32_bf16 v[170:173], v[80:83], v[210:213], v[186:189]
	v_mfma_f32_16x16x32_bf16 v[178:181], v[84:87], v[210:213], v[190:193]
	s_setprio 0
	s_barrier
	v_mbcnt_lo_u32_b32 v128, -1, 0
	v_mbcnt_hi_u32_b32 v128, -1, v128
	v_cvt_pk_bf16_f32 v112, v112, v113
	v_cvt_pk_bf16_f32 v113, v114, v115
	v_cvt_pk_bf16_f32 v114, v116, v117
	v_cvt_pk_bf16_f32 v115, v118, v119
	s_lshl_b32 s89, s64, 9
	v_add_u32_e32 v153, s72, v128
	v_ashrrev_i32_e32 v182, 6, v153
	v_and_b32_e32 v183, 15, v128
	v_and_b32_e32 v184, 48, v128
	v_mul_lo_u32 v185, v182, s77
	v_bfe_u32 v186, v128, 3, 3
	v_lshlrev_b32_e32 v128, 4, v128
	v_add_u32_e32 v185, 0x20000, v185
	v_lshrrev_b32_e32 v153, 2, v153
	v_and_b32_e32 v128, 0x70, v128
	v_mul_u32_u24_e32 v183, 0x90, v183
	v_and_b32_e32 v153, 64, v153
	v_add3_u32 v183, v185, v183, v184
	v_or_b32_e32 v184, v185, v128
	v_or3_b32 v153, s97, v153, v186
	v_mad_u32_u24 v184, v186, s79, v184
	ds_write_b128 v183, v[112:115]
	v_cvt_pk_bf16_f32 v112, v174, v175
	v_cvt_pk_bf16_f32 v113, v176, v177
	v_cvt_pk_bf16_f32 v114, v130, v131
	v_cvt_pk_bf16_f32 v115, v132, v133
	ds_write_b128 v183, v[112:115] offset:64
	v_lshlrev_b32_e32 v182, 7, v182
	ds_read_b128 v[112:115], v184
	v_lshlrev_b32_e32 v116, 12, v153
	v_and_or_b32 v116, v182, s80, v116
	v_or3_b32 v128, v116, s89, v128
	ds_read_b128 v[116:119], v184 offset:1152
	v_lshl_add_u64 v[130:131], s[0:1], 0, v[128:129]
	s_mov_b32 s20, 0x8000
	s_waitcnt lgkmcnt(0)
	global_store_dwordx4 v128, v[112:115], s[0:1]
	v_cvt_pk_bf16_f32 v108, v108, v109
	v_cvt_pk_bf16_f32 v109, v110, v111
	v_cvt_pk_bf16_f32 v110, v104, v105
	v_cvt_pk_bf16_f32 v111, v106, v107
	v_cvt_pk_bf16_f32 v104, v162, v163
	s_nop 1
	v_add_co_u32_e32 v112, vcc, s20, v130
	v_cvt_pk_bf16_f32 v114, v124, v125
	v_cvt_pk_bf16_f32 v115, v126, v127
	v_cvt_pk_bf16_f32 v105, v164, v165
	v_cvt_pk_bf16_f32 v106, v166, v167
	s_nop 1
	v_addc_co_u32_e32 v113, vcc, 0, v131, vcc
	global_store_dwordx4 v[112:113], v[116:119], off
	v_cvt_pk_bf16_f32 v112, v120, v121
	v_cvt_pk_bf16_f32 v113, v122, v123
	ds_write_b128 v183, v[112:115]
	v_cvt_pk_bf16_f32 v112, v154, v155
	v_cvt_pk_bf16_f32 v113, v156, v157
	v_cvt_pk_bf16_f32 v114, v158, v159
	v_cvt_pk_bf16_f32 v115, v160, v161
	ds_write_b128 v183, v[112:115] offset:64
	ds_read_b128 v[112:115], v184
	ds_read_b128 v[116:119], v184 offset:1152
	v_add_co_u32_e32 v120, vcc, s74, v130
	ds_write_b128 v183, v[108:111]
	v_cvt_pk_bf16_f32 v107, v168, v169
	ds_write_b128 v183, v[104:107] offset:64
	v_addc_co_u32_e32 v121, vcc, 0, v131, vcc
	ds_read_b128 v[104:107], v184
	ds_read_b128 v[108:111], v184 offset:1152
	s_waitcnt lgkmcnt(0)
	global_store_dwordx4 v[120:121], v[112:115], off
	v_cvt_pk_bf16_f32 v100, v100, v101
	v_cvt_pk_bf16_f32 v101, v102, v103
	v_cvt_pk_bf16_f32 v102, v96, v97
	v_cvt_pk_bf16_f32 v103, v98, v99
	ds_write_b128 v183, v[100:103]
	s_nop 0
	v_add_co_u32_e32 v112, vcc, s75, v130
	v_cvt_pk_bf16_f32 v96, v170, v171
	v_cvt_pk_bf16_f32 v97, v172, v173
	v_cvt_pk_bf16_f32 v98, v178, v179
	v_cvt_pk_bf16_f32 v99, v180, v181
	s_nop 1
	v_addc_co_u32_e32 v113, vcc, 0, v131, vcc
	global_store_dwordx4 v[112:113], v[116:119], off
	v_add_co_u32_e32 v112, vcc, s78, v130
	ds_write_b128 v183, v[96:99] offset:64
	s_nop 0
	v_addc_co_u32_e32 v113, vcc, 0, v131, vcc
	ds_read_b128 v[96:99], v184
	ds_read_b128 v[100:103], v184 offset:1152
	global_store_dwordx4 v[112:113], v[104:107], off
	s_nop 1
	v_add_co_u32_e32 v104, vcc, s81, v130
	s_nop 1
	v_addc_co_u32_e32 v105, vcc, 0, v131, vcc
	global_store_dwordx4 v[104:105], v[108:111], off
	v_add_co_u32_e32 v104, vcc, s82, v130
	s_nop 1
	v_addc_co_u32_e32 v105, vcc, 0, v131, vcc
	s_waitcnt lgkmcnt(0)
	global_store_dwordx4 v[104:105], v[96:99], off
	s_nop 1
	v_add_co_u32_e32 v96, vcc, s83, v130
	s_nop 1
	v_addc_co_u32_e32 v97, vcc, 0, v131, vcc
	global_store_dwordx4 v[96:97], v[100:103], off
	ds_read_b128 v[96:99], v152 offset:49152
	ds_read_b128 v[100:103], v152 offset:50176
	ds_read_b128 v[104:107], v151 offset:49152
	ds_read_b128 v[108:111], v151 offset:50176
	ds_read_b128 v[112:115], v150 offset:49152
	ds_read_b128 v[116:119], v150 offset:50176
	ds_read_b128 v[120:123], v149 offset:49152
	ds_read_b128 v[124:127], v149 offset:50176
	s_barrier
	s_waitcnt lgkmcnt(0)
	s_setprio 1
	s_waitcnt lgkmcnt(0)
	v_mfma_f32_16x16x32_bf16 v[32:35], v[8:11], v[96:99], v[32:35]
	v_mfma_f32_16x16x32_bf16 v[36:39], v[76:79], v[96:99], v[36:39]
	v_mfma_f32_16x16x32_bf16 v[40:43], v[8:11], v[104:107], v[40:43]
	v_mfma_f32_16x16x32_bf16 v[130:133], v[76:79], v[104:107], v[44:47]
	v_mfma_f32_16x16x32_bf16 v[150:153], v[8:11], v[112:115], v[48:51]
	v_mfma_f32_16x16x32_bf16 v[52:55], v[76:79], v[112:115], v[52:55]
	v_mfma_f32_16x16x32_bf16 v[8:11], v[8:11], v[120:123], v[56:59]
	v_mfma_f32_16x16x32_bf16 v[60:63], v[76:79], v[120:123], v[60:63]
	v_mfma_f32_16x16x32_bf16 v[56:59], v[0:3], v[100:103], v[32:35]
	v_mfma_f32_16x16x32_bf16 v[48:51], v[72:75], v[100:103], v[36:39]
	v_mfma_f32_16x16x32_bf16 v[44:47], v[0:3], v[108:111], v[40:43]
	v_mfma_f32_16x16x32_bf16 v[40:43], v[72:75], v[108:111], v[130:133]
	v_mfma_f32_16x16x32_bf16 v[36:39], v[0:3], v[116:119], v[150:153]
	v_mfma_f32_16x16x32_bf16 v[32:35], v[72:75], v[116:119], v[52:55]
	v_mfma_f32_16x16x32_bf16 v[8:11], v[0:3], v[124:127], v[8:11]
	v_mfma_f32_16x16x32_bf16 v[0:3], v[72:75], v[124:127], v[60:63]
	s_setprio 0
	s_setprio 1
	v_mfma_f32_16x16x32_bf16 v[4:7], v[88:91], v[96:99], v[4:7]
	v_mfma_f32_16x16x32_bf16 v[12:15], v[92:95], v[96:99], v[12:15]
	v_mfma_f32_16x16x32_bf16 v[16:19], v[88:91], v[104:107], v[16:19]
	v_mfma_f32_16x16x32_bf16 v[20:23], v[92:95], v[104:107], v[20:23]
	v_mfma_f32_16x16x32_bf16 v[72:75], v[88:91], v[112:115], v[24:27]
	v_mfma_f32_16x16x32_bf16 v[76:79], v[92:95], v[112:115], v[28:31]
	v_mfma_f32_16x16x32_bf16 v[64:67], v[88:91], v[120:123], v[64:67]
	v_mfma_f32_16x16x32_bf16 v[68:71], v[92:95], v[120:123], v[68:71]
	v_mfma_f32_16x16x32_bf16 v[60:63], v[80:83], v[100:103], v[4:7]
	v_mfma_f32_16x16x32_bf16 v[52:55], v[84:87], v[100:103], v[12:15]
	v_mfma_f32_16x16x32_bf16 v[28:31], v[80:83], v[108:111], v[16:19]
	v_mfma_f32_16x16x32_bf16 v[24:27], v[84:87], v[108:111], v[20:23]
	v_mfma_f32_16x16x32_bf16 v[20:23], v[80:83], v[116:119], v[72:75]
	v_mfma_f32_16x16x32_bf16 v[16:19], v[84:87], v[116:119], v[76:79]
	v_mfma_f32_16x16x32_bf16 v[12:15], v[80:83], v[124:127], v[64:67]
	v_mfma_f32_16x16x32_bf16 v[4:7], v[84:87], v[124:127], v[68:71]
	s_setprio 0
	v_cmp_gt_u32_e32 vcc, s85, v135
	s_barrier
	s_and_saveexec_b64 s[64:65], vcc
	s_cbranch_execz .LBB0_277
	s_barrier

.LBB0_355:
	s_lshl_b32 s14, s70, 3
	v_cvt_f32_u32_e32 v2, s14
	s_sub_i32 s17, 0, s14
	s_abs_i32 s16, s69
	s_ashr_i32 s15, s69, 31
	v_rcp_iflag_f32_e32 v2, v2
	v_and_b32_e32 v3, 15, v0
	v_lshlrev_b32_e32 v3, 6, v3
	v_lshlrev_b32_e32 v6, 2, v0
	v_mul_f32_e32 v2, 0x4f7ffffe, v2
	v_cvt_u32_f32_e32 v2, v2
	v_lshlrev_b32_e32 v4, 6, v183
	v_and_b32_e32 v6, 32, v6
	v_lshlrev_b32_e32 v1, 13, v1
	v_readfirstlane_b32 s24, v2
	s_mul_i32 s17, s17, s24
	s_mul_hi_u32 s17, s24, s17
	s_add_i32 s24, s24, s17
	s_mul_hi_u32 s17, s16, s24
	s_mul_i32 s24, s17, s14
	s_sub_i32 s16, s16, s24
	s_add_i32 s25, s17, 1
	s_sub_i32 s24, s16, s14
	s_cmp_ge_u32 s16, s14
	s_cselect_b32 s17, s25, s17
	s_cselect_b32 s16, s24, s16
	s_add_i32 s24, s17, 1
	s_cmp_ge_u32 s16, s14
	s_cselect_b32 s16, s24, s17
	s_xor_b32 s16, s16, s15
	s_sub_i32 s67, s16, s15
	s_mul_i32 s14, s67, s14
	s_sub_i32 s14, s69, s14
	s_lshl_b32 s15, s67, 3
	s_and_b32 s16, s14, 7
	s_ashr_i32 s66, s14, 3
	s_or_b32 s68, s16, s15
	s_lshl_b32 s16, s66, 8
	s_lshl_b32 s14, s68, 8
	s_and_b64 s[24:25], s[22:23], exec
	s_cselect_b32 s24, s45, 0x40000
	s_cselect_b32 s36, 32, 0x80
	s_cselect_b32 s25, s46, 0x1000
	s_or_b32 s26, s14, 0x80
	s_ashr_i32 s27, s26, 31
	s_and_b64 s[28:29], s[22:23], exec
	s_cselect_b32 s37, 6, 12
	s_lshl_b64 s[26:27], s[26:27], s37
	s_add_u32 s26, s18, s26
	s_addc_u32 s27, s19, s27
	s_and_b64 s[28:29], s[22:23], exec
	s_cselect_b32 s28, 18, 7
	s_ashr_i32 s17, s16, 31
	s_and_b64 s[30:31], s[22:23], exec
	s_cselect_b32 s69, 12, 6
	s_lshl_b64 s[30:31], s[16:17], s69
	s_add_u32 s17, s20, s30
	s_addc_u32 s29, s21, s31
	s_ashr_i32 s15, s14, 31
	s_lshl_b64 s[30:31], s[14:15], s37
	s_add_u32 s15, s18, s30
	s_addc_u32 s30, s19, s31
	s_or_b32 s18, s16, s36
	s_ashr_i32 s19, s18, 31
	s_lshl_b64 s[18:19], s[18:19], s69
	v_and_b32_e32 v2, 48, v0
	s_add_u32 s20, s20, s18
	v_lshlrev_b32_e32 v0, 6, v0
	v_or_b32_e32 v5, v3, v2
	s_addc_u32 s21, s21, s19
	v_and_b32_e32 v0, 0x3c0, v0
	v_and_b32_e32 v4, 0x3000, v4
	v_bitop3_b32 v3, v3, v6, v2 bitop3:0x36
	v_bitop3_b32 v7, v5, s56, v6 bitop3:0xde
	v_bitop3_b32 v8, v5, s57, v6 bitop3:0xde
	v_bitop3_b32 v9, v5, s58, v6 bitop3:0xde
	v_bitop3_b32 v5, v5, s59, v6 bitop3:0xde
	v_bitop3_b32 v2, v0, v6, v2 bitop3:0x36
	v_or_b32_e32 v6, 0x800, v1
	v_or_b32_e32 v10, 0x1000, v1
	v_or_b32_e32 v11, 0x1800, v1
	s_and_b64 s[18:19], s[22:23], exec
	v_mov_b32_e32 v0, 0
	v_mov_b32_e32 v129, v165
	s_cselect_b32 s22, 7, 18
	s_mov_b64 s[18:19], 1
	v_add_u32_e32 v134, v7, v4
	v_add_u32_e32 v187, v3, v1
	v_add_u32_e32 v186, v2, v6
	v_add_u32_e32 v185, v2, v10
	v_add_u32_e32 v184, v2, v11
	v_add_u32_e32 v133, 0xc000, v169
	v_add_u32_e32 v132, 0xe000, v169
	v_add_u32_e32 v131, v8, v4
	v_add_u32_e32 v182, 0x10000, v169
	v_add_u32_e32 v181, 0x12000, v169
	v_add_u32_e32 v180, 0x2000, v169
	v_add_u32_e32 v179, 0x14000, v169
	v_add_u32_e32 v178, 0x16000, v169
	v_add_u32_e32 v130, v9, v4
	v_add_u32_e32 v177, 0x4000, v169
	v_add_u32_e32 v176, 0x6000, v169
	v_add_u32_e32 v136, v5, v4
	v_add_u32_e32 v175, 0x18000, v169
	v_add_u32_e32 v174, 0x1a000, v169
	v_add_u32_e32 v173, 0x8000, v169
	v_add_u32_e32 v172, 0xa000, v169
	v_add_u32_e32 v171, 0x1c000, v169
	v_add_u32_e32 v170, 0x1e000, v169
	v_mov_b32_e32 v1, v0
	v_mov_b32_e32 v2, v0
	v_mov_b32_e32 v3, v0
	v_mov_b32_e32 v4, v0
	v_mov_b32_e32 v5, v0
	v_mov_b32_e32 v6, v0
	v_mov_b32_e32 v7, v0
	v_mov_b32_e32 v8, v0
	v_mov_b32_e32 v9, v0
	v_mov_b32_e32 v10, v0
	v_mov_b32_e32 v11, v0
	v_mov_b32_e32 v12, v0
	v_mov_b32_e32 v13, v0
	v_mov_b32_e32 v14, v0
	v_mov_b32_e32 v15, v0
	v_mov_b32_e32 v16, v0
	v_mov_b32_e32 v17, v0
	v_mov_b32_e32 v18, v0
	v_mov_b32_e32 v19, v0
	v_mov_b32_e32 v20, v0
	v_mov_b32_e32 v21, v0
	v_mov_b32_e32 v22, v0
	v_mov_b32_e32 v23, v0
	v_mov_b32_e32 v24, v0
	v_mov_b32_e32 v25, v0
	v_mov_b32_e32 v26, v0
	v_mov_b32_e32 v27, v0
	v_mov_b32_e32 v28, v0
	v_mov_b32_e32 v29, v0
	v_mov_b32_e32 v30, v0
	v_mov_b32_e32 v31, v0
	v_mov_b32_e32 v32, v0
	v_mov_b32_e32 v33, v0
	v_mov_b32_e32 v34, v0
	v_mov_b32_e32 v35, v0
	v_mov_b32_e32 v36, v0
	v_mov_b32_e32 v37, v0
	v_mov_b32_e32 v38, v0
	v_mov_b32_e32 v39, v0
	v_mov_b32_e32 v40, v0
	v_mov_b32_e32 v41, v0
	v_mov_b32_e32 v42, v0
	v_mov_b32_e32 v43, v0
	v_mov_b32_e32 v44, v0
	v_mov_b32_e32 v45, v0
	v_mov_b32_e32 v46, v0
	v_mov_b32_e32 v47, v0
	v_mov_b32_e32 v48, v0
	v_mov_b32_e32 v49, v0
	v_mov_b32_e32 v50, v0
	v_mov_b32_e32 v51, v0
	v_mov_b32_e32 v52, v0
	v_mov_b32_e32 v53, v0
	v_mov_b32_e32 v54, v0
	v_mov_b32_e32 v55, v0
	v_mov_b32_e32 v56, v0
	v_mov_b32_e32 v57, v0
	v_mov_b32_e32 v58, v0
	v_mov_b32_e32 v59, v0
	v_mov_b32_e32 v60, v0
	v_mov_b32_e32 v61, v0
	v_mov_b32_e32 v62, v0
	v_mov_b32_e32 v63, v0
	v_mov_b32_e32 v64, v0
	v_mov_b32_e32 v65, v0
	v_mov_b32_e32 v66, v0
	v_mov_b32_e32 v67, v0
	v_mov_b32_e32 v68, v0
	v_mov_b32_e32 v69, v0
	v_mov_b32_e32 v70, v0
	v_mov_b32_e32 v71, v0
	v_mov_b32_e32 v72, v0
	v_mov_b32_e32 v73, v0
	v_mov_b32_e32 v74, v0
	v_mov_b32_e32 v75, v0
	v_mov_b32_e32 v76, v0
	v_mov_b32_e32 v77, v0
	v_mov_b32_e32 v78, v0
	v_mov_b32_e32 v79, v0
	v_mov_b32_e32 v80, v0
	v_mov_b32_e32 v81, v0
	v_mov_b32_e32 v82, v0
	v_mov_b32_e32 v83, v0
	v_mov_b32_e32 v84, v0
	v_mov_b32_e32 v85, v0
	v_mov_b32_e32 v86, v0
	v_mov_b32_e32 v87, v0
	v_mov_b32_e32 v88, v0
	v_mov_b32_e32 v89, v0
	v_mov_b32_e32 v90, v0
	v_mov_b32_e32 v91, v0
	v_mov_b32_e32 v92, v0
	v_mov_b32_e32 v93, v0
	v_mov_b32_e32 v94, v0
	v_mov_b32_e32 v95, v0
	v_mov_b32_e32 v96, v0
	v_mov_b32_e32 v97, v0
	v_mov_b32_e32 v98, v0
	v_mov_b32_e32 v99, v0
	v_mov_b32_e32 v100, v0
	v_mov_b32_e32 v101, v0
	v_mov_b32_e32 v102, v0
	v_mov_b32_e32 v103, v0
	v_mov_b32_e32 v104, v0
	v_mov_b32_e32 v105, v0
	v_mov_b32_e32 v106, v0
	v_mov_b32_e32 v107, v0
	v_mov_b32_e32 v108, v0
	v_mov_b32_e32 v109, v0
	v_mov_b32_e32 v110, v0
	v_mov_b32_e32 v111, v0
	v_mov_b32_e32 v112, v0
	v_mov_b32_e32 v113, v0
	v_mov_b32_e32 v114, v0
	v_mov_b32_e32 v115, v0
	v_mov_b32_e32 v116, v0
	v_mov_b32_e32 v117, v0
	v_mov_b32_e32 v118, v0
	v_mov_b32_e32 v119, v0
	v_mov_b32_e32 v120, v0
	v_mov_b32_e32 v121, v0
	v_mov_b32_e32 v122, v0
	v_mov_b32_e32 v123, v0
	v_mov_b32_e32 v124, v0
	v_mov_b32_e32 v125, v0
	v_mov_b32_e32 v126, v0
	v_mov_b32_e32 v127, v0
	s_barrier
	s_lshl_b64 s[70:71], s[18:19], s28
	s_add_u32 s70, s26, s70
	s_addc_u32 s71, s27, s71
	v_lshl_add_u64 v[162:163], s[70:71], 0, v[164:165]
	v_readfirstlane_b32 s23, v133
	s_add_u32 s70, s70, s24
	s_mov_b32 m0, s23
	s_addc_u32 s71, s71, 0
	v_readfirstlane_b32 s23, v132
	global_load_lds_dwordx4 v[162:163], off
	v_lshl_add_u64 v[162:163], s[70:71], 0, v[164:165]
	s_mov_b32 m0, s23
	s_nop 0
	global_load_lds_dwordx4 v[162:163], off
	ds_read_b128 v[138:141], v134
	ds_read_b128 v[142:145], v134 offset:1024
	ds_read_b128 v[146:149], v134 offset:2048
	ds_read_b128 v[150:153], v134 offset:3072
	ds_read_b128 v[154:157], v187
	ds_read_b128 v[158:161], v187 offset:1024
	ds_read_b128 v[188:191], v186
	ds_read_b128 v[192:195], v186 offset:1024
	ds_read_b128 v[196:199], v185
	ds_read_b128 v[200:203], v185 offset:1024
	ds_read_b128 v[204:207], v184
	ds_read_b128 v[208:211], v184 offset:1024
	s_waitcnt lgkmcnt(8)
	s_barrier
	s_branch .Lkent_356

.Lkent_356:
	s_waitcnt lgkmcnt(0)
	s_setprio 1
	s_waitcnt lgkmcnt(0)
	v_mfma_f32_16x16x32_bf16 v[124:127], v[138:141], v[154:157], v[124:127]
	v_mfma_f32_16x16x32_bf16 v[120:123], v[146:149], v[154:157], v[120:123]
	v_mfma_f32_16x16x32_bf16 v[116:119], v[138:141], v[188:191], v[116:119]
	v_mfma_f32_16x16x32_bf16 v[112:115], v[146:149], v[188:191], v[112:115]
	v_mfma_f32_16x16x32_bf16 v[108:111], v[138:141], v[196:199], v[108:111]
	v_mfma_f32_16x16x32_bf16 v[104:107], v[146:149], v[196:199], v[104:107]
	v_mfma_f32_16x16x32_bf16 v[100:103], v[138:141], v[204:207], v[100:103]
	v_mfma_f32_16x16x32_bf16 v[96:99], v[146:149], v[204:207], v[96:99]
	v_mfma_f32_16x16x32_bf16 v[124:127], v[142:145], v[158:161], v[124:127]
	v_mfma_f32_16x16x32_bf16 v[120:123], v[150:153], v[158:161], v[120:123]
	v_mfma_f32_16x16x32_bf16 v[116:119], v[142:145], v[192:195], v[116:119]
	v_mfma_f32_16x16x32_bf16 v[112:115], v[150:153], v[192:195], v[112:115]
	v_mfma_f32_16x16x32_bf16 v[108:111], v[142:145], v[200:203], v[108:111]
	v_mfma_f32_16x16x32_bf16 v[104:107], v[150:153], v[200:203], v[104:107]
	v_mfma_f32_16x16x32_bf16 v[100:103], v[142:145], v[208:211], v[100:103]
	v_mfma_f32_16x16x32_bf16 v[96:99], v[150:153], v[208:211], v[96:99]
	s_setprio 0
	s_barrier
	s_add_u32 s70, s18, 1
	s_addc_u32 s71, s19, 0
	s_lshl_b64 s[72:73], s[70:71], s22
	s_add_u32 s74, s17, s72
	s_addc_u32 s75, s29, s73
	v_lshl_add_u64 v[162:163], s[74:75], 0, v[128:129]
	v_readfirstlane_b32 s23, v182
	s_add_u32 s74, s74, s25
	s_mov_b32 m0, s23
	s_addc_u32 s75, s75, 0
	v_readfirstlane_b32 s23, v181
	ds_read_b128 v[212:215], v131
	ds_read_b128 v[216:219], v131 offset:1024
	ds_read_b128 v[220:223], v131 offset:2048
	ds_read_b128 v[224:227], v131 offset:3072
	global_load_lds_dwordx4 v[162:163], off
	v_lshl_add_u64 v[162:163], s[74:75], 0, v[128:129]
	s_mov_b32 m0, s23
	s_nop 0
	global_load_lds_dwordx4 v[162:163], off
	s_lshl_b64 s[70:71], s[70:71], s28
	s_add_u32 s74, s15, s70
	s_addc_u32 s75, s30, s71
	v_lshl_add_u64 v[162:163], s[74:75], 0, v[164:165]
	v_readfirstlane_b32 s23, v169
	s_add_u32 s74, s74, s24
	s_mov_b32 m0, s23
	s_addc_u32 s75, s75, 0
	v_readfirstlane_b32 s23, v180
	global_load_lds_dwordx4 v[162:163], off
	v_lshl_add_u64 v[162:163], s[74:75], 0, v[164:165]
	s_mov_b32 m0, s23
	s_nop 0
	global_load_lds_dwordx4 v[162:163], off
	s_waitcnt vmcnt(12)
	s_barrier
	s_waitcnt lgkmcnt(0)
	s_setprio 1
	s_waitcnt lgkmcnt(0)
	v_mfma_f32_16x16x32_bf16 v[92:95], v[212:215], v[154:157], v[92:95]
	v_mfma_f32_16x16x32_bf16 v[88:91], v[220:223], v[154:157], v[88:91]
	v_mfma_f32_16x16x32_bf16 v[84:87], v[212:215], v[188:191], v[84:87]
	v_mfma_f32_16x16x32_bf16 v[80:83], v[220:223], v[188:191], v[80:83]
	v_mfma_f32_16x16x32_bf16 v[76:79], v[212:215], v[196:199], v[76:79]
	v_mfma_f32_16x16x32_bf16 v[72:75], v[220:223], v[196:199], v[72:75]
	v_mfma_f32_16x16x32_bf16 v[68:71], v[212:215], v[204:207], v[68:71]
	v_mfma_f32_16x16x32_bf16 v[64:67], v[220:223], v[204:207], v[64:67]
	v_mfma_f32_16x16x32_bf16 v[92:95], v[216:219], v[158:161], v[92:95]
	v_mfma_f32_16x16x32_bf16 v[88:91], v[224:227], v[158:161], v[88:91]
	v_mfma_f32_16x16x32_bf16 v[84:87], v[216:219], v[192:195], v[84:87]
	v_mfma_f32_16x16x32_bf16 v[80:83], v[224:227], v[192:195], v[80:83]
	v_mfma_f32_16x16x32_bf16 v[76:79], v[216:219], v[200:203], v[76:79]
	v_mfma_f32_16x16x32_bf16 v[72:75], v[224:227], v[200:203], v[72:75]
	v_mfma_f32_16x16x32_bf16 v[68:71], v[216:219], v[208:211], v[68:71]
	v_mfma_f32_16x16x32_bf16 v[64:67], v[224:227], v[208:211], v[64:67]
	s_setprio 0
	s_barrier
	ds_read_b128 v[154:157], v187 offset:16384
	ds_read_b128 v[158:161], v187 offset:17408
	ds_read_b128 v[188:191], v186 offset:16384
	ds_read_b128 v[192:195], v186 offset:17408
	ds_read_b128 v[196:199], v185 offset:16384
	ds_read_b128 v[200:203], v185 offset:17408
	ds_read_b128 v[204:207], v184 offset:16384
	ds_read_b128 v[208:211], v184 offset:17408
	s_add_u32 s72, s20, s72
	s_addc_u32 s73, s21, s73
	v_lshl_add_u64 v[162:163], s[72:73], 0, v[128:129]
	v_readfirstlane_b32 s23, v179
	s_add_u32 s72, s72, s25
	s_mov_b32 m0, s23
	s_addc_u32 s73, s73, 0
	v_readfirstlane_b32 s23, v178
	global_load_lds_dwordx4 v[162:163], off
	v_lshl_add_u64 v[162:163], s[72:73], 0, v[128:129]
	s_mov_b32 m0, s23
	s_nop 0
	global_load_lds_dwordx4 v[162:163], off
	s_barrier
	s_waitcnt lgkmcnt(0)
	s_setprio 1
	s_waitcnt lgkmcnt(0)
	v_mfma_f32_16x16x32_bf16 v[60:63], v[138:141], v[154:157], v[60:63]
	v_mfma_f32_16x16x32_bf16 v[56:59], v[146:149], v[154:157], v[56:59]
	v_mfma_f32_16x16x32_bf16 v[52:55], v[138:141], v[188:191], v[52:55]
	v_mfma_f32_16x16x32_bf16 v[48:51], v[146:149], v[188:191], v[48:51]
	v_mfma_f32_16x16x32_bf16 v[44:47], v[138:141], v[196:199], v[44:47]
	v_mfma_f32_16x16x32_bf16 v[40:43], v[146:149], v[196:199], v[40:43]
	v_mfma_f32_16x16x32_bf16 v[36:39], v[138:141], v[204:207], v[36:39]
	v_mfma_f32_16x16x32_bf16 v[32:35], v[146:149], v[204:207], v[32:35]
	v_mfma_f32_16x16x32_bf16 v[60:63], v[142:145], v[158:161], v[60:63]
	v_mfma_f32_16x16x32_bf16 v[56:59], v[150:153], v[158:161], v[56:59]
	v_mfma_f32_16x16x32_bf16 v[52:55], v[142:145], v[192:195], v[52:55]
	v_mfma_f32_16x16x32_bf16 v[48:51], v[150:153], v[192:195], v[48:51]
	v_mfma_f32_16x16x32_bf16 v[44:47], v[142:145], v[200:203], v[44:47]
	v_mfma_f32_16x16x32_bf16 v[40:43], v[150:153], v[200:203], v[40:43]
	v_mfma_f32_16x16x32_bf16 v[36:39], v[142:145], v[208:211], v[36:39]
	v_mfma_f32_16x16x32_bf16 v[32:35], v[150:153], v[208:211], v[32:35]
	s_setprio 0
	s_barrier
	s_add_u32 s70, s26, s70
	s_addc_u32 s71, s27, s71
	v_lshl_add_u64 v[162:163], s[70:71], 0, v[164:165]
	v_readfirstlane_b32 s23, v177
	s_add_u32 s70, s70, s24
	s_mov_b32 m0, s23
	s_addc_u32 s71, s71, 0
	v_readfirstlane_b32 s23, v176
	global_load_lds_dwordx4 v[162:163], off
	v_lshl_add_u64 v[162:163], s[70:71], 0, v[164:165]
	s_mov_b32 m0, s23
	s_nop 0
	global_load_lds_dwordx4 v[162:163], off
	s_waitcnt vmcnt(12)
	s_barrier
	s_setprio 1
	v_mfma_f32_16x16x32_bf16 v[28:31], v[212:215], v[154:157], v[28:31]
	v_mfma_f32_16x16x32_bf16 v[24:27], v[220:223], v[154:157], v[24:27]
	v_mfma_f32_16x16x32_bf16 v[20:23], v[212:215], v[188:191], v[20:23]
	v_mfma_f32_16x16x32_bf16 v[16:19], v[220:223], v[188:191], v[16:19]
	v_mfma_f32_16x16x32_bf16 v[12:15], v[212:215], v[196:199], v[12:15]
	v_mfma_f32_16x16x32_bf16 v[8:11], v[220:223], v[196:199], v[8:11]
	v_mfma_f32_16x16x32_bf16 v[4:7], v[212:215], v[204:207], v[4:7]
	v_mfma_f32_16x16x32_bf16 v[0:3], v[220:223], v[204:207], v[0:3]
	v_mfma_f32_16x16x32_bf16 v[28:31], v[216:219], v[158:161], v[28:31]
	v_mfma_f32_16x16x32_bf16 v[24:27], v[224:227], v[158:161], v[24:27]
	v_mfma_f32_16x16x32_bf16 v[20:23], v[216:219], v[192:195], v[20:23]
	v_mfma_f32_16x16x32_bf16 v[16:19], v[224:227], v[192:195], v[16:19]
	v_mfma_f32_16x16x32_bf16 v[12:15], v[216:219], v[200:203], v[12:15]
	v_mfma_f32_16x16x32_bf16 v[8:11], v[224:227], v[200:203], v[8:11]
	v_mfma_f32_16x16x32_bf16 v[4:7], v[216:219], v[208:211], v[4:7]
	v_mfma_f32_16x16x32_bf16 v[0:3], v[224:227], v[208:211], v[0:3]
	s_setprio 0
	s_barrier
	ds_read_b128 v[138:141], v130
	ds_read_b128 v[142:145], v130 offset:1024
	ds_read_b128 v[146:149], v130 offset:2048
	ds_read_b128 v[150:153], v130 offset:3072
	ds_read_b128 v[154:157], v187 offset:32768
	ds_read_b128 v[158:161], v187 offset:33792
	ds_read_b128 v[188:191], v186 offset:32768
	ds_read_b128 v[192:195], v186 offset:33792
	ds_read_b128 v[196:199], v185 offset:32768
	ds_read_b128 v[200:203], v185 offset:33792
	ds_read_b128 v[204:207], v184 offset:32768
	ds_read_b128 v[208:211], v184 offset:33792
	s_waitcnt lgkmcnt(8)
	s_waitcnt vmcnt(10)
	s_barrier
	s_waitcnt lgkmcnt(0)
	s_setprio 1
	s_waitcnt lgkmcnt(0)
	v_mfma_f32_16x16x32_bf16 v[124:127], v[138:141], v[154:157], v[124:127]
	v_mfma_f32_16x16x32_bf16 v[120:123], v[146:149], v[154:157], v[120:123]
	v_mfma_f32_16x16x32_bf16 v[116:119], v[138:141], v[188:191], v[116:119]
	v_mfma_f32_16x16x32_bf16 v[112:115], v[146:149], v[188:191], v[112:115]
	v_mfma_f32_16x16x32_bf16 v[108:111], v[138:141], v[196:199], v[108:111]
	v_mfma_f32_16x16x32_bf16 v[104:107], v[146:149], v[196:199], v[104:107]
	v_mfma_f32_16x16x32_bf16 v[100:103], v[138:141], v[204:207], v[100:103]
	v_mfma_f32_16x16x32_bf16 v[96:99], v[146:149], v[204:207], v[96:99]
	v_mfma_f32_16x16x32_bf16 v[124:127], v[142:145], v[158:161], v[124:127]
	v_mfma_f32_16x16x32_bf16 v[120:123], v[150:153], v[158:161], v[120:123]
	v_mfma_f32_16x16x32_bf16 v[116:119], v[142:145], v[192:195], v[116:119]
	v_mfma_f32_16x16x32_bf16 v[112:115], v[150:153], v[192:195], v[112:115]
	v_mfma_f32_16x16x32_bf16 v[108:111], v[142:145], v[200:203], v[108:111]
	v_mfma_f32_16x16x32_bf16 v[104:107], v[150:153], v[200:203], v[104:107]
	v_mfma_f32_16x16x32_bf16 v[100:103], v[142:145], v[208:211], v[100:103]
	v_mfma_f32_16x16x32_bf16 v[96:99], v[150:153], v[208:211], v[96:99]
	s_setprio 0
	s_barrier
	s_add_u32 s18, s18, 2
	s_addc_u32 s19, s19, 0
	s_lshl_b64 s[70:71], s[18:19], s22
	s_add_u32 s72, s17, s70
	s_addc_u32 s73, s29, s71
	v_lshl_add_u64 v[162:163], s[72:73], 0, v[128:129]
	v_readfirstlane_b32 s23, v175
	s_add_u32 s72, s72, s25
	s_mov_b32 m0, s23
	s_addc_u32 s73, s73, 0
	v_readfirstlane_b32 s23, v174
	ds_read_b128 v[212:215], v136
	ds_read_b128 v[216:219], v136 offset:1024
	ds_read_b128 v[220:223], v136 offset:2048
	ds_read_b128 v[224:227], v136 offset:3072
	global_load_lds_dwordx4 v[162:163], off
	v_lshl_add_u64 v[162:163], s[72:73], 0, v[128:129]
	s_mov_b32 m0, s23
	s_nop 0
	global_load_lds_dwordx4 v[162:163], off
	s_lshl_b64 s[72:73], s[18:19], s28
	s_add_u32 s72, s15, s72
	s_addc_u32 s73, s30, s73
	v_lshl_add_u64 v[162:163], s[72:73], 0, v[164:165]
	v_readfirstlane_b32 s23, v173
	s_add_u32 s72, s72, s24
	s_mov_b32 m0, s23
	s_addc_u32 s73, s73, 0
	v_readfirstlane_b32 s23, v172
	global_load_lds_dwordx4 v[162:163], off
	v_lshl_add_u64 v[162:163], s[72:73], 0, v[164:165]
	s_mov_b32 m0, s23
	s_nop 0
	global_load_lds_dwordx4 v[162:163], off
	s_waitcnt vmcnt(12)
	s_barrier
	s_waitcnt lgkmcnt(0)
	s_setprio 1
	s_waitcnt lgkmcnt(0)
	v_mfma_f32_16x16x32_bf16 v[92:95], v[212:215], v[154:157], v[92:95]
	v_mfma_f32_16x16x32_bf16 v[88:91], v[220:223], v[154:157], v[88:91]
	v_mfma_f32_16x16x32_bf16 v[84:87], v[212:215], v[188:191], v[84:87]
	v_mfma_f32_16x16x32_bf16 v[80:83], v[220:223], v[188:191], v[80:83]
	v_mfma_f32_16x16x32_bf16 v[76:79], v[212:215], v[196:199], v[76:79]
	v_mfma_f32_16x16x32_bf16 v[72:75], v[220:223], v[196:199], v[72:75]
	v_mfma_f32_16x16x32_bf16 v[68:71], v[212:215], v[204:207], v[68:71]
	v_mfma_f32_16x16x32_bf16 v[64:67], v[220:223], v[204:207], v[64:67]
	v_mfma_f32_16x16x32_bf16 v[92:95], v[216:219], v[158:161], v[92:95]
	v_mfma_f32_16x16x32_bf16 v[88:91], v[224:227], v[158:161], v[88:91]
	v_mfma_f32_16x16x32_bf16 v[84:87], v[216:219], v[192:195], v[84:87]
	v_mfma_f32_16x16x32_bf16 v[80:83], v[224:227], v[192:195], v[80:83]
	v_mfma_f32_16x16x32_bf16 v[76:79], v[216:219], v[200:203], v[76:79]
	v_mfma_f32_16x16x32_bf16 v[72:75], v[224:227], v[200:203], v[72:75]
	v_mfma_f32_16x16x32_bf16 v[68:71], v[216:219], v[208:211], v[68:71]
	v_mfma_f32_16x16x32_bf16 v[64:67], v[224:227], v[208:211], v[64:67]
	s_setprio 0
	s_barrier
	ds_read_b128 v[154:157], v187 offset:49152
	ds_read_b128 v[158:161], v187 offset:50176
	ds_read_b128 v[188:191], v186 offset:49152
	ds_read_b128 v[192:195], v186 offset:50176
	ds_read_b128 v[196:199], v185 offset:49152
	ds_read_b128 v[200:203], v185 offset:50176
	ds_read_b128 v[204:207], v184 offset:49152
	ds_read_b128 v[208:211], v184 offset:50176
	s_add_u32 s70, s20, s70
	s_addc_u32 s71, s21, s71
	v_lshl_add_u64 v[162:163], s[70:71], 0, v[128:129]
	v_readfirstlane_b32 s23, v171
	s_add_u32 s70, s70, s25
	s_mov_b32 m0, s23
	s_addc_u32 s71, s71, 0
	v_readfirstlane_b32 s23, v170
	global_load_lds_dwordx4 v[162:163], off
	v_lshl_add_u64 v[162:163], s[70:71], 0, v[128:129]
	s_mov_b32 m0, s23
	s_nop 0
	global_load_lds_dwordx4 v[162:163], off
	s_barrier
	s_waitcnt lgkmcnt(0)
	s_setprio 1
	s_waitcnt lgkmcnt(0)
	v_mfma_f32_16x16x32_bf16 v[60:63], v[138:141], v[154:157], v[60:63]
	v_mfma_f32_16x16x32_bf16 v[56:59], v[146:149], v[154:157], v[56:59]
	v_mfma_f32_16x16x32_bf16 v[52:55], v[138:141], v[188:191], v[52:55]
	v_mfma_f32_16x16x32_bf16 v[48:51], v[146:149], v[188:191], v[48:51]
	v_mfma_f32_16x16x32_bf16 v[44:47], v[138:141], v[196:199], v[44:47]
	v_mfma_f32_16x16x32_bf16 v[40:43], v[146:149], v[196:199], v[40:43]
	v_mfma_f32_16x16x32_bf16 v[36:39], v[138:141], v[204:207], v[36:39]
	v_mfma_f32_16x16x32_bf16 v[32:35], v[146:149], v[204:207], v[32:35]
	v_mfma_f32_16x16x32_bf16 v[60:63], v[142:145], v[158:161], v[60:63]
	v_mfma_f32_16x16x32_bf16 v[56:59], v[150:153], v[158:161], v[56:59]
	v_mfma_f32_16x16x32_bf16 v[52:55], v[142:145], v[192:195], v[52:55]
	v_mfma_f32_16x16x32_bf16 v[48:51], v[150:153], v[192:195], v[48:51]
	v_mfma_f32_16x16x32_bf16 v[44:47], v[142:145], v[200:203], v[44:47]
	v_mfma_f32_16x16x32_bf16 v[40:43], v[150:153], v[200:203], v[40:43]
	v_mfma_f32_16x16x32_bf16 v[36:39], v[142:145], v[208:211], v[36:39]
	v_mfma_f32_16x16x32_bf16 v[32:35], v[150:153], v[208:211], v[32:35]
	s_setprio 0
	s_barrier
	s_lshl_b64 s[70:71], s[18:19], s28
	s_add_u32 s70, s26, s70
	s_addc_u32 s71, s27, s71
	v_lshl_add_u64 v[162:163], s[70:71], 0, v[164:165]
	v_readfirstlane_b32 s23, v133
	s_add_u32 s70, s70, s24
	s_mov_b32 m0, s23
	s_addc_u32 s71, s71, 0
	v_readfirstlane_b32 s23, v132
	global_load_lds_dwordx4 v[162:163], off
	v_lshl_add_u64 v[162:163], s[70:71], 0, v[164:165]
	s_mov_b32 m0, s23
	s_nop 0
	global_load_lds_dwordx4 v[162:163], off
	s_waitcnt vmcnt(12)
	s_barrier
	s_setprio 1
	v_mfma_f32_16x16x32_bf16 v[28:31], v[212:215], v[154:157], v[28:31]
	v_mfma_f32_16x16x32_bf16 v[24:27], v[220:223], v[154:157], v[24:27]
	v_mfma_f32_16x16x32_bf16 v[20:23], v[212:215], v[188:191], v[20:23]
	v_mfma_f32_16x16x32_bf16 v[16:19], v[220:223], v[188:191], v[16:19]
	v_mfma_f32_16x16x32_bf16 v[12:15], v[212:215], v[196:199], v[12:15]
	v_mfma_f32_16x16x32_bf16 v[8:11], v[220:223], v[196:199], v[8:11]
	v_mfma_f32_16x16x32_bf16 v[4:7], v[212:215], v[204:207], v[4:7]
	v_mfma_f32_16x16x32_bf16 v[0:3], v[220:223], v[204:207], v[0:3]
	v_mfma_f32_16x16x32_bf16 v[28:31], v[216:219], v[158:161], v[28:31]
	v_mfma_f32_16x16x32_bf16 v[24:27], v[224:227], v[158:161], v[24:27]
	v_mfma_f32_16x16x32_bf16 v[20:23], v[216:219], v[192:195], v[20:23]
	v_mfma_f32_16x16x32_bf16 v[16:19], v[224:227], v[192:195], v[16:19]
	v_mfma_f32_16x16x32_bf16 v[12:15], v[216:219], v[200:203], v[12:15]
	v_mfma_f32_16x16x32_bf16 v[8:11], v[224:227], v[200:203], v[8:11]
	v_mfma_f32_16x16x32_bf16 v[4:7], v[216:219], v[208:211], v[4:7]
	v_mfma_f32_16x16x32_bf16 v[0:3], v[224:227], v[208:211], v[0:3]
	s_setprio 0
	s_add_i32 s23, s18, -3
	s_cmp_lt_u32 s23, 28
	s_barrier
	s_cbranch_scc1 .LBB0_356
	s_lshl_b64 s[18:19], 31, s28
	s_add_u32 s18, s26, s18
	s_addc_u32 s19, s27, s19
	v_lshl_add_u64 v[128:129], s[18:19], 0, v[164:165]
	v_readfirstlane_b32 s15, v133
	s_add_u32 s18, s18, s24
	s_mov_b32 m0, s15
	s_addc_u32 s19, s19, 0
	v_readfirstlane_b32 s15, v132
	ds_read_b128 v[138:141], v134
	ds_read_b128 v[142:145], v134 offset:1024
	ds_read_b128 v[146:149], v134 offset:2048
	ds_read_b128 v[150:153], v134 offset:3072
	ds_read_b128 v[154:157], v187
	ds_read_b128 v[158:161], v187 offset:1024
	ds_read_b128 v[188:191], v186
	ds_read_b128 v[192:195], v186 offset:1024
	ds_read_b128 v[196:199], v185
	ds_read_b128 v[200:203], v185 offset:1024
	ds_read_b128 v[204:207], v184
	ds_read_b128 v[208:211], v184 offset:1024
	global_load_lds_dwordx4 v[128:129], off
	v_lshl_add_u64 v[128:129], s[18:19], 0, v[164:165]
	s_mov_b32 m0, s15
	s_nop 0
	global_load_lds_dwordx4 v[128:129], off
	s_waitcnt vmcnt(10)
	s_barrier
	s_waitcnt lgkmcnt(0)
	s_setprio 1
	s_waitcnt lgkmcnt(0)
	v_mfma_f32_16x16x32_bf16 v[124:127], v[138:141], v[154:157], v[124:127]
	v_mfma_f32_16x16x32_bf16 v[120:123], v[146:149], v[154:157], v[120:123]
	v_mfma_f32_16x16x32_bf16 v[116:119], v[138:141], v[188:191], v[116:119]
	v_mfma_f32_16x16x32_bf16 v[112:115], v[146:149], v[188:191], v[112:115]
	v_mfma_f32_16x16x32_bf16 v[108:111], v[138:141], v[196:199], v[108:111]
	v_mfma_f32_16x16x32_bf16 v[104:107], v[146:149], v[196:199], v[104:107]
	v_mfma_f32_16x16x32_bf16 v[100:103], v[138:141], v[204:207], v[100:103]
	v_mfma_f32_16x16x32_bf16 v[96:99], v[146:149], v[204:207], v[96:99]
	v_mfma_f32_16x16x32_bf16 v[124:127], v[142:145], v[158:161], v[124:127]
	v_mfma_f32_16x16x32_bf16 v[120:123], v[150:153], v[158:161], v[120:123]
	v_mfma_f32_16x16x32_bf16 v[116:119], v[142:145], v[192:195], v[116:119]
	v_mfma_f32_16x16x32_bf16 v[112:115], v[150:153], v[192:195], v[112:115]
	v_mfma_f32_16x16x32_bf16 v[108:111], v[142:145], v[200:203], v[108:111]
	v_mfma_f32_16x16x32_bf16 v[104:107], v[150:153], v[200:203], v[104:107]
	v_mfma_f32_16x16x32_bf16 v[100:103], v[142:145], v[208:211], v[100:103]
	v_mfma_f32_16x16x32_bf16 v[96:99], v[150:153], v[208:211], v[96:99]
	s_setprio 0
	s_barrier
	ds_read_b128 v[132:135], v131
	ds_read_b128 v[212:215], v131 offset:1024
	ds_read_b128 v[216:219], v131 offset:2048
	ds_read_b128 v[220:223], v131 offset:3072
	s_barrier
	s_waitcnt lgkmcnt(0)
	s_setprio 1
	s_waitcnt lgkmcnt(0)
	v_mfma_f32_16x16x32_bf16 v[92:95], v[132:135], v[154:157], v[92:95]
	v_mfma_f32_16x16x32_bf16 v[88:91], v[216:219], v[154:157], v[88:91]
	v_mfma_f32_16x16x32_bf16 v[84:87], v[132:135], v[188:191], v[84:87]
	v_mfma_f32_16x16x32_bf16 v[80:83], v[216:219], v[188:191], v[80:83]
	v_mfma_f32_16x16x32_bf16 v[76:79], v[132:135], v[196:199], v[76:79]
	v_mfma_f32_16x16x32_bf16 v[72:75], v[216:219], v[196:199], v[72:75]
	v_mfma_f32_16x16x32_bf16 v[68:71], v[132:135], v[204:207], v[68:71]
	v_mfma_f32_16x16x32_bf16 v[64:67], v[216:219], v[204:207], v[64:67]
	v_mfma_f32_16x16x32_bf16 v[154:157], v[212:215], v[158:161], v[92:95]
	v_mfma_f32_16x16x32_bf16 v[158:161], v[220:223], v[158:161], v[88:91]
	v_mfma_f32_16x16x32_bf16 v[188:191], v[212:215], v[192:195], v[84:87]
	v_mfma_f32_16x16x32_bf16 v[192:195], v[220:223], v[192:195], v[80:83]
	v_mfma_f32_16x16x32_bf16 v[196:199], v[212:215], v[200:203], v[76:79]
	v_mfma_f32_16x16x32_bf16 v[200:203], v[220:223], v[200:203], v[72:75]
	v_mfma_f32_16x16x32_bf16 v[204:207], v[212:215], v[208:211], v[68:71]
	v_mfma_f32_16x16x32_bf16 v[208:211], v[220:223], v[208:211], v[64:67]
	s_setprio 0
	s_barrier
	s_nop 0
	ds_read_b128 v[64:67], v187 offset:16384
	ds_read_b128 v[68:71], v187 offset:17408
	ds_read_b128 v[72:75], v186 offset:16384
	ds_read_b128 v[76:79], v186 offset:17408
	ds_read_b128 v[80:83], v185 offset:16384
	ds_read_b128 v[84:87], v185 offset:17408
	ds_read_b128 v[88:91], v184 offset:16384
	ds_read_b128 v[92:95], v184 offset:17408
	s_waitcnt vmcnt(4)
	s_barrier
	s_waitcnt lgkmcnt(0)
	s_setprio 1
	s_waitcnt lgkmcnt(0)
	v_mfma_f32_16x16x32_bf16 v[60:63], v[138:141], v[64:67], v[60:63]
	v_mfma_f32_16x16x32_bf16 v[56:59], v[146:149], v[64:67], v[56:59]
	v_mfma_f32_16x16x32_bf16 v[52:55], v[138:141], v[72:75], v[52:55]
	v_mfma_f32_16x16x32_bf16 v[48:51], v[146:149], v[72:75], v[48:51]
	v_mfma_f32_16x16x32_bf16 v[224:227], v[138:141], v[80:83], v[44:47]
	v_mfma_f32_16x16x32_bf16 v[228:231], v[146:149], v[80:83], v[40:43]
	v_mfma_f32_16x16x32_bf16 v[138:141], v[138:141], v[88:91], v[36:39]
	v_mfma_f32_16x16x32_bf16 v[146:149], v[146:149], v[88:91], v[32:35]
	v_mfma_f32_16x16x32_bf16 v[32:35], v[142:145], v[68:71], v[60:63]
	v_mfma_f32_16x16x32_bf16 v[36:39], v[150:153], v[68:71], v[56:59]
	v_mfma_f32_16x16x32_bf16 v[40:43], v[142:145], v[76:79], v[52:55]
	v_mfma_f32_16x16x32_bf16 v[44:47], v[150:153], v[76:79], v[48:51]
	v_mfma_f32_16x16x32_bf16 v[48:51], v[142:145], v[84:87], v[224:227]
	v_mfma_f32_16x16x32_bf16 v[52:55], v[150:153], v[84:87], v[228:231]
	v_mfma_f32_16x16x32_bf16 v[56:59], v[142:145], v[92:95], v[138:141]
	v_mfma_f32_16x16x32_bf16 v[60:63], v[150:153], v[92:95], v[146:149]
	s_setprio 0
	s_setprio 1
	v_mfma_f32_16x16x32_bf16 v[28:31], v[132:135], v[64:67], v[28:31]
	v_mfma_f32_16x16x32_bf16 v[24:27], v[216:219], v[64:67], v[24:27]
	v_mfma_f32_16x16x32_bf16 v[20:23], v[132:135], v[72:75], v[20:23]
	v_mfma_f32_16x16x32_bf16 v[16:19], v[216:219], v[72:75], v[16:19]
	v_mfma_f32_16x16x32_bf16 v[64:67], v[132:135], v[80:83], v[12:15]
	v_mfma_f32_16x16x32_bf16 v[8:11], v[216:219], v[80:83], v[8:11]
	v_mfma_f32_16x16x32_bf16 v[72:75], v[132:135], v[88:91], v[4:7]
	v_mfma_f32_16x16x32_bf16 v[0:3], v[216:219], v[88:91], v[0:3]
	v_mfma_f32_16x16x32_bf16 v[4:7], v[212:215], v[68:71], v[28:31]
	v_mfma_f32_16x16x32_bf16 v[12:15], v[220:223], v[68:71], v[24:27]
	v_mfma_f32_16x16x32_bf16 v[20:23], v[212:215], v[76:79], v[20:23]
	v_mfma_f32_16x16x32_bf16 v[28:31], v[220:223], v[76:79], v[16:19]
	v_mfma_f32_16x16x32_bf16 v[64:67], v[212:215], v[84:87], v[64:67]
	v_mfma_f32_16x16x32_bf16 v[68:71], v[220:223], v[84:87], v[8:11]
	v_mfma_f32_16x16x32_bf16 v[72:75], v[212:215], v[92:95], v[72:75]
	v_mfma_f32_16x16x32_bf16 v[76:79], v[220:223], v[92:95], v[0:3]
	s_setprio 0
	s_barrier
	ds_read_b128 v[8:11], v130
	ds_read_b128 v[0:3], v130 offset:1024
	ds_read_b128 v[16:19], v130 offset:2048
	ds_read_b128 v[80:83], v130 offset:3072
	ds_read_b128 v[138:141], v187 offset:32768
	ds_read_b128 v[212:215], v187 offset:33792
	ds_read_b128 v[216:219], v186 offset:32768
	ds_read_b128 v[220:223], v186 offset:33792
	ds_read_b128 v[224:227], v185 offset:32768
	ds_read_b128 v[228:231], v185 offset:33792
	ds_read_b128 v[232:235], v184 offset:32768
	ds_read_b128 v[236:239], v184 offset:33792
	s_waitcnt vmcnt(2)
	s_barrier
	s_waitcnt lgkmcnt(0)
	s_setprio 1
	s_waitcnt lgkmcnt(0)
	v_mfma_f32_16x16x32_bf16 v[24:27], v[8:11], v[138:141], v[124:127]
	v_mfma_f32_16x16x32_bf16 v[84:87], v[16:19], v[138:141], v[120:123]
	v_mfma_f32_16x16x32_bf16 v[88:91], v[8:11], v[216:219], v[116:119]
	v_mfma_f32_16x16x32_bf16 v[92:95], v[16:19], v[216:219], v[112:115]
	v_mfma_f32_16x16x32_bf16 v[108:111], v[8:11], v[224:227], v[108:111]
	v_mfma_f32_16x16x32_bf16 v[104:107], v[16:19], v[224:227], v[104:107]
	v_mfma_f32_16x16x32_bf16 v[100:103], v[8:11], v[232:235], v[100:103]
	v_mfma_f32_16x16x32_bf16 v[96:99], v[16:19], v[232:235], v[96:99]
	v_mfma_f32_16x16x32_bf16 v[148:151], v[0:3], v[212:215], v[24:27]
	v_mfma_f32_16x16x32_bf16 v[144:147], v[80:83], v[212:215], v[84:87]
	v_mfma_f32_16x16x32_bf16 v[132:135], v[0:3], v[220:223], v[88:91]
	v_mfma_f32_16x16x32_bf16 v[128:131], v[80:83], v[220:223], v[92:95]
	v_mfma_f32_16x16x32_bf16 v[116:119], v[0:3], v[228:231], v[108:111]
	v_mfma_f32_16x16x32_bf16 v[112:115], v[80:83], v[228:231], v[104:107]
	v_mfma_f32_16x16x32_bf16 v[100:103], v[0:3], v[236:239], v[100:103]
	v_mfma_f32_16x16x32_bf16 v[24:27], v[80:83], v[236:239], v[96:99]
	s_setprio 0
	s_barrier
	ds_read_b128 v[92:95], v136
	ds_read_b128 v[84:87], v136 offset:1024
	ds_read_b128 v[96:99], v136 offset:2048
	ds_read_b128 v[88:91], v136 offset:3072
	s_waitcnt vmcnt(0)
	s_barrier
	s_waitcnt lgkmcnt(0)
	s_setprio 1
	s_waitcnt lgkmcnt(0)
	v_mfma_f32_16x16x32_bf16 v[104:107], v[92:95], v[138:141], v[154:157]
	v_mfma_f32_16x16x32_bf16 v[108:111], v[96:99], v[138:141], v[158:161]
	v_mfma_f32_16x16x32_bf16 v[120:123], v[92:95], v[216:219], v[188:191]
	v_mfma_f32_16x16x32_bf16 v[124:127], v[96:99], v[216:219], v[192:195]
	v_mfma_f32_16x16x32_bf16 v[160:163], v[92:95], v[224:227], v[196:199]
	v_mfma_f32_16x16x32_bf16 v[188:191], v[96:99], v[224:227], v[200:203]
	v_mfma_f32_16x16x32_bf16 v[192:195], v[92:95], v[232:235], v[204:207]
	v_mfma_f32_16x16x32_bf16 v[196:199], v[96:99], v[232:235], v[208:211]
	v_mfma_f32_16x16x32_bf16 v[156:159], v[84:87], v[212:215], v[104:107]
	v_mfma_f32_16x16x32_bf16 v[152:155], v[88:91], v[212:215], v[108:111]
	v_mfma_f32_16x16x32_bf16 v[140:143], v[84:87], v[220:223], v[120:123]
	v_mfma_f32_16x16x32_bf16 v[136:139], v[88:91], v[220:223], v[124:127]
	v_mfma_f32_16x16x32_bf16 v[124:127], v[84:87], v[228:231], v[160:163]
	v_mfma_f32_16x16x32_bf16 v[120:123], v[88:91], v[228:231], v[188:191]
	v_mfma_f32_16x16x32_bf16 v[108:111], v[84:87], v[236:239], v[192:195]
	v_mfma_f32_16x16x32_bf16 v[104:107], v[88:91], v[236:239], v[196:199]
	s_setprio 0
	s_barrier
	v_mbcnt_lo_u32_b32 v164, -1, 0
	v_mbcnt_hi_u32_b32 v164, -1, v164
	s_cmp_lt_i32 s64, 3
	v_add_u32_e32 v160, s34, v164
	v_ashrrev_i32_e32 v192, 6, v160
	v_bfe_u32 v190, v160, 8, 1
	v_and_b32_e32 v191, 3, v192
	v_and_b32_e32 v188, 15, v164
	v_bfe_u32 v189, v160, 4, 2
	s_mov_b64 s[18:19], 0
	s_cbranch_scc1 .LBB0_362
	v_lshrrev_b32_e32 v160, 4, v160
	v_lshlrev_b32_e32 v162, 9, v189
	v_lshlrev_b32_e32 v163, 9, v160
	s_mov_b64 s[20:21], -1
	s_cmp_gt_i32 s64, 3
	v_lshlrev_b32_e32 v161, 4, v188
	v_and_b32_e32 v160, 0x400, v162
	v_and_b32_e32 v162, 0x200, v163
	s_cbranch_scc0 .LBB0_360
	s_lshl_b32 s15, s66, 20
	s_lshl_b32 s20, s66, 16
	s_and_b32 s15, s15, 0xff000000
	s_and_b32 s20, s20, 0xf0000
	s_lshl_b32 s17, s68, 21
	s_or_b32 s15, s20, s15
	v_lshlrev_b32_e32 v163, 14, v191
	s_add_i32 s15, s15, s17
	v_lshlrev_b32_e32 v166, 12, v190
	v_or3_b32 v163, s15, v161, v163
	v_or3_b32 v163, v163, v166, v162
	v_add_u32_e32 v166, v163, v160
	s_mov_b64 s[20:21], 0

.LBB0_464:
	v_bfe_i32 v5, v136, 27, 1
	v_lshlrev_b32_e32 v135, 4, v136
	v_lshrrev_b32_e32 v5, 22, v5
	v_add_u32_e32 v5, v135, v5
	v_and_b32_e32 v5, 0xfffffc00, v5
	v_sub_u32_e32 v5, v135, v5
	v_lshrrev_b32_e32 v6, 4, v5
	v_bitop3_b32 v5, v6, v5, 32 bitop3:0x6c
	v_ashrrev_i32_e32 v6, 31, v5
	v_lshrrev_b32_e32 v6, 26, v6
	v_add_u32_e32 v6, v5, v6
	v_ashrrev_i32_e32 v157, 6, v6
	v_and_b32_e32 v6, 0xc0, v6
	v_sub_u32_e32 v5, v5, v6
	v_ashrrev_i16_sdwa v5, v134, sext(v5) dst_sel:DWORD dst_unused:UNUSED_PAD src0_sel:DWORD src1_sel:BYTE_0
	v_and_b32_e32 v2, 15, v0
	v_and_b32_e32 v3, 48, v0
	v_bfe_i32 v158, v5, 0, 16
	v_and_b32_e32 v5, 32, v0
	v_lshlrev_b32_e32 v8, 2, v0
	v_lshlrev_b32_e32 v0, 6, v0
	s_movk_i32 s36, 0x3f0
	v_lshlrev_b32_e32 v2, 6, v2
	v_and_b32_e32 v8, 32, v8
	v_and_b32_e32 v0, 0x3c0, v0
	v_ashrrev_i32_e32 v4, 31, v136
	v_bitop3_b32 v5, v135, v5, s36 bitop3:0x6c
	v_or_b32_e32 v7, v2, v3
	v_bitop3_b32 v2, v2, v8, v3 bitop3:0x36
	v_bitop3_b32 v3, v0, v8, v3 bitop3:0x36
	v_lshlrev_b32_e32 v0, 11, v136
	v_lshrrev_b32_e32 v4, 26, v4
	v_and_or_b32 v0, v0, s78, v5
	v_lshlrev_b32_e32 v5, 3, v136
	s_bfe_u32 s66, s86, 0x30003
	v_add_u32_e32 v4, v136, v4
	s_mov_b32 s36, 0x14000
	v_and_b32_e32 v5, 0xfffffc00, v5
	s_lshl_b32 s24, s66, 14
	v_ashrrev_i32_e32 v156, 6, v4
	v_bitop3_b32 v10, v7, s36, v8 bitop3:0xde
	s_mov_b32 s36, 0x1c000
	v_add_u32_e32 v128, v0, v5
	v_bitop3_b32 v9, v7, s76, v8 bitop3:0xde
	v_bitop3_b32 v11, v7, s77, v8 bitop3:0xde
	v_bitop3_b32 v7, v7, s36, v8 bitop3:0xde
	v_lshl_add_u64 v[130:131], s[24:25], 0, v[128:129]
	v_lshlrev_b32_e32 v0, 15, v156
	s_lshl_b32 s24, s86, 17
	s_and_b32 s36, s86, 7
	v_and_b32_e32 v0, 0xffff0000, v0
	s_and_b32 s24, s24, 0x1800000
	s_lshl_b32 s36, s36, 20
	v_lshl_add_u32 v0, v157, 12, v0
	s_or_b32 s24, s24, s36
	v_lshlrev_b32_e32 v6, 6, v136
	v_lshlrev_b32_e32 v1, 13, v1
	v_and_or_b32 v0, v4, 64, v0
	s_add_u32 s68, s24, s90
	v_and_b32_e32 v6, 0x3000, v6
	v_or_b32_e32 v8, 0x800, v1
	v_or_b32_e32 v12, 0x1000, v1
	v_or_b32_e32 v13, 0x1800, v1
	v_lshl_add_u32 v128, v158, 1, v0
	s_addc_u32 s69, 0, 0
	v_mov_b32_e32 v0, 0
	v_lshl_add_u64 v[132:133], s[68:69], 0, v[128:129]
	s_mov_b32 s24, -2
	v_add_u32_e32 v162, v9, v6
	v_add_u32_e32 v153, v2, v1
	v_add_u32_e32 v152, v3, v8
	v_add_u32_e32 v151, v3, v12
	v_add_u32_e32 v150, v3, v13
	v_add_u32_e32 v161, 0xc000, v135
	v_add_u32_e32 v160, 0xe000, v135
	v_add_u32_e32 v159, v10, v6
	v_add_u32_e32 v149, 0x10000, v135
	v_add_u32_e32 v148, 0x12000, v135
	v_add_u32_e32 v147, 0x2000, v135
	v_add_u32_e32 v146, 0x14000, v135
	v_add_u32_e32 v145, 0x16000, v135
	v_add_u32_e32 v155, v11, v6
	v_add_u32_e32 v144, 0x4000, v135
	v_add_u32_e32 v143, 0x6000, v135
	v_add_u32_e32 v154, v7, v6
	v_add_u32_e32 v142, 0x18000, v135
	v_add_u32_e32 v141, 0x1a000, v135
	v_add_u32_e32 v140, 0x8000, v135
	v_add_u32_e32 v139, 0xa000, v135
	v_add_u32_e32 v138, 0x1c000, v135
	v_add_u32_e32 v137, 0x1e000, v135
	v_mov_b32_e32 v1, v0
	v_mov_b32_e32 v2, v0
	v_mov_b32_e32 v3, v0
	v_mov_b32_e32 v4, v0
	v_mov_b32_e32 v5, v0
	v_mov_b32_e32 v6, v0
	v_mov_b32_e32 v7, v0
	v_mov_b32_e32 v8, v0
	v_mov_b32_e32 v9, v0
	v_mov_b32_e32 v10, v0
	v_mov_b32_e32 v11, v0
	v_mov_b32_e32 v12, v0
	v_mov_b32_e32 v13, v0
	v_mov_b32_e32 v14, v0
	v_mov_b32_e32 v15, v0
	v_mov_b32_e32 v16, v0
	v_mov_b32_e32 v17, v0
	v_mov_b32_e32 v18, v0
	v_mov_b32_e32 v19, v0
	v_mov_b32_e32 v20, v0
	v_mov_b32_e32 v21, v0
	v_mov_b32_e32 v22, v0
	v_mov_b32_e32 v23, v0
	v_mov_b32_e32 v24, v0
	v_mov_b32_e32 v25, v0
	v_mov_b32_e32 v26, v0
	v_mov_b32_e32 v27, v0
	v_mov_b32_e32 v28, v0
	v_mov_b32_e32 v29, v0
	v_mov_b32_e32 v30, v0
	v_mov_b32_e32 v31, v0
	v_mov_b32_e32 v32, v0
	v_mov_b32_e32 v33, v0
	v_mov_b32_e32 v34, v0
	v_mov_b32_e32 v35, v0
	v_mov_b32_e32 v36, v0
	v_mov_b32_e32 v37, v0
	v_mov_b32_e32 v38, v0
	v_mov_b32_e32 v39, v0
	v_mov_b32_e32 v40, v0
	v_mov_b32_e32 v41, v0
	v_mov_b32_e32 v42, v0
	v_mov_b32_e32 v43, v0
	v_mov_b32_e32 v44, v0
	v_mov_b32_e32 v45, v0
	v_mov_b32_e32 v46, v0
	v_mov_b32_e32 v47, v0
	v_mov_b32_e32 v48, v0
	v_mov_b32_e32 v49, v0
	v_mov_b32_e32 v50, v0
	v_mov_b32_e32 v51, v0
	v_mov_b32_e32 v52, v0
	v_mov_b32_e32 v53, v0
	v_mov_b32_e32 v54, v0
	v_mov_b32_e32 v55, v0
	v_mov_b32_e32 v56, v0
	v_mov_b32_e32 v57, v0
	v_mov_b32_e32 v58, v0
	v_mov_b32_e32 v59, v0
	v_mov_b32_e32 v60, v0
	v_mov_b32_e32 v61, v0
	v_mov_b32_e32 v62, v0
	v_mov_b32_e32 v63, v0
	v_mov_b32_e32 v64, v0
	v_mov_b32_e32 v65, v0
	v_mov_b32_e32 v66, v0
	v_mov_b32_e32 v67, v0
	v_mov_b32_e32 v68, v0
	v_mov_b32_e32 v69, v0
	v_mov_b32_e32 v70, v0
	v_mov_b32_e32 v71, v0
	v_mov_b32_e32 v72, v0
	v_mov_b32_e32 v73, v0
	v_mov_b32_e32 v74, v0
	v_mov_b32_e32 v75, v0
	v_mov_b32_e32 v76, v0
	v_mov_b32_e32 v77, v0
	v_mov_b32_e32 v78, v0
	v_mov_b32_e32 v79, v0
	v_mov_b32_e32 v80, v0
	v_mov_b32_e32 v81, v0
	v_mov_b32_e32 v82, v0
	v_mov_b32_e32 v83, v0
	v_mov_b32_e32 v84, v0
	v_mov_b32_e32 v85, v0
	v_mov_b32_e32 v86, v0
	v_mov_b32_e32 v87, v0
	v_mov_b32_e32 v88, v0
	v_mov_b32_e32 v89, v0
	v_mov_b32_e32 v90, v0
	v_mov_b32_e32 v91, v0
	v_mov_b32_e32 v92, v0
	v_mov_b32_e32 v93, v0
	v_mov_b32_e32 v94, v0
	v_mov_b32_e32 v95, v0
	v_mov_b32_e32 v96, v0
	v_mov_b32_e32 v97, v0
	v_mov_b32_e32 v98, v0
	v_mov_b32_e32 v99, v0
	v_mov_b32_e32 v100, v0
	v_mov_b32_e32 v101, v0
	v_mov_b32_e32 v102, v0
	v_mov_b32_e32 v103, v0
	v_mov_b32_e32 v104, v0
	v_mov_b32_e32 v105, v0
	v_mov_b32_e32 v106, v0
	v_mov_b32_e32 v107, v0
	v_mov_b32_e32 v108, v0
	v_mov_b32_e32 v109, v0
	v_mov_b32_e32 v110, v0
	v_mov_b32_e32 v111, v0
	v_mov_b32_e32 v112, v0
	v_mov_b32_e32 v113, v0
	v_mov_b32_e32 v114, v0
	v_mov_b32_e32 v115, v0
	v_mov_b32_e32 v116, v0
	v_mov_b32_e32 v117, v0
	v_mov_b32_e32 v118, v0
	v_mov_b32_e32 v119, v0
	v_mov_b32_e32 v120, v0
	v_mov_b32_e32 v121, v0
	v_mov_b32_e32 v122, v0
	v_mov_b32_e32 v123, v0
	v_mov_b32_e32 v124, v0
	v_mov_b32_e32 v125, v0
	v_mov_b32_e32 v126, v0
	v_mov_b32_e32 v127, v0
	s_barrier
	v_lshl_add_u64 v[228:229], s[50:51], 0, v[132:133]
	s_mov_b64 s[68:69], 0xe080080
	v_readfirstlane_b32 s36, v161
	v_lshl_add_u64 v[166:167], v[228:229], 0, s[68:69]
	s_mov_b32 m0, s36
	s_mov_b64 s[68:69], 0xe0c0080
	v_readfirstlane_b32 s36, v160
	global_load_lds_dwordx4 v[166:167], off
	v_lshl_add_u64 v[166:167], v[228:229], 0, s[68:69]
	s_mov_b32 m0, s36
	s_nop 0
	global_load_lds_dwordx4 v[166:167], off
	ds_read_b128 v[164:167], v162
	ds_read_b128 v[168:171], v162 offset:1024
	ds_read_b128 v[172:175], v162 offset:2048
	ds_read_b128 v[176:179], v162 offset:3072
	ds_read_b128 v[180:183], v153
	ds_read_b128 v[184:187], v153 offset:1024
	ds_read_b128 v[188:191], v152
	ds_read_b128 v[192:195], v152 offset:1024
	ds_read_b128 v[196:199], v151
	ds_read_b128 v[200:203], v151 offset:1024
	ds_read_b128 v[204:207], v150
	ds_read_b128 v[208:211], v150 offset:1024
	s_waitcnt lgkmcnt(8)
	s_barrier
	s_branch .Lkent_465

.Lkent_465:
	s_waitcnt lgkmcnt(0)
	s_setprio 1
	s_waitcnt lgkmcnt(0)
	v_mfma_f32_16x16x32_bf16 v[124:127], v[164:167], v[180:183], v[124:127]
	v_mfma_f32_16x16x32_bf16 v[120:123], v[172:175], v[180:183], v[120:123]
	v_mfma_f32_16x16x32_bf16 v[116:119], v[164:167], v[188:191], v[116:119]
	v_mfma_f32_16x16x32_bf16 v[112:115], v[172:175], v[188:191], v[112:115]
	v_mfma_f32_16x16x32_bf16 v[108:111], v[164:167], v[196:199], v[108:111]
	v_mfma_f32_16x16x32_bf16 v[104:107], v[172:175], v[196:199], v[104:107]
	v_mfma_f32_16x16x32_bf16 v[100:103], v[164:167], v[204:207], v[100:103]
	v_mfma_f32_16x16x32_bf16 v[96:99], v[172:175], v[204:207], v[96:99]
	v_mfma_f32_16x16x32_bf16 v[124:127], v[168:171], v[184:187], v[124:127]
	v_mfma_f32_16x16x32_bf16 v[120:123], v[176:179], v[184:187], v[120:123]
	v_mfma_f32_16x16x32_bf16 v[116:119], v[168:171], v[192:195], v[116:119]
	v_mfma_f32_16x16x32_bf16 v[112:115], v[176:179], v[192:195], v[112:115]
	v_mfma_f32_16x16x32_bf16 v[108:111], v[168:171], v[200:203], v[108:111]
	v_mfma_f32_16x16x32_bf16 v[104:107], v[176:179], v[200:203], v[104:107]
	v_mfma_f32_16x16x32_bf16 v[100:103], v[168:171], v[208:211], v[100:103]
	v_mfma_f32_16x16x32_bf16 v[96:99], v[176:179], v[208:211], v[96:99]
	s_setprio 0
	s_barrier
	v_lshl_add_u64 v[230:231], s[50:51], 0, v[130:131]
	s_mov_b64 s[68:69], 0x3880000
	v_readfirstlane_b32 s36, v149
	v_lshl_add_u64 v[232:233], v[230:231], 0, s[68:69]
	s_mov_b32 m0, s36
	s_mov_b64 s[68:69], 0x3881000
	v_readfirstlane_b32 s36, v148
	ds_read_b128 v[212:215], v159
	ds_read_b128 v[216:219], v159 offset:1024
	ds_read_b128 v[220:223], v159 offset:2048
	ds_read_b128 v[224:227], v159 offset:3072
	global_load_lds_dwordx4 v[232:233], off
	v_lshl_add_u64 v[232:233], v[230:231], 0, s[68:69]
	s_mov_b32 m0, s36
	s_nop 0
	global_load_lds_dwordx4 v[232:233], off
	s_mov_b64 s[68:69], 0xe000100
	v_readfirstlane_b32 s36, v135
	v_lshl_add_u64 v[232:233], v[228:229], 0, s[68:69]
	s_mov_b32 m0, s36
	s_mov_b64 s[68:69], 0xe040100
	v_readfirstlane_b32 s36, v147
	global_load_lds_dwordx4 v[232:233], off
	v_lshl_add_u64 v[232:233], v[228:229], 0, s[68:69]
	s_mov_b32 m0, s36
	s_nop 0
	global_load_lds_dwordx4 v[232:233], off
	s_waitcnt vmcnt(12)
	s_barrier
	s_waitcnt lgkmcnt(0)
	s_setprio 1
	s_waitcnt lgkmcnt(0)
	v_mfma_f32_16x16x32_bf16 v[92:95], v[212:215], v[180:183], v[92:95]
	v_mfma_f32_16x16x32_bf16 v[88:91], v[220:223], v[180:183], v[88:91]
	v_mfma_f32_16x16x32_bf16 v[84:87], v[212:215], v[188:191], v[84:87]
	v_mfma_f32_16x16x32_bf16 v[80:83], v[220:223], v[188:191], v[80:83]
	v_mfma_f32_16x16x32_bf16 v[76:79], v[212:215], v[196:199], v[76:79]
	v_mfma_f32_16x16x32_bf16 v[72:75], v[220:223], v[196:199], v[72:75]
	v_mfma_f32_16x16x32_bf16 v[68:71], v[212:215], v[204:207], v[68:71]
	v_mfma_f32_16x16x32_bf16 v[64:67], v[220:223], v[204:207], v[64:67]
	v_mfma_f32_16x16x32_bf16 v[92:95], v[216:219], v[184:187], v[92:95]
	v_mfma_f32_16x16x32_bf16 v[88:91], v[224:227], v[184:187], v[88:91]
	v_mfma_f32_16x16x32_bf16 v[84:87], v[216:219], v[192:195], v[84:87]
	v_mfma_f32_16x16x32_bf16 v[80:83], v[224:227], v[192:195], v[80:83]
	v_mfma_f32_16x16x32_bf16 v[76:79], v[216:219], v[200:203], v[76:79]
	v_mfma_f32_16x16x32_bf16 v[72:75], v[224:227], v[200:203], v[72:75]
	v_mfma_f32_16x16x32_bf16 v[68:71], v[216:219], v[208:211], v[68:71]
	v_mfma_f32_16x16x32_bf16 v[64:67], v[224:227], v[208:211], v[64:67]
	s_setprio 0
	s_barrier
	ds_read_b128 v[180:183], v153 offset:16384
	ds_read_b128 v[184:187], v153 offset:17408
	ds_read_b128 v[188:191], v152 offset:16384
	ds_read_b128 v[192:195], v152 offset:17408
	ds_read_b128 v[196:199], v151 offset:16384
	ds_read_b128 v[200:203], v151 offset:17408
	ds_read_b128 v[204:207], v150 offset:16384
	ds_read_b128 v[208:211], v150 offset:17408
	s_mov_b64 s[68:69], 0x3882000
	v_readfirstlane_b32 s36, v146
	v_lshl_add_u64 v[232:233], v[230:231], 0, s[68:69]
	s_mov_b32 m0, s36
	s_mov_b64 s[68:69], 0x3883000
	v_readfirstlane_b32 s36, v145
	global_load_lds_dwordx4 v[232:233], off
	v_lshl_add_u64 v[232:233], v[230:231], 0, s[68:69]
	s_mov_b32 m0, s36
	s_nop 0
	global_load_lds_dwordx4 v[232:233], off
	s_barrier
	s_waitcnt lgkmcnt(0)
	s_setprio 1
	s_waitcnt lgkmcnt(0)
	v_mfma_f32_16x16x32_bf16 v[60:63], v[164:167], v[180:183], v[60:63]
	v_mfma_f32_16x16x32_bf16 v[56:59], v[172:175], v[180:183], v[56:59]
	v_mfma_f32_16x16x32_bf16 v[52:55], v[164:167], v[188:191], v[52:55]
	v_mfma_f32_16x16x32_bf16 v[48:51], v[172:175], v[188:191], v[48:51]
	v_mfma_f32_16x16x32_bf16 v[44:47], v[164:167], v[196:199], v[44:47]
	v_mfma_f32_16x16x32_bf16 v[40:43], v[172:175], v[196:199], v[40:43]
	v_mfma_f32_16x16x32_bf16 v[36:39], v[164:167], v[204:207], v[36:39]
	v_mfma_f32_16x16x32_bf16 v[32:35], v[172:175], v[204:207], v[32:35]
	v_mfma_f32_16x16x32_bf16 v[60:63], v[168:171], v[184:187], v[60:63]
	v_mfma_f32_16x16x32_bf16 v[56:59], v[176:179], v[184:187], v[56:59]
	v_mfma_f32_16x16x32_bf16 v[52:55], v[168:171], v[192:195], v[52:55]
	v_mfma_f32_16x16x32_bf16 v[48:51], v[176:179], v[192:195], v[48:51]
	v_mfma_f32_16x16x32_bf16 v[44:47], v[168:171], v[200:203], v[44:47]
	v_mfma_f32_16x16x32_bf16 v[40:43], v[176:179], v[200:203], v[40:43]
	v_mfma_f32_16x16x32_bf16 v[36:39], v[168:171], v[208:211], v[36:39]
	v_mfma_f32_16x16x32_bf16 v[32:35], v[176:179], v[208:211], v[32:35]
	s_setprio 0
	s_barrier
	v_readfirstlane_b32 s36, v144
	v_lshl_add_u64 v[166:167], v[228:229], 0, s[26:27]
	s_mov_b32 m0, s36
	v_readfirstlane_b32 s36, v143
	global_load_lds_dwordx4 v[166:167], off
	v_lshl_add_u64 v[166:167], v[228:229], 0, s[28:29]
	s_mov_b32 m0, s36
	s_nop 0
	global_load_lds_dwordx4 v[166:167], off
	s_waitcnt vmcnt(12)
	s_barrier
	s_setprio 1
	v_mfma_f32_16x16x32_bf16 v[28:31], v[212:215], v[180:183], v[28:31]
	v_mfma_f32_16x16x32_bf16 v[24:27], v[220:223], v[180:183], v[24:27]
	v_mfma_f32_16x16x32_bf16 v[20:23], v[212:215], v[188:191], v[20:23]
	v_mfma_f32_16x16x32_bf16 v[16:19], v[220:223], v[188:191], v[16:19]
	v_mfma_f32_16x16x32_bf16 v[12:15], v[212:215], v[196:199], v[12:15]
	v_mfma_f32_16x16x32_bf16 v[8:11], v[220:223], v[196:199], v[8:11]
	v_mfma_f32_16x16x32_bf16 v[4:7], v[212:215], v[204:207], v[4:7]
	v_mfma_f32_16x16x32_bf16 v[0:3], v[220:223], v[204:207], v[0:3]
	v_mfma_f32_16x16x32_bf16 v[28:31], v[216:219], v[184:187], v[28:31]
	v_mfma_f32_16x16x32_bf16 v[24:27], v[224:227], v[184:187], v[24:27]
	v_mfma_f32_16x16x32_bf16 v[20:23], v[216:219], v[192:195], v[20:23]
	v_mfma_f32_16x16x32_bf16 v[16:19], v[224:227], v[192:195], v[16:19]
	v_mfma_f32_16x16x32_bf16 v[12:15], v[216:219], v[200:203], v[12:15]
	v_mfma_f32_16x16x32_bf16 v[8:11], v[224:227], v[200:203], v[8:11]
	v_mfma_f32_16x16x32_bf16 v[4:7], v[216:219], v[208:211], v[4:7]
	v_mfma_f32_16x16x32_bf16 v[0:3], v[224:227], v[208:211], v[0:3]
	s_setprio 0
	s_barrier
	ds_read_b128 v[164:167], v155
	ds_read_b128 v[168:171], v155 offset:1024
	ds_read_b128 v[172:175], v155 offset:2048
	ds_read_b128 v[176:179], v155 offset:3072
	ds_read_b128 v[180:183], v153 offset:32768
	ds_read_b128 v[184:187], v153 offset:33792
	ds_read_b128 v[188:191], v152 offset:32768
	ds_read_b128 v[192:195], v152 offset:33792
	ds_read_b128 v[196:199], v151 offset:32768
	ds_read_b128 v[200:203], v151 offset:33792
	ds_read_b128 v[204:207], v150 offset:32768
	ds_read_b128 v[208:211], v150 offset:33792
	s_waitcnt lgkmcnt(8)
	s_waitcnt vmcnt(10)
	s_barrier
	s_waitcnt lgkmcnt(0)
	s_setprio 1
	s_waitcnt lgkmcnt(0)
	v_mfma_f32_16x16x32_bf16 v[124:127], v[164:167], v[180:183], v[124:127]
	v_mfma_f32_16x16x32_bf16 v[120:123], v[172:175], v[180:183], v[120:123]
	v_mfma_f32_16x16x32_bf16 v[116:119], v[164:167], v[188:191], v[116:119]
	v_mfma_f32_16x16x32_bf16 v[112:115], v[172:175], v[188:191], v[112:115]
	v_mfma_f32_16x16x32_bf16 v[108:111], v[164:167], v[196:199], v[108:111]
	v_mfma_f32_16x16x32_bf16 v[104:107], v[172:175], v[196:199], v[104:107]
	v_mfma_f32_16x16x32_bf16 v[100:103], v[164:167], v[204:207], v[100:103]
	v_mfma_f32_16x16x32_bf16 v[96:99], v[172:175], v[204:207], v[96:99]
	v_mfma_f32_16x16x32_bf16 v[124:127], v[168:171], v[184:187], v[124:127]
	v_mfma_f32_16x16x32_bf16 v[120:123], v[176:179], v[184:187], v[120:123]
	v_mfma_f32_16x16x32_bf16 v[116:119], v[168:171], v[192:195], v[116:119]
	v_mfma_f32_16x16x32_bf16 v[112:115], v[176:179], v[192:195], v[112:115]
	v_mfma_f32_16x16x32_bf16 v[108:111], v[168:171], v[200:203], v[108:111]
	v_mfma_f32_16x16x32_bf16 v[104:107], v[176:179], v[200:203], v[104:107]
	v_mfma_f32_16x16x32_bf16 v[100:103], v[168:171], v[208:211], v[100:103]
	v_mfma_f32_16x16x32_bf16 v[96:99], v[176:179], v[208:211], v[96:99]
	s_setprio 0
	s_barrier
	v_readfirstlane_b32 s36, v142
	v_lshl_add_u64 v[232:233], v[230:231], 0, s[30:31]
	s_mov_b32 m0, s36
	v_readfirstlane_b32 s36, v141
	ds_read_b128 v[212:215], v154
	ds_read_b128 v[216:219], v154 offset:1024
	ds_read_b128 v[220:223], v154 offset:2048
	ds_read_b128 v[224:227], v154 offset:3072
	global_load_lds_dwordx4 v[232:233], off
	v_lshl_add_u64 v[232:233], v[230:231], 0, s[34:35]
	s_mov_b32 m0, s36
	s_nop 0
	global_load_lds_dwordx4 v[232:233], off
	v_readfirstlane_b32 s36, v140
	v_lshl_add_u64 v[232:233], v[228:229], 0, s[44:45]
	s_mov_b32 m0, s36
	v_readfirstlane_b32 s36, v139
	global_load_lds_dwordx4 v[232:233], off
	v_lshl_add_u64 v[228:229], v[228:229], 0, s[46:47]
	s_mov_b32 m0, s36
	s_nop 0
	global_load_lds_dwordx4 v[228:229], off
	s_waitcnt vmcnt(12)
	s_barrier
	s_waitcnt lgkmcnt(0)
	s_setprio 1
	s_waitcnt lgkmcnt(0)
	v_mfma_f32_16x16x32_bf16 v[92:95], v[212:215], v[180:183], v[92:95]
	v_mfma_f32_16x16x32_bf16 v[88:91], v[220:223], v[180:183], v[88:91]
	v_mfma_f32_16x16x32_bf16 v[84:87], v[212:215], v[188:191], v[84:87]
	v_mfma_f32_16x16x32_bf16 v[80:83], v[220:223], v[188:191], v[80:83]
	v_mfma_f32_16x16x32_bf16 v[76:79], v[212:215], v[196:199], v[76:79]
	v_mfma_f32_16x16x32_bf16 v[72:75], v[220:223], v[196:199], v[72:75]
	v_mfma_f32_16x16x32_bf16 v[68:71], v[212:215], v[204:207], v[68:71]
	v_mfma_f32_16x16x32_bf16 v[64:67], v[220:223], v[204:207], v[64:67]
	v_mfma_f32_16x16x32_bf16 v[92:95], v[216:219], v[184:187], v[92:95]
	v_mfma_f32_16x16x32_bf16 v[88:91], v[224:227], v[184:187], v[88:91]
	v_mfma_f32_16x16x32_bf16 v[84:87], v[216:219], v[192:195], v[84:87]
	v_mfma_f32_16x16x32_bf16 v[80:83], v[224:227], v[192:195], v[80:83]
	v_mfma_f32_16x16x32_bf16 v[76:79], v[216:219], v[200:203], v[76:79]
	v_mfma_f32_16x16x32_bf16 v[72:75], v[224:227], v[200:203], v[72:75]
	v_mfma_f32_16x16x32_bf16 v[68:71], v[216:219], v[208:211], v[68:71]
	v_mfma_f32_16x16x32_bf16 v[64:67], v[224:227], v[208:211], v[64:67]
	s_setprio 0
	s_barrier
	ds_read_b128 v[180:183], v153 offset:49152
	ds_read_b128 v[184:187], v153 offset:50176
	ds_read_b128 v[188:191], v152 offset:49152
	ds_read_b128 v[192:195], v152 offset:50176
	ds_read_b128 v[196:199], v151 offset:49152
	ds_read_b128 v[200:203], v151 offset:50176
	ds_read_b128 v[204:207], v150 offset:49152
	ds_read_b128 v[208:211], v150 offset:50176
	v_readfirstlane_b32 s36, v138
	v_lshl_add_u64 v[232:233], v[230:231], 0, s[56:57]
	s_mov_b32 m0, s36
	v_readfirstlane_b32 s36, v137
	global_load_lds_dwordx4 v[232:233], off
	v_lshl_add_u64 v[232:233], v[230:231], 0, s[58:59]
	s_mov_b32 m0, s36
	s_nop 0
	global_load_lds_dwordx4 v[232:233], off
	s_barrier
	s_waitcnt lgkmcnt(0)
	s_setprio 1
	s_waitcnt lgkmcnt(0)
	v_mfma_f32_16x16x32_bf16 v[60:63], v[164:167], v[180:183], v[60:63]
	v_mfma_f32_16x16x32_bf16 v[56:59], v[172:175], v[180:183], v[56:59]
	v_mfma_f32_16x16x32_bf16 v[52:55], v[164:167], v[188:191], v[52:55]
	v_mfma_f32_16x16x32_bf16 v[48:51], v[172:175], v[188:191], v[48:51]
	v_mfma_f32_16x16x32_bf16 v[44:47], v[164:167], v[196:199], v[44:47]
	v_mfma_f32_16x16x32_bf16 v[40:43], v[172:175], v[196:199], v[40:43]
	v_mfma_f32_16x16x32_bf16 v[36:39], v[164:167], v[204:207], v[36:39]
	v_mfma_f32_16x16x32_bf16 v[32:35], v[172:175], v[204:207], v[32:35]
	v_mfma_f32_16x16x32_bf16 v[60:63], v[168:171], v[184:187], v[60:63]
	v_mfma_f32_16x16x32_bf16 v[56:59], v[176:179], v[184:187], v[56:59]
	v_mfma_f32_16x16x32_bf16 v[52:55], v[168:171], v[192:195], v[52:55]
	v_mfma_f32_16x16x32_bf16 v[48:51], v[176:179], v[192:195], v[48:51]
	v_mfma_f32_16x16x32_bf16 v[44:47], v[168:171], v[200:203], v[44:47]
	v_mfma_f32_16x16x32_bf16 v[40:43], v[176:179], v[200:203], v[40:43]
	v_mfma_f32_16x16x32_bf16 v[36:39], v[168:171], v[208:211], v[36:39]
	v_mfma_f32_16x16x32_bf16 v[32:35], v[176:179], v[208:211], v[32:35]
	s_setprio 0
	s_barrier
	v_lshl_add_u64 v[132:133], v[132:133], 0, s[60:61]
	v_lshl_add_u64 v[228:229], s[50:51], 0, v[132:133]
	s_mov_b64 s[68:69], 0xe080080
	v_readfirstlane_b32 s36, v161
	v_lshl_add_u64 v[166:167], v[228:229], 0, s[68:69]
	s_mov_b32 m0, s36
	s_mov_b64 s[68:69], 0xe0c0080
	v_readfirstlane_b32 s36, v160
	global_load_lds_dwordx4 v[166:167], off
	v_lshl_add_u64 v[166:167], v[228:229], 0, s[68:69]
	s_mov_b32 m0, s36
	s_nop 0
	global_load_lds_dwordx4 v[166:167], off
	s_waitcnt vmcnt(12)
	s_barrier
	s_setprio 1
	v_mfma_f32_16x16x32_bf16 v[28:31], v[212:215], v[180:183], v[28:31]
	v_mfma_f32_16x16x32_bf16 v[24:27], v[220:223], v[180:183], v[24:27]
	v_mfma_f32_16x16x32_bf16 v[20:23], v[212:215], v[188:191], v[20:23]
	v_mfma_f32_16x16x32_bf16 v[16:19], v[220:223], v[188:191], v[16:19]
	v_mfma_f32_16x16x32_bf16 v[12:15], v[212:215], v[196:199], v[12:15]
	v_mfma_f32_16x16x32_bf16 v[8:11], v[220:223], v[196:199], v[8:11]
	v_mfma_f32_16x16x32_bf16 v[4:7], v[212:215], v[204:207], v[4:7]
	v_mfma_f32_16x16x32_bf16 v[0:3], v[220:223], v[204:207], v[0:3]
	v_mfma_f32_16x16x32_bf16 v[28:31], v[216:219], v[184:187], v[28:31]
	v_mfma_f32_16x16x32_bf16 v[24:27], v[224:227], v[184:187], v[24:27]
	v_mfma_f32_16x16x32_bf16 v[20:23], v[216:219], v[192:195], v[20:23]
	v_mfma_f32_16x16x32_bf16 v[16:19], v[224:227], v[192:195], v[16:19]
	v_mfma_f32_16x16x32_bf16 v[12:15], v[216:219], v[200:203], v[12:15]
	v_mfma_f32_16x16x32_bf16 v[8:11], v[224:227], v[200:203], v[8:11]
	v_mfma_f32_16x16x32_bf16 v[4:7], v[216:219], v[208:211], v[4:7]
	v_mfma_f32_16x16x32_bf16 v[0:3], v[224:227], v[208:211], v[0:3]
	s_setprio 0
	s_add_i32 s24, s24, 2
	v_lshl_add_u64 v[130:131], v[130:131], 0, s[10:11]
	s_cmp_lt_u32 s24, 28
	s_barrier
	s_cbranch_scc1 .LBB0_465
	s_lshl_b32 s24, s86, 5
	s_lshl_b32 s36, s86, 8
	s_and_b32 s24, s24, 0x1800
	s_and_b32 s36, s36, 0x700
	s_or_b32 s24, s36, s24
	v_lshlrev_b32_e32 v128, 3, v156
	v_lshlrev_b32_e32 v130, 5, v156
	v_and_b32_e32 v128, 0xffff0, v128
	v_and_b32_e32 v130, 32, v130
	s_lshl_b32 s36, s24, 12
	v_add_u32_e32 v130, v130, v158
	v_add_lshl_u32 v128, v157, v128, 12
	s_add_u32 s68, s70, s36
	v_lshl_add_u32 v128, v130, 1, v128
	s_addc_u32 s69, s71, 0
	v_lshl_add_u64 v[156:157], s[68:69], 0, v[128:129]
	v_readfirstlane_b32 s36, v161
	ds_read_b128 v[130:133], v162
	ds_read_b128 v[164:167], v162 offset:1024
	ds_read_b128 v[168:171], v162 offset:2048
	ds_read_b128 v[172:175], v162 offset:3072
	ds_read_b128 v[176:179], v153
	ds_read_b128 v[180:183], v153 offset:1024
	ds_read_b128 v[184:187], v152
	ds_read_b128 v[188:191], v152 offset:1024
	ds_read_b128 v[192:195], v151
	ds_read_b128 v[196:199], v151 offset:1024
	ds_read_b128 v[200:203], v150
	ds_read_b128 v[204:207], v150 offset:1024
	v_lshl_add_u64 v[162:163], v[156:157], 0, s[62:63]
	s_mov_b32 m0, s36
	v_readfirstlane_b32 s36, v160
	global_load_lds_dwordx4 v[162:163], off
	v_lshl_add_u64 v[156:157], v[156:157], 0, s[64:65]
	s_mov_b32 m0, s36
	s_nop 0
	global_load_lds_dwordx4 v[156:157], off
	s_waitcnt vmcnt(10)
	s_barrier
	s_waitcnt lgkmcnt(0)
	s_setprio 1
	s_waitcnt lgkmcnt(0)
	v_mfma_f32_16x16x32_bf16 v[124:127], v[130:133], v[176:179], v[124:127]
	v_mfma_f32_16x16x32_bf16 v[120:123], v[168:171], v[176:179], v[120:123]
	v_mfma_f32_16x16x32_bf16 v[116:119], v[130:133], v[184:187], v[116:119]
	v_mfma_f32_16x16x32_bf16 v[112:115], v[168:171], v[184:187], v[112:115]
	v_mfma_f32_16x16x32_bf16 v[108:111], v[130:133], v[192:195], v[108:111]
	v_mfma_f32_16x16x32_bf16 v[104:107], v[168:171], v[192:195], v[104:107]
	v_mfma_f32_16x16x32_bf16 v[100:103], v[130:133], v[200:203], v[100:103]
	v_mfma_f32_16x16x32_bf16 v[96:99], v[168:171], v[200:203], v[96:99]
	v_mfma_f32_16x16x32_bf16 v[124:127], v[164:167], v[180:183], v[124:127]
	v_mfma_f32_16x16x32_bf16 v[120:123], v[172:175], v[180:183], v[120:123]
	v_mfma_f32_16x16x32_bf16 v[116:119], v[164:167], v[188:191], v[116:119]
	v_mfma_f32_16x16x32_bf16 v[112:115], v[172:175], v[188:191], v[112:115]
	v_mfma_f32_16x16x32_bf16 v[108:111], v[164:167], v[196:199], v[108:111]
	v_mfma_f32_16x16x32_bf16 v[104:107], v[172:175], v[196:199], v[104:107]
	v_mfma_f32_16x16x32_bf16 v[100:103], v[164:167], v[204:207], v[100:103]
	v_mfma_f32_16x16x32_bf16 v[96:99], v[172:175], v[204:207], v[96:99]
	s_setprio 0
	s_barrier
	ds_read_b128 v[160:163], v159
	ds_read_b128 v[208:211], v159 offset:1024
	ds_read_b128 v[212:215], v159 offset:2048
	ds_read_b128 v[156:159], v159 offset:3072
	s_barrier
	s_waitcnt lgkmcnt(0)
	s_setprio 1
	s_waitcnt lgkmcnt(0)
	v_mfma_f32_16x16x32_bf16 v[92:95], v[160:163], v[176:179], v[92:95]
	v_mfma_f32_16x16x32_bf16 v[88:91], v[212:215], v[176:179], v[88:91]
	v_mfma_f32_16x16x32_bf16 v[84:87], v[160:163], v[184:187], v[84:87]
	v_mfma_f32_16x16x32_bf16 v[80:83], v[212:215], v[184:187], v[80:83]
	v_mfma_f32_16x16x32_bf16 v[76:79], v[160:163], v[192:195], v[76:79]
	v_mfma_f32_16x16x32_bf16 v[72:75], v[212:215], v[192:195], v[72:75]
	v_mfma_f32_16x16x32_bf16 v[68:71], v[160:163], v[200:203], v[68:71]
	v_mfma_f32_16x16x32_bf16 v[64:67], v[212:215], v[200:203], v[64:67]
	v_mfma_f32_16x16x32_bf16 v[176:179], v[208:211], v[180:183], v[92:95]
	v_mfma_f32_16x16x32_bf16 v[180:183], v[156:159], v[180:183], v[88:91]
	v_mfma_f32_16x16x32_bf16 v[184:187], v[208:211], v[188:191], v[84:87]
	v_mfma_f32_16x16x32_bf16 v[188:191], v[156:159], v[188:191], v[80:83]
	v_mfma_f32_16x16x32_bf16 v[192:195], v[208:211], v[196:199], v[76:79]
	v_mfma_f32_16x16x32_bf16 v[196:199], v[156:159], v[196:199], v[72:75]
	v_mfma_f32_16x16x32_bf16 v[200:203], v[208:211], v[204:207], v[68:71]
	v_mfma_f32_16x16x32_bf16 v[204:207], v[156:159], v[204:207], v[64:67]
	s_setprio 0
	s_barrier
	s_nop 0
	ds_read_b128 v[64:67], v153 offset:16384
	ds_read_b128 v[68:71], v153 offset:17408
	ds_read_b128 v[72:75], v152 offset:16384
	ds_read_b128 v[76:79], v152 offset:17408
	ds_read_b128 v[80:83], v151 offset:16384
	ds_read_b128 v[84:87], v151 offset:17408
	ds_read_b128 v[88:91], v150 offset:16384
	ds_read_b128 v[92:95], v150 offset:17408
	s_waitcnt vmcnt(4)
	s_barrier
	s_waitcnt lgkmcnt(0)
	s_setprio 1
	s_waitcnt lgkmcnt(0)
	v_mfma_f32_16x16x32_bf16 v[60:63], v[130:133], v[64:67], v[60:63]
	v_mfma_f32_16x16x32_bf16 v[56:59], v[168:171], v[64:67], v[56:59]
	v_mfma_f32_16x16x32_bf16 v[52:55], v[130:133], v[72:75], v[52:55]
	v_mfma_f32_16x16x32_bf16 v[48:51], v[168:171], v[72:75], v[48:51]
	v_mfma_f32_16x16x32_bf16 v[216:219], v[130:133], v[80:83], v[44:47]
	v_mfma_f32_16x16x32_bf16 v[220:223], v[168:171], v[80:83], v[40:43]
	v_mfma_f32_16x16x32_bf16 v[130:133], v[130:133], v[88:91], v[36:39]
	v_mfma_f32_16x16x32_bf16 v[168:171], v[168:171], v[88:91], v[32:35]
	v_mfma_f32_16x16x32_bf16 v[32:35], v[164:167], v[68:71], v[60:63]
	v_mfma_f32_16x16x32_bf16 v[36:39], v[172:175], v[68:71], v[56:59]
	v_mfma_f32_16x16x32_bf16 v[40:43], v[164:167], v[76:79], v[52:55]
	v_mfma_f32_16x16x32_bf16 v[44:47], v[172:175], v[76:79], v[48:51]
	v_mfma_f32_16x16x32_bf16 v[48:51], v[164:167], v[84:87], v[216:219]
	v_mfma_f32_16x16x32_bf16 v[52:55], v[172:175], v[84:87], v[220:223]
	v_mfma_f32_16x16x32_bf16 v[56:59], v[164:167], v[92:95], v[130:133]
	v_mfma_f32_16x16x32_bf16 v[60:63], v[172:175], v[92:95], v[168:171]
	s_setprio 0
	s_setprio 1
	v_mfma_f32_16x16x32_bf16 v[28:31], v[160:163], v[64:67], v[28:31]
	v_mfma_f32_16x16x32_bf16 v[24:27], v[212:215], v[64:67], v[24:27]
	v_mfma_f32_16x16x32_bf16 v[20:23], v[160:163], v[72:75], v[20:23]
	v_mfma_f32_16x16x32_bf16 v[64:67], v[212:215], v[72:75], v[16:19]
	v_mfma_f32_16x16x32_bf16 v[72:75], v[160:163], v[80:83], v[12:15]
	v_mfma_f32_16x16x32_bf16 v[8:11], v[212:215], v[80:83], v[8:11]
	v_mfma_f32_16x16x32_bf16 v[80:83], v[160:163], v[88:91], v[4:7]
	v_mfma_f32_16x16x32_bf16 v[0:3], v[212:215], v[88:91], v[0:3]
	v_mfma_f32_16x16x32_bf16 v[4:7], v[208:211], v[68:71], v[28:31]
	v_mfma_f32_16x16x32_bf16 v[12:15], v[156:159], v[68:71], v[24:27]
	v_mfma_f32_16x16x32_bf16 v[16:19], v[208:211], v[76:79], v[20:23]
	v_mfma_f32_16x16x32_bf16 v[20:23], v[156:159], v[76:79], v[64:67]
	v_mfma_f32_16x16x32_bf16 v[24:27], v[208:211], v[84:87], v[72:75]
	v_mfma_f32_16x16x32_bf16 v[28:31], v[156:159], v[84:87], v[8:11]
	v_mfma_f32_16x16x32_bf16 v[64:67], v[208:211], v[92:95], v[80:83]
	v_mfma_f32_16x16x32_bf16 v[68:71], v[156:159], v[92:95], v[0:3]
	s_setprio 0
	s_barrier
	ds_read_b128 v[8:11], v155
	ds_read_b128 v[0:3], v155 offset:1024
	ds_read_b128 v[76:79], v155 offset:2048
	ds_read_b128 v[72:75], v155 offset:3072
	ds_read_b128 v[130:133], v153 offset:32768
	ds_read_b128 v[156:159], v153 offset:33792
	ds_read_b128 v[160:163], v152 offset:32768
	ds_read_b128 v[164:167], v152 offset:33792
	ds_read_b128 v[168:171], v151 offset:32768
	ds_read_b128 v[172:175], v151 offset:33792
	ds_read_b128 v[208:211], v150 offset:32768
	ds_read_b128 v[212:215], v150 offset:33792
	s_waitcnt vmcnt(2)
	s_barrier
	s_waitcnt lgkmcnt(0)
	s_setprio 1
	s_waitcnt lgkmcnt(0)
	v_mfma_f32_16x16x32_bf16 v[80:83], v[8:11], v[130:133], v[124:127]
	v_mfma_f32_16x16x32_bf16 v[84:87], v[76:79], v[130:133], v[120:123]
	v_mfma_f32_16x16x32_bf16 v[88:91], v[8:11], v[160:163], v[116:119]
	v_mfma_f32_16x16x32_bf16 v[92:95], v[76:79], v[160:163], v[112:115]
	v_mfma_f32_16x16x32_bf16 v[108:111], v[8:11], v[168:171], v[108:111]
	v_mfma_f32_16x16x32_bf16 v[104:107], v[76:79], v[168:171], v[104:107]
	v_mfma_f32_16x16x32_bf16 v[100:103], v[8:11], v[208:211], v[100:103]
	v_mfma_f32_16x16x32_bf16 v[96:99], v[76:79], v[208:211], v[96:99]
	v_mfma_f32_16x16x32_bf16 v[112:115], v[0:3], v[156:159], v[80:83]
	v_mfma_f32_16x16x32_bf16 v[116:119], v[72:75], v[156:159], v[84:87]
	v_mfma_f32_16x16x32_bf16 v[120:123], v[0:3], v[164:167], v[88:91]
	v_mfma_f32_16x16x32_bf16 v[124:127], v[72:75], v[164:167], v[92:95]
	v_mfma_f32_16x16x32_bf16 v[108:111], v[0:3], v[172:175], v[108:111]
	v_mfma_f32_16x16x32_bf16 v[104:107], v[72:75], v[172:175], v[104:107]
	v_mfma_f32_16x16x32_bf16 v[100:103], v[0:3], v[212:215], v[100:103]
	v_mfma_f32_16x16x32_bf16 v[96:99], v[72:75], v[212:215], v[96:99]
	s_setprio 0
	s_barrier
	ds_read_b128 v[88:91], v154
	ds_read_b128 v[80:83], v154 offset:1024
	ds_read_b128 v[92:95], v154 offset:2048
	ds_read_b128 v[84:87], v154 offset:3072
	s_waitcnt vmcnt(0)
	s_barrier
	s_waitcnt lgkmcnt(0)
	s_setprio 1
	s_waitcnt lgkmcnt(0)
	v_mfma_f32_16x16x32_bf16 v[176:179], v[88:91], v[130:133], v[176:179]
	v_mfma_f32_16x16x32_bf16 v[130:133], v[92:95], v[130:133], v[180:183]
	v_mfma_f32_16x16x32_bf16 v[180:183], v[88:91], v[160:163], v[184:187]
	v_mfma_f32_16x16x32_bf16 v[160:163], v[92:95], v[160:163], v[188:191]
	v_mfma_f32_16x16x32_bf16 v[184:187], v[88:91], v[168:171], v[192:195]
	v_mfma_f32_16x16x32_bf16 v[168:171], v[92:95], v[168:171], v[196:199]
	v_mfma_f32_16x16x32_bf16 v[188:191], v[88:91], v[208:211], v[200:203]
	v_mfma_f32_16x16x32_bf16 v[192:195], v[92:95], v[208:211], v[204:207]
	v_mfma_f32_16x16x32_bf16 v[176:179], v[80:83], v[156:159], v[176:179]
	v_mfma_f32_16x16x32_bf16 v[130:133], v[84:87], v[156:159], v[130:133]
	v_mfma_f32_16x16x32_bf16 v[154:157], v[80:83], v[164:167], v[180:183]
	v_mfma_f32_16x16x32_bf16 v[158:161], v[84:87], v[164:167], v[160:163]
	v_mfma_f32_16x16x32_bf16 v[162:165], v[80:83], v[172:175], v[184:187]
	v_mfma_f32_16x16x32_bf16 v[166:169], v[84:87], v[172:175], v[168:171]
	v_mfma_f32_16x16x32_bf16 v[170:173], v[80:83], v[212:215], v[188:191]
	v_mfma_f32_16x16x32_bf16 v[180:183], v[84:87], v[212:215], v[192:195]
	s_setprio 0
	s_barrier
	v_mbcnt_lo_u32_b32 v128, -1, 0
	v_mbcnt_hi_u32_b32 v128, -1, v128
	v_cvt_pk_bf16_f32 v112, v112, v113
	v_cvt_pk_bf16_f32 v113, v114, v115
	v_cvt_pk_bf16_f32 v114, v116, v117
	v_cvt_pk_bf16_f32 v115, v118, v119
	s_lshl_b32 s68, s66, 9
	v_add_u32_e32 v174, s74, v128
	v_ashrrev_i32_e32 v175, 6, v174
	v_and_b32_e32 v184, 15, v128
	v_and_b32_e32 v185, 48, v128
	v_mul_lo_u32 v186, v175, s79
	v_bfe_u32 v187, v128, 3, 3
	v_lshlrev_b32_e32 v128, 4, v128
	v_add_u32_e32 v186, 0x20000, v186
	v_lshrrev_b32_e32 v174, 2, v174
	v_and_b32_e32 v128, 0x70, v128
	v_mul_u32_u24_e32 v184, 0x90, v184
	v_and_b32_e32 v174, 64, v174
	v_add3_u32 v184, v186, v184, v185
	v_or_b32_e32 v185, v186, v128
	v_or3_b32 v174, s24, v174, v187
	v_mad_u32_u24 v185, v187, s80, v185
	ds_write_b128 v184, v[112:115]
	v_cvt_pk_bf16_f32 v112, v176, v177
	v_cvt_pk_bf16_f32 v113, v178, v179
	v_cvt_pk_bf16_f32 v114, v130, v131
	v_cvt_pk_bf16_f32 v115, v132, v133
	ds_write_b128 v184, v[112:115] offset:64
	v_lshlrev_b32_e32 v175, 7, v175
	ds_read_b128 v[112:115], v185
	v_lshlrev_b32_e32 v116, 12, v174
	v_and_or_b32 v116, v175, s81, v116
	v_or3_b32 v128, v116, s68, v128
	ds_read_b128 v[116:119], v185 offset:1152
	v_lshl_add_u64 v[130:131], s[0:1], 0, v[128:129]
	s_mov_b32 s36, 0x8000
	s_waitcnt lgkmcnt(0)
	global_store_dwordx4 v128, v[112:115], s[0:1]
	v_cvt_pk_bf16_f32 v108, v108, v109
	v_cvt_pk_bf16_f32 v109, v110, v111
	v_cvt_pk_bf16_f32 v110, v104, v105
	v_cvt_pk_bf16_f32 v111, v106, v107
	v_cvt_pk_bf16_f32 v104, v162, v163
	s_nop 1
	v_add_co_u32_e32 v112, vcc, s36, v130
	v_cvt_pk_bf16_f32 v114, v124, v125
	v_cvt_pk_bf16_f32 v115, v126, v127
	v_cvt_pk_bf16_f32 v105, v164, v165
	v_cvt_pk_bf16_f32 v106, v166, v167
	s_nop 1
	v_addc_co_u32_e32 v113, vcc, 0, v131, vcc
	global_store_dwordx4 v[112:113], v[116:119], off
	v_cvt_pk_bf16_f32 v112, v120, v121
	v_cvt_pk_bf16_f32 v113, v122, v123
	ds_write_b128 v184, v[112:115]
	v_cvt_pk_bf16_f32 v112, v154, v155
	v_cvt_pk_bf16_f32 v113, v156, v157
	v_cvt_pk_bf16_f32 v114, v158, v159
	v_cvt_pk_bf16_f32 v115, v160, v161
	ds_write_b128 v184, v[112:115] offset:64
	ds_read_b128 v[112:115], v185
	ds_read_b128 v[116:119], v185 offset:1152
	v_add_co_u32_e32 v120, vcc, s76, v130
	ds_write_b128 v184, v[108:111]
	v_cvt_pk_bf16_f32 v107, v168, v169
	ds_write_b128 v184, v[104:107] offset:64
	v_addc_co_u32_e32 v121, vcc, 0, v131, vcc
	ds_read_b128 v[104:107], v185
	ds_read_b128 v[108:111], v185 offset:1152
	s_waitcnt lgkmcnt(0)
	global_store_dwordx4 v[120:121], v[112:115], off
	v_cvt_pk_bf16_f32 v100, v100, v101
	v_cvt_pk_bf16_f32 v101, v102, v103
	v_cvt_pk_bf16_f32 v102, v96, v97
	v_cvt_pk_bf16_f32 v103, v98, v99
	ds_write_b128 v184, v[100:103]
	s_nop 0
	v_add_co_u32_e32 v112, vcc, s77, v130
	v_cvt_pk_bf16_f32 v96, v170, v171
	v_cvt_pk_bf16_f32 v97, v172, v173
	v_cvt_pk_bf16_f32 v98, v180, v181
	v_cvt_pk_bf16_f32 v99, v182, v183
	s_nop 1
	v_addc_co_u32_e32 v113, vcc, 0, v131, vcc
	global_store_dwordx4 v[112:113], v[116:119], off
	v_add_co_u32_e32 v112, vcc, s78, v130
	ds_write_b128 v184, v[96:99] offset:64
	s_nop 0
	v_addc_co_u32_e32 v113, vcc, 0, v131, vcc
	ds_read_b128 v[96:99], v185
	ds_read_b128 v[100:103], v185 offset:1152
	global_store_dwordx4 v[112:113], v[104:107], off
	s_nop 1
	v_add_co_u32_e32 v104, vcc, s82, v130
	s_nop 1
	v_addc_co_u32_e32 v105, vcc, 0, v131, vcc
	global_store_dwordx4 v[104:105], v[108:111], off
	v_add_co_u32_e32 v104, vcc, s83, v130
	s_nop 1
	v_addc_co_u32_e32 v105, vcc, 0, v131, vcc
	s_waitcnt lgkmcnt(0)
	global_store_dwordx4 v[104:105], v[96:99], off
	s_nop 1
	v_add_co_u32_e32 v96, vcc, s91, v130
	s_nop 1
	v_addc_co_u32_e32 v97, vcc, 0, v131, vcc
	global_store_dwordx4 v[96:97], v[100:103], off
	ds_read_b128 v[96:99], v153 offset:49152
	ds_read_b128 v[100:103], v153 offset:50176
	ds_read_b128 v[104:107], v152 offset:49152
	ds_read_b128 v[108:111], v152 offset:50176
	ds_read_b128 v[112:115], v151 offset:49152
	ds_read_b128 v[116:119], v151 offset:50176
	ds_read_b128 v[120:123], v150 offset:49152
	ds_read_b128 v[124:127], v150 offset:50176
	s_barrier
	s_waitcnt lgkmcnt(0)
	s_setprio 1
	s_waitcnt lgkmcnt(0)
	v_mfma_f32_16x16x32_bf16 v[32:35], v[8:11], v[96:99], v[32:35]
	v_mfma_f32_16x16x32_bf16 v[36:39], v[76:79], v[96:99], v[36:39]
	v_mfma_f32_16x16x32_bf16 v[40:43], v[8:11], v[104:107], v[40:43]
	v_mfma_f32_16x16x32_bf16 v[130:133], v[76:79], v[104:107], v[44:47]
	v_mfma_f32_16x16x32_bf16 v[150:153], v[8:11], v[112:115], v[48:51]
	v_mfma_f32_16x16x32_bf16 v[52:55], v[76:79], v[112:115], v[52:55]
	v_mfma_f32_16x16x32_bf16 v[8:11], v[8:11], v[120:123], v[56:59]
	v_mfma_f32_16x16x32_bf16 v[60:63], v[76:79], v[120:123], v[60:63]
	v_mfma_f32_16x16x32_bf16 v[56:59], v[0:3], v[100:103], v[32:35]
	v_mfma_f32_16x16x32_bf16 v[48:51], v[72:75], v[100:103], v[36:39]
	v_mfma_f32_16x16x32_bf16 v[44:47], v[0:3], v[108:111], v[40:43]
	v_mfma_f32_16x16x32_bf16 v[40:43], v[72:75], v[108:111], v[130:133]
	v_mfma_f32_16x16x32_bf16 v[36:39], v[0:3], v[116:119], v[150:153]
	v_mfma_f32_16x16x32_bf16 v[32:35], v[72:75], v[116:119], v[52:55]
	v_mfma_f32_16x16x32_bf16 v[8:11], v[0:3], v[124:127], v[8:11]
	v_mfma_f32_16x16x32_bf16 v[0:3], v[72:75], v[124:127], v[60:63]
	s_setprio 0
	s_setprio 1
	v_mfma_f32_16x16x32_bf16 v[4:7], v[88:91], v[96:99], v[4:7]
	v_mfma_f32_16x16x32_bf16 v[12:15], v[92:95], v[96:99], v[12:15]
	v_mfma_f32_16x16x32_bf16 v[16:19], v[88:91], v[104:107], v[16:19]
	v_mfma_f32_16x16x32_bf16 v[20:23], v[92:95], v[104:107], v[20:23]
	v_mfma_f32_16x16x32_bf16 v[72:75], v[88:91], v[112:115], v[24:27]
	v_mfma_f32_16x16x32_bf16 v[76:79], v[92:95], v[112:115], v[28:31]
	v_mfma_f32_16x16x32_bf16 v[64:67], v[88:91], v[120:123], v[64:67]
	v_mfma_f32_16x16x32_bf16 v[68:71], v[92:95], v[120:123], v[68:71]
	v_mfma_f32_16x16x32_bf16 v[60:63], v[80:83], v[100:103], v[4:7]
	v_mfma_f32_16x16x32_bf16 v[52:55], v[84:87], v[100:103], v[12:15]
	v_mfma_f32_16x16x32_bf16 v[28:31], v[80:83], v[108:111], v[16:19]
	v_mfma_f32_16x16x32_bf16 v[24:27], v[84:87], v[108:111], v[20:23]
	v_mfma_f32_16x16x32_bf16 v[20:23], v[80:83], v[116:119], v[72:75]
	v_mfma_f32_16x16x32_bf16 v[16:19], v[84:87], v[116:119], v[76:79]
	v_mfma_f32_16x16x32_bf16 v[12:15], v[80:83], v[124:127], v[64:67]
	v_mfma_f32_16x16x32_bf16 v[4:7], v[84:87], v[124:127], v[68:71]
	s_setprio 0
	v_cmp_gt_u32_e32 vcc, s92, v136
	s_barrier
	s_and_saveexec_b64 s[66:67], vcc
	s_cbranch_execz .LBB0_468
	s_barrier

.LBB0_520:
	v_bfe_i32 v5, v179, 27, 1
	v_lshlrev_b32_e32 v169, 4, v179
	v_lshrrev_b32_e32 v5, 22, v5
	v_add_u32_e32 v5, v169, v5
	v_and_b32_e32 v5, 0xfffffc00, v5
	v_sub_u32_e32 v5, v169, v5
	v_lshrrev_b32_e32 v6, 4, v5
	v_bitop3_b32 v5, v6, v5, 32 bitop3:0x6c
	v_ashrrev_i32_e32 v6, 31, v5
	v_lshrrev_b32_e32 v6, 26, v6
	v_ashrrev_i32_e32 v4, 31, v179
	v_add_u32_e32 v6, v5, v6
	s_lshl_b32 s36, s81, 3
	v_lshrrev_b32_e32 v4, 26, v4
	v_ashrrev_i32_e32 v133, 6, v6
	v_and_b32_e32 v6, 0xc0, v6
	s_ff1_i32_b32 s37, s36
	v_and_b32_e32 v2, 15, v0
	v_and_b32_e32 v3, 48, v0
	v_add_u32_e32 v4, v179, v4
	v_sub_u32_e32 v5, v5, v6
	v_and_b32_e32 v6, 32, v0
	v_lshlrev_b32_e32 v10, 2, v0
	v_lshlrev_b32_e32 v0, 6, v0
	s_lshr_b32 s60, s82, s37
	s_add_i32 s36, s36, -1
	s_and_b32 s61, s82, 7
	v_ashrrev_i32_e32 v131, 6, v4
	v_lshlrev_b32_e32 v2, 6, v2
	v_and_b32_e32 v10, 32, v10
	v_and_b32_e32 v0, 0x3c0, v0
	s_and_b32 s36, s82, s36
	v_or_b32_e32 v9, v2, v3
	v_bitop3_b32 v2, v2, v10, v3 bitop3:0x36
	v_bitop3_b32 v3, v0, v10, v3 bitop3:0x36
	s_lshl_b32 s37, s60, 11
	s_lshl_b32 s46, s61, 8
	v_lshlrev_b32_e32 v0, 16, v131
	s_lshr_b32 s78, s36, 3
	s_or_b32 s46, s37, s46
	s_mov_b32 s47, s15
	v_and_b32_e32 v0, 0xfffe0000, v0
	s_lshl_b32 s36, s78, 14
	v_ashrrev_i16_sdwa v5, v167, sext(v5) dst_sel:DWORD dst_unused:UNUSED_PAD src0_sel:DWORD src1_sel:BYTE_0
	s_lshl_b64 s[46:47], s[46:47], 13
	v_lshl_add_u32 v0, v133, 13, v0
	v_bfe_i32 v134, v5, 0, 16
	v_and_or_b32 v0, v4, 64, v0
	s_add_u32 s46, s40, s46
	v_lshl_add_u32 v164, v134, 1, v0
	s_addc_u32 s47, s41, s47
	v_lshlrev_b32_e32 v14, 13, v1
	v_lshl_add_u64 v[0:1], s[46:47], 0, v[164:165]
	s_mul_i32 s46, s14, 0x1800
	s_mul_hi_u32 s37, s14, 0x1800
	s_add_u32 s46, s46, s36
	s_addc_u32 s37, s37, 0
	s_add_u32 s46, s62, s46
	v_bfe_i32 v7, v179, 6, 1
	s_addc_u32 s47, s63, s37
	s_lshl_b64 s[56:57], s[14:15], 12
	v_and_b32_e32 v7, s14, v7
	v_lshrrev_b32_e32 v8, 7, v179
	s_add_u32 s14, s56, s36
	v_add_lshl_u32 v7, v7, v8, 10
	v_lshlrev_b32_e32 v8, 6, v179
	s_addc_u32 s36, s57, 0
	v_and_b32_e32 v5, 0x3f0, v169
	v_and_b32_e32 v8, 0x3000, v8
	v_bitop3_b32 v11, v9, s65, v10 bitop3:0xde
	v_bitop3_b32 v12, v9, s67, v10 bitop3:0xde
	v_bitop3_b32 v13, v9, s68, v10 bitop3:0xde
	v_bitop3_b32 v9, v9, s69, v10 bitop3:0xde
	v_or_b32_e32 v10, 0x800, v14
	v_or_b32_e32 v15, 0x1000, v14
	v_or_b32_e32 v16, 0x1800, v14
	v_lshl_add_u64 v[128:129], v[0:1], 0, s[16:17]
	s_add_u32 s58, s62, s14
	v_mov_b32_e32 v0, 0
	v_bitop3_b32 v164, v5, v7, v6 bitop3:0xde
	s_addc_u32 s59, s63, s36
	s_mov_b32 s14, -2
	v_add_u32_e32 v138, v11, v8
	v_add_u32_e32 v193, v2, v14
	v_add_u32_e32 v192, v3, v10
	v_add_u32_e32 v191, v3, v15
	v_add_u32_e32 v190, v3, v16
	v_add_u32_e32 v137, 0xc000, v169
	v_add_u32_e32 v136, 0xe000, v169
	v_add_u32_e32 v135, v12, v8
	v_add_u32_e32 v189, 0x10000, v169
	v_add_u32_e32 v188, 0x12000, v169
	v_add_u32_e32 v187, 0x2000, v169
	v_add_u32_e32 v186, 0x14000, v169
	v_add_u32_e32 v185, 0x16000, v169
	v_add_u32_e32 v130, v13, v8
	v_add_u32_e32 v184, 0x4000, v169
	v_add_u32_e32 v183, 0x6000, v169
	v_add_u32_e32 v132, v9, v8
	v_add_u32_e32 v182, 0x18000, v169
	v_add_u32_e32 v181, 0x1a000, v169
	v_add_u32_e32 v177, 0x8000, v169
	v_add_u32_e32 v175, 0xa000, v169
	v_add_u32_e32 v173, 0x1c000, v169
	v_add_u32_e32 v171, 0x1e000, v169
	v_mov_b32_e32 v1, v0
	v_mov_b32_e32 v2, v0
	v_mov_b32_e32 v3, v0
	v_mov_b32_e32 v4, v0
	v_mov_b32_e32 v5, v0
	v_mov_b32_e32 v6, v0
	v_mov_b32_e32 v7, v0
	v_mov_b32_e32 v8, v0
	v_mov_b32_e32 v9, v0
	v_mov_b32_e32 v10, v0
	v_mov_b32_e32 v11, v0
	v_mov_b32_e32 v12, v0
	v_mov_b32_e32 v13, v0
	v_mov_b32_e32 v14, v0
	v_mov_b32_e32 v15, v0
	v_mov_b32_e32 v16, v0
	v_mov_b32_e32 v17, v0
	v_mov_b32_e32 v18, v0
	v_mov_b32_e32 v19, v0
	v_mov_b32_e32 v20, v0
	v_mov_b32_e32 v21, v0
	v_mov_b32_e32 v22, v0
	v_mov_b32_e32 v23, v0
	v_mov_b32_e32 v24, v0
	v_mov_b32_e32 v25, v0
	v_mov_b32_e32 v26, v0
	v_mov_b32_e32 v27, v0
	v_mov_b32_e32 v28, v0
	v_mov_b32_e32 v29, v0
	v_mov_b32_e32 v30, v0
	v_mov_b32_e32 v31, v0
	v_mov_b32_e32 v32, v0
	v_mov_b32_e32 v33, v0
	v_mov_b32_e32 v34, v0
	v_mov_b32_e32 v35, v0
	v_mov_b32_e32 v36, v0
	v_mov_b32_e32 v37, v0
	v_mov_b32_e32 v38, v0
	v_mov_b32_e32 v39, v0
	v_mov_b32_e32 v40, v0
	v_mov_b32_e32 v41, v0
	v_mov_b32_e32 v42, v0
	v_mov_b32_e32 v43, v0
	v_mov_b32_e32 v44, v0
	v_mov_b32_e32 v45, v0
	v_mov_b32_e32 v46, v0
	v_mov_b32_e32 v47, v0
	v_mov_b32_e32 v48, v0
	v_mov_b32_e32 v49, v0
	v_mov_b32_e32 v50, v0
	v_mov_b32_e32 v51, v0
	v_mov_b32_e32 v52, v0
	v_mov_b32_e32 v53, v0
	v_mov_b32_e32 v54, v0
	v_mov_b32_e32 v55, v0
	v_mov_b32_e32 v56, v0
	v_mov_b32_e32 v57, v0
	v_mov_b32_e32 v58, v0
	v_mov_b32_e32 v59, v0
	v_mov_b32_e32 v60, v0
	v_mov_b32_e32 v61, v0
	v_mov_b32_e32 v62, v0
	v_mov_b32_e32 v63, v0
	v_mov_b32_e32 v64, v0
	v_mov_b32_e32 v65, v0
	v_mov_b32_e32 v66, v0
	v_mov_b32_e32 v67, v0
	v_mov_b32_e32 v68, v0
	v_mov_b32_e32 v69, v0
	v_mov_b32_e32 v70, v0
	v_mov_b32_e32 v71, v0
	v_mov_b32_e32 v72, v0
	v_mov_b32_e32 v73, v0
	v_mov_b32_e32 v74, v0
	v_mov_b32_e32 v75, v0
	v_mov_b32_e32 v76, v0
	v_mov_b32_e32 v77, v0
	v_mov_b32_e32 v78, v0
	v_mov_b32_e32 v79, v0
	v_mov_b32_e32 v80, v0
	v_mov_b32_e32 v81, v0
	v_mov_b32_e32 v82, v0
	v_mov_b32_e32 v83, v0
	v_mov_b32_e32 v84, v0
	v_mov_b32_e32 v85, v0
	v_mov_b32_e32 v86, v0
	v_mov_b32_e32 v87, v0
	v_mov_b32_e32 v88, v0
	v_mov_b32_e32 v89, v0
	v_mov_b32_e32 v90, v0
	v_mov_b32_e32 v91, v0
	v_mov_b32_e32 v92, v0
	v_mov_b32_e32 v93, v0
	v_mov_b32_e32 v94, v0
	v_mov_b32_e32 v95, v0
	v_mov_b32_e32 v96, v0
	v_mov_b32_e32 v97, v0
	v_mov_b32_e32 v98, v0
	v_mov_b32_e32 v99, v0
	v_mov_b32_e32 v100, v0
	v_mov_b32_e32 v101, v0
	v_mov_b32_e32 v102, v0
	v_mov_b32_e32 v103, v0
	v_mov_b32_e32 v104, v0
	v_mov_b32_e32 v105, v0
	v_mov_b32_e32 v106, v0
	v_mov_b32_e32 v107, v0
	v_mov_b32_e32 v108, v0
	v_mov_b32_e32 v109, v0
	v_mov_b32_e32 v110, v0
	v_mov_b32_e32 v111, v0
	v_mov_b32_e32 v112, v0
	v_mov_b32_e32 v113, v0
	v_mov_b32_e32 v114, v0
	v_mov_b32_e32 v115, v0
	v_mov_b32_e32 v116, v0
	v_mov_b32_e32 v117, v0
	v_mov_b32_e32 v118, v0
	v_mov_b32_e32 v119, v0
	v_mov_b32_e32 v120, v0
	v_mov_b32_e32 v121, v0
	v_mov_b32_e32 v122, v0
	v_mov_b32_e32 v123, v0
	v_mov_b32_e32 v124, v0
	v_mov_b32_e32 v125, v0
	v_mov_b32_e32 v126, v0
	v_mov_b32_e32 v127, v0
	s_barrier
	v_readfirstlane_b32 s36, v137
	v_lshl_add_u64 v[142:143], v[128:129], 0, s[18:19]
	s_mov_b32 m0, s36
	v_readfirstlane_b32 s36, v136
	global_load_lds_dwordx4 v[142:143], off
	v_lshl_add_u64 v[142:143], v[128:129], 0, s[20:21]
	s_mov_b32 m0, s36
	s_nop 0
	global_load_lds_dwordx4 v[142:143], off
	ds_read_b128 v[140:143], v138
	ds_read_b128 v[144:147], v138 offset:1024
	ds_read_b128 v[148:151], v138 offset:2048
	ds_read_b128 v[152:155], v138 offset:3072
	ds_read_b128 v[156:159], v193
	ds_read_b128 v[160:163], v193 offset:1024
	ds_read_b128 v[194:197], v192
	ds_read_b128 v[198:201], v192 offset:1024
	ds_read_b128 v[202:205], v191
	ds_read_b128 v[206:209], v191 offset:1024
	ds_read_b128 v[210:213], v190
	ds_read_b128 v[214:217], v190 offset:1024
	s_waitcnt lgkmcnt(8)
	s_barrier
	s_branch .Lkent_521

.Lkent_521:
	s_waitcnt lgkmcnt(0)
	s_setprio 1
	s_waitcnt lgkmcnt(0)
	v_mfma_f32_16x16x32_bf16 v[124:127], v[140:143], v[156:159], v[124:127]
	v_mfma_f32_16x16x32_bf16 v[120:123], v[148:151], v[156:159], v[120:123]
	v_mfma_f32_16x16x32_bf16 v[116:119], v[140:143], v[194:197], v[116:119]
	v_mfma_f32_16x16x32_bf16 v[112:115], v[148:151], v[194:197], v[112:115]
	v_mfma_f32_16x16x32_bf16 v[108:111], v[140:143], v[202:205], v[108:111]
	v_mfma_f32_16x16x32_bf16 v[104:107], v[148:151], v[202:205], v[104:107]
	v_mfma_f32_16x16x32_bf16 v[100:103], v[140:143], v[210:213], v[100:103]
	v_mfma_f32_16x16x32_bf16 v[96:99], v[148:151], v[210:213], v[96:99]
	v_mfma_f32_16x16x32_bf16 v[124:127], v[144:147], v[160:163], v[124:127]
	v_mfma_f32_16x16x32_bf16 v[120:123], v[152:155], v[160:163], v[120:123]
	v_mfma_f32_16x16x32_bf16 v[116:119], v[144:147], v[198:201], v[116:119]
	v_mfma_f32_16x16x32_bf16 v[112:115], v[152:155], v[198:201], v[112:115]
	v_mfma_f32_16x16x32_bf16 v[108:111], v[144:147], v[206:209], v[108:111]
	v_mfma_f32_16x16x32_bf16 v[104:107], v[152:155], v[206:209], v[104:107]
	v_mfma_f32_16x16x32_bf16 v[100:103], v[144:147], v[214:217], v[100:103]
	v_mfma_f32_16x16x32_bf16 v[96:99], v[152:155], v[214:217], v[96:99]
	s_setprio 0
	s_barrier
	v_readfirstlane_b32 s36, v189
	v_lshl_add_u64 v[234:235], s[58:59], 0, v[164:165]
	s_mov_b32 m0, s36
	v_readfirstlane_b32 s36, v188
	ds_read_b128 v[218:221], v135
	ds_read_b128 v[222:225], v135 offset:1024
	ds_read_b128 v[226:229], v135 offset:2048
	ds_read_b128 v[230:233], v135 offset:3072
	global_load_lds_dwordx4 v[234:235], off
	v_lshl_add_u64 v[236:237], v[234:235], 0, s[2:3]
	s_mov_b32 m0, s36
	s_nop 0
	global_load_lds_dwordx4 v[236:237], off
	v_readfirstlane_b32 s36, v169
	v_lshl_add_u64 v[236:237], v[128:129], 0, s[22:23]
	s_mov_b32 m0, s36
	v_readfirstlane_b32 s36, v187
	global_load_lds_dwordx4 v[236:237], off
	v_lshl_add_u64 v[236:237], v[128:129], 0, s[24:25]
	s_mov_b32 m0, s36
	s_nop 0
	global_load_lds_dwordx4 v[236:237], off
	s_waitcnt vmcnt(12)
	s_barrier
	s_waitcnt lgkmcnt(0)
	s_setprio 1
	s_waitcnt lgkmcnt(0)
	v_mfma_f32_16x16x32_bf16 v[92:95], v[218:221], v[156:159], v[92:95]
	v_mfma_f32_16x16x32_bf16 v[88:91], v[226:229], v[156:159], v[88:91]
	v_mfma_f32_16x16x32_bf16 v[84:87], v[218:221], v[194:197], v[84:87]
	v_mfma_f32_16x16x32_bf16 v[80:83], v[226:229], v[194:197], v[80:83]
	v_mfma_f32_16x16x32_bf16 v[76:79], v[218:221], v[202:205], v[76:79]
	v_mfma_f32_16x16x32_bf16 v[72:75], v[226:229], v[202:205], v[72:75]
	v_mfma_f32_16x16x32_bf16 v[68:71], v[218:221], v[210:213], v[68:71]
	v_mfma_f32_16x16x32_bf16 v[64:67], v[226:229], v[210:213], v[64:67]
	v_mfma_f32_16x16x32_bf16 v[92:95], v[222:225], v[160:163], v[92:95]
	v_mfma_f32_16x16x32_bf16 v[88:91], v[230:233], v[160:163], v[88:91]
	v_mfma_f32_16x16x32_bf16 v[84:87], v[222:225], v[198:201], v[84:87]
	v_mfma_f32_16x16x32_bf16 v[80:83], v[230:233], v[198:201], v[80:83]
	v_mfma_f32_16x16x32_bf16 v[76:79], v[222:225], v[206:209], v[76:79]
	v_mfma_f32_16x16x32_bf16 v[72:75], v[230:233], v[206:209], v[72:75]
	v_mfma_f32_16x16x32_bf16 v[68:71], v[222:225], v[214:217], v[68:71]
	v_mfma_f32_16x16x32_bf16 v[64:67], v[230:233], v[214:217], v[64:67]
	s_setprio 0
	s_barrier
	ds_read_b128 v[156:159], v193 offset:16384
	ds_read_b128 v[160:163], v193 offset:17408
	ds_read_b128 v[194:197], v192 offset:16384
	ds_read_b128 v[198:201], v192 offset:17408
	ds_read_b128 v[202:205], v191 offset:16384
	ds_read_b128 v[206:209], v191 offset:17408
	ds_read_b128 v[210:213], v190 offset:16384
	ds_read_b128 v[214:217], v190 offset:17408
	v_readfirstlane_b32 s36, v186
	v_lshl_add_u64 v[236:237], v[234:235], 0, s[6:7]
	s_mov_b32 m0, s36
	v_readfirstlane_b32 s36, v185
	global_load_lds_dwordx4 v[236:237], off
	v_lshl_add_u64 v[236:237], v[234:235], 0, s[8:9]
	s_mov_b32 m0, s36
	s_nop 0
	global_load_lds_dwordx4 v[236:237], off
	s_barrier
	s_waitcnt lgkmcnt(0)
	s_setprio 1
	s_waitcnt lgkmcnt(0)
	v_mfma_f32_16x16x32_bf16 v[60:63], v[140:143], v[156:159], v[60:63]
	v_mfma_f32_16x16x32_bf16 v[56:59], v[148:151], v[156:159], v[56:59]
	v_mfma_f32_16x16x32_bf16 v[52:55], v[140:143], v[194:197], v[52:55]
	v_mfma_f32_16x16x32_bf16 v[48:51], v[148:151], v[194:197], v[48:51]
	v_mfma_f32_16x16x32_bf16 v[44:47], v[140:143], v[202:205], v[44:47]
	v_mfma_f32_16x16x32_bf16 v[40:43], v[148:151], v[202:205], v[40:43]
	v_mfma_f32_16x16x32_bf16 v[36:39], v[140:143], v[210:213], v[36:39]
	v_mfma_f32_16x16x32_bf16 v[32:35], v[148:151], v[210:213], v[32:35]
	v_mfma_f32_16x16x32_bf16 v[60:63], v[144:147], v[160:163], v[60:63]
	v_mfma_f32_16x16x32_bf16 v[56:59], v[152:155], v[160:163], v[56:59]
	v_mfma_f32_16x16x32_bf16 v[52:55], v[144:147], v[198:201], v[52:55]
	v_mfma_f32_16x16x32_bf16 v[48:51], v[152:155], v[198:201], v[48:51]
	v_mfma_f32_16x16x32_bf16 v[44:47], v[144:147], v[206:209], v[44:47]
	v_mfma_f32_16x16x32_bf16 v[40:43], v[152:155], v[206:209], v[40:43]
	v_mfma_f32_16x16x32_bf16 v[36:39], v[144:147], v[214:217], v[36:39]
	v_mfma_f32_16x16x32_bf16 v[32:35], v[152:155], v[214:217], v[32:35]
	s_setprio 0
	s_barrier
	v_readfirstlane_b32 s36, v184
	v_lshl_add_u64 v[142:143], v[128:129], 0, s[26:27]
	s_mov_b32 m0, s36
	v_readfirstlane_b32 s36, v183
	global_load_lds_dwordx4 v[142:143], off
	s_mov_b32 m0, s36
	s_nop 0
	global_load_lds_dwordx4 v[128:129], off
	s_waitcnt vmcnt(12)
	s_barrier
	s_setprio 1
	v_mfma_f32_16x16x32_bf16 v[28:31], v[218:221], v[156:159], v[28:31]
	v_mfma_f32_16x16x32_bf16 v[24:27], v[226:229], v[156:159], v[24:27]
	v_mfma_f32_16x16x32_bf16 v[20:23], v[218:221], v[194:197], v[20:23]
	v_mfma_f32_16x16x32_bf16 v[16:19], v[226:229], v[194:197], v[16:19]
	v_mfma_f32_16x16x32_bf16 v[12:15], v[218:221], v[202:205], v[12:15]
	v_mfma_f32_16x16x32_bf16 v[8:11], v[226:229], v[202:205], v[8:11]
	v_mfma_f32_16x16x32_bf16 v[4:7], v[218:221], v[210:213], v[4:7]
	v_mfma_f32_16x16x32_bf16 v[0:3], v[226:229], v[210:213], v[0:3]
	v_mfma_f32_16x16x32_bf16 v[28:31], v[222:225], v[160:163], v[28:31]
	v_mfma_f32_16x16x32_bf16 v[24:27], v[230:233], v[160:163], v[24:27]
	v_mfma_f32_16x16x32_bf16 v[20:23], v[222:225], v[198:201], v[20:23]
	v_mfma_f32_16x16x32_bf16 v[16:19], v[230:233], v[198:201], v[16:19]
	v_mfma_f32_16x16x32_bf16 v[12:15], v[222:225], v[206:209], v[12:15]
	v_mfma_f32_16x16x32_bf16 v[8:11], v[230:233], v[206:209], v[8:11]
	v_mfma_f32_16x16x32_bf16 v[4:7], v[222:225], v[214:217], v[4:7]
	v_mfma_f32_16x16x32_bf16 v[0:3], v[230:233], v[214:217], v[0:3]
	s_setprio 0
	s_barrier
	ds_read_b128 v[140:143], v130
	ds_read_b128 v[144:147], v130 offset:1024
	ds_read_b128 v[148:151], v130 offset:2048
	ds_read_b128 v[152:155], v130 offset:3072
	ds_read_b128 v[156:159], v193 offset:32768
	ds_read_b128 v[160:163], v193 offset:33792
	ds_read_b128 v[194:197], v192 offset:32768
	ds_read_b128 v[198:201], v192 offset:33792
	ds_read_b128 v[202:205], v191 offset:32768
	ds_read_b128 v[206:209], v191 offset:33792
	ds_read_b128 v[210:213], v190 offset:32768
	ds_read_b128 v[214:217], v190 offset:33792
	s_waitcnt lgkmcnt(8)
	s_waitcnt vmcnt(10)
	s_barrier
	s_waitcnt lgkmcnt(0)
	s_setprio 1
	s_waitcnt lgkmcnt(0)
	v_mfma_f32_16x16x32_bf16 v[124:127], v[140:143], v[156:159], v[124:127]
	v_mfma_f32_16x16x32_bf16 v[120:123], v[148:151], v[156:159], v[120:123]
	v_mfma_f32_16x16x32_bf16 v[116:119], v[140:143], v[194:197], v[116:119]
	v_mfma_f32_16x16x32_bf16 v[112:115], v[148:151], v[194:197], v[112:115]
	v_mfma_f32_16x16x32_bf16 v[108:111], v[140:143], v[202:205], v[108:111]
	v_mfma_f32_16x16x32_bf16 v[104:107], v[148:151], v[202:205], v[104:107]
	v_mfma_f32_16x16x32_bf16 v[100:103], v[140:143], v[210:213], v[100:103]
	v_mfma_f32_16x16x32_bf16 v[96:99], v[148:151], v[210:213], v[96:99]
	v_mfma_f32_16x16x32_bf16 v[124:127], v[144:147], v[160:163], v[124:127]
	v_mfma_f32_16x16x32_bf16 v[120:123], v[152:155], v[160:163], v[120:123]
	v_mfma_f32_16x16x32_bf16 v[116:119], v[144:147], v[198:201], v[116:119]
	v_mfma_f32_16x16x32_bf16 v[112:115], v[152:155], v[198:201], v[112:115]
	v_mfma_f32_16x16x32_bf16 v[108:111], v[144:147], v[206:209], v[108:111]
	v_mfma_f32_16x16x32_bf16 v[104:107], v[152:155], v[206:209], v[104:107]
	v_mfma_f32_16x16x32_bf16 v[100:103], v[144:147], v[214:217], v[100:103]
	v_mfma_f32_16x16x32_bf16 v[96:99], v[152:155], v[214:217], v[96:99]
	s_setprio 0
	s_barrier
	v_readfirstlane_b32 s36, v182
	v_lshl_add_u64 v[234:235], s[46:47], 0, v[164:165]
	s_mov_b32 m0, s36
	v_readfirstlane_b32 s36, v181
	ds_read_b128 v[218:221], v132
	ds_read_b128 v[222:225], v132 offset:1024
	ds_read_b128 v[226:229], v132 offset:2048
	ds_read_b128 v[230:233], v132 offset:3072
	global_load_lds_dwordx4 v[234:235], off
	v_lshl_add_u64 v[236:237], v[234:235], 0, s[2:3]
	s_mov_b32 m0, s36
	s_nop 0
	global_load_lds_dwordx4 v[236:237], off
	v_readfirstlane_b32 s36, v177
	v_lshl_add_u64 v[236:237], v[128:129], 0, s[28:29]
	s_mov_b32 m0, s36
	v_readfirstlane_b32 s36, v175
	global_load_lds_dwordx4 v[236:237], off
	v_lshl_add_u64 v[236:237], v[128:129], 0, s[30:31]
	s_mov_b32 m0, s36
	s_nop 0
	global_load_lds_dwordx4 v[236:237], off
	s_waitcnt vmcnt(12)
	s_barrier
	s_waitcnt lgkmcnt(0)
	s_setprio 1
	s_waitcnt lgkmcnt(0)
	v_mfma_f32_16x16x32_bf16 v[92:95], v[218:221], v[156:159], v[92:95]
	v_mfma_f32_16x16x32_bf16 v[88:91], v[226:229], v[156:159], v[88:91]
	v_mfma_f32_16x16x32_bf16 v[84:87], v[218:221], v[194:197], v[84:87]
	v_mfma_f32_16x16x32_bf16 v[80:83], v[226:229], v[194:197], v[80:83]
	v_mfma_f32_16x16x32_bf16 v[76:79], v[218:221], v[202:205], v[76:79]
	v_mfma_f32_16x16x32_bf16 v[72:75], v[226:229], v[202:205], v[72:75]
	v_mfma_f32_16x16x32_bf16 v[68:71], v[218:221], v[210:213], v[68:71]
	v_mfma_f32_16x16x32_bf16 v[64:67], v[226:229], v[210:213], v[64:67]
	v_mfma_f32_16x16x32_bf16 v[92:95], v[222:225], v[160:163], v[92:95]
	v_mfma_f32_16x16x32_bf16 v[88:91], v[230:233], v[160:163], v[88:91]
	v_mfma_f32_16x16x32_bf16 v[84:87], v[222:225], v[198:201], v[84:87]
	v_mfma_f32_16x16x32_bf16 v[80:83], v[230:233], v[198:201], v[80:83]
	v_mfma_f32_16x16x32_bf16 v[76:79], v[222:225], v[206:209], v[76:79]
	v_mfma_f32_16x16x32_bf16 v[72:75], v[230:233], v[206:209], v[72:75]
	v_mfma_f32_16x16x32_bf16 v[68:71], v[222:225], v[214:217], v[68:71]
	v_mfma_f32_16x16x32_bf16 v[64:67], v[230:233], v[214:217], v[64:67]
	s_setprio 0
	s_barrier
	ds_read_b128 v[156:159], v193 offset:49152
	ds_read_b128 v[160:163], v193 offset:50176
	ds_read_b128 v[194:197], v192 offset:49152
	ds_read_b128 v[198:201], v192 offset:50176
	ds_read_b128 v[202:205], v191 offset:49152
	ds_read_b128 v[206:209], v191 offset:50176
	ds_read_b128 v[210:213], v190 offset:49152
	ds_read_b128 v[214:217], v190 offset:50176
	v_readfirstlane_b32 s36, v173
	v_lshl_add_u64 v[236:237], v[234:235], 0, s[6:7]
	s_mov_b32 m0, s36
	v_readfirstlane_b32 s36, v171
	global_load_lds_dwordx4 v[236:237], off
	v_lshl_add_u64 v[236:237], v[234:235], 0, s[8:9]
	s_mov_b32 m0, s36
	s_nop 0
	global_load_lds_dwordx4 v[236:237], off
	s_barrier
	s_waitcnt lgkmcnt(0)
	s_setprio 1
	s_waitcnt lgkmcnt(0)
	v_mfma_f32_16x16x32_bf16 v[60:63], v[140:143], v[156:159], v[60:63]
	v_mfma_f32_16x16x32_bf16 v[56:59], v[148:151], v[156:159], v[56:59]
	v_mfma_f32_16x16x32_bf16 v[52:55], v[140:143], v[194:197], v[52:55]
	v_mfma_f32_16x16x32_bf16 v[48:51], v[148:151], v[194:197], v[48:51]
	v_mfma_f32_16x16x32_bf16 v[44:47], v[140:143], v[202:205], v[44:47]
	v_mfma_f32_16x16x32_bf16 v[40:43], v[148:151], v[202:205], v[40:43]
	v_mfma_f32_16x16x32_bf16 v[36:39], v[140:143], v[210:213], v[36:39]
	v_mfma_f32_16x16x32_bf16 v[32:35], v[148:151], v[210:213], v[32:35]
	v_mfma_f32_16x16x32_bf16 v[60:63], v[144:147], v[160:163], v[60:63]
	v_mfma_f32_16x16x32_bf16 v[56:59], v[152:155], v[160:163], v[56:59]
	v_mfma_f32_16x16x32_bf16 v[52:55], v[144:147], v[198:201], v[52:55]
	v_mfma_f32_16x16x32_bf16 v[48:51], v[152:155], v[198:201], v[48:51]
	v_mfma_f32_16x16x32_bf16 v[44:47], v[144:147], v[206:209], v[44:47]
	v_mfma_f32_16x16x32_bf16 v[40:43], v[152:155], v[206:209], v[40:43]
	v_mfma_f32_16x16x32_bf16 v[36:39], v[144:147], v[214:217], v[36:39]
	v_mfma_f32_16x16x32_bf16 v[32:35], v[152:155], v[214:217], v[32:35]
	s_setprio 0
	s_barrier
	v_lshl_add_u64 v[128:129], v[128:129], 0, s[34:35]
	v_readfirstlane_b32 s36, v137
	v_lshl_add_u64 v[142:143], v[128:129], 0, s[18:19]
	s_mov_b32 m0, s36
	v_readfirstlane_b32 s36, v136
	global_load_lds_dwordx4 v[142:143], off
	v_lshl_add_u64 v[142:143], v[128:129], 0, s[20:21]
	s_mov_b32 m0, s36
	s_nop 0
	global_load_lds_dwordx4 v[142:143], off
	s_waitcnt vmcnt(12)
	s_barrier
	s_setprio 1
	v_mfma_f32_16x16x32_bf16 v[28:31], v[218:221], v[156:159], v[28:31]
	v_mfma_f32_16x16x32_bf16 v[24:27], v[226:229], v[156:159], v[24:27]
	v_mfma_f32_16x16x32_bf16 v[20:23], v[218:221], v[194:197], v[20:23]
	v_mfma_f32_16x16x32_bf16 v[16:19], v[226:229], v[194:197], v[16:19]
	v_mfma_f32_16x16x32_bf16 v[12:15], v[218:221], v[202:205], v[12:15]
	v_mfma_f32_16x16x32_bf16 v[8:11], v[226:229], v[202:205], v[8:11]
	v_mfma_f32_16x16x32_bf16 v[4:7], v[218:221], v[210:213], v[4:7]
	v_mfma_f32_16x16x32_bf16 v[0:3], v[226:229], v[210:213], v[0:3]
	v_mfma_f32_16x16x32_bf16 v[28:31], v[222:225], v[160:163], v[28:31]
	v_mfma_f32_16x16x32_bf16 v[24:27], v[230:233], v[160:163], v[24:27]
	v_mfma_f32_16x16x32_bf16 v[20:23], v[222:225], v[198:201], v[20:23]
	v_mfma_f32_16x16x32_bf16 v[16:19], v[230:233], v[198:201], v[16:19]
	v_mfma_f32_16x16x32_bf16 v[12:15], v[222:225], v[206:209], v[12:15]
	v_mfma_f32_16x16x32_bf16 v[8:11], v[230:233], v[206:209], v[8:11]
	v_mfma_f32_16x16x32_bf16 v[4:7], v[222:225], v[214:217], v[4:7]
	v_mfma_f32_16x16x32_bf16 v[0:3], v[230:233], v[214:217], v[0:3]
	s_setprio 0
	s_add_i32 s14, s14, 2
	s_add_u32 s46, s46, s56
	s_addc_u32 s47, s47, s57
	s_add_u32 s58, s58, s56
	s_addc_u32 s59, s59, s57
	s_cmp_lt_u32 s14, 28
	s_barrier
	s_cbranch_scc1 .LBB0_521
	s_lshl_b32 s14, s60, 3
	s_or_b32 s80, s61, s14
	s_lshl_b32 s46, s80, 8
	v_lshlrev_b32_e32 v128, 3, v131
	v_lshlrev_b32_e32 v129, 5, v131
	s_or_b32 s14, s46, 0x80
	v_and_b32_e32 v128, 0x7fff0, v128
	v_and_b32_e32 v129, 32, v129
	s_lshl_b64 s[56:57], s[14:15], 13
	v_add_u32_e32 v129, v129, v134
	v_add_lshl_u32 v128, v133, v128, 13
	s_add_u32 s56, s40, s56
	v_lshl_add_u32 v164, v129, 1, v128
	s_addc_u32 s57, s41, s57
	v_lshl_add_u64 v[128:129], s[56:57], 0, v[164:165]
	v_readfirstlane_b32 s14, v137
	ds_read_b128 v[140:143], v138
	ds_read_b128 v[144:147], v138 offset:1024
	ds_read_b128 v[148:151], v138 offset:2048
	ds_read_b128 v[152:155], v138 offset:3072
	ds_read_b128 v[156:159], v193
	ds_read_b128 v[160:163], v193 offset:1024
	ds_read_b128 v[194:197], v192
	ds_read_b128 v[198:201], v192 offset:1024
	ds_read_b128 v[202:205], v191
	ds_read_b128 v[206:209], v191 offset:1024
	ds_read_b128 v[210:213], v190
	ds_read_b128 v[214:217], v190 offset:1024
	v_lshl_add_u64 v[138:139], v[128:129], 0, s[38:39]
	s_mov_b32 m0, s14
	v_readfirstlane_b32 s14, v136
	global_load_lds_dwordx4 v[138:139], off
	v_lshl_add_u64 v[128:129], v[128:129], 0, s[44:45]
	s_mov_b32 m0, s14
	s_mov_b32 s47, s15
	global_load_lds_dwordx4 v[128:129], off
	s_waitcnt vmcnt(10)
	s_barrier
	s_waitcnt lgkmcnt(0)
	s_setprio 1
	s_waitcnt lgkmcnt(0)
	v_mfma_f32_16x16x32_bf16 v[124:127], v[140:143], v[156:159], v[124:127]
	v_mfma_f32_16x16x32_bf16 v[120:123], v[148:151], v[156:159], v[120:123]
	v_mfma_f32_16x16x32_bf16 v[116:119], v[140:143], v[194:197], v[116:119]
	v_mfma_f32_16x16x32_bf16 v[112:115], v[148:151], v[194:197], v[112:115]
	v_mfma_f32_16x16x32_bf16 v[108:111], v[140:143], v[202:205], v[108:111]
	v_mfma_f32_16x16x32_bf16 v[104:107], v[148:151], v[202:205], v[104:107]
	v_mfma_f32_16x16x32_bf16 v[100:103], v[140:143], v[210:213], v[100:103]
	v_mfma_f32_16x16x32_bf16 v[96:99], v[148:151], v[210:213], v[96:99]
	v_mfma_f32_16x16x32_bf16 v[124:127], v[144:147], v[160:163], v[124:127]
	v_mfma_f32_16x16x32_bf16 v[120:123], v[152:155], v[160:163], v[120:123]
	v_mfma_f32_16x16x32_bf16 v[116:119], v[144:147], v[198:201], v[116:119]
	v_mfma_f32_16x16x32_bf16 v[112:115], v[152:155], v[198:201], v[112:115]
	v_mfma_f32_16x16x32_bf16 v[108:111], v[144:147], v[206:209], v[108:111]
	v_mfma_f32_16x16x32_bf16 v[104:107], v[152:155], v[206:209], v[104:107]
	v_mfma_f32_16x16x32_bf16 v[100:103], v[144:147], v[214:217], v[100:103]
	v_mfma_f32_16x16x32_bf16 v[96:99], v[152:155], v[214:217], v[96:99]
	s_setprio 0
	s_barrier
	ds_read_b128 v[136:139], v135
	ds_read_b128 v[218:221], v135 offset:1024
	ds_read_b128 v[222:225], v135 offset:2048
	ds_read_b128 v[226:229], v135 offset:3072
	s_barrier
	s_waitcnt lgkmcnt(0)
	s_setprio 1
	s_waitcnt lgkmcnt(0)
	v_mfma_f32_16x16x32_bf16 v[92:95], v[136:139], v[156:159], v[92:95]
	v_mfma_f32_16x16x32_bf16 v[84:87], v[136:139], v[194:197], v[84:87]
	v_mfma_f32_16x16x32_bf16 v[80:83], v[222:225], v[194:197], v[80:83]
	v_mfma_f32_16x16x32_bf16 v[88:91], v[222:225], v[156:159], v[88:91]
	v_mfma_f32_16x16x32_bf16 v[76:79], v[136:139], v[202:205], v[76:79]
	v_mfma_f32_16x16x32_bf16 v[72:75], v[222:225], v[202:205], v[72:75]
	v_mfma_f32_16x16x32_bf16 v[68:71], v[136:139], v[210:213], v[68:71]
	v_mfma_f32_16x16x32_bf16 v[64:67], v[222:225], v[210:213], v[64:67]
	v_mfma_f32_16x16x32_bf16 v[156:159], v[218:221], v[160:163], v[92:95]
	v_mfma_f32_16x16x32_bf16 v[194:197], v[218:221], v[198:201], v[84:87]
	v_mfma_f32_16x16x32_bf16 v[198:201], v[226:229], v[198:201], v[80:83]
	v_mfma_f32_16x16x32_bf16 v[160:163], v[226:229], v[160:163], v[88:91]
	v_mfma_f32_16x16x32_bf16 v[202:205], v[218:221], v[206:209], v[76:79]
	v_mfma_f32_16x16x32_bf16 v[206:209], v[226:229], v[206:209], v[72:75]
	v_mfma_f32_16x16x32_bf16 v[210:213], v[218:221], v[214:217], v[68:71]
	v_mfma_f32_16x16x32_bf16 v[214:217], v[226:229], v[214:217], v[64:67]
	s_setprio 0
	s_barrier
	s_nop 0
	ds_read_b128 v[64:67], v193 offset:16384
	ds_read_b128 v[68:71], v193 offset:17408
	ds_read_b128 v[72:75], v192 offset:16384
	ds_read_b128 v[76:79], v192 offset:17408
	ds_read_b128 v[80:83], v191 offset:16384
	ds_read_b128 v[84:87], v191 offset:17408
	ds_read_b128 v[88:91], v190 offset:16384
	ds_read_b128 v[92:95], v190 offset:17408
	s_waitcnt vmcnt(4)
	s_barrier
	s_waitcnt lgkmcnt(0)
	s_setprio 1
	s_waitcnt lgkmcnt(0)
	v_mfma_f32_16x16x32_bf16 v[60:63], v[140:143], v[64:67], v[60:63]
	v_mfma_f32_16x16x32_bf16 v[56:59], v[148:151], v[64:67], v[56:59]
	v_mfma_f32_16x16x32_bf16 v[52:55], v[140:143], v[72:75], v[52:55]
	v_mfma_f32_16x16x32_bf16 v[48:51], v[148:151], v[72:75], v[48:51]
	v_mfma_f32_16x16x32_bf16 v[230:233], v[140:143], v[80:83], v[44:47]
	v_mfma_f32_16x16x32_bf16 v[234:237], v[148:151], v[80:83], v[40:43]
	v_mfma_f32_16x16x32_bf16 v[140:143], v[140:143], v[88:91], v[36:39]
	v_mfma_f32_16x16x32_bf16 v[148:151], v[148:151], v[88:91], v[32:35]
	v_mfma_f32_16x16x32_bf16 v[32:35], v[144:147], v[68:71], v[60:63]
	v_mfma_f32_16x16x32_bf16 v[36:39], v[152:155], v[68:71], v[56:59]
	v_mfma_f32_16x16x32_bf16 v[40:43], v[144:147], v[76:79], v[52:55]
	v_mfma_f32_16x16x32_bf16 v[44:47], v[152:155], v[76:79], v[48:51]
	v_mfma_f32_16x16x32_bf16 v[48:51], v[144:147], v[84:87], v[230:233]
	v_mfma_f32_16x16x32_bf16 v[52:55], v[152:155], v[84:87], v[234:237]
	v_mfma_f32_16x16x32_bf16 v[56:59], v[144:147], v[92:95], v[140:143]
	v_mfma_f32_16x16x32_bf16 v[60:63], v[152:155], v[92:95], v[148:151]
	s_setprio 0
	s_setprio 1
	v_mfma_f32_16x16x32_bf16 v[28:31], v[136:139], v[64:67], v[28:31]
	v_mfma_f32_16x16x32_bf16 v[24:27], v[222:225], v[64:67], v[24:27]
	v_mfma_f32_16x16x32_bf16 v[20:23], v[136:139], v[72:75], v[20:23]
	v_mfma_f32_16x16x32_bf16 v[64:67], v[222:225], v[72:75], v[16:19]
	v_mfma_f32_16x16x32_bf16 v[12:15], v[136:139], v[80:83], v[12:15]
	v_mfma_f32_16x16x32_bf16 v[8:11], v[222:225], v[80:83], v[8:11]
	v_mfma_f32_16x16x32_bf16 v[72:75], v[136:139], v[88:91], v[4:7]
	v_mfma_f32_16x16x32_bf16 v[80:83], v[222:225], v[88:91], v[0:3]
	v_mfma_f32_16x16x32_bf16 v[0:3], v[218:221], v[68:71], v[28:31]
	v_mfma_f32_16x16x32_bf16 v[4:7], v[226:229], v[68:71], v[24:27]
	v_mfma_f32_16x16x32_bf16 v[16:19], v[218:221], v[76:79], v[20:23]
	v_mfma_f32_16x16x32_bf16 v[20:23], v[226:229], v[76:79], v[64:67]
	v_mfma_f32_16x16x32_bf16 v[24:27], v[218:221], v[84:87], v[12:15]
	v_mfma_f32_16x16x32_bf16 v[28:31], v[226:229], v[84:87], v[8:11]
	v_mfma_f32_16x16x32_bf16 v[64:67], v[218:221], v[92:95], v[72:75]
	v_mfma_f32_16x16x32_bf16 v[68:71], v[226:229], v[92:95], v[80:83]
	s_setprio 0
	s_barrier
	ds_read_b128 v[12:15], v130
	ds_read_b128 v[8:11], v130 offset:1024
	ds_read_b128 v[76:79], v130 offset:2048
	ds_read_b128 v[72:75], v130 offset:3072
	ds_read_b128 v[140:143], v193 offset:32768
	ds_read_b128 v[148:151], v193 offset:33792
	ds_read_b128 v[218:221], v192 offset:32768
	ds_read_b128 v[222:225], v192 offset:33792
	ds_read_b128 v[226:229], v191 offset:32768
	ds_read_b128 v[230:233], v191 offset:33792
	ds_read_b128 v[234:237], v190 offset:32768
	ds_read_b128 v[238:241], v190 offset:33792
	s_waitcnt vmcnt(2)
	s_barrier
	s_waitcnt lgkmcnt(0)
	s_setprio 1
	s_waitcnt lgkmcnt(0)
	v_mfma_f32_16x16x32_bf16 v[80:83], v[12:15], v[140:143], v[124:127]
	v_mfma_f32_16x16x32_bf16 v[84:87], v[76:79], v[140:143], v[120:123]
	v_mfma_f32_16x16x32_bf16 v[88:91], v[12:15], v[218:221], v[116:119]
	v_mfma_f32_16x16x32_bf16 v[92:95], v[76:79], v[218:221], v[112:115]
	v_mfma_f32_16x16x32_bf16 v[108:111], v[12:15], v[226:229], v[108:111]
	v_mfma_f32_16x16x32_bf16 v[104:107], v[76:79], v[226:229], v[104:107]
	v_mfma_f32_16x16x32_bf16 v[100:103], v[12:15], v[234:237], v[100:103]
	v_mfma_f32_16x16x32_bf16 v[96:99], v[76:79], v[234:237], v[96:99]
	v_mfma_f32_16x16x32_bf16 v[152:155], v[8:11], v[148:151], v[80:83]
	v_mfma_f32_16x16x32_bf16 v[144:147], v[72:75], v[148:151], v[84:87]
	v_mfma_f32_16x16x32_bf16 v[136:139], v[8:11], v[222:225], v[88:91]
	v_mfma_f32_16x16x32_bf16 v[128:131], v[72:75], v[222:225], v[92:95]
	v_mfma_f32_16x16x32_bf16 v[120:123], v[8:11], v[230:233], v[108:111]
	v_mfma_f32_16x16x32_bf16 v[112:115], v[72:75], v[230:233], v[104:107]
	v_mfma_f32_16x16x32_bf16 v[104:107], v[8:11], v[238:241], v[100:103]
	v_mfma_f32_16x16x32_bf16 v[96:99], v[72:75], v[238:241], v[96:99]
	s_setprio 0
	s_barrier
	ds_read_b128 v[88:91], v132
	ds_read_b128 v[80:83], v132 offset:1024
	ds_read_b128 v[92:95], v132 offset:2048
	ds_read_b128 v[84:87], v132 offset:3072
	s_waitcnt vmcnt(0)
	s_barrier
	s_waitcnt lgkmcnt(0)
	s_setprio 1
	s_waitcnt lgkmcnt(0)
	v_mfma_f32_16x16x32_bf16 v[100:103], v[88:91], v[140:143], v[156:159]
	v_mfma_f32_16x16x32_bf16 v[108:111], v[92:95], v[140:143], v[160:163]
	v_mfma_f32_16x16x32_bf16 v[116:119], v[88:91], v[218:221], v[194:197]
	v_mfma_f32_16x16x32_bf16 v[124:127], v[92:95], v[218:221], v[198:201]
	v_mfma_f32_16x16x32_bf16 v[160:163], v[88:91], v[226:229], v[202:205]
	v_mfma_f32_16x16x32_bf16 v[194:197], v[92:95], v[226:229], v[206:209]
	v_mfma_f32_16x16x32_bf16 v[198:201], v[88:91], v[234:237], v[210:213]
	v_mfma_f32_16x16x32_bf16 v[202:205], v[92:95], v[234:237], v[214:217]
	v_mfma_f32_16x16x32_bf16 v[156:159], v[80:83], v[148:151], v[100:103]
	v_mfma_f32_16x16x32_bf16 v[148:151], v[84:87], v[148:151], v[108:111]
	v_mfma_f32_16x16x32_bf16 v[140:143], v[80:83], v[222:225], v[116:119]
	v_mfma_f32_16x16x32_bf16 v[132:135], v[84:87], v[222:225], v[124:127]
	v_mfma_f32_16x16x32_bf16 v[124:127], v[80:83], v[230:233], v[160:163]
	v_mfma_f32_16x16x32_bf16 v[116:119], v[84:87], v[230:233], v[194:197]
	v_mfma_f32_16x16x32_bf16 v[108:111], v[80:83], v[238:241], v[198:201]
	v_mfma_f32_16x16x32_bf16 v[100:103], v[84:87], v[238:241], v[202:205]
	s_setprio 0
	s_lshl_b64 s[56:57], s[46:47], 2
	s_barrier
	v_mbcnt_lo_u32_b32 v162, -1, 0
	v_mbcnt_hi_u32_b32 v162, -1, v162
	s_add_u32 s56, s87, s56
	v_add_u32_e32 v160, s64, v162
	s_addc_u32 s57, s88, s57
	v_and_b32_e32 v164, 0x100, v160
	v_and_b32_e32 v162, 15, v162
	v_lshl_add_u64 v[160:161], s[56:57], 0, v[164:165]
	v_lshlrev_b32_e32 v164, 2, v162
	v_lshl_add_u64 v[160:161], v[160:161], 0, v[164:165]
	global_load_dword v180, v[160:161], off
	global_load_dword v178, v[160:161], off offset:64
	global_load_dword v176, v[160:161], off offset:128
	global_load_dword v174, v[160:161], off offset:192
	global_load_dword v172, v[160:161], off offset:512
	global_load_dword v170, v[160:161], off offset:576
	global_load_dword v168, v[160:161], off offset:640
	global_load_dword v166, v[160:161], off offset:704
	v_mbcnt_lo_u32_b32 v194, -1, 0
	v_mbcnt_hi_u32_b32 v194, -1, v194
	s_cmp_lg_u32 s79, 0
	v_add_u32_e32 v160, s64, v194
	v_bfe_u32 v196, v160, 8, 1
	v_ashrrev_i32_e32 v199, 6, v160
	v_bfe_u32 v160, v194, 4, 2
	s_cselect_b64 s[56:57], -1, 0
	v_and_b32_e32 v197, 3, v199
	v_and_b32_e32 v195, 15, v194
	s_and_b64 vcc, exec, s[56:57]
	v_lshlrev_b32_e32 v198, 4, v160
	s_cbranch_vccz .LBB0_533
	s_lshl_b32 s14, s78, 22
	s_lshl_b32 s36, s80, 14
	s_add_i32 s36, s36, s14
	v_lshlrev_b32_e32 v160, 6, v195
	v_or3_b32 v160, s36, v160, v198
	v_lshl_add_u32 v160, v197, 20, v160
	v_lshl_or_b32 v164, v196, 12, v160
	s_waitcnt vmcnt(0)
	v_pk_mul_f32 v[160:161], v[154:155], v[180:181] op_sel_hi:[1,0]
	v_pk_mul_f32 v[200:201], v[146:147], v[180:181] op_sel_hi:[1,0]
	v_max_f32_e32 v160, 0, v160
	v_mul_f32_e32 v204, v160, v160
	v_max_f32_e32 v160, 0, v200
	v_pk_mul_f32 v[162:163], v[152:153], v[180:181] op_sel_hi:[1,0]
	v_mul_f32_e32 v200, v160, v160
	v_max_f32_e32 v160, 0, v161
	v_pk_mul_f32 v[202:203], v[144:145], v[180:181] op_sel_hi:[1,0]
	v_max_f32_e32 v162, 0, v162
	v_max_f32_e32 v163, 0, v163
	v_mul_f32_e32 v161, v160, v160
	v_max_f32_e32 v160, 0, v201
	v_mul_f32_e32 v162, v162, v162
	v_max_f32_e32 v202, 0, v202
	v_mul_f32_e32 v163, v163, v163
	v_max_f32_e32 v203, 0, v203
	v_mul_f32_e32 v201, v160, v160
	v_cvt_pk_bf16_f32 v160, v162, v163
	v_cvt_pk_bf16_f32 v161, v204, v161
	v_mul_f32_e32 v202, v202, v202
	v_mul_f32_e32 v203, v203, v203
	v_cvt_pk_bf16_f32 v162, v202, v203
	v_cvt_pk_bf16_f32 v163, v200, v201
	global_store_dwordx4 v164, v[160:163], s[0:1]
	v_pk_mul_f32 v[202:203], v[150:151], v[180:181] op_sel_hi:[1,0]
	v_lshl_add_u64 v[200:201], s[0:1], 0, v[164:165]
	v_pk_mul_f32 v[160:161], v[158:159], v[180:181] op_sel_hi:[1,0]
	v_pk_mul_f32 v[162:163], v[156:157], v[180:181] op_sel_hi:[1,0]
	v_max_f32_e32 v160, 0, v160
	v_mul_f32_e32 v206, v160, v160
	v_max_f32_e32 v160, 0, v202
	v_mul_f32_e32 v202, v160, v160
	v_max_f32_e32 v160, 0, v161
	v_pk_mul_f32 v[204:205], v[148:149], v[180:181] op_sel_hi:[1,0]
	v_max_f32_e32 v162, 0, v162
	v_max_f32_e32 v163, 0, v163
	v_mul_f32_e32 v161, v160, v160
	v_max_f32_e32 v160, 0, v203
	v_add_co_u32_e32 v200, vcc, s72, v200
	v_mul_f32_e32 v162, v162, v162
	v_max_f32_e32 v204, 0, v204
	v_mul_f32_e32 v163, v163, v163
	v_max_f32_e32 v205, 0, v205
	v_mul_f32_e32 v203, v160, v160
	v_cvt_pk_bf16_f32 v160, v162, v163
	v_cvt_pk_bf16_f32 v161, v206, v161
	v_addc_co_u32_e32 v201, vcc, 0, v201, vcc
	v_mul_f32_e32 v204, v204, v204
	v_mul_f32_e32 v205, v205, v205
	v_cvt_pk_bf16_f32 v162, v204, v205
	v_cvt_pk_bf16_f32 v163, v202, v203
	global_store_dwordx4 v[200:201], v[160:163], off
	v_pk_mul_f32 v[202:203], v[130:131], v[178:179] op_sel_hi:[1,0]
	v_pk_mul_f32 v[204:205], v[128:129], v[178:179] op_sel_hi:[1,0]
	v_pk_mul_f32 v[160:161], v[138:139], v[178:179] op_sel_hi:[1,0]
	v_pk_mul_f32 v[162:163], v[136:137], v[178:179] op_sel_hi:[1,0]
	v_max_f32_e32 v160, 0, v160
	v_mul_f32_e32 v206, v160, v160
	v_max_f32_e32 v160, 0, v202
	v_mul_f32_e32 v202, v160, v160
	v_max_f32_e32 v160, 0, v161
	v_max_f32_e32 v162, 0, v162
	v_max_f32_e32 v163, 0, v163
	v_mul_f32_e32 v161, v160, v160
	v_max_f32_e32 v160, 0, v203
	v_mul_f32_e32 v162, v162, v162
	v_max_f32_e32 v204, 0, v204
	v_mul_f32_e32 v163, v163, v163
	v_max_f32_e32 v205, 0, v205
	v_mul_f32_e32 v203, v160, v160
	v_cvt_pk_bf16_f32 v160, v162, v163
	v_cvt_pk_bf16_f32 v161, v206, v161
	v_mul_f32_e32 v204, v204, v204
	v_mul_f32_e32 v205, v205, v205
	v_cvt_pk_bf16_f32 v162, v204, v205
	v_cvt_pk_bf16_f32 v163, v202, v203
	global_store_dwordx4 v164, v[160:163], s[0:1] offset:1024
	v_pk_mul_f32 v[202:203], v[134:135], v[178:179] op_sel_hi:[1,0]
	v_pk_mul_f32 v[204:205], v[132:133], v[178:179] op_sel_hi:[1,0]
	v_pk_mul_f32 v[160:161], v[142:143], v[178:179] op_sel_hi:[1,0]
	v_pk_mul_f32 v[162:163], v[140:141], v[178:179] op_sel_hi:[1,0]
	v_max_f32_e32 v160, 0, v160
	v_mul_f32_e32 v206, v160, v160
	v_max_f32_e32 v160, 0, v202
	v_mul_f32_e32 v202, v160, v160
	v_max_f32_e32 v160, 0, v161
	v_max_f32_e32 v162, 0, v162
	v_max_f32_e32 v163, 0, v163
	v_mul_f32_e32 v161, v160, v160
	v_max_f32_e32 v160, 0, v203
	v_mul_f32_e32 v162, v162, v162
	v_max_f32_e32 v204, 0, v204
	v_mul_f32_e32 v163, v163, v163
	v_max_f32_e32 v205, 0, v205
	v_mul_f32_e32 v203, v160, v160
	v_cvt_pk_bf16_f32 v160, v162, v163
	v_cvt_pk_bf16_f32 v161, v206, v161
	v_mul_f32_e32 v204, v204, v204
	v_mul_f32_e32 v205, v205, v205
	v_cvt_pk_bf16_f32 v162, v204, v205
	v_cvt_pk_bf16_f32 v163, v202, v203
	global_store_dwordx4 v[200:201], v[160:163], off offset:1024
	v_pk_mul_f32 v[202:203], v[114:115], v[176:177] op_sel_hi:[1,0]
	v_pk_mul_f32 v[204:205], v[112:113], v[176:177] op_sel_hi:[1,0]
	v_pk_mul_f32 v[160:161], v[122:123], v[176:177] op_sel_hi:[1,0]
	v_pk_mul_f32 v[162:163], v[120:121], v[176:177] op_sel_hi:[1,0]
	v_max_f32_e32 v160, 0, v160
	v_mul_f32_e32 v206, v160, v160
	v_max_f32_e32 v160, 0, v202
	v_mul_f32_e32 v202, v160, v160
	v_max_f32_e32 v160, 0, v161
	v_max_f32_e32 v162, 0, v162
	v_max_f32_e32 v163, 0, v163
	v_mul_f32_e32 v161, v160, v160
	v_max_f32_e32 v160, 0, v203
	v_mul_f32_e32 v162, v162, v162
	v_max_f32_e32 v204, 0, v204
	v_mul_f32_e32 v163, v163, v163
	v_max_f32_e32 v205, 0, v205
	v_mul_f32_e32 v203, v160, v160
	v_cvt_pk_bf16_f32 v160, v162, v163
	v_cvt_pk_bf16_f32 v161, v206, v161
	v_mul_f32_e32 v204, v204, v204
	v_mul_f32_e32 v205, v205, v205
	v_cvt_pk_bf16_f32 v162, v204, v205
	v_cvt_pk_bf16_f32 v163, v202, v203
	global_store_dwordx4 v164, v[160:163], s[0:1] offset:2048
	v_pk_mul_f32 v[202:203], v[118:119], v[176:177] op_sel_hi:[1,0]
	v_pk_mul_f32 v[204:205], v[116:117], v[176:177] op_sel_hi:[1,0]
	v_pk_mul_f32 v[160:161], v[126:127], v[176:177] op_sel_hi:[1,0]
	v_pk_mul_f32 v[162:163], v[124:125], v[176:177] op_sel_hi:[1,0]
	v_max_f32_e32 v160, 0, v160
	v_mul_f32_e32 v206, v160, v160
	v_max_f32_e32 v160, 0, v202
	v_mul_f32_e32 v202, v160, v160
	v_max_f32_e32 v160, 0, v161
	v_max_f32_e32 v162, 0, v162
	v_max_f32_e32 v163, 0, v163
	v_mul_f32_e32 v161, v160, v160
	v_max_f32_e32 v160, 0, v203
	v_mul_f32_e32 v162, v162, v162
	v_max_f32_e32 v204, 0, v204
	v_mul_f32_e32 v163, v163, v163
	v_max_f32_e32 v205, 0, v205
	v_mul_f32_e32 v203, v160, v160
	v_cvt_pk_bf16_f32 v160, v162, v163
	v_cvt_pk_bf16_f32 v161, v206, v161
	v_mul_f32_e32 v204, v204, v204
	v_mul_f32_e32 v205, v205, v205
	v_cvt_pk_bf16_f32 v162, v204, v205
	v_cvt_pk_bf16_f32 v163, v202, v203
	global_store_dwordx4 v[200:201], v[160:163], off offset:2048
	v_pk_mul_f32 v[200:201], v[98:99], v[174:175] op_sel_hi:[1,0]
	v_pk_mul_f32 v[202:203], v[96:97], v[174:175] op_sel_hi:[1,0]
	v_pk_mul_f32 v[160:161], v[106:107], v[174:175] op_sel_hi:[1,0]
	v_pk_mul_f32 v[162:163], v[104:105], v[174:175] op_sel_hi:[1,0]
	v_max_f32_e32 v160, 0, v160
	v_mul_f32_e32 v204, v160, v160
	v_max_f32_e32 v160, 0, v200
	v_mul_f32_e32 v200, v160, v160
	v_max_f32_e32 v160, 0, v161
	v_max_f32_e32 v162, 0, v162
	v_max_f32_e32 v163, 0, v163
	v_mul_f32_e32 v161, v160, v160
	v_max_f32_e32 v160, 0, v201
	v_mul_f32_e32 v162, v162, v162
	v_max_f32_e32 v202, 0, v202
	v_mul_f32_e32 v163, v163, v163
	v_max_f32_e32 v203, 0, v203
	v_mul_f32_e32 v201, v160, v160
	v_cvt_pk_bf16_f32 v160, v162, v163
	v_cvt_pk_bf16_f32 v161, v204, v161
	v_mul_f32_e32 v202, v202, v202
	v_mul_f32_e32 v203, v203, v203
	v_cvt_pk_bf16_f32 v162, v202, v203
	v_cvt_pk_bf16_f32 v163, v200, v201
	global_store_dwordx4 v164, v[160:163], s[0:1] offset:3072
	v_pk_mul_f32 v[200:201], v[102:103], v[174:175] op_sel_hi:[1,0]
	v_pk_mul_f32 v[202:203], v[100:101], v[174:175] op_sel_hi:[1,0]
	v_pk_mul_f32 v[160:161], v[110:111], v[174:175] op_sel_hi:[1,0]
	v_pk_mul_f32 v[162:163], v[108:109], v[174:175] op_sel_hi:[1,0]
	v_max_f32_e32 v160, 0, v160
	v_mul_f32_e32 v204, v160, v160
	v_max_f32_e32 v160, 0, v200
	v_max_f32_e32 v162, 0, v162
	v_max_f32_e32 v163, 0, v163
	v_mul_f32_e32 v200, v160, v160
	v_max_f32_e32 v160, 0, v161
	v_mul_f32_e32 v162, v162, v162
	v_max_f32_e32 v202, 0, v202
	v_mul_f32_e32 v163, v163, v163
	v_max_f32_e32 v203, 0, v203
	v_mul_f32_e32 v161, v160, v160
	v_max_f32_e32 v160, 0, v201
	v_mul_f32_e32 v202, v202, v202
	v_mul_f32_e32 v203, v203, v203
	v_mul_f32_e32 v201, v160, v160
	v_cvt_pk_bf16_f32 v160, v162, v163
	v_cvt_pk_bf16_f32 v161, v204, v161
	v_cvt_pk_bf16_f32 v162, v202, v203
	v_cvt_pk_bf16_f32 v163, v200, v201
	v_add_u32_e32 v164, 0x80c00, v164
	s_cbranch_execnz .LBB0_525

.LBB0_560:
	v_and_b32_e32 v2, 15, v0
	s_bfe_u32 s66, s86, 0x30003
	v_and_b32_e32 v3, 48, v0
	v_lshlrev_b32_e32 v134, 4, v135
	v_and_b32_e32 v5, 32, v0
	s_movk_i32 s37, 0x3f0
	v_lshlrev_b32_e32 v2, 6, v2
	v_lshlrev_b32_e32 v9, 2, v0
	s_lshl_b32 s36, s66, 14
	v_bitop3_b32 v155, v134, v5, s37 bitop3:0x6c
	v_and_b32_e32 v6, 64, v135
	s_add_i32 s67, s20, -2
	v_or_b32_e32 v8, v2, v3
	v_and_b32_e32 v9, 32, v9
	s_mov_b32 s37, 0x14000
	v_lshlrev_b32_e32 v0, 6, v0
	v_and_b32_e32 v4, 0x3f0, v134
	v_lshlrev_b32_e32 v156, 13, v6
	v_lshlrev_b32_e32 v7, 3, v135
	v_mul_i32_i24_e32 v6, 0xffffe800, v6
	v_bitop3_b32 v11, v8, s37, v9 bitop3:0xde
	s_mov_b32 s37, 0x1c000
	v_and_b32_e32 v0, 0x3c0, v0
	s_add_u32 s68, s72, s36
	v_and_b32_e32 v157, 0xfffffc00, v7
	v_bitop3_b32 v2, v2, v9, v3 bitop3:0x36
	v_bitop3_b32 v10, v8, s76, v9 bitop3:0xde
	v_bitop3_b32 v12, v8, s77, v9 bitop3:0xde
	v_bitop3_b32 v8, v8, s37, v9 bitop3:0xde
	v_bitop3_b32 v3, v0, v9, v3 bitop3:0x36
	v_bitop3_b32 v0, v6, v4, v5 bitop3:0xf6
	s_addc_u32 s69, s73, 0
	s_lshl_b32 s36, s86, 11
	s_and_b32 s37, s86, 7
	v_add3_u32 v128, v0, v156, v157
	s_and_b32 s36, s36, 0x60000
	s_lshl_b32 s37, s37, 14
	v_lshlrev_b32_e32 v13, 13, v1
	v_lshl_add_u64 v[0:1], s[68:69], 0, v[128:129]
	s_mov_b64 s[68:69], 0xc3000
	s_or_b32 s36, s36, s37
	v_lshl_add_u64 v[130:131], v[0:1], 0, s[68:69]
	v_bitop3_b32 v0, v4, v156, v5 bitop3:0xde
	s_add_u32 s68, s70, s36
	v_add_u32_e32 v128, v0, v157
	s_addc_u32 s69, s71, 0
	v_lshlrev_b32_e32 v7, 6, v135
	v_lshl_add_u64 v[0:1], s[68:69], 0, v[128:129]
	s_mov_b64 s[68:69], 0x301000
	v_and_b32_e32 v7, 0x3000, v7
	v_or_b32_e32 v9, 0x800, v13
	v_or_b32_e32 v14, 0x1000, v13
	v_or_b32_e32 v15, 0x1800, v13
	v_lshl_add_u64 v[132:133], v[0:1], 0, s[68:69]
	v_mov_b32_e32 v0, 0
	s_mov_b32 s68, 0
	v_add_u32_e32 v161, v10, v7
	v_add_u32_e32 v152, v2, v13
	v_add_u32_e32 v151, v3, v9
	v_add_u32_e32 v150, v3, v14
	v_add_u32_e32 v149, v3, v15
	v_add_u32_e32 v160, 0xc000, v134
	v_add_u32_e32 v159, 0xe000, v134
	v_add_u32_e32 v158, v11, v7
	v_add_u32_e32 v148, 0x10000, v134
	v_add_u32_e32 v147, 0x12000, v134
	v_add_u32_e32 v146, 0x2000, v134
	v_add_u32_e32 v145, 0x14000, v134
	v_add_u32_e32 v144, 0x16000, v134
	v_add_u32_e32 v154, v12, v7
	v_add_u32_e32 v143, 0x4000, v134
	v_add_u32_e32 v142, 0x6000, v134
	v_add_u32_e32 v153, v8, v7
	v_add_u32_e32 v141, 0x18000, v134
	v_add_u32_e32 v140, 0x1a000, v134
	v_add_u32_e32 v139, 0x8000, v134
	v_add_u32_e32 v138, 0xa000, v134
	v_add_u32_e32 v137, 0x1c000, v134
	v_add_u32_e32 v136, 0x1e000, v134
	v_mov_b32_e32 v1, v0
	v_mov_b32_e32 v2, v0
	v_mov_b32_e32 v3, v0
	v_mov_b32_e32 v4, v0
	v_mov_b32_e32 v5, v0
	v_mov_b32_e32 v6, v0
	v_mov_b32_e32 v7, v0
	v_mov_b32_e32 v8, v0
	v_mov_b32_e32 v9, v0
	v_mov_b32_e32 v10, v0
	v_mov_b32_e32 v11, v0
	v_mov_b32_e32 v12, v0
	v_mov_b32_e32 v13, v0
	v_mov_b32_e32 v14, v0
	v_mov_b32_e32 v15, v0
	v_mov_b32_e32 v16, v0
	v_mov_b32_e32 v17, v0
	v_mov_b32_e32 v18, v0
	v_mov_b32_e32 v19, v0
	v_mov_b32_e32 v20, v0
	v_mov_b32_e32 v21, v0
	v_mov_b32_e32 v22, v0
	v_mov_b32_e32 v23, v0
	v_mov_b32_e32 v24, v0
	v_mov_b32_e32 v25, v0
	v_mov_b32_e32 v26, v0
	v_mov_b32_e32 v27, v0
	v_mov_b32_e32 v28, v0
	v_mov_b32_e32 v29, v0
	v_mov_b32_e32 v30, v0
	v_mov_b32_e32 v31, v0
	v_mov_b32_e32 v32, v0
	v_mov_b32_e32 v33, v0
	v_mov_b32_e32 v34, v0
	v_mov_b32_e32 v35, v0
	v_mov_b32_e32 v36, v0
	v_mov_b32_e32 v37, v0
	v_mov_b32_e32 v38, v0
	v_mov_b32_e32 v39, v0
	v_mov_b32_e32 v40, v0
	v_mov_b32_e32 v41, v0
	v_mov_b32_e32 v42, v0
	v_mov_b32_e32 v43, v0
	v_mov_b32_e32 v44, v0
	v_mov_b32_e32 v45, v0
	v_mov_b32_e32 v46, v0
	v_mov_b32_e32 v47, v0
	v_mov_b32_e32 v48, v0
	v_mov_b32_e32 v49, v0
	v_mov_b32_e32 v50, v0
	v_mov_b32_e32 v51, v0
	v_mov_b32_e32 v52, v0
	v_mov_b32_e32 v53, v0
	v_mov_b32_e32 v54, v0
	v_mov_b32_e32 v55, v0
	v_mov_b32_e32 v56, v0
	v_mov_b32_e32 v57, v0
	v_mov_b32_e32 v58, v0
	v_mov_b32_e32 v59, v0
	v_mov_b32_e32 v60, v0
	v_mov_b32_e32 v61, v0
	v_mov_b32_e32 v62, v0
	v_mov_b32_e32 v63, v0
	v_mov_b32_e32 v64, v0
	v_mov_b32_e32 v65, v0
	v_mov_b32_e32 v66, v0
	v_mov_b32_e32 v67, v0
	v_mov_b32_e32 v68, v0
	v_mov_b32_e32 v69, v0
	v_mov_b32_e32 v70, v0
	v_mov_b32_e32 v71, v0
	v_mov_b32_e32 v72, v0
	v_mov_b32_e32 v73, v0
	v_mov_b32_e32 v74, v0
	v_mov_b32_e32 v75, v0
	v_mov_b32_e32 v76, v0
	v_mov_b32_e32 v77, v0
	v_mov_b32_e32 v78, v0
	v_mov_b32_e32 v79, v0
	v_mov_b32_e32 v80, v0
	v_mov_b32_e32 v81, v0
	v_mov_b32_e32 v82, v0
	v_mov_b32_e32 v83, v0
	v_mov_b32_e32 v84, v0
	v_mov_b32_e32 v85, v0
	v_mov_b32_e32 v86, v0
	v_mov_b32_e32 v87, v0
	v_mov_b32_e32 v88, v0
	v_mov_b32_e32 v89, v0
	v_mov_b32_e32 v90, v0
	v_mov_b32_e32 v91, v0
	v_mov_b32_e32 v92, v0
	v_mov_b32_e32 v93, v0
	v_mov_b32_e32 v94, v0
	v_mov_b32_e32 v95, v0
	v_mov_b32_e32 v96, v0
	v_mov_b32_e32 v97, v0
	v_mov_b32_e32 v98, v0
	v_mov_b32_e32 v99, v0
	v_mov_b32_e32 v100, v0
	v_mov_b32_e32 v101, v0
	v_mov_b32_e32 v102, v0
	v_mov_b32_e32 v103, v0
	v_mov_b32_e32 v104, v0
	v_mov_b32_e32 v105, v0
	v_mov_b32_e32 v106, v0
	v_mov_b32_e32 v107, v0
	v_mov_b32_e32 v108, v0
	v_mov_b32_e32 v109, v0
	v_mov_b32_e32 v110, v0
	v_mov_b32_e32 v111, v0
	v_mov_b32_e32 v112, v0
	v_mov_b32_e32 v113, v0
	v_mov_b32_e32 v114, v0
	v_mov_b32_e32 v115, v0
	v_mov_b32_e32 v116, v0
	v_mov_b32_e32 v117, v0
	v_mov_b32_e32 v118, v0
	v_mov_b32_e32 v119, v0
	v_mov_b32_e32 v120, v0
	v_mov_b32_e32 v121, v0
	v_mov_b32_e32 v122, v0
	v_mov_b32_e32 v123, v0
	v_mov_b32_e32 v124, v0
	v_mov_b32_e32 v125, v0
	v_mov_b32_e32 v126, v0
	v_mov_b32_e32 v127, v0
	s_barrier
	v_readfirstlane_b32 s36, v160
	v_lshl_add_u64 v[164:165], v[132:133], 0, s[22:23]
	s_mov_b32 m0, s36
	v_readfirstlane_b32 s36, v159
	global_load_lds_dwordx4 v[164:165], off
	v_lshl_add_u64 v[164:165], v[132:133], 0, s[24:25]
	s_mov_b32 m0, s36
	s_nop 0
	global_load_lds_dwordx4 v[164:165], off
	ds_read_b128 v[162:165], v161
	ds_read_b128 v[166:169], v161 offset:1024
	ds_read_b128 v[170:173], v161 offset:2048
	ds_read_b128 v[174:177], v161 offset:3072
	ds_read_b128 v[178:181], v152
	ds_read_b128 v[182:185], v152 offset:1024
	ds_read_b128 v[186:189], v151
	ds_read_b128 v[190:193], v151 offset:1024
	ds_read_b128 v[194:197], v150
	ds_read_b128 v[198:201], v150 offset:1024
	ds_read_b128 v[202:205], v149
	ds_read_b128 v[206:209], v149 offset:1024
	s_waitcnt lgkmcnt(8)
	s_barrier
	s_branch .Lkent_561

.Lkent_561:
	s_waitcnt lgkmcnt(0)
	s_setprio 1
	s_waitcnt lgkmcnt(0)
	v_mfma_f32_16x16x32_bf16 v[124:127], v[162:165], v[178:181], v[124:127]
	v_mfma_f32_16x16x32_bf16 v[120:123], v[170:173], v[178:181], v[120:123]
	v_mfma_f32_16x16x32_bf16 v[116:119], v[162:165], v[186:189], v[116:119]
	v_mfma_f32_16x16x32_bf16 v[112:115], v[170:173], v[186:189], v[112:115]
	v_mfma_f32_16x16x32_bf16 v[108:111], v[162:165], v[194:197], v[108:111]
	v_mfma_f32_16x16x32_bf16 v[104:107], v[170:173], v[194:197], v[104:107]
	v_mfma_f32_16x16x32_bf16 v[100:103], v[162:165], v[202:205], v[100:103]
	v_mfma_f32_16x16x32_bf16 v[96:99], v[170:173], v[202:205], v[96:99]
	v_mfma_f32_16x16x32_bf16 v[124:127], v[166:169], v[182:185], v[124:127]
	v_mfma_f32_16x16x32_bf16 v[120:123], v[174:177], v[182:185], v[120:123]
	v_mfma_f32_16x16x32_bf16 v[116:119], v[166:169], v[190:193], v[116:119]
	v_mfma_f32_16x16x32_bf16 v[112:115], v[174:177], v[190:193], v[112:115]
	v_mfma_f32_16x16x32_bf16 v[108:111], v[166:169], v[198:201], v[108:111]
	v_mfma_f32_16x16x32_bf16 v[104:107], v[174:177], v[198:201], v[104:107]
	v_mfma_f32_16x16x32_bf16 v[100:103], v[166:169], v[206:209], v[100:103]
	v_mfma_f32_16x16x32_bf16 v[96:99], v[174:177], v[206:209], v[96:99]
	s_setprio 0
	s_barrier
	v_readfirstlane_b32 s36, v148
	v_lshl_add_u64 v[226:227], v[130:131], 0, s[26:27]
	s_mov_b32 m0, s36
	v_readfirstlane_b32 s36, v147
	ds_read_b128 v[210:213], v158
	ds_read_b128 v[214:217], v158 offset:1024
	ds_read_b128 v[218:221], v158 offset:2048
	ds_read_b128 v[222:225], v158 offset:3072
	global_load_lds_dwordx4 v[226:227], off
	v_lshl_add_u64 v[226:227], v[130:131], 0, s[28:29]
	s_mov_b32 m0, s36
	s_add_i32 s68, s68, 2
	global_load_lds_dwordx4 v[226:227], off
	v_readfirstlane_b32 s36, v134
	v_lshl_add_u64 v[226:227], v[132:133], 0, s[30:31]
	s_mov_b32 m0, s36
	v_readfirstlane_b32 s36, v146
	global_load_lds_dwordx4 v[226:227], off
	v_lshl_add_u64 v[226:227], v[132:133], 0, s[34:35]
	s_mov_b32 m0, s36
	s_nop 0
	global_load_lds_dwordx4 v[226:227], off
	s_waitcnt vmcnt(12)
	s_barrier
	s_waitcnt lgkmcnt(0)
	s_setprio 1
	s_waitcnt lgkmcnt(0)
	v_mfma_f32_16x16x32_bf16 v[92:95], v[210:213], v[178:181], v[92:95]
	v_mfma_f32_16x16x32_bf16 v[88:91], v[218:221], v[178:181], v[88:91]
	v_mfma_f32_16x16x32_bf16 v[84:87], v[210:213], v[186:189], v[84:87]
	v_mfma_f32_16x16x32_bf16 v[80:83], v[218:221], v[186:189], v[80:83]
	v_mfma_f32_16x16x32_bf16 v[76:79], v[210:213], v[194:197], v[76:79]
	v_mfma_f32_16x16x32_bf16 v[72:75], v[218:221], v[194:197], v[72:75]
	v_mfma_f32_16x16x32_bf16 v[68:71], v[210:213], v[202:205], v[68:71]
	v_mfma_f32_16x16x32_bf16 v[64:67], v[218:221], v[202:205], v[64:67]
	v_mfma_f32_16x16x32_bf16 v[92:95], v[214:217], v[182:185], v[92:95]
	v_mfma_f32_16x16x32_bf16 v[88:91], v[222:225], v[182:185], v[88:91]
	v_mfma_f32_16x16x32_bf16 v[84:87], v[214:217], v[190:193], v[84:87]
	v_mfma_f32_16x16x32_bf16 v[80:83], v[222:225], v[190:193], v[80:83]
	v_mfma_f32_16x16x32_bf16 v[76:79], v[214:217], v[198:201], v[76:79]
	v_mfma_f32_16x16x32_bf16 v[72:75], v[222:225], v[198:201], v[72:75]
	v_mfma_f32_16x16x32_bf16 v[68:71], v[214:217], v[206:209], v[68:71]
	v_mfma_f32_16x16x32_bf16 v[64:67], v[222:225], v[206:209], v[64:67]
	s_setprio 0
	s_barrier
	ds_read_b128 v[178:181], v152 offset:16384
	ds_read_b128 v[182:185], v152 offset:17408
	ds_read_b128 v[186:189], v151 offset:16384
	ds_read_b128 v[190:193], v151 offset:17408
	ds_read_b128 v[194:197], v150 offset:16384
	ds_read_b128 v[198:201], v150 offset:17408
	ds_read_b128 v[202:205], v149 offset:16384
	ds_read_b128 v[206:209], v149 offset:17408
	v_readfirstlane_b32 s36, v145
	v_lshl_add_u64 v[226:227], v[130:131], 0, s[38:39]
	s_mov_b32 m0, s36
	v_readfirstlane_b32 s36, v144
	global_load_lds_dwordx4 v[226:227], off
	v_lshl_add_u64 v[226:227], v[130:131], 0, s[44:45]
	s_mov_b32 m0, s36
	s_nop 0
	global_load_lds_dwordx4 v[226:227], off
	s_barrier
	s_waitcnt lgkmcnt(0)
	s_setprio 1
	s_waitcnt lgkmcnt(0)
	v_mfma_f32_16x16x32_bf16 v[60:63], v[162:165], v[178:181], v[60:63]
	v_mfma_f32_16x16x32_bf16 v[56:59], v[170:173], v[178:181], v[56:59]
	v_mfma_f32_16x16x32_bf16 v[52:55], v[162:165], v[186:189], v[52:55]
	v_mfma_f32_16x16x32_bf16 v[48:51], v[170:173], v[186:189], v[48:51]
	v_mfma_f32_16x16x32_bf16 v[44:47], v[162:165], v[194:197], v[44:47]
	v_mfma_f32_16x16x32_bf16 v[40:43], v[170:173], v[194:197], v[40:43]
	v_mfma_f32_16x16x32_bf16 v[36:39], v[162:165], v[202:205], v[36:39]
	v_mfma_f32_16x16x32_bf16 v[32:35], v[170:173], v[202:205], v[32:35]
	v_mfma_f32_16x16x32_bf16 v[60:63], v[166:169], v[182:185], v[60:63]
	v_mfma_f32_16x16x32_bf16 v[56:59], v[174:177], v[182:185], v[56:59]
	v_mfma_f32_16x16x32_bf16 v[52:55], v[166:169], v[190:193], v[52:55]
	v_mfma_f32_16x16x32_bf16 v[48:51], v[174:177], v[190:193], v[48:51]
	v_mfma_f32_16x16x32_bf16 v[44:47], v[166:169], v[198:201], v[44:47]
	v_mfma_f32_16x16x32_bf16 v[40:43], v[174:177], v[198:201], v[40:43]
	v_mfma_f32_16x16x32_bf16 v[36:39], v[166:169], v[206:209], v[36:39]
	v_mfma_f32_16x16x32_bf16 v[32:35], v[174:177], v[206:209], v[32:35]
	s_setprio 0
	s_barrier
	v_readfirstlane_b32 s36, v143
	v_lshl_add_u64 v[164:165], v[132:133], 0, s[46:47]
	s_mov_b32 m0, s36
	v_readfirstlane_b32 s36, v142
	global_load_lds_dwordx4 v[164:165], off
	v_lshl_add_u64 v[164:165], v[132:133], 0, s[50:51]
	s_mov_b32 m0, s36
	s_nop 0
	global_load_lds_dwordx4 v[164:165], off
	s_waitcnt vmcnt(12)
	s_barrier
	s_setprio 1
	v_mfma_f32_16x16x32_bf16 v[28:31], v[210:213], v[178:181], v[28:31]
	v_mfma_f32_16x16x32_bf16 v[24:27], v[218:221], v[178:181], v[24:27]
	v_mfma_f32_16x16x32_bf16 v[20:23], v[210:213], v[186:189], v[20:23]
	v_mfma_f32_16x16x32_bf16 v[16:19], v[218:221], v[186:189], v[16:19]
	v_mfma_f32_16x16x32_bf16 v[12:15], v[210:213], v[194:197], v[12:15]
	v_mfma_f32_16x16x32_bf16 v[8:11], v[218:221], v[194:197], v[8:11]
	v_mfma_f32_16x16x32_bf16 v[4:7], v[210:213], v[202:205], v[4:7]
	v_mfma_f32_16x16x32_bf16 v[0:3], v[218:221], v[202:205], v[0:3]
	v_mfma_f32_16x16x32_bf16 v[28:31], v[214:217], v[182:185], v[28:31]
	v_mfma_f32_16x16x32_bf16 v[24:27], v[222:225], v[182:185], v[24:27]
	v_mfma_f32_16x16x32_bf16 v[20:23], v[214:217], v[190:193], v[20:23]
	v_mfma_f32_16x16x32_bf16 v[16:19], v[222:225], v[190:193], v[16:19]
	v_mfma_f32_16x16x32_bf16 v[12:15], v[214:217], v[198:201], v[12:15]
	v_mfma_f32_16x16x32_bf16 v[8:11], v[222:225], v[198:201], v[8:11]
	v_mfma_f32_16x16x32_bf16 v[4:7], v[214:217], v[206:209], v[4:7]
	v_mfma_f32_16x16x32_bf16 v[0:3], v[222:225], v[206:209], v[0:3]
	s_setprio 0
	s_barrier
	ds_read_b128 v[162:165], v154
	ds_read_b128 v[166:169], v154 offset:1024
	ds_read_b128 v[170:173], v154 offset:2048
	ds_read_b128 v[174:177], v154 offset:3072
	ds_read_b128 v[178:181], v152 offset:32768
	ds_read_b128 v[182:185], v152 offset:33792
	ds_read_b128 v[186:189], v151 offset:32768
	ds_read_b128 v[190:193], v151 offset:33792
	ds_read_b128 v[194:197], v150 offset:32768
	ds_read_b128 v[198:201], v150 offset:33792
	ds_read_b128 v[202:205], v149 offset:32768
	ds_read_b128 v[206:209], v149 offset:33792
	s_waitcnt lgkmcnt(8)
	s_waitcnt vmcnt(10)
	s_barrier
	s_waitcnt lgkmcnt(0)
	s_setprio 1
	s_waitcnt lgkmcnt(0)
	v_mfma_f32_16x16x32_bf16 v[124:127], v[162:165], v[178:181], v[124:127]
	v_mfma_f32_16x16x32_bf16 v[120:123], v[170:173], v[178:181], v[120:123]
	v_mfma_f32_16x16x32_bf16 v[116:119], v[162:165], v[186:189], v[116:119]
	v_mfma_f32_16x16x32_bf16 v[112:115], v[170:173], v[186:189], v[112:115]
	v_mfma_f32_16x16x32_bf16 v[108:111], v[162:165], v[194:197], v[108:111]
	v_mfma_f32_16x16x32_bf16 v[104:107], v[170:173], v[194:197], v[104:107]
	v_mfma_f32_16x16x32_bf16 v[100:103], v[162:165], v[202:205], v[100:103]
	v_mfma_f32_16x16x32_bf16 v[96:99], v[170:173], v[202:205], v[96:99]
	v_mfma_f32_16x16x32_bf16 v[124:127], v[166:169], v[182:185], v[124:127]
	v_mfma_f32_16x16x32_bf16 v[120:123], v[174:177], v[182:185], v[120:123]
	v_mfma_f32_16x16x32_bf16 v[116:119], v[166:169], v[190:193], v[116:119]
	v_mfma_f32_16x16x32_bf16 v[112:115], v[174:177], v[190:193], v[112:115]
	v_mfma_f32_16x16x32_bf16 v[108:111], v[166:169], v[198:201], v[108:111]
	v_mfma_f32_16x16x32_bf16 v[104:107], v[174:177], v[198:201], v[104:107]
	v_mfma_f32_16x16x32_bf16 v[100:103], v[166:169], v[206:209], v[100:103]
	v_mfma_f32_16x16x32_bf16 v[96:99], v[174:177], v[206:209], v[96:99]
	s_setprio 0
	s_barrier
	v_readfirstlane_b32 s36, v141
	v_lshl_add_u64 v[226:227], v[130:131], 0, s[56:57]
	s_mov_b32 m0, s36
	v_readfirstlane_b32 s36, v140
	ds_read_b128 v[210:213], v153
	ds_read_b128 v[214:217], v153 offset:1024
	ds_read_b128 v[218:221], v153 offset:2048
	ds_read_b128 v[222:225], v153 offset:3072
	global_load_lds_dwordx4 v[226:227], off
	v_lshl_add_u64 v[226:227], v[130:131], 0, s[58:59]
	s_mov_b32 m0, s36
	s_nop 0
	global_load_lds_dwordx4 v[226:227], off
	v_readfirstlane_b32 s36, v139
	v_lshl_add_u64 v[226:227], v[132:133], 0, s[60:61]
	s_mov_b32 m0, s36
	v_readfirstlane_b32 s36, v138
	global_load_lds_dwordx4 v[226:227], off
	s_mov_b32 m0, s36
	s_nop 0
	global_load_lds_dwordx4 v[132:133], off
	s_waitcnt vmcnt(12)
	s_barrier
	s_waitcnt lgkmcnt(0)
	s_setprio 1
	s_waitcnt lgkmcnt(0)
	v_mfma_f32_16x16x32_bf16 v[92:95], v[210:213], v[178:181], v[92:95]
	v_mfma_f32_16x16x32_bf16 v[88:91], v[218:221], v[178:181], v[88:91]
	v_mfma_f32_16x16x32_bf16 v[84:87], v[210:213], v[186:189], v[84:87]
	v_mfma_f32_16x16x32_bf16 v[80:83], v[218:221], v[186:189], v[80:83]
	v_mfma_f32_16x16x32_bf16 v[76:79], v[210:213], v[194:197], v[76:79]
	v_mfma_f32_16x16x32_bf16 v[72:75], v[218:221], v[194:197], v[72:75]
	v_mfma_f32_16x16x32_bf16 v[68:71], v[210:213], v[202:205], v[68:71]
	v_mfma_f32_16x16x32_bf16 v[64:67], v[218:221], v[202:205], v[64:67]
	v_mfma_f32_16x16x32_bf16 v[92:95], v[214:217], v[182:185], v[92:95]
	v_mfma_f32_16x16x32_bf16 v[88:91], v[222:225], v[182:185], v[88:91]
	v_mfma_f32_16x16x32_bf16 v[84:87], v[214:217], v[190:193], v[84:87]
	v_mfma_f32_16x16x32_bf16 v[80:83], v[222:225], v[190:193], v[80:83]
	v_mfma_f32_16x16x32_bf16 v[76:79], v[214:217], v[198:201], v[76:79]
	v_mfma_f32_16x16x32_bf16 v[72:75], v[222:225], v[198:201], v[72:75]
	v_mfma_f32_16x16x32_bf16 v[68:71], v[214:217], v[206:209], v[68:71]
	v_mfma_f32_16x16x32_bf16 v[64:67], v[222:225], v[206:209], v[64:67]
	s_setprio 0
	s_barrier
	ds_read_b128 v[178:181], v152 offset:49152
	ds_read_b128 v[182:185], v152 offset:50176
	ds_read_b128 v[186:189], v151 offset:49152
	ds_read_b128 v[190:193], v151 offset:50176
	ds_read_b128 v[194:197], v150 offset:49152
	ds_read_b128 v[198:201], v150 offset:50176
	ds_read_b128 v[202:205], v149 offset:49152
	ds_read_b128 v[206:209], v149 offset:50176
	v_readfirstlane_b32 s36, v137
	v_lshl_add_u64 v[226:227], v[130:131], 0, s[60:61]
	s_mov_b32 m0, s36
	v_readfirstlane_b32 s36, v136
	global_load_lds_dwordx4 v[226:227], off
	s_mov_b32 m0, s36
	s_nop 0
	global_load_lds_dwordx4 v[130:131], off
	s_barrier
	s_waitcnt lgkmcnt(0)
	s_setprio 1
	s_waitcnt lgkmcnt(0)
	v_mfma_f32_16x16x32_bf16 v[60:63], v[162:165], v[178:181], v[60:63]
	v_mfma_f32_16x16x32_bf16 v[56:59], v[170:173], v[178:181], v[56:59]
	v_mfma_f32_16x16x32_bf16 v[52:55], v[162:165], v[186:189], v[52:55]
	v_mfma_f32_16x16x32_bf16 v[48:51], v[170:173], v[186:189], v[48:51]
	v_mfma_f32_16x16x32_bf16 v[44:47], v[162:165], v[194:197], v[44:47]
	v_mfma_f32_16x16x32_bf16 v[40:43], v[170:173], v[194:197], v[40:43]
	v_mfma_f32_16x16x32_bf16 v[36:39], v[162:165], v[202:205], v[36:39]
	v_mfma_f32_16x16x32_bf16 v[32:35], v[170:173], v[202:205], v[32:35]
	v_mfma_f32_16x16x32_bf16 v[60:63], v[166:169], v[182:185], v[60:63]
	v_mfma_f32_16x16x32_bf16 v[56:59], v[174:177], v[182:185], v[56:59]
	v_mfma_f32_16x16x32_bf16 v[52:55], v[166:169], v[190:193], v[52:55]
	v_mfma_f32_16x16x32_bf16 v[48:51], v[174:177], v[190:193], v[48:51]
	v_mfma_f32_16x16x32_bf16 v[44:47], v[166:169], v[198:201], v[44:47]
	v_mfma_f32_16x16x32_bf16 v[40:43], v[174:177], v[198:201], v[40:43]
	v_mfma_f32_16x16x32_bf16 v[36:39], v[166:169], v[206:209], v[36:39]
	v_mfma_f32_16x16x32_bf16 v[32:35], v[174:177], v[206:209], v[32:35]
	s_setprio 0
	s_barrier
	v_lshl_add_u64 v[132:133], v[132:133], 0, s[64:65]
	v_readfirstlane_b32 s36, v160
	v_lshl_add_u64 v[164:165], v[132:133], 0, s[22:23]
	s_mov_b32 m0, s36
	v_readfirstlane_b32 s36, v159
	global_load_lds_dwordx4 v[164:165], off
	v_lshl_add_u64 v[164:165], v[132:133], 0, s[24:25]
	s_mov_b32 m0, s36
	s_nop 0
	global_load_lds_dwordx4 v[164:165], off
	s_waitcnt vmcnt(12)
	s_barrier
	s_setprio 1
	v_mfma_f32_16x16x32_bf16 v[28:31], v[210:213], v[178:181], v[28:31]
	v_mfma_f32_16x16x32_bf16 v[24:27], v[218:221], v[178:181], v[24:27]
	v_mfma_f32_16x16x32_bf16 v[20:23], v[210:213], v[186:189], v[20:23]
	v_mfma_f32_16x16x32_bf16 v[16:19], v[218:221], v[186:189], v[16:19]
	v_mfma_f32_16x16x32_bf16 v[12:15], v[210:213], v[194:197], v[12:15]
	v_mfma_f32_16x16x32_bf16 v[8:11], v[218:221], v[194:197], v[8:11]
	v_mfma_f32_16x16x32_bf16 v[4:7], v[210:213], v[202:205], v[4:7]
	v_mfma_f32_16x16x32_bf16 v[0:3], v[218:221], v[202:205], v[0:3]
	v_mfma_f32_16x16x32_bf16 v[28:31], v[214:217], v[182:185], v[28:31]
	v_mfma_f32_16x16x32_bf16 v[24:27], v[222:225], v[182:185], v[24:27]
	v_mfma_f32_16x16x32_bf16 v[20:23], v[214:217], v[190:193], v[20:23]
	v_mfma_f32_16x16x32_bf16 v[16:19], v[222:225], v[190:193], v[16:19]
	v_mfma_f32_16x16x32_bf16 v[12:15], v[214:217], v[198:201], v[12:15]
	v_mfma_f32_16x16x32_bf16 v[8:11], v[222:225], v[198:201], v[8:11]
	v_mfma_f32_16x16x32_bf16 v[4:7], v[214:217], v[206:209], v[4:7]
	v_mfma_f32_16x16x32_bf16 v[0:3], v[222:225], v[206:209], v[0:3]
	s_setprio 0
	v_lshl_add_u64 v[130:131], v[130:131], 0, s[62:63]
	s_cmp_lt_u32 s68, s67
	s_barrier
	s_cbranch_scc1 .LBB0_561
	s_lshl_b32 s36, s86, 5
	s_lshl_b32 s37, s86, 8
	s_and_b32 s36, s36, 0x1800
	s_and_b32 s37, s37, 0x700
	s_or_b32 s96, s37, s36
	s_lshl_b32 s36, s96, 6
	s_add_u32 s36, s70, s36
	s_addc_u32 s37, s71, 0
	s_add_i32 s20, s20, -1
	s_lshl_b64 s[68:69], s[20:21], 20
	v_add_u32_e32 v128, v156, v157
	s_add_u32 s68, s36, s68
	v_or_b32_e32 v128, v128, v155
	s_addc_u32 s69, s37, s69
	v_lshl_add_u64 v[156:157], s[68:69], 0, v[128:129]
	v_readfirstlane_b32 s20, v160
	v_lshl_add_u64 v[206:207], v[156:157], 0, s[4:5]
	s_mov_b32 m0, s20
	v_readfirstlane_b32 s20, v159
	ds_read_b128 v[130:133], v161
	ds_read_b128 v[162:165], v161 offset:1024
	ds_read_b128 v[166:169], v161 offset:2048
	ds_read_b128 v[170:173], v161 offset:3072
	ds_read_b128 v[174:177], v152
	ds_read_b128 v[178:181], v152 offset:1024
	ds_read_b128 v[182:185], v151
	ds_read_b128 v[186:189], v151 offset:1024
	ds_read_b128 v[190:193], v150
	ds_read_b128 v[194:197], v150 offset:1024
	ds_read_b128 v[198:201], v149
	ds_read_b128 v[202:205], v149 offset:1024
	global_load_lds_dwordx4 v[206:207], off
	v_lshl_add_u64 v[156:157], v[156:157], 0, s[6:7]
	s_mov_b32 m0, s20
	s_nop 0
	global_load_lds_dwordx4 v[156:157], off
	s_waitcnt vmcnt(10)
	s_barrier
	s_waitcnt lgkmcnt(0)
	s_setprio 1
	s_waitcnt lgkmcnt(0)
	v_mfma_f32_16x16x32_bf16 v[124:127], v[130:133], v[174:177], v[124:127]
	v_mfma_f32_16x16x32_bf16 v[120:123], v[166:169], v[174:177], v[120:123]
	v_mfma_f32_16x16x32_bf16 v[116:119], v[130:133], v[182:185], v[116:119]
	v_mfma_f32_16x16x32_bf16 v[112:115], v[166:169], v[182:185], v[112:115]
	v_mfma_f32_16x16x32_bf16 v[108:111], v[130:133], v[190:193], v[108:111]
	v_mfma_f32_16x16x32_bf16 v[104:107], v[166:169], v[190:193], v[104:107]
	v_mfma_f32_16x16x32_bf16 v[100:103], v[130:133], v[198:201], v[100:103]
	v_mfma_f32_16x16x32_bf16 v[96:99], v[166:169], v[198:201], v[96:99]
	v_mfma_f32_16x16x32_bf16 v[124:127], v[162:165], v[178:181], v[124:127]
	v_mfma_f32_16x16x32_bf16 v[120:123], v[170:173], v[178:181], v[120:123]
	v_mfma_f32_16x16x32_bf16 v[116:119], v[162:165], v[186:189], v[116:119]
	v_mfma_f32_16x16x32_bf16 v[112:115], v[170:173], v[186:189], v[112:115]
	v_mfma_f32_16x16x32_bf16 v[108:111], v[162:165], v[194:197], v[108:111]
	v_mfma_f32_16x16x32_bf16 v[104:107], v[170:173], v[194:197], v[104:107]
	v_mfma_f32_16x16x32_bf16 v[100:103], v[162:165], v[202:205], v[100:103]
	v_mfma_f32_16x16x32_bf16 v[96:99], v[170:173], v[202:205], v[96:99]
	s_setprio 0
	s_barrier
	ds_read_b128 v[206:209], v158
	ds_read_b128 v[210:213], v158 offset:1024
	ds_read_b128 v[214:217], v158 offset:2048
	ds_read_b128 v[156:159], v158 offset:3072
	s_barrier
	s_waitcnt lgkmcnt(0)
	s_setprio 1
	s_waitcnt lgkmcnt(0)
	v_mfma_f32_16x16x32_bf16 v[92:95], v[206:209], v[174:177], v[92:95]
	v_mfma_f32_16x16x32_bf16 v[88:91], v[214:217], v[174:177], v[88:91]
	v_mfma_f32_16x16x32_bf16 v[84:87], v[206:209], v[182:185], v[84:87]
	v_mfma_f32_16x16x32_bf16 v[80:83], v[214:217], v[182:185], v[80:83]
	v_mfma_f32_16x16x32_bf16 v[76:79], v[206:209], v[190:193], v[76:79]
	v_mfma_f32_16x16x32_bf16 v[72:75], v[214:217], v[190:193], v[72:75]
	v_mfma_f32_16x16x32_bf16 v[68:71], v[206:209], v[198:201], v[68:71]
	v_mfma_f32_16x16x32_bf16 v[64:67], v[214:217], v[198:201], v[64:67]
	v_mfma_f32_16x16x32_bf16 v[174:177], v[210:213], v[178:181], v[92:95]
	v_mfma_f32_16x16x32_bf16 v[178:181], v[156:159], v[178:181], v[88:91]
	v_mfma_f32_16x16x32_bf16 v[182:185], v[210:213], v[186:189], v[84:87]
	v_mfma_f32_16x16x32_bf16 v[186:189], v[156:159], v[186:189], v[80:83]
	v_mfma_f32_16x16x32_bf16 v[190:193], v[210:213], v[194:197], v[76:79]
	v_mfma_f32_16x16x32_bf16 v[194:197], v[156:159], v[194:197], v[72:75]
	v_mfma_f32_16x16x32_bf16 v[198:201], v[210:213], v[202:205], v[68:71]
	v_mfma_f32_16x16x32_bf16 v[202:205], v[156:159], v[202:205], v[64:67]
	s_setprio 0
	s_barrier
	s_nop 0
	ds_read_b128 v[64:67], v152 offset:16384
	ds_read_b128 v[68:71], v152 offset:17408
	ds_read_b128 v[72:75], v151 offset:16384
	ds_read_b128 v[76:79], v151 offset:17408
	ds_read_b128 v[80:83], v150 offset:16384
	ds_read_b128 v[84:87], v150 offset:17408
	ds_read_b128 v[88:91], v149 offset:16384
	ds_read_b128 v[92:95], v149 offset:17408
	s_waitcnt vmcnt(4)
	s_barrier
	s_waitcnt lgkmcnt(0)
	s_setprio 1
	s_waitcnt lgkmcnt(0)
	v_mfma_f32_16x16x32_bf16 v[60:63], v[130:133], v[64:67], v[60:63]
	v_mfma_f32_16x16x32_bf16 v[56:59], v[166:169], v[64:67], v[56:59]
	v_mfma_f32_16x16x32_bf16 v[52:55], v[130:133], v[72:75], v[52:55]
	v_mfma_f32_16x16x32_bf16 v[48:51], v[166:169], v[72:75], v[48:51]
	v_mfma_f32_16x16x32_bf16 v[218:221], v[130:133], v[80:83], v[44:47]
	v_mfma_f32_16x16x32_bf16 v[222:225], v[166:169], v[80:83], v[40:43]
	v_mfma_f32_16x16x32_bf16 v[130:133], v[130:133], v[88:91], v[36:39]
	v_mfma_f32_16x16x32_bf16 v[166:169], v[166:169], v[88:91], v[32:35]
	v_mfma_f32_16x16x32_bf16 v[32:35], v[162:165], v[68:71], v[60:63]
	v_mfma_f32_16x16x32_bf16 v[36:39], v[170:173], v[68:71], v[56:59]
	v_mfma_f32_16x16x32_bf16 v[40:43], v[162:165], v[76:79], v[52:55]
	v_mfma_f32_16x16x32_bf16 v[44:47], v[170:173], v[76:79], v[48:51]
	v_mfma_f32_16x16x32_bf16 v[48:51], v[162:165], v[84:87], v[218:221]
	v_mfma_f32_16x16x32_bf16 v[52:55], v[170:173], v[84:87], v[222:225]
	v_mfma_f32_16x16x32_bf16 v[56:59], v[162:165], v[92:95], v[130:133]
	v_mfma_f32_16x16x32_bf16 v[60:63], v[170:173], v[92:95], v[166:169]
	s_setprio 0
	s_setprio 1
	v_mfma_f32_16x16x32_bf16 v[28:31], v[206:209], v[64:67], v[28:31]
	v_mfma_f32_16x16x32_bf16 v[24:27], v[214:217], v[64:67], v[24:27]
	v_mfma_f32_16x16x32_bf16 v[20:23], v[206:209], v[72:75], v[20:23]
	v_mfma_f32_16x16x32_bf16 v[64:67], v[214:217], v[72:75], v[16:19]
	v_mfma_f32_16x16x32_bf16 v[72:75], v[206:209], v[80:83], v[12:15]
	v_mfma_f32_16x16x32_bf16 v[8:11], v[214:217], v[80:83], v[8:11]
	v_mfma_f32_16x16x32_bf16 v[80:83], v[206:209], v[88:91], v[4:7]
	v_mfma_f32_16x16x32_bf16 v[0:3], v[214:217], v[88:91], v[0:3]
	v_mfma_f32_16x16x32_bf16 v[4:7], v[210:213], v[68:71], v[28:31]
	v_mfma_f32_16x16x32_bf16 v[12:15], v[156:159], v[68:71], v[24:27]
	v_mfma_f32_16x16x32_bf16 v[16:19], v[210:213], v[76:79], v[20:23]
	v_mfma_f32_16x16x32_bf16 v[20:23], v[156:159], v[76:79], v[64:67]
	v_mfma_f32_16x16x32_bf16 v[24:27], v[210:213], v[84:87], v[72:75]
	v_mfma_f32_16x16x32_bf16 v[28:31], v[156:159], v[84:87], v[8:11]
	v_mfma_f32_16x16x32_bf16 v[64:67], v[210:213], v[92:95], v[80:83]
	v_mfma_f32_16x16x32_bf16 v[68:71], v[156:159], v[92:95], v[0:3]
	s_setprio 0
	s_barrier
	ds_read_b128 v[8:11], v154
	ds_read_b128 v[0:3], v154 offset:1024
	ds_read_b128 v[76:79], v154 offset:2048
	ds_read_b128 v[72:75], v154 offset:3072
	ds_read_b128 v[130:133], v152 offset:32768
	ds_read_b128 v[154:157], v152 offset:33792
	ds_read_b128 v[158:161], v151 offset:32768
	ds_read_b128 v[162:165], v151 offset:33792
	ds_read_b128 v[166:169], v150 offset:32768
	ds_read_b128 v[170:173], v150 offset:33792
	ds_read_b128 v[206:209], v149 offset:32768
	ds_read_b128 v[210:213], v149 offset:33792
	s_waitcnt vmcnt(2)
	s_barrier
	s_waitcnt lgkmcnt(0)
	s_setprio 1
	s_waitcnt lgkmcnt(0)
	v_mfma_f32_16x16x32_bf16 v[80:83], v[8:11], v[130:133], v[124:127]
	v_mfma_f32_16x16x32_bf16 v[84:87], v[76:79], v[130:133], v[120:123]
	v_mfma_f32_16x16x32_bf16 v[88:91], v[8:11], v[158:161], v[116:119]
	v_mfma_f32_16x16x32_bf16 v[92:95], v[76:79], v[158:161], v[112:115]
	v_mfma_f32_16x16x32_bf16 v[108:111], v[8:11], v[166:169], v[108:111]
	v_mfma_f32_16x16x32_bf16 v[104:107], v[76:79], v[166:169], v[104:107]
	v_mfma_f32_16x16x32_bf16 v[100:103], v[8:11], v[206:209], v[100:103]
	v_mfma_f32_16x16x32_bf16 v[96:99], v[76:79], v[206:209], v[96:99]
	v_mfma_f32_16x16x32_bf16 v[112:115], v[0:3], v[154:157], v[80:83]
	v_mfma_f32_16x16x32_bf16 v[116:119], v[72:75], v[154:157], v[84:87]
	v_mfma_f32_16x16x32_bf16 v[120:123], v[0:3], v[162:165], v[88:91]
	v_mfma_f32_16x16x32_bf16 v[124:127], v[72:75], v[162:165], v[92:95]
	v_mfma_f32_16x16x32_bf16 v[108:111], v[0:3], v[170:173], v[108:111]
	v_mfma_f32_16x16x32_bf16 v[104:107], v[72:75], v[170:173], v[104:107]
	v_mfma_f32_16x16x32_bf16 v[100:103], v[0:3], v[210:213], v[100:103]
	v_mfma_f32_16x16x32_bf16 v[96:99], v[72:75], v[210:213], v[96:99]
	s_setprio 0
	s_barrier
	ds_read_b128 v[88:91], v153
	ds_read_b128 v[80:83], v153 offset:1024
	ds_read_b128 v[92:95], v153 offset:2048
	ds_read_b128 v[84:87], v153 offset:3072
	s_waitcnt vmcnt(0)
	s_barrier
	s_waitcnt lgkmcnt(0)
	s_setprio 1
	s_waitcnt lgkmcnt(0)
	v_mfma_f32_16x16x32_bf16 v[174:177], v[88:91], v[130:133], v[174:177]
	v_mfma_f32_16x16x32_bf16 v[130:133], v[92:95], v[130:133], v[178:181]
	v_mfma_f32_16x16x32_bf16 v[178:181], v[88:91], v[158:161], v[182:185]
	v_mfma_f32_16x16x32_bf16 v[158:161], v[92:95], v[158:161], v[186:189]
	v_mfma_f32_16x16x32_bf16 v[182:185], v[88:91], v[166:169], v[190:193]
	v_mfma_f32_16x16x32_bf16 v[166:169], v[92:95], v[166:169], v[194:197]
	v_mfma_f32_16x16x32_bf16 v[186:189], v[88:91], v[206:209], v[198:201]
	v_mfma_f32_16x16x32_bf16 v[190:193], v[92:95], v[206:209], v[202:205]
	v_mfma_f32_16x16x32_bf16 v[174:177], v[80:83], v[154:157], v[174:177]
	v_mfma_f32_16x16x32_bf16 v[130:133], v[84:87], v[154:157], v[130:133]
	v_mfma_f32_16x16x32_bf16 v[154:157], v[80:83], v[162:165], v[178:181]
	v_mfma_f32_16x16x32_bf16 v[158:161], v[84:87], v[162:165], v[158:161]
	v_mfma_f32_16x16x32_bf16 v[162:165], v[80:83], v[170:173], v[182:185]
	v_mfma_f32_16x16x32_bf16 v[166:169], v[84:87], v[170:173], v[166:169]
	v_mfma_f32_16x16x32_bf16 v[170:173], v[80:83], v[210:213], v[186:189]
	v_mfma_f32_16x16x32_bf16 v[178:181], v[84:87], v[210:213], v[190:193]
	s_setprio 0
	s_barrier
	v_mbcnt_lo_u32_b32 v128, -1, 0
	v_mbcnt_hi_u32_b32 v128, -1, v128
	v_cvt_pk_bf16_f32 v112, v112, v113
	v_cvt_pk_bf16_f32 v113, v114, v115
	v_cvt_pk_bf16_f32 v114, v116, v117
	v_cvt_pk_bf16_f32 v115, v118, v119
	s_lshl_b32 s89, s66, 9
	v_add_u32_e32 v153, s74, v128
	v_ashrrev_i32_e32 v182, 6, v153
	v_and_b32_e32 v183, 15, v128
	v_and_b32_e32 v184, 48, v128
	v_mul_lo_u32 v185, v182, s79
	v_bfe_u32 v186, v128, 3, 3
	v_lshlrev_b32_e32 v128, 4, v128
	v_add_u32_e32 v185, 0x20000, v185
	v_lshrrev_b32_e32 v153, 2, v153
	v_and_b32_e32 v128, 0x70, v128
	v_mul_u32_u24_e32 v183, 0x90, v183
	v_and_b32_e32 v153, 64, v153
	v_add3_u32 v183, v185, v183, v184
	v_or_b32_e32 v184, v185, v128
	v_or3_b32 v153, s96, v153, v186
	v_mad_u32_u24 v184, v186, s81, v184
	ds_write_b128 v183, v[112:115]
	v_cvt_pk_bf16_f32 v112, v174, v175
	v_cvt_pk_bf16_f32 v113, v176, v177
	v_cvt_pk_bf16_f32 v114, v130, v131
	v_cvt_pk_bf16_f32 v115, v132, v133
	ds_write_b128 v183, v[112:115] offset:64
	v_lshlrev_b32_e32 v182, 7, v182
	ds_read_b128 v[112:115], v184
	v_lshlrev_b32_e32 v116, 12, v153
	v_and_or_b32 v116, v182, s82, v116
	v_or3_b32 v128, v116, s89, v128
	ds_read_b128 v[116:119], v184 offset:1152
	v_lshl_add_u64 v[130:131], s[0:1], 0, v[128:129]
	s_mov_b32 s20, 0x8000
	s_waitcnt lgkmcnt(0)
	global_store_dwordx4 v128, v[112:115], s[0:1]
	v_cvt_pk_bf16_f32 v108, v108, v109
	v_cvt_pk_bf16_f32 v109, v110, v111
	v_cvt_pk_bf16_f32 v110, v104, v105
	v_cvt_pk_bf16_f32 v111, v106, v107
	v_cvt_pk_bf16_f32 v104, v162, v163
	s_nop 1
	v_add_co_u32_e32 v112, vcc, s20, v130
	v_cvt_pk_bf16_f32 v114, v124, v125
	v_cvt_pk_bf16_f32 v115, v126, v127
	v_cvt_pk_bf16_f32 v105, v164, v165
	v_cvt_pk_bf16_f32 v106, v166, v167
	s_nop 1
	v_addc_co_u32_e32 v113, vcc, 0, v131, vcc
	global_store_dwordx4 v[112:113], v[116:119], off
	v_cvt_pk_bf16_f32 v112, v120, v121
	v_cvt_pk_bf16_f32 v113, v122, v123
	ds_write_b128 v183, v[112:115]
	v_cvt_pk_bf16_f32 v112, v154, v155
	v_cvt_pk_bf16_f32 v113, v156, v157
	v_cvt_pk_bf16_f32 v114, v158, v159
	v_cvt_pk_bf16_f32 v115, v160, v161
	ds_write_b128 v183, v[112:115] offset:64
	ds_read_b128 v[112:115], v184
	ds_read_b128 v[116:119], v184 offset:1152
	v_add_co_u32_e32 v120, vcc, s76, v130
	ds_write_b128 v183, v[108:111]
	v_cvt_pk_bf16_f32 v107, v168, v169
	ds_write_b128 v183, v[104:107] offset:64
	v_addc_co_u32_e32 v121, vcc, 0, v131, vcc
	ds_read_b128 v[104:107], v184
	ds_read_b128 v[108:111], v184 offset:1152
	s_waitcnt lgkmcnt(0)
	global_store_dwordx4 v[120:121], v[112:115], off
	v_cvt_pk_bf16_f32 v100, v100, v101
	v_cvt_pk_bf16_f32 v101, v102, v103
	v_cvt_pk_bf16_f32 v102, v96, v97
	v_cvt_pk_bf16_f32 v103, v98, v99
	ds_write_b128 v183, v[100:103]
	s_nop 0
	v_add_co_u32_e32 v112, vcc, s77, v130
	v_cvt_pk_bf16_f32 v96, v170, v171
	v_cvt_pk_bf16_f32 v97, v172, v173
	v_cvt_pk_bf16_f32 v98, v178, v179
	v_cvt_pk_bf16_f32 v99, v180, v181
	s_nop 1
	v_addc_co_u32_e32 v113, vcc, 0, v131, vcc
	global_store_dwordx4 v[112:113], v[116:119], off
	v_add_co_u32_e32 v112, vcc, s80, v130
	ds_write_b128 v183, v[96:99] offset:64
	s_nop 0
	v_addc_co_u32_e32 v113, vcc, 0, v131, vcc
	ds_read_b128 v[96:99], v184
	ds_read_b128 v[100:103], v184 offset:1152
	global_store_dwordx4 v[112:113], v[104:107], off
	s_nop 1
	v_add_co_u32_e32 v104, vcc, s83, v130
	s_nop 1
	v_addc_co_u32_e32 v105, vcc, 0, v131, vcc
	global_store_dwordx4 v[104:105], v[108:111], off
	v_add_co_u32_e32 v104, vcc, s85, v130
	s_nop 1
	v_addc_co_u32_e32 v105, vcc, 0, v131, vcc
	s_waitcnt lgkmcnt(0)
	global_store_dwordx4 v[104:105], v[96:99], off
	s_nop 1
	v_add_co_u32_e32 v96, vcc, s87, v130
	s_nop 1
	v_addc_co_u32_e32 v97, vcc, 0, v131, vcc
	global_store_dwordx4 v[96:97], v[100:103], off
	ds_read_b128 v[96:99], v152 offset:49152
	ds_read_b128 v[100:103], v152 offset:50176
	ds_read_b128 v[104:107], v151 offset:49152
	ds_read_b128 v[108:111], v151 offset:50176
	ds_read_b128 v[112:115], v150 offset:49152
	ds_read_b128 v[116:119], v150 offset:50176
	ds_read_b128 v[120:123], v149 offset:49152
	ds_read_b128 v[124:127], v149 offset:50176
	s_barrier
	s_waitcnt lgkmcnt(0)
	s_setprio 1
	s_waitcnt lgkmcnt(0)
	v_mfma_f32_16x16x32_bf16 v[32:35], v[8:11], v[96:99], v[32:35]
	v_mfma_f32_16x16x32_bf16 v[36:39], v[76:79], v[96:99], v[36:39]
	v_mfma_f32_16x16x32_bf16 v[40:43], v[8:11], v[104:107], v[40:43]
	v_mfma_f32_16x16x32_bf16 v[130:133], v[76:79], v[104:107], v[44:47]
	v_mfma_f32_16x16x32_bf16 v[150:153], v[8:11], v[112:115], v[48:51]
	v_mfma_f32_16x16x32_bf16 v[52:55], v[76:79], v[112:115], v[52:55]
	v_mfma_f32_16x16x32_bf16 v[8:11], v[8:11], v[120:123], v[56:59]
	v_mfma_f32_16x16x32_bf16 v[60:63], v[76:79], v[120:123], v[60:63]
	v_mfma_f32_16x16x32_bf16 v[56:59], v[0:3], v[100:103], v[32:35]
	v_mfma_f32_16x16x32_bf16 v[48:51], v[72:75], v[100:103], v[36:39]
	v_mfma_f32_16x16x32_bf16 v[44:47], v[0:3], v[108:111], v[40:43]
	v_mfma_f32_16x16x32_bf16 v[40:43], v[72:75], v[108:111], v[130:133]
	v_mfma_f32_16x16x32_bf16 v[36:39], v[0:3], v[116:119], v[150:153]
	v_mfma_f32_16x16x32_bf16 v[32:35], v[72:75], v[116:119], v[52:55]
	v_mfma_f32_16x16x32_bf16 v[8:11], v[0:3], v[124:127], v[8:11]
	v_mfma_f32_16x16x32_bf16 v[0:3], v[72:75], v[124:127], v[60:63]
	s_setprio 0
	s_setprio 1
	v_mfma_f32_16x16x32_bf16 v[4:7], v[88:91], v[96:99], v[4:7]
	v_mfma_f32_16x16x32_bf16 v[12:15], v[92:95], v[96:99], v[12:15]
	v_mfma_f32_16x16x32_bf16 v[16:19], v[88:91], v[104:107], v[16:19]
	v_mfma_f32_16x16x32_bf16 v[20:23], v[92:95], v[104:107], v[20:23]
	v_mfma_f32_16x16x32_bf16 v[72:75], v[88:91], v[112:115], v[24:27]
	v_mfma_f32_16x16x32_bf16 v[76:79], v[92:95], v[112:115], v[28:31]
	v_mfma_f32_16x16x32_bf16 v[64:67], v[88:91], v[120:123], v[64:67]
	v_mfma_f32_16x16x32_bf16 v[68:71], v[92:95], v[120:123], v[68:71]
	v_mfma_f32_16x16x32_bf16 v[60:63], v[80:83], v[100:103], v[4:7]
	v_mfma_f32_16x16x32_bf16 v[52:55], v[84:87], v[100:103], v[12:15]
	v_mfma_f32_16x16x32_bf16 v[28:31], v[80:83], v[108:111], v[16:19]
	v_mfma_f32_16x16x32_bf16 v[24:27], v[84:87], v[108:111], v[20:23]
	v_mfma_f32_16x16x32_bf16 v[20:23], v[80:83], v[116:119], v[72:75]
	v_mfma_f32_16x16x32_bf16 v[16:19], v[84:87], v[116:119], v[76:79]
	v_mfma_f32_16x16x32_bf16 v[12:15], v[80:83], v[124:127], v[64:67]
	v_mfma_f32_16x16x32_bf16 v[4:7], v[84:87], v[124:127], v[68:71]
	s_setprio 0
	v_cmp_gt_u32_e32 vcc, s88, v135
	s_barrier
	s_and_saveexec_b64 s[66:67], vcc
	s_cbranch_execz .LBB0_564
	s_barrier
